# adds flag-selected relaxed vmcnt on the first two in-loop waits of each GEMM unit after an epilogue (store acks no longer waited); keeps mid_opt LDS fix
# baseline (speedup 1.0000x reference)
_Z6mk_fwd4Args:
	s_mov_b32 s98, 0
	s_load_dwordx8 s[64:71], s[0:1], 0xa0
	s_load_dwordx8 s[72:79], s[0:1], 0x80
	s_load_dword s33, s[0:1], 0xc0
	s_mov_b32 s94, s2
	s_add_u32 s2, s0, 0xc0
	s_addc_u32 s3, s1, 0
	v_readfirstlane_b32 s6, v0
	v_writelane_b32 v254, s2, 0
	v_cmp_gt_u32_e32 vcc, 64, v0
	v_lshl_add_u32 v183, v0, 2, 0
	v_writelane_b32 v254, s3, 1
	s_and_saveexec_b64 s[2:3], vcc
	v_lshl_add_u32 v1, v0, 2, 0
	v_add_u32_e32 v1, 0x23f00, v1
	v_mov_b32_e32 v2, 0
	ds_write_b32 v1, v2
	s_or_b64 exec, exec, s[2:3]
	s_waitcnt lgkmcnt(0)
	s_barrier
	s_add_u32 s96, s68, 0x1000
	s_getreg_b32 s2, hwreg(HW_REG_XCC_ID, 0, 4)
	s_addc_u32 s97, s69, 0
	s_and_b32 s2, s2, 15
	v_writelane_b32 v254, s2, 2
	v_cmp_ne_u32_e64 s[2:3], 0, v0
	v_cmp_eq_u32_e64 s[4:5], 0, v0
	s_nop 0
	v_writelane_b32 v254, s2, 3
	s_nop 1
	v_writelane_b32 v254, s3, 4
	s_mov_b64 s[2:3], exec
	v_writelane_b32 v254, s4, 5
	s_nop 1
	v_writelane_b32 v254, s5, 6
	s_and_b64 s[4:5], s[2:3], s[4:5]
	s_mov_b64 exec, s[4:5]
	s_cbranch_execz .LBB0_5
	s_mov_b64 s[4:5], exec
	v_mbcnt_lo_u32_b32 v1, s4, 0
	v_mbcnt_hi_u32_b32 v1, s5, v1
	v_cmp_eq_u32_e32 vcc, 0, v1
	s_and_b64 s[8:9], exec, vcc
	s_mov_b64 exec, s[8:9]
	s_cbranch_execz .LBB0_5
	v_readlane_b32 s7, v254, 2
	s_lshl_b32 s7, s7, 8
	s_bcnt1_i32_b64 s4, s[4:5]
	v_mov_b32_e32 v1, s7
	v_mov_b32_e32 v2, s4
	global_atomic_add v1, v2, s[96:97] offset:1024

.LBB0_177:
	ds_read_b128 v[164:167], v153
	ds_read_b128 v[168:171], v153 offset:1024
	ds_read_b128 v[172:175], v153 offset:2048
	ds_read_b128 v[176:179], v153 offset:3072
	ds_read_b128 v[184:187], v160
	ds_read_b128 v[188:191], v160 offset:1024
	ds_read_b128 v[192:195], v160 offset:2048
	ds_read_b128 v[196:199], v160 offset:3072
	s_add_u32 s28, s26, 0xfff00080
	s_addc_u32 s29, s27, -1
	s_cmp_eq_u32 s80, 60
	s_cselect_b32 s31, s19, s29
	s_cselect_b32 s30, s58, s28
	s_cselect_b32 s29, s17, s63
	s_cselect_b32 s28, s59, s62
	v_lshl_add_u64 v[148:149], s[26:27], 0, v[140:141]
	s_add_i32 m0, s25, 0xc000
	ds_read_b128 v[200:203], v161
	ds_read_b128 v[204:207], v161 offset:1024
	ds_read_b128 v[208:211], v161 offset:2048
	ds_read_b128 v[212:215], v161 offset:3072
	ds_read_b128 v[216:219], v161 offset:4096
	ds_read_b128 v[220:223], v161 offset:5120
	ds_read_b128 v[224:227], v161 offset:6144
	ds_read_b128 v[228:231], v161 offset:7168
	global_load_lds_dwordx4 v[148:149], off
	v_lshl_add_u64 v[148:149], s[26:27], 0, v[142:143]
	s_add_i32 m0, s25, 0xe000
	s_nop 0
	global_load_lds_dwordx4 v[148:149], off
	s_cmp_eq_u32 s98, 0
	s_cbranch_scc1 .Lgw177_0a
	s_waitcnt vmcnt(24)
	s_branch .Lgw177_0b
.Lgw177_0a:
	s_waitcnt vmcnt(8)
.Lgw177_0b:
	s_waitcnt lgkmcnt(0)
	s_barrier
	s_setprio 1
	s_waitcnt lgkmcnt(0)
	v_mfma_f32_16x16x32_bf16 v[126:129], v[164:167], v[200:203], v[126:129]
	v_mfma_f32_16x16x32_bf16 v[122:125], v[172:175], v[200:203], v[122:125]
	v_mfma_f32_16x16x32_bf16 v[118:121], v[164:167], v[208:211], v[118:121]
	v_mfma_f32_16x16x32_bf16 v[110:113], v[172:175], v[208:211], v[110:113]
	v_mfma_f32_16x16x32_bf16 v[102:105], v[164:167], v[216:219], v[102:105]
	v_mfma_f32_16x16x32_bf16 v[94:97], v[172:175], v[216:219], v[94:97]
	v_mfma_f32_16x16x32_bf16 v[86:89], v[164:167], v[224:227], v[86:89]
	v_mfma_f32_16x16x32_bf16 v[78:81], v[172:175], v[224:227], v[78:81]
	v_mfma_f32_16x16x32_bf16 v[126:129], v[168:171], v[204:207], v[126:129]
	v_mfma_f32_16x16x32_bf16 v[122:125], v[176:179], v[204:207], v[122:125]
	v_mfma_f32_16x16x32_bf16 v[118:121], v[168:171], v[212:215], v[118:121]
	v_mfma_f32_16x16x32_bf16 v[110:113], v[176:179], v[212:215], v[110:113]
	v_mfma_f32_16x16x32_bf16 v[102:105], v[168:171], v[220:223], v[102:105]
	v_mfma_f32_16x16x32_bf16 v[94:97], v[176:179], v[220:223], v[94:97]
	v_mfma_f32_16x16x32_bf16 v[86:89], v[168:171], v[228:231], v[86:89]
	v_mfma_f32_16x16x32_bf16 v[78:81], v[176:179], v[228:231], v[78:81]
	s_setprio 0
	s_setprio 1
	v_mfma_f32_16x16x32_bf16 v[114:117], v[184:187], v[200:203], v[114:117]
	v_mfma_f32_16x16x32_bf16 v[106:109], v[192:195], v[200:203], v[106:109]
	v_mfma_f32_16x16x32_bf16 v[98:101], v[184:187], v[208:211], v[98:101]
	v_mfma_f32_16x16x32_bf16 v[90:93], v[192:195], v[208:211], v[90:93]
	v_mfma_f32_16x16x32_bf16 v[82:85], v[184:187], v[216:219], v[82:85]
	v_mfma_f32_16x16x32_bf16 v[74:77], v[192:195], v[216:219], v[74:77]
	v_mfma_f32_16x16x32_bf16 v[70:73], v[184:187], v[224:227], v[70:73]
	v_mfma_f32_16x16x32_bf16 v[66:69], v[192:195], v[224:227], v[66:69]
	v_mfma_f32_16x16x32_bf16 v[114:117], v[188:191], v[204:207], v[114:117]
	v_mfma_f32_16x16x32_bf16 v[106:109], v[196:199], v[204:207], v[106:109]
	v_mfma_f32_16x16x32_bf16 v[98:101], v[188:191], v[212:215], v[98:101]
	v_mfma_f32_16x16x32_bf16 v[90:93], v[196:199], v[212:215], v[90:93]
	v_mfma_f32_16x16x32_bf16 v[82:85], v[188:191], v[220:223], v[82:85]
	v_mfma_f32_16x16x32_bf16 v[74:77], v[196:199], v[220:223], v[74:77]
	v_mfma_f32_16x16x32_bf16 v[70:73], v[188:191], v[228:231], v[70:73]
	v_mfma_f32_16x16x32_bf16 v[66:69], v[196:199], v[228:231], v[66:69]
	s_setprio 0
	s_barrier
	s_add_i32 s81, s51, s34
	v_lshl_add_u64 v[148:149], s[28:29], 0, v[132:133]
	s_mov_b32 m0, s81
	ds_read_b128 v[200:203], v161 offset:16384
	ds_read_b128 v[204:207], v161 offset:17408
	ds_read_b128 v[208:211], v161 offset:18432
	ds_read_b128 v[212:215], v161 offset:19456
	ds_read_b128 v[216:219], v161 offset:20480
	ds_read_b128 v[220:223], v161 offset:21504
	ds_read_b128 v[224:227], v161 offset:22528
	ds_read_b128 v[228:231], v161 offset:23552
	global_load_lds_dwordx4 v[148:149], off
	s_add_i32 m0, s81, 0x2000
	s_add_u32 s82, s28, 0x100000
	v_lshl_add_u64 v[180:181], s[28:29], 0, v[136:137]
	s_addc_u32 s83, s29, 0
	s_add_i32 s81, s52, s34
	global_load_lds_dwordx4 v[180:181], off
	v_lshl_add_u64 v[232:233], s[82:83], 0, v[132:133]
	s_mov_b32 m0, s81
	v_lshl_add_u64 v[234:235], s[30:31], 0, v[134:135]
	global_load_lds_dwordx4 v[232:233], off
	v_lshl_add_u64 v[232:233], s[82:83], 0, v[136:137]
	s_add_i32 m0, s81, 0x2000
	s_nop 0
	global_load_lds_dwordx4 v[232:233], off
	v_lshl_add_u64 v[232:233], s[30:31], 0, v[130:131]
	s_mov_b32 m0, s25
	s_nop 0
	global_load_lds_dwordx4 v[232:233], off
	s_mov_b32 m0, s43
	s_nop 0
	global_load_lds_dwordx4 v[234:235], off
	s_cmp_eq_u32 s98, 0
	s_cbranch_scc1 .Lgw177_1a
	s_waitcnt vmcnt(24)
	s_branch .Lgw177_1b

.Lgw177_1b:
	s_mov_b32 s98, 0
	s_waitcnt lgkmcnt(0)
	s_barrier
	s_setprio 1
	s_waitcnt lgkmcnt(0)
	v_mfma_f32_16x16x32_bf16 v[62:65], v[164:167], v[200:203], v[62:65]
	v_mfma_f32_16x16x32_bf16 v[58:61], v[172:175], v[200:203], v[58:61]
	v_mfma_f32_16x16x32_bf16 v[54:57], v[164:167], v[208:211], v[54:57]
	v_mfma_f32_16x16x32_bf16 v[46:49], v[172:175], v[208:211], v[46:49]
	v_mfma_f32_16x16x32_bf16 v[38:41], v[164:167], v[216:219], v[38:41]
	v_mfma_f32_16x16x32_bf16 v[30:33], v[172:175], v[216:219], v[30:33]
	v_mfma_f32_16x16x32_bf16 v[22:25], v[164:167], v[224:227], v[22:25]
	v_mfma_f32_16x16x32_bf16 v[14:17], v[172:175], v[224:227], v[14:17]
	v_mfma_f32_16x16x32_bf16 v[62:65], v[168:171], v[204:207], v[62:65]
	v_mfma_f32_16x16x32_bf16 v[58:61], v[176:179], v[204:207], v[58:61]
	v_mfma_f32_16x16x32_bf16 v[54:57], v[168:171], v[212:215], v[54:57]
	v_mfma_f32_16x16x32_bf16 v[46:49], v[176:179], v[212:215], v[46:49]
	v_mfma_f32_16x16x32_bf16 v[38:41], v[168:171], v[220:223], v[38:41]
	v_mfma_f32_16x16x32_bf16 v[30:33], v[176:179], v[220:223], v[30:33]
	v_mfma_f32_16x16x32_bf16 v[22:25], v[168:171], v[228:231], v[22:25]
	v_mfma_f32_16x16x32_bf16 v[14:17], v[176:179], v[228:231], v[14:17]
	s_setprio 0
	s_setprio 1
	v_mfma_f32_16x16x32_bf16 v[50:53], v[184:187], v[200:203], v[50:53]
	v_mfma_f32_16x16x32_bf16 v[42:45], v[192:195], v[200:203], v[42:45]
	v_mfma_f32_16x16x32_bf16 v[34:37], v[184:187], v[208:211], v[34:37]
	v_mfma_f32_16x16x32_bf16 v[26:29], v[192:195], v[208:211], v[26:29]
	v_mfma_f32_16x16x32_bf16 v[18:21], v[184:187], v[216:219], v[18:21]
	v_mfma_f32_16x16x32_bf16 v[10:13], v[192:195], v[216:219], v[10:13]
	v_mfma_f32_16x16x32_bf16 v[6:9], v[184:187], v[224:227], v[6:9]
	v_mfma_f32_16x16x32_bf16 v[2:5], v[192:195], v[224:227], v[2:5]
	v_mfma_f32_16x16x32_bf16 v[50:53], v[188:191], v[204:207], v[50:53]
	v_mfma_f32_16x16x32_bf16 v[42:45], v[196:199], v[204:207], v[42:45]
	v_mfma_f32_16x16x32_bf16 v[34:37], v[188:191], v[212:215], v[34:37]
	v_mfma_f32_16x16x32_bf16 v[26:29], v[196:199], v[212:215], v[26:29]
	v_mfma_f32_16x16x32_bf16 v[18:21], v[188:191], v[220:223], v[18:21]
	v_mfma_f32_16x16x32_bf16 v[10:13], v[196:199], v[220:223], v[10:13]
	v_mfma_f32_16x16x32_bf16 v[6:9], v[188:191], v[228:231], v[6:9]
	v_mfma_f32_16x16x32_bf16 v[2:5], v[196:199], v[228:231], v[2:5]
	s_setprio 0
	s_barrier
	s_add_i32 s81, 0, 0x18000
	v_add_u32_e32 v162, s81, v151
	s_add_i32 s82, 0, 0x1c000
	ds_read_b128 v[164:167], v162
	ds_read_b128 v[168:171], v162 offset:1024
	ds_read_b128 v[172:175], v162 offset:2048
	ds_read_b128 v[176:179], v162 offset:3072
	v_add_u32_e32 v162, s82, v151
	ds_read_b128 v[184:187], v162
	ds_read_b128 v[188:191], v162 offset:1024
	ds_read_b128 v[192:195], v162 offset:2048
	ds_read_b128 v[196:199], v162 offset:3072
	s_add_u32 s30, s30, 0x100000
	s_addc_u32 s31, s31, 0
	s_mov_b32 m0, s44
	v_lshl_add_u64 v[236:237], s[30:31], 0, v[130:131]
	ds_read_b128 v[200:203], v161 offset:32768
	ds_read_b128 v[204:207], v161 offset:33792
	ds_read_b128 v[208:211], v161 offset:34816
	ds_read_b128 v[212:215], v161 offset:35840
	ds_read_b128 v[216:219], v161 offset:36864
	ds_read_b128 v[220:223], v161 offset:37888
	ds_read_b128 v[224:227], v161 offset:38912
	ds_read_b128 v[228:231], v161 offset:39936
	global_load_lds_dwordx4 v[236:237], off
	v_lshl_add_u64 v[236:237], s[30:31], 0, v[134:135]
	s_mov_b32 m0, s45
	s_nop 0
	global_load_lds_dwordx4 v[236:237], off
	s_waitcnt vmcnt(8)
	s_waitcnt lgkmcnt(0)
	s_barrier
	s_setprio 1
	s_waitcnt lgkmcnt(0)
	v_mfma_f32_16x16x32_bf16 v[126:129], v[164:167], v[200:203], v[126:129]
	v_mfma_f32_16x16x32_bf16 v[122:125], v[172:175], v[200:203], v[122:125]
	v_mfma_f32_16x16x32_bf16 v[118:121], v[164:167], v[208:211], v[118:121]
	v_mfma_f32_16x16x32_bf16 v[110:113], v[172:175], v[208:211], v[110:113]
	v_mfma_f32_16x16x32_bf16 v[102:105], v[164:167], v[216:219], v[102:105]
	v_mfma_f32_16x16x32_bf16 v[94:97], v[172:175], v[216:219], v[94:97]
	v_mfma_f32_16x16x32_bf16 v[86:89], v[164:167], v[224:227], v[86:89]
	v_mfma_f32_16x16x32_bf16 v[78:81], v[172:175], v[224:227], v[78:81]
	v_mfma_f32_16x16x32_bf16 v[126:129], v[168:171], v[204:207], v[126:129]
	v_mfma_f32_16x16x32_bf16 v[122:125], v[176:179], v[204:207], v[122:125]
	v_mfma_f32_16x16x32_bf16 v[118:121], v[168:171], v[212:215], v[118:121]
	v_mfma_f32_16x16x32_bf16 v[110:113], v[176:179], v[212:215], v[110:113]
	v_mfma_f32_16x16x32_bf16 v[102:105], v[168:171], v[220:223], v[102:105]
	v_mfma_f32_16x16x32_bf16 v[94:97], v[176:179], v[220:223], v[94:97]
	v_mfma_f32_16x16x32_bf16 v[86:89], v[168:171], v[228:231], v[86:89]
	v_mfma_f32_16x16x32_bf16 v[78:81], v[176:179], v[228:231], v[78:81]
	s_setprio 0
	s_setprio 1
	v_mfma_f32_16x16x32_bf16 v[114:117], v[184:187], v[200:203], v[114:117]
	v_mfma_f32_16x16x32_bf16 v[106:109], v[192:195], v[200:203], v[106:109]
	v_mfma_f32_16x16x32_bf16 v[98:101], v[184:187], v[208:211], v[98:101]
	v_mfma_f32_16x16x32_bf16 v[90:93], v[192:195], v[208:211], v[90:93]
	v_mfma_f32_16x16x32_bf16 v[82:85], v[184:187], v[216:219], v[82:85]
	v_mfma_f32_16x16x32_bf16 v[74:77], v[192:195], v[216:219], v[74:77]
	v_mfma_f32_16x16x32_bf16 v[70:73], v[184:187], v[224:227], v[70:73]
	v_mfma_f32_16x16x32_bf16 v[66:69], v[192:195], v[224:227], v[66:69]
	v_mfma_f32_16x16x32_bf16 v[114:117], v[188:191], v[204:207], v[114:117]
	v_mfma_f32_16x16x32_bf16 v[106:109], v[196:199], v[204:207], v[106:109]
	v_mfma_f32_16x16x32_bf16 v[98:101], v[188:191], v[212:215], v[98:101]
	v_mfma_f32_16x16x32_bf16 v[90:93], v[196:199], v[212:215], v[90:93]
	v_mfma_f32_16x16x32_bf16 v[82:85], v[188:191], v[220:223], v[82:85]
	v_mfma_f32_16x16x32_bf16 v[74:77], v[196:199], v[220:223], v[74:77]
	v_mfma_f32_16x16x32_bf16 v[70:73], v[188:191], v[228:231], v[70:73]
	v_mfma_f32_16x16x32_bf16 v[66:69], v[196:199], v[228:231], v[66:69]
	s_setprio 0
	s_barrier
	s_add_i32 s30, s81, s34
	v_lshl_add_u64 v[148:149], v[148:149], 0, s[12:13]
	s_mov_b32 m0, s30
	ds_read_b128 v[200:203], v161 offset:49152
	ds_read_b128 v[204:207], v161 offset:50176
	ds_read_b128 v[208:211], v161 offset:51200
	ds_read_b128 v[212:215], v161 offset:52224
	ds_read_b128 v[216:219], v161 offset:53248
	ds_read_b128 v[220:223], v161 offset:54272
	ds_read_b128 v[224:227], v161 offset:55296
	ds_read_b128 v[228:231], v161 offset:56320
	global_load_lds_dwordx4 v[148:149], off
	s_add_i32 m0, s30, 0x2000
	s_add_u32 s28, s28, 0x100080
	v_lshl_add_u64 v[148:149], v[180:181], 0, s[12:13]
	s_addc_u32 s29, s29, 0
	s_add_i32 s30, s82, s34
	global_load_lds_dwordx4 v[148:149], off
	v_lshl_add_u64 v[148:149], s[28:29], 0, v[132:133]
	s_mov_b32 m0, s30
	s_nop 0
	global_load_lds_dwordx4 v[148:149], off
	v_lshl_add_u64 v[148:149], s[28:29], 0, v[136:137]
	s_add_i32 m0, s30, 0x2000
	s_nop 0
	global_load_lds_dwordx4 v[148:149], off
	v_lshl_add_u64 v[148:149], v[232:233], 0, s[12:13]
	s_mov_b32 m0, s46
	s_nop 0
	global_load_lds_dwordx4 v[148:149], off
	v_lshl_add_u64 v[148:149], v[234:235], 0, s[12:13]
	s_mov_b32 m0, s47
	s_nop 0
	global_load_lds_dwordx4 v[148:149], off
	s_waitcnt vmcnt(8)
	s_waitcnt lgkmcnt(0)
	s_barrier
	s_setprio 1
	s_waitcnt lgkmcnt(0)
	v_mfma_f32_16x16x32_bf16 v[62:65], v[164:167], v[200:203], v[62:65]
	v_mfma_f32_16x16x32_bf16 v[58:61], v[172:175], v[200:203], v[58:61]
	v_mfma_f32_16x16x32_bf16 v[54:57], v[164:167], v[208:211], v[54:57]
	v_mfma_f32_16x16x32_bf16 v[46:49], v[172:175], v[208:211], v[46:49]
	v_mfma_f32_16x16x32_bf16 v[38:41], v[164:167], v[216:219], v[38:41]
	v_mfma_f32_16x16x32_bf16 v[30:33], v[172:175], v[216:219], v[30:33]
	v_mfma_f32_16x16x32_bf16 v[22:25], v[164:167], v[224:227], v[22:25]
	v_mfma_f32_16x16x32_bf16 v[14:17], v[172:175], v[224:227], v[14:17]
	v_mfma_f32_16x16x32_bf16 v[62:65], v[168:171], v[204:207], v[62:65]
	v_mfma_f32_16x16x32_bf16 v[58:61], v[176:179], v[204:207], v[58:61]
	v_mfma_f32_16x16x32_bf16 v[54:57], v[168:171], v[212:215], v[54:57]
	v_mfma_f32_16x16x32_bf16 v[46:49], v[176:179], v[212:215], v[46:49]
	v_mfma_f32_16x16x32_bf16 v[38:41], v[168:171], v[220:223], v[38:41]
	v_mfma_f32_16x16x32_bf16 v[30:33], v[176:179], v[220:223], v[30:33]
	v_mfma_f32_16x16x32_bf16 v[22:25], v[168:171], v[228:231], v[22:25]
	v_mfma_f32_16x16x32_bf16 v[14:17], v[176:179], v[228:231], v[14:17]
	s_setprio 0
	s_setprio 1
	v_mfma_f32_16x16x32_bf16 v[50:53], v[184:187], v[200:203], v[50:53]
	v_mfma_f32_16x16x32_bf16 v[42:45], v[192:195], v[200:203], v[42:45]
	v_mfma_f32_16x16x32_bf16 v[34:37], v[184:187], v[208:211], v[34:37]
	v_mfma_f32_16x16x32_bf16 v[26:29], v[192:195], v[208:211], v[26:29]
	v_mfma_f32_16x16x32_bf16 v[18:21], v[184:187], v[216:219], v[18:21]
	v_mfma_f32_16x16x32_bf16 v[10:13], v[192:195], v[216:219], v[10:13]
	v_mfma_f32_16x16x32_bf16 v[6:9], v[184:187], v[224:227], v[6:9]
	v_mfma_f32_16x16x32_bf16 v[2:5], v[192:195], v[224:227], v[2:5]
	v_mfma_f32_16x16x32_bf16 v[50:53], v[188:191], v[204:207], v[50:53]
	v_mfma_f32_16x16x32_bf16 v[42:45], v[196:199], v[204:207], v[42:45]
	v_mfma_f32_16x16x32_bf16 v[34:37], v[188:191], v[212:215], v[34:37]
	v_mfma_f32_16x16x32_bf16 v[26:29], v[196:199], v[212:215], v[26:29]
	v_mfma_f32_16x16x32_bf16 v[18:21], v[188:191], v[220:223], v[18:21]
	v_mfma_f32_16x16x32_bf16 v[10:13], v[196:199], v[220:223], v[10:13]
	v_mfma_f32_16x16x32_bf16 v[6:9], v[188:191], v[228:231], v[6:9]
	v_mfma_f32_16x16x32_bf16 v[2:5], v[196:199], v[228:231], v[2:5]
	s_setprio 0
	s_barrier
	s_add_i32 s80, s80, 2
	s_add_u32 s26, s26, 0x100
	s_addc_u32 s27, s27, 0
	s_add_u32 s62, s62, 0x100
	s_addc_u32 s63, s63, 0
	s_cmp_gt_u32 s80, 61
	s_cbranch_scc0 .LBB0_177
	s_and_b64 vcc, exec, s[14:15]
	s_cbranch_vccz .LBB0_180
	s_barrier
.LBB0_180:
	v_lshl_add_u32 v164, s24, 8, v150
	v_lshl_or_b32 v148, s53, 8, v152
	v_ashrrev_i32_e32 v165, 31, v164
	v_ashrrev_i32_e32 v149, 31, v148
	v_lshlrev_b64 v[166:167], 13, v[164:165]
	v_lshl_add_u64 v[166:167], s[10:11], 0, v[166:167]
	v_lshlrev_b64 v[168:169], 1, v[148:149]
	v_lshl_add_u64 v[148:149], v[166:167], 0, v[168:169]
	v_cvt_pk_bf16_f32 v126, v126, v127
	v_cvt_pk_bf16_f32 v127, v128, v129
	v_cvt_pk_bf16_f32 v128, v122, v123
	v_cvt_pk_bf16_f32 v129, v124, v125
	global_store_dwordx4 v[148:149], v[126:129], off
	v_cvt_pk_bf16_f32 v114, v114, v115
	v_cvt_pk_bf16_f32 v115, v116, v117
	v_cvt_pk_bf16_f32 v116, v106, v107
	v_or_b32_e32 v106, 16, v164
	v_ashrrev_i32_e32 v107, 31, v106
	v_lshlrev_b64 v[106:107], 13, v[106:107]
	v_lshl_add_u64 v[106:107], s[10:11], 0, v[106:107]
	v_cvt_pk_bf16_f32 v117, v108, v109
	global_store_dwordx4 v[148:149], v[114:117], off offset:256
	s_mov_b32 s17, 0x100000
	s_mov_b64 s[26:27], 0x100000
	v_lshl_add_u64 v[114:115], v[106:107], 0, v[168:169]
	v_cvt_pk_bf16_f32 v106, v118, v119
	v_cvt_pk_bf16_f32 v107, v120, v121
	v_cvt_pk_bf16_f32 v108, v110, v111
	v_cvt_pk_bf16_f32 v109, v112, v113
	global_store_dwordx4 v[114:115], v[106:109], off
	v_cvt_pk_bf16_f32 v98, v98, v99
	v_cvt_pk_bf16_f32 v99, v100, v101
	v_cvt_pk_bf16_f32 v100, v90, v91
	v_or_b32_e32 v90, 32, v164
	v_ashrrev_i32_e32 v91, 31, v90
	v_lshlrev_b64 v[90:91], 13, v[90:91]
	v_lshl_add_u64 v[90:91], s[10:11], 0, v[90:91]
	v_cvt_pk_bf16_f32 v101, v92, v93
	global_store_dwordx4 v[114:115], v[98:101], off offset:256
	s_nop 1
	v_lshl_add_u64 v[98:99], v[90:91], 0, v[168:169]
	v_cvt_pk_bf16_f32 v90, v102, v103
	v_cvt_pk_bf16_f32 v91, v104, v105
	v_cvt_pk_bf16_f32 v92, v94, v95
	v_cvt_pk_bf16_f32 v93, v96, v97
	global_store_dwordx4 v[98:99], v[90:93], off
	v_cvt_pk_bf16_f32 v82, v82, v83
	v_cvt_pk_bf16_f32 v83, v84, v85
	v_cvt_pk_bf16_f32 v84, v74, v75
	v_or_b32_e32 v74, 48, v164
	v_ashrrev_i32_e32 v75, 31, v74
	v_lshlrev_b64 v[74:75], 13, v[74:75]
	v_lshl_add_u64 v[74:75], s[10:11], 0, v[74:75]
	v_cvt_pk_bf16_f32 v85, v76, v77
	global_store_dwordx4 v[98:99], v[82:85], off offset:256
	s_nop 1
	v_lshl_add_u64 v[82:83], v[74:75], 0, v[168:169]
	v_cvt_pk_bf16_f32 v74, v86, v87
	v_cvt_pk_bf16_f32 v75, v88, v89
	v_cvt_pk_bf16_f32 v76, v78, v79
	v_cvt_pk_bf16_f32 v77, v80, v81
	global_store_dwordx4 v[82:83], v[74:77], off
	v_cvt_pk_bf16_f32 v70, v70, v71
	v_cvt_pk_bf16_f32 v71, v72, v73
	v_cvt_pk_bf16_f32 v72, v66, v67
	v_cvt_pk_bf16_f32 v73, v68, v69
	global_store_dwordx4 v[82:83], v[70:73], off offset:256
	v_cvt_pk_bf16_f32 v62, v62, v63
	v_cvt_pk_bf16_f32 v63, v64, v65
	v_cvt_pk_bf16_f32 v64, v58, v59
	v_add_co_u32_e32 v58, vcc, s17, v148
	v_lshl_add_u64 v[66:67], v[148:149], 0, s[26:27]
	s_nop 0
	v_addc_co_u32_e32 v59, vcc, 0, v149, vcc
	s_mov_b32 s17, 0x120000
	v_cvt_pk_bf16_f32 v65, v60, v61
	global_store_dwordx4 v[58:59], v[62:65], off
	v_cvt_pk_bf16_f32 v50, v50, v51
	v_cvt_pk_bf16_f32 v51, v52, v53
	v_cvt_pk_bf16_f32 v52, v42, v43
	v_cvt_pk_bf16_f32 v53, v44, v45
	global_store_dwordx4 v[66:67], v[50:53], off offset:256
	s_mov_b64 s[26:27], 0x120000
	v_cvt_pk_bf16_f32 v42, v54, v55
	v_cvt_pk_bf16_f32 v43, v56, v57
	v_cvt_pk_bf16_f32 v44, v46, v47
	v_add_co_u32_e32 v46, vcc, s17, v148
	v_lshl_add_u64 v[50:51], v[148:149], 0, s[26:27]
	s_nop 0
	v_addc_co_u32_e32 v47, vcc, 0, v149, vcc
	s_mov_b32 s17, 0x140000
	v_cvt_pk_bf16_f32 v45, v48, v49
	global_store_dwordx4 v[46:47], v[42:45], off
	v_cvt_pk_bf16_f32 v34, v34, v35
	v_cvt_pk_bf16_f32 v35, v36, v37
	v_cvt_pk_bf16_f32 v36, v26, v27
	v_cvt_pk_bf16_f32 v37, v28, v29
	global_store_dwordx4 v[50:51], v[34:37], off offset:256
	s_mov_b64 s[26:27], 0x140000
	v_cvt_pk_bf16_f32 v26, v38, v39
	v_cvt_pk_bf16_f32 v27, v40, v41
	v_cvt_pk_bf16_f32 v28, v30, v31
	v_add_co_u32_e32 v30, vcc, s17, v148
	v_lshl_add_u64 v[34:35], v[148:149], 0, s[26:27]
	s_nop 0
	v_addc_co_u32_e32 v31, vcc, 0, v149, vcc
	s_mov_b32 s17, 0x160000
	v_cvt_pk_bf16_f32 v29, v32, v33
	global_store_dwordx4 v[30:31], v[26:29], off
	v_cvt_pk_bf16_f32 v18, v18, v19
	v_cvt_pk_bf16_f32 v19, v20, v21
	v_cvt_pk_bf16_f32 v20, v10, v11
	v_cvt_pk_bf16_f32 v21, v12, v13
	global_store_dwordx4 v[34:35], v[18:21], off offset:256
	v_cvt_pk_bf16_f32 v10, v22, v23
	v_cvt_pk_bf16_f32 v11, v24, v25
	v_cvt_pk_bf16_f32 v12, v14, v15
	v_add_co_u32_e32 v14, vcc, s17, v148
	s_mov_b64 s[26:27], 0x160000
	s_nop 0
	v_addc_co_u32_e32 v15, vcc, 0, v149, vcc
	v_lshl_add_u64 v[18:19], v[148:149], 0, s[26:27]
	s_andn2_b64 vcc, exec, s[0:1]
	s_mov_b64 s[0:1], -1
	v_cvt_pk_bf16_f32 v13, v16, v17
	global_store_dwordx4 v[14:15], v[10:13], off
	v_cvt_pk_bf16_f32 v6, v6, v7
	v_cvt_pk_bf16_f32 v7, v8, v9
	v_cvt_pk_bf16_f32 v8, v2, v3
	v_cvt_pk_bf16_f32 v9, v4, v5
	global_store_dwordx4 v[18:19], v[6:9], off offset:256
	s_cbranch_vccnz .LBB0_169
	s_mov_b32 s98, 1
	s_andn2_b64 vcc, exec, s[4:5]
	s_cbranch_vccnz .LBB0_168
	s_barrier
	s_branch .LBB0_168

.LBB0_197:
	ds_read_b128 v[164:167], v153
	ds_read_b128 v[168:171], v153 offset:1024
	ds_read_b128 v[172:175], v153 offset:2048
	ds_read_b128 v[176:179], v153 offset:3072
	ds_read_b128 v[184:187], v160
	ds_read_b128 v[188:191], v160 offset:1024
	ds_read_b128 v[192:195], v160 offset:2048
	ds_read_b128 v[196:199], v160 offset:3072
	s_add_u32 s30, s28, 0xfff00080
	s_addc_u32 s31, s29, -1
	s_cmp_eq_u32 s83, 60
	s_cselect_b32 s35, s21, s31
	s_cselect_b32 s34, s63, s30
	s_cselect_b32 s31, s19, s82
	s_cselect_b32 s30, s80, s81
	v_lshl_add_u64 v[148:149], s[28:29], 0, v[140:141]
	s_add_i32 m0, s27, 0xc000
	ds_read_b128 v[200:203], v161
	ds_read_b128 v[204:207], v161 offset:1024
	ds_read_b128 v[208:211], v161 offset:2048
	ds_read_b128 v[212:215], v161 offset:3072
	ds_read_b128 v[216:219], v161 offset:4096
	ds_read_b128 v[220:223], v161 offset:5120
	ds_read_b128 v[224:227], v161 offset:6144
	ds_read_b128 v[228:231], v161 offset:7168
	global_load_lds_dwordx4 v[148:149], off
	v_lshl_add_u64 v[148:149], s[28:29], 0, v[142:143]
	s_add_i32 m0, s27, 0xe000
	s_nop 0
	global_load_lds_dwordx4 v[148:149], off
	s_cmp_eq_u32 s98, 0
	s_cbranch_scc1 .Lgw197_0a
	s_waitcnt vmcnt(16)
	s_branch .Lgw197_0b

.Lgw197_0b:
	s_waitcnt lgkmcnt(0)
	s_barrier
	s_setprio 1
	s_waitcnt lgkmcnt(0)
	v_mfma_f32_16x16x32_bf16 v[126:129], v[164:167], v[200:203], v[126:129]
	v_mfma_f32_16x16x32_bf16 v[122:125], v[172:175], v[200:203], v[122:125]
	v_mfma_f32_16x16x32_bf16 v[110:113], v[164:167], v[208:211], v[110:113]
	v_mfma_f32_16x16x32_bf16 v[106:109], v[172:175], v[208:211], v[106:109]
	v_mfma_f32_16x16x32_bf16 v[94:97], v[164:167], v[216:219], v[94:97]
	v_mfma_f32_16x16x32_bf16 v[90:93], v[172:175], v[216:219], v[90:93]
	v_mfma_f32_16x16x32_bf16 v[78:81], v[164:167], v[224:227], v[78:81]
	v_mfma_f32_16x16x32_bf16 v[74:77], v[172:175], v[224:227], v[74:77]
	v_mfma_f32_16x16x32_bf16 v[126:129], v[168:171], v[204:207], v[126:129]
	v_mfma_f32_16x16x32_bf16 v[122:125], v[176:179], v[204:207], v[122:125]
	v_mfma_f32_16x16x32_bf16 v[110:113], v[168:171], v[212:215], v[110:113]
	v_mfma_f32_16x16x32_bf16 v[106:109], v[176:179], v[212:215], v[106:109]
	v_mfma_f32_16x16x32_bf16 v[94:97], v[168:171], v[220:223], v[94:97]
	v_mfma_f32_16x16x32_bf16 v[90:93], v[176:179], v[220:223], v[90:93]
	v_mfma_f32_16x16x32_bf16 v[78:81], v[168:171], v[228:231], v[78:81]
	v_mfma_f32_16x16x32_bf16 v[74:77], v[176:179], v[228:231], v[74:77]
	s_setprio 0
	s_setprio 1
	v_mfma_f32_16x16x32_bf16 v[118:121], v[184:187], v[200:203], v[118:121]
	v_mfma_f32_16x16x32_bf16 v[114:117], v[192:195], v[200:203], v[114:117]
	v_mfma_f32_16x16x32_bf16 v[102:105], v[184:187], v[208:211], v[102:105]
	v_mfma_f32_16x16x32_bf16 v[98:101], v[192:195], v[208:211], v[98:101]
	v_mfma_f32_16x16x32_bf16 v[86:89], v[184:187], v[216:219], v[86:89]
	v_mfma_f32_16x16x32_bf16 v[82:85], v[192:195], v[216:219], v[82:85]
	v_mfma_f32_16x16x32_bf16 v[70:73], v[184:187], v[224:227], v[70:73]
	v_mfma_f32_16x16x32_bf16 v[66:69], v[192:195], v[224:227], v[66:69]
	v_mfma_f32_16x16x32_bf16 v[118:121], v[188:191], v[204:207], v[118:121]
	v_mfma_f32_16x16x32_bf16 v[114:117], v[196:199], v[204:207], v[114:117]
	v_mfma_f32_16x16x32_bf16 v[102:105], v[188:191], v[212:215], v[102:105]
	v_mfma_f32_16x16x32_bf16 v[98:101], v[196:199], v[212:215], v[98:101]
	v_mfma_f32_16x16x32_bf16 v[86:89], v[188:191], v[220:223], v[86:89]
	v_mfma_f32_16x16x32_bf16 v[82:85], v[196:199], v[220:223], v[82:85]
	v_mfma_f32_16x16x32_bf16 v[70:73], v[188:191], v[228:231], v[70:73]
	v_mfma_f32_16x16x32_bf16 v[66:69], v[196:199], v[228:231], v[66:69]
	s_setprio 0
	s_barrier
	s_add_i32 s84, s58, s43
	v_lshl_add_u64 v[148:149], s[30:31], 0, v[132:133]
	s_mov_b32 m0, s84
	ds_read_b128 v[200:203], v161 offset:16384
	ds_read_b128 v[204:207], v161 offset:17408
	ds_read_b128 v[208:211], v161 offset:18432
	ds_read_b128 v[212:215], v161 offset:19456
	ds_read_b128 v[216:219], v161 offset:20480
	ds_read_b128 v[220:223], v161 offset:21504
	ds_read_b128 v[224:227], v161 offset:22528
	ds_read_b128 v[228:231], v161 offset:23552
	global_load_lds_dwordx4 v[148:149], off
	s_add_i32 m0, s84, 0x2000
	s_add_u32 s84, s30, 0x100000
	v_lshl_add_u64 v[180:181], s[30:31], 0, v[136:137]
	s_addc_u32 s85, s31, 0
	s_add_i32 s86, s59, s43
	global_load_lds_dwordx4 v[180:181], off
	v_lshl_add_u64 v[232:233], s[84:85], 0, v[132:133]
	s_mov_b32 m0, s86
	v_lshl_add_u64 v[234:235], s[34:35], 0, v[134:135]
	global_load_lds_dwordx4 v[232:233], off
	v_lshl_add_u64 v[232:233], s[84:85], 0, v[136:137]
	s_add_i32 m0, s86, 0x2000
	s_nop 0
	global_load_lds_dwordx4 v[232:233], off
	v_lshl_add_u64 v[232:233], s[34:35], 0, v[130:131]
	s_mov_b32 m0, s27
	s_nop 0
	global_load_lds_dwordx4 v[232:233], off
	s_mov_b32 m0, s46
	s_nop 0
	global_load_lds_dwordx4 v[234:235], off
	s_cmp_eq_u32 s98, 0
	s_cbranch_scc1 .Lgw197_1a
	s_waitcnt vmcnt(16)
	s_branch .Lgw197_1b

.Lgw197_1b:
	s_mov_b32 s98, 0
	s_waitcnt lgkmcnt(0)
	s_barrier
	s_setprio 1
	s_waitcnt lgkmcnt(0)
	v_mfma_f32_16x16x32_bf16 v[62:65], v[164:167], v[200:203], v[62:65]
	v_mfma_f32_16x16x32_bf16 v[58:61], v[172:175], v[200:203], v[58:61]
	v_mfma_f32_16x16x32_bf16 v[46:49], v[164:167], v[208:211], v[46:49]
	v_mfma_f32_16x16x32_bf16 v[42:45], v[172:175], v[208:211], v[42:45]
	v_mfma_f32_16x16x32_bf16 v[30:33], v[164:167], v[216:219], v[30:33]
	v_mfma_f32_16x16x32_bf16 v[26:29], v[172:175], v[216:219], v[26:29]
	v_mfma_f32_16x16x32_bf16 v[14:17], v[164:167], v[224:227], v[14:17]
	v_mfma_f32_16x16x32_bf16 v[10:13], v[172:175], v[224:227], v[10:13]
	v_mfma_f32_16x16x32_bf16 v[62:65], v[168:171], v[204:207], v[62:65]
	v_mfma_f32_16x16x32_bf16 v[58:61], v[176:179], v[204:207], v[58:61]
	v_mfma_f32_16x16x32_bf16 v[46:49], v[168:171], v[212:215], v[46:49]
	v_mfma_f32_16x16x32_bf16 v[42:45], v[176:179], v[212:215], v[42:45]
	v_mfma_f32_16x16x32_bf16 v[30:33], v[168:171], v[220:223], v[30:33]
	v_mfma_f32_16x16x32_bf16 v[26:29], v[176:179], v[220:223], v[26:29]
	v_mfma_f32_16x16x32_bf16 v[14:17], v[168:171], v[228:231], v[14:17]
	v_mfma_f32_16x16x32_bf16 v[10:13], v[176:179], v[228:231], v[10:13]
	s_setprio 0
	s_setprio 1
	v_mfma_f32_16x16x32_bf16 v[54:57], v[184:187], v[200:203], v[54:57]
	v_mfma_f32_16x16x32_bf16 v[50:53], v[192:195], v[200:203], v[50:53]
	v_mfma_f32_16x16x32_bf16 v[38:41], v[184:187], v[208:211], v[38:41]
	v_mfma_f32_16x16x32_bf16 v[34:37], v[192:195], v[208:211], v[34:37]
	v_mfma_f32_16x16x32_bf16 v[22:25], v[184:187], v[216:219], v[22:25]
	v_mfma_f32_16x16x32_bf16 v[18:21], v[192:195], v[216:219], v[18:21]
	v_mfma_f32_16x16x32_bf16 v[6:9], v[184:187], v[224:227], v[6:9]
	v_mfma_f32_16x16x32_bf16 v[2:5], v[192:195], v[224:227], v[2:5]
	v_mfma_f32_16x16x32_bf16 v[54:57], v[188:191], v[204:207], v[54:57]
	v_mfma_f32_16x16x32_bf16 v[50:53], v[196:199], v[204:207], v[50:53]
	v_mfma_f32_16x16x32_bf16 v[38:41], v[188:191], v[212:215], v[38:41]
	v_mfma_f32_16x16x32_bf16 v[34:37], v[196:199], v[212:215], v[34:37]
	v_mfma_f32_16x16x32_bf16 v[22:25], v[188:191], v[220:223], v[22:25]
	v_mfma_f32_16x16x32_bf16 v[18:21], v[196:199], v[220:223], v[18:21]
	v_mfma_f32_16x16x32_bf16 v[6:9], v[188:191], v[228:231], v[6:9]
	v_mfma_f32_16x16x32_bf16 v[2:5], v[196:199], v[228:231], v[2:5]
	s_setprio 0
	s_barrier
	s_add_i32 s84, 0, 0x18000
	v_add_u32_e32 v162, s84, v151
	s_add_i32 s85, 0, 0x1c000
	ds_read_b128 v[164:167], v162
	ds_read_b128 v[168:171], v162 offset:1024
	ds_read_b128 v[172:175], v162 offset:2048
	ds_read_b128 v[176:179], v162 offset:3072
	v_add_u32_e32 v162, s85, v151
	ds_read_b128 v[184:187], v162
	ds_read_b128 v[188:191], v162 offset:1024
	ds_read_b128 v[192:195], v162 offset:2048
	ds_read_b128 v[196:199], v162 offset:3072
	s_add_u32 s34, s34, 0x100000
	s_addc_u32 s35, s35, 0
	s_mov_b32 m0, s47
	v_lshl_add_u64 v[236:237], s[34:35], 0, v[130:131]
	ds_read_b128 v[200:203], v161 offset:32768
	ds_read_b128 v[204:207], v161 offset:33792
	ds_read_b128 v[208:211], v161 offset:34816
	ds_read_b128 v[212:215], v161 offset:35840
	ds_read_b128 v[216:219], v161 offset:36864
	ds_read_b128 v[220:223], v161 offset:37888
	ds_read_b128 v[224:227], v161 offset:38912
	ds_read_b128 v[228:231], v161 offset:39936
	global_load_lds_dwordx4 v[236:237], off
	v_lshl_add_u64 v[236:237], s[34:35], 0, v[134:135]
	s_mov_b32 m0, s50
	s_nop 0
	global_load_lds_dwordx4 v[236:237], off
	s_waitcnt vmcnt(8)
	s_waitcnt lgkmcnt(0)
	s_barrier
	s_setprio 1
	s_waitcnt lgkmcnt(0)
	v_mfma_f32_16x16x32_bf16 v[126:129], v[164:167], v[200:203], v[126:129]
	v_mfma_f32_16x16x32_bf16 v[122:125], v[172:175], v[200:203], v[122:125]
	v_mfma_f32_16x16x32_bf16 v[110:113], v[164:167], v[208:211], v[110:113]
	v_mfma_f32_16x16x32_bf16 v[106:109], v[172:175], v[208:211], v[106:109]
	v_mfma_f32_16x16x32_bf16 v[94:97], v[164:167], v[216:219], v[94:97]
	v_mfma_f32_16x16x32_bf16 v[90:93], v[172:175], v[216:219], v[90:93]
	v_mfma_f32_16x16x32_bf16 v[78:81], v[164:167], v[224:227], v[78:81]
	v_mfma_f32_16x16x32_bf16 v[74:77], v[172:175], v[224:227], v[74:77]
	v_mfma_f32_16x16x32_bf16 v[126:129], v[168:171], v[204:207], v[126:129]
	v_mfma_f32_16x16x32_bf16 v[122:125], v[176:179], v[204:207], v[122:125]
	v_mfma_f32_16x16x32_bf16 v[110:113], v[168:171], v[212:215], v[110:113]
	v_mfma_f32_16x16x32_bf16 v[106:109], v[176:179], v[212:215], v[106:109]
	v_mfma_f32_16x16x32_bf16 v[94:97], v[168:171], v[220:223], v[94:97]
	v_mfma_f32_16x16x32_bf16 v[90:93], v[176:179], v[220:223], v[90:93]
	v_mfma_f32_16x16x32_bf16 v[78:81], v[168:171], v[228:231], v[78:81]
	v_mfma_f32_16x16x32_bf16 v[74:77], v[176:179], v[228:231], v[74:77]
	s_setprio 0
	s_setprio 1
	v_mfma_f32_16x16x32_bf16 v[118:121], v[184:187], v[200:203], v[118:121]
	v_mfma_f32_16x16x32_bf16 v[114:117], v[192:195], v[200:203], v[114:117]
	v_mfma_f32_16x16x32_bf16 v[102:105], v[184:187], v[208:211], v[102:105]
	v_mfma_f32_16x16x32_bf16 v[98:101], v[192:195], v[208:211], v[98:101]
	v_mfma_f32_16x16x32_bf16 v[86:89], v[184:187], v[216:219], v[86:89]
	v_mfma_f32_16x16x32_bf16 v[82:85], v[192:195], v[216:219], v[82:85]
	v_mfma_f32_16x16x32_bf16 v[70:73], v[184:187], v[224:227], v[70:73]
	v_mfma_f32_16x16x32_bf16 v[66:69], v[192:195], v[224:227], v[66:69]
	v_mfma_f32_16x16x32_bf16 v[118:121], v[188:191], v[204:207], v[118:121]
	v_mfma_f32_16x16x32_bf16 v[114:117], v[196:199], v[204:207], v[114:117]
	v_mfma_f32_16x16x32_bf16 v[102:105], v[188:191], v[212:215], v[102:105]
	v_mfma_f32_16x16x32_bf16 v[98:101], v[196:199], v[212:215], v[98:101]
	v_mfma_f32_16x16x32_bf16 v[86:89], v[188:191], v[220:223], v[86:89]
	v_mfma_f32_16x16x32_bf16 v[82:85], v[196:199], v[220:223], v[82:85]
	v_mfma_f32_16x16x32_bf16 v[70:73], v[188:191], v[228:231], v[70:73]
	v_mfma_f32_16x16x32_bf16 v[66:69], v[196:199], v[228:231], v[66:69]
	s_setprio 0
	s_barrier
	s_add_i32 s34, s84, s43
	v_lshl_add_u64 v[148:149], v[148:149], 0, s[14:15]
	s_mov_b32 m0, s34
	ds_read_b128 v[200:203], v161 offset:49152
	ds_read_b128 v[204:207], v161 offset:50176
	ds_read_b128 v[208:211], v161 offset:51200
	ds_read_b128 v[212:215], v161 offset:52224
	ds_read_b128 v[216:219], v161 offset:53248
	ds_read_b128 v[220:223], v161 offset:54272
	ds_read_b128 v[224:227], v161 offset:55296
	ds_read_b128 v[228:231], v161 offset:56320
	global_load_lds_dwordx4 v[148:149], off
	s_add_i32 m0, s34, 0x2000
	s_add_u32 s30, s30, 0x100080
	v_lshl_add_u64 v[148:149], v[180:181], 0, s[14:15]
	s_addc_u32 s31, s31, 0
	s_add_i32 s34, s85, s43
	global_load_lds_dwordx4 v[148:149], off
	v_lshl_add_u64 v[148:149], s[30:31], 0, v[132:133]
	s_mov_b32 m0, s34
	s_nop 0
	global_load_lds_dwordx4 v[148:149], off
	v_lshl_add_u64 v[148:149], s[30:31], 0, v[136:137]
	s_add_i32 m0, s34, 0x2000
	s_nop 0
	global_load_lds_dwordx4 v[148:149], off
	v_lshl_add_u64 v[148:149], v[232:233], 0, s[14:15]
	s_mov_b32 m0, s52
	s_nop 0
	global_load_lds_dwordx4 v[148:149], off
	v_lshl_add_u64 v[148:149], v[234:235], 0, s[14:15]
	s_mov_b32 m0, s53
	s_nop 0
	global_load_lds_dwordx4 v[148:149], off
	s_waitcnt vmcnt(8)
	s_waitcnt lgkmcnt(0)
	s_barrier
	s_setprio 1
	s_waitcnt lgkmcnt(0)
	v_mfma_f32_16x16x32_bf16 v[62:65], v[164:167], v[200:203], v[62:65]
	v_mfma_f32_16x16x32_bf16 v[58:61], v[172:175], v[200:203], v[58:61]
	v_mfma_f32_16x16x32_bf16 v[46:49], v[164:167], v[208:211], v[46:49]
	v_mfma_f32_16x16x32_bf16 v[42:45], v[172:175], v[208:211], v[42:45]
	v_mfma_f32_16x16x32_bf16 v[30:33], v[164:167], v[216:219], v[30:33]
	v_mfma_f32_16x16x32_bf16 v[26:29], v[172:175], v[216:219], v[26:29]
	v_mfma_f32_16x16x32_bf16 v[14:17], v[164:167], v[224:227], v[14:17]
	v_mfma_f32_16x16x32_bf16 v[10:13], v[172:175], v[224:227], v[10:13]
	v_mfma_f32_16x16x32_bf16 v[62:65], v[168:171], v[204:207], v[62:65]
	v_mfma_f32_16x16x32_bf16 v[58:61], v[176:179], v[204:207], v[58:61]
	v_mfma_f32_16x16x32_bf16 v[46:49], v[168:171], v[212:215], v[46:49]
	v_mfma_f32_16x16x32_bf16 v[42:45], v[176:179], v[212:215], v[42:45]
	v_mfma_f32_16x16x32_bf16 v[30:33], v[168:171], v[220:223], v[30:33]
	v_mfma_f32_16x16x32_bf16 v[26:29], v[176:179], v[220:223], v[26:29]
	v_mfma_f32_16x16x32_bf16 v[14:17], v[168:171], v[228:231], v[14:17]
	v_mfma_f32_16x16x32_bf16 v[10:13], v[176:179], v[228:231], v[10:13]
	s_setprio 0
	s_setprio 1
	v_mfma_f32_16x16x32_bf16 v[54:57], v[184:187], v[200:203], v[54:57]
	v_mfma_f32_16x16x32_bf16 v[50:53], v[192:195], v[200:203], v[50:53]
	v_mfma_f32_16x16x32_bf16 v[38:41], v[184:187], v[208:211], v[38:41]
	v_mfma_f32_16x16x32_bf16 v[34:37], v[192:195], v[208:211], v[34:37]
	v_mfma_f32_16x16x32_bf16 v[22:25], v[184:187], v[216:219], v[22:25]
	v_mfma_f32_16x16x32_bf16 v[18:21], v[192:195], v[216:219], v[18:21]
	v_mfma_f32_16x16x32_bf16 v[6:9], v[184:187], v[224:227], v[6:9]
	v_mfma_f32_16x16x32_bf16 v[2:5], v[192:195], v[224:227], v[2:5]
	v_mfma_f32_16x16x32_bf16 v[54:57], v[188:191], v[204:207], v[54:57]
	v_mfma_f32_16x16x32_bf16 v[50:53], v[196:199], v[204:207], v[50:53]
	v_mfma_f32_16x16x32_bf16 v[38:41], v[188:191], v[212:215], v[38:41]
	v_mfma_f32_16x16x32_bf16 v[34:37], v[196:199], v[212:215], v[34:37]
	v_mfma_f32_16x16x32_bf16 v[22:25], v[188:191], v[220:223], v[22:25]
	v_mfma_f32_16x16x32_bf16 v[18:21], v[196:199], v[220:223], v[18:21]
	v_mfma_f32_16x16x32_bf16 v[6:9], v[188:191], v[228:231], v[6:9]
	v_mfma_f32_16x16x32_bf16 v[2:5], v[196:199], v[228:231], v[2:5]
	s_setprio 0
	s_barrier
	s_add_i32 s83, s83, 2
	s_add_u32 s28, s28, 0x100
	s_addc_u32 s29, s29, 0
	s_add_u32 s81, s81, 0x100
	s_addc_u32 s82, s82, 0
	s_cmp_gt_u32 s83, 61
	s_cbranch_scc0 .LBB0_197
	s_and_b64 vcc, exec, s[16:17]
	s_cbranch_vccz .LBB0_200
	s_barrier
.LBB0_200:
	v_mul_f32_e32 v162, 0xbfb8aa3b, v118
	v_exp_f32_e32 v162, v162
	v_lshl_add_u32 v148, s26, 8, v150
	v_ashrrev_i32_e32 v149, 31, v148
	v_lshlrev_b64 v[166:167], 13, v[148:149]
	v_mul_f32_e32 v126, 0xbfb8aa3b, v126
	v_add_f32_e32 v149, 1.0, v162
	v_exp_f32_e32 v126, v126
	v_rcp_f32_e32 v149, v149
	v_mul_f32_e32 v122, 0xbfb8aa3b, v122
	v_exp_f32_e32 v122, v122
	v_add_f32_e32 v126, 1.0, v126
	v_mul_f32_e32 v118, v118, v149
	v_mul_f32_e32 v149, 0xbfb8aa3b, v114
	v_rcp_f32_e32 v126, v126
	v_exp_f32_e32 v149, v149
	v_add_f32_e32 v122, 1.0, v122
	v_mul_f32_e32 v127, 0xbfb8aa3b, v127
	v_mul_f32_e32 v118, v126, v118
	v_add_f32_e32 v126, 1.0, v149
	v_rcp_f32_e32 v126, v126
	v_mul_f32_e32 v149, 0xbfb8aa3b, v119
	v_rcp_f32_e32 v122, v122
	v_exp_f32_e32 v127, v127
	v_exp_f32_e32 v149, v149
	v_mul_f32_e32 v114, v114, v126
	v_mul_f32_e32 v122, v122, v114
	v_add_f32_e32 v114, 1.0, v127
	v_add_f32_e32 v126, 1.0, v149
	v_mul_f32_e32 v127, 0xbfb8aa3b, v115
	v_rcp_f32_e32 v126, v126
	v_exp_f32_e32 v127, v127
	v_mul_f32_e32 v123, 0xbfb8aa3b, v123
	v_rcp_f32_e32 v114, v114
	v_mul_f32_e32 v119, v119, v126
	v_add_f32_e32 v126, 1.0, v127
	v_exp_f32_e32 v123, v123
	v_rcp_f32_e32 v126, v126
	v_mul_f32_e32 v119, v114, v119
	v_lshl_or_b32 v164, s62, 7, v152
	v_add_f32_e32 v114, 1.0, v123
	v_mul_f32_e32 v115, v115, v126
	v_mul_f32_e32 v123, 0xbfb8aa3b, v128
	v_mul_f32_e32 v126, 0xbfb8aa3b, v120
	v_rcp_f32_e32 v114, v114
	v_exp_f32_e32 v123, v123
	v_exp_f32_e32 v126, v126
	v_ashrrev_i32_e32 v165, 31, v164
	v_mul_f32_e32 v127, v114, v115
	v_add_f32_e32 v114, 1.0, v123
	v_add_f32_e32 v115, 1.0, v126
	v_mul_f32_e32 v123, 0xbfb8aa3b, v124
	v_mul_f32_e32 v124, 0xbfb8aa3b, v116
	v_rcp_f32_e32 v115, v115
	v_exp_f32_e32 v123, v123
	v_exp_f32_e32 v124, v124
	v_rcp_f32_e32 v114, v114
	v_mul_f32_e32 v115, v120, v115
	v_add_f32_e32 v120, 1.0, v123
	v_add_f32_e32 v123, 1.0, v124
	v_rcp_f32_e32 v123, v123
	v_rcp_f32_e32 v120, v120
	v_mul_f32_e32 v126, v114, v115
	v_mul_f32_e32 v115, 0xbfb8aa3b, v121
	v_mul_f32_e32 v114, v116, v123
	v_mul_f32_e32 v124, 0xbfb8aa3b, v129
	v_mul_f32_e32 v123, v120, v114
	v_exp_f32_e32 v115, v115
	v_mul_f32_e32 v120, 0xbfb8aa3b, v117
	v_exp_f32_e32 v124, v124
	v_mul_f32_e32 v116, 0xbfb8aa3b, v125
	v_exp_f32_e32 v120, v120
	v_exp_f32_e32 v116, v116
	v_add_f32_e32 v115, 1.0, v115
	v_add_f32_e32 v114, 1.0, v124
	v_rcp_f32_e32 v115, v115
	v_add_f32_e32 v120, 1.0, v120
	v_rcp_f32_e32 v114, v114
	v_add_f32_e32 v116, 1.0, v116
	v_rcp_f32_e32 v120, v120
	v_rcp_f32_e32 v116, v116
	v_mul_f32_e32 v115, v121, v115
	v_mul_f32_e32 v121, v114, v115
	v_mul_f32_e32 v114, v117, v120
	v_lshl_add_u64 v[166:167], s[12:13], 0, v[166:167]
	v_mul_f32_e32 v124, v116, v114
	v_lshlrev_b64 v[116:117], 1, v[164:165]
	v_lshl_add_u64 v[114:115], v[166:167], 0, v[116:117]
	v_cvt_pk_bf16_f32 v118, v118, v119
	v_cvt_pk_bf16_f32 v119, v126, v121
	v_cvt_pk_bf16_f32 v120, v122, v127
	v_cvt_pk_bf16_f32 v121, v123, v124
	global_store_dwordx4 v[114:115], v[118:121], off
	v_mul_f32_e32 v110, 0xbfb8aa3b, v110
	v_exp_f32_e32 v110, v110
	v_mul_f32_e32 v120, 0xbfb8aa3b, v102
	v_exp_f32_e32 v120, v120
	v_mul_f32_e32 v106, 0xbfb8aa3b, v106
	v_add_f32_e32 v110, 1.0, v110
	v_rcp_f32_e32 v110, v110
	v_add_f32_e32 v120, 1.0, v120
	v_rcp_f32_e32 v120, v120
	v_exp_f32_e32 v106, v106
	v_mul_f32_e32 v111, 0xbfb8aa3b, v111
	v_exp_f32_e32 v111, v111
	v_mul_f32_e32 v102, v102, v120
	v_mul_f32_e32 v120, 0xbfb8aa3b, v98
	v_exp_f32_e32 v120, v120
	v_mul_f32_e32 v110, v110, v102
	v_add_f32_e32 v102, 1.0, v106
	v_rcp_f32_e32 v102, v102
	v_add_f32_e32 v106, 1.0, v120
	v_rcp_f32_e32 v106, v106
	v_mul_f32_e32 v120, 0xbfb8aa3b, v103
	v_exp_f32_e32 v120, v120
	v_or_b32_e32 v118, 16, v148
	v_mul_f32_e32 v98, v98, v106
	v_mul_f32_e32 v106, v102, v98
	v_add_f32_e32 v98, 1.0, v111
	v_add_f32_e32 v102, 1.0, v120
	v_mul_f32_e32 v111, 0xbfb8aa3b, v99
	v_rcp_f32_e32 v102, v102
	v_exp_f32_e32 v111, v111
	v_rcp_f32_e32 v98, v98
	v_ashrrev_i32_e32 v119, 31, v118
	v_mul_f32_e32 v102, v103, v102
	v_mul_f32_e32 v103, 0xbfb8aa3b, v107
	v_add_f32_e32 v107, 1.0, v111
	v_exp_f32_e32 v103, v103
	v_rcp_f32_e32 v107, v107
	v_mul_f32_e32 v98, v98, v102
	v_lshlrev_b64 v[118:119], 13, v[118:119]
	v_add_f32_e32 v102, 1.0, v103
	v_mul_f32_e32 v99, v99, v107
	v_mul_f32_e32 v107, 0xbfb8aa3b, v104
	v_rcp_f32_e32 v102, v102
	v_mul_f32_e32 v103, 0xbfb8aa3b, v112
	v_exp_f32_e32 v107, v107
	v_exp_f32_e32 v103, v103
	v_mul_f32_e32 v111, v102, v99
	v_lshl_add_u64 v[118:119], s[12:13], 0, v[118:119]
	v_add_f32_e32 v102, 1.0, v107
	v_mul_f32_e32 v107, 0xbfb8aa3b, v100
	v_add_f32_e32 v99, 1.0, v103
	v_rcp_f32_e32 v102, v102
	v_mul_f32_e32 v103, 0xbfb8aa3b, v108
	v_exp_f32_e32 v107, v107
	v_exp_f32_e32 v103, v103
	v_mul_f32_e32 v102, v104, v102
	v_rcp_f32_e32 v99, v99
	v_add_f32_e32 v104, 1.0, v107
	v_add_f32_e32 v103, 1.0, v103
	v_rcp_f32_e32 v104, v104
	v_mul_f32_e32 v107, 0xbfb8aa3b, v113
	v_rcp_f32_e32 v103, v103
	v_exp_f32_e32 v107, v107
	v_mul_f32_e32 v99, v99, v102
	v_mul_f32_e32 v100, v100, v104
	v_mul_f32_e32 v102, 0xbfb8aa3b, v105
	v_mul_f32_e32 v104, v103, v100
	v_add_f32_e32 v100, 1.0, v107
	v_exp_f32_e32 v102, v102
	v_mul_f32_e32 v107, 0xbfb8aa3b, v101
	v_mul_f32_e32 v103, 0xbfb8aa3b, v109
	v_exp_f32_e32 v107, v107
	v_exp_f32_e32 v103, v103
	v_add_f32_e32 v102, 1.0, v102
	v_rcp_f32_e32 v102, v102
	v_add_f32_e32 v107, 1.0, v107
	v_rcp_f32_e32 v100, v100
	v_add_f32_e32 v103, 1.0, v103
	v_rcp_f32_e32 v107, v107
	v_rcp_f32_e32 v103, v103
	v_mul_f32_e32 v102, v105, v102
	v_mul_f32_e32 v100, v100, v102
	v_mul_f32_e32 v101, v101, v107
	v_mul_f32_e32 v101, v103, v101
	v_lshl_add_u64 v[102:103], v[118:119], 0, v[116:117]
	v_cvt_pk_bf16_f32 v98, v110, v98
	v_cvt_pk_bf16_f32 v99, v99, v100
	v_cvt_pk_bf16_f32 v100, v106, v111
	v_cvt_pk_bf16_f32 v101, v104, v101
	global_store_dwordx4 v[102:103], v[98:101], off
	v_mul_f32_e32 v94, 0xbfb8aa3b, v94
	v_exp_f32_e32 v94, v94
	v_mul_f32_e32 v100, 0xbfb8aa3b, v86
	v_exp_f32_e32 v100, v100
	v_mul_f32_e32 v90, 0xbfb8aa3b, v90
	v_add_f32_e32 v94, 1.0, v94
	v_rcp_f32_e32 v94, v94
	v_add_f32_e32 v100, 1.0, v100
	v_rcp_f32_e32 v100, v100
	v_exp_f32_e32 v90, v90
	v_mul_f32_e32 v95, 0xbfb8aa3b, v95
	v_exp_f32_e32 v95, v95
	v_mul_f32_e32 v86, v86, v100
	v_mul_f32_e32 v100, 0xbfb8aa3b, v82
	v_exp_f32_e32 v100, v100
	v_mul_f32_e32 v94, v94, v86
	v_add_f32_e32 v86, 1.0, v90
	v_rcp_f32_e32 v86, v86
	v_add_f32_e32 v90, 1.0, v100
	v_rcp_f32_e32 v90, v90
	v_mul_f32_e32 v100, 0xbfb8aa3b, v87
	v_exp_f32_e32 v100, v100
	v_or_b32_e32 v98, 32, v148
	v_mul_f32_e32 v82, v82, v90
	v_mul_f32_e32 v90, v86, v82
	v_add_f32_e32 v82, 1.0, v95
	v_add_f32_e32 v86, 1.0, v100
	v_mul_f32_e32 v95, 0xbfb8aa3b, v83
	v_rcp_f32_e32 v86, v86
	v_exp_f32_e32 v95, v95
	v_rcp_f32_e32 v82, v82
	v_ashrrev_i32_e32 v99, 31, v98
	v_mul_f32_e32 v86, v87, v86
	v_mul_f32_e32 v87, 0xbfb8aa3b, v91
	v_add_f32_e32 v91, 1.0, v95
	v_exp_f32_e32 v87, v87
	v_rcp_f32_e32 v91, v91
	v_mul_f32_e32 v82, v82, v86
	v_lshlrev_b64 v[98:99], 13, v[98:99]
	v_add_f32_e32 v86, 1.0, v87
	v_mul_f32_e32 v83, v83, v91
	v_mul_f32_e32 v91, 0xbfb8aa3b, v88
	v_rcp_f32_e32 v86, v86
	v_mul_f32_e32 v87, 0xbfb8aa3b, v96
	v_exp_f32_e32 v91, v91
	v_exp_f32_e32 v87, v87
	v_mul_f32_e32 v95, v86, v83
	v_lshl_add_u64 v[98:99], s[12:13], 0, v[98:99]
	v_add_f32_e32 v86, 1.0, v91
	v_mul_f32_e32 v91, 0xbfb8aa3b, v84
	v_add_f32_e32 v83, 1.0, v87
	v_rcp_f32_e32 v86, v86
	v_mul_f32_e32 v87, 0xbfb8aa3b, v92
	v_exp_f32_e32 v91, v91
	v_exp_f32_e32 v87, v87
	v_mul_f32_e32 v86, v88, v86
	v_rcp_f32_e32 v83, v83
	v_add_f32_e32 v88, 1.0, v91
	v_add_f32_e32 v87, 1.0, v87
	v_rcp_f32_e32 v88, v88
	v_mul_f32_e32 v91, 0xbfb8aa3b, v97
	v_rcp_f32_e32 v87, v87
	v_exp_f32_e32 v91, v91
	v_mul_f32_e32 v83, v83, v86
	v_mul_f32_e32 v84, v84, v88
	v_mul_f32_e32 v86, 0xbfb8aa3b, v89
	v_mul_f32_e32 v88, v87, v84
	v_add_f32_e32 v84, 1.0, v91
	v_exp_f32_e32 v86, v86
	v_mul_f32_e32 v91, 0xbfb8aa3b, v85
	v_mul_f32_e32 v87, 0xbfb8aa3b, v93
	v_exp_f32_e32 v91, v91
	v_exp_f32_e32 v87, v87
	v_add_f32_e32 v86, 1.0, v86
	v_rcp_f32_e32 v86, v86
	v_add_f32_e32 v91, 1.0, v91
	v_rcp_f32_e32 v84, v84
	v_add_f32_e32 v87, 1.0, v87
	v_rcp_f32_e32 v91, v91
	v_rcp_f32_e32 v87, v87
	v_mul_f32_e32 v86, v89, v86
	v_mul_f32_e32 v84, v84, v86
	v_mul_f32_e32 v85, v85, v91
	v_mul_f32_e32 v85, v87, v85
	v_lshl_add_u64 v[86:87], v[98:99], 0, v[116:117]
	v_cvt_pk_bf16_f32 v82, v94, v82
	v_cvt_pk_bf16_f32 v83, v83, v84
	v_cvt_pk_bf16_f32 v84, v90, v95
	v_cvt_pk_bf16_f32 v85, v88, v85
	global_store_dwordx4 v[86:87], v[82:85], off
	v_mul_f32_e32 v78, 0xbfb8aa3b, v78
	v_exp_f32_e32 v78, v78
	v_mul_f32_e32 v84, 0xbfb8aa3b, v70
	v_exp_f32_e32 v84, v84
	v_mul_f32_e32 v74, 0xbfb8aa3b, v74
	v_add_f32_e32 v78, 1.0, v78
	v_rcp_f32_e32 v78, v78
	v_add_f32_e32 v84, 1.0, v84
	v_rcp_f32_e32 v84, v84
	v_exp_f32_e32 v74, v74
	v_mul_f32_e32 v79, 0xbfb8aa3b, v79
	v_exp_f32_e32 v79, v79
	v_mul_f32_e32 v70, v70, v84
	v_mul_f32_e32 v84, 0xbfb8aa3b, v66
	v_exp_f32_e32 v84, v84
	v_mul_f32_e32 v78, v78, v70
	v_add_f32_e32 v70, 1.0, v74
	v_rcp_f32_e32 v70, v70
	v_add_f32_e32 v74, 1.0, v84
	v_rcp_f32_e32 v74, v74
	v_mul_f32_e32 v84, 0xbfb8aa3b, v71
	v_exp_f32_e32 v84, v84
	v_or_b32_e32 v82, 48, v148
	v_mul_f32_e32 v66, v66, v74
	v_mul_f32_e32 v74, v70, v66
	v_add_f32_e32 v66, 1.0, v79
	v_add_f32_e32 v70, 1.0, v84
	v_mul_f32_e32 v79, 0xbfb8aa3b, v67
	v_rcp_f32_e32 v70, v70
	v_exp_f32_e32 v79, v79
	v_rcp_f32_e32 v66, v66
	v_mul_f32_e32 v62, 0xbfb8aa3b, v62
	v_mul_f32_e32 v70, v71, v70
	v_mul_f32_e32 v71, 0xbfb8aa3b, v75
	v_add_f32_e32 v75, 1.0, v79
	v_exp_f32_e32 v71, v71
	v_rcp_f32_e32 v75, v75
	v_mul_f32_e32 v66, v66, v70
	v_ashrrev_i32_e32 v83, 31, v82
	v_add_f32_e32 v70, 1.0, v71
	v_mul_f32_e32 v67, v67, v75
	v_mul_f32_e32 v75, 0xbfb8aa3b, v72
	v_rcp_f32_e32 v70, v70
	v_mul_f32_e32 v71, 0xbfb8aa3b, v80
	v_exp_f32_e32 v75, v75
	v_exp_f32_e32 v71, v71
	v_mul_f32_e32 v79, v70, v67
	v_exp_f32_e32 v62, v62
	v_add_f32_e32 v70, 1.0, v75
	v_mul_f32_e32 v75, 0xbfb8aa3b, v68
	v_add_f32_e32 v67, 1.0, v71
	v_rcp_f32_e32 v70, v70
	v_mul_f32_e32 v71, 0xbfb8aa3b, v76
	v_exp_f32_e32 v75, v75
	v_exp_f32_e32 v71, v71
	v_rcp_f32_e32 v67, v67
	v_mul_f32_e32 v70, v72, v70
	v_add_f32_e32 v72, 1.0, v75
	v_add_f32_e32 v71, 1.0, v71
	v_rcp_f32_e32 v72, v72
	v_mul_f32_e32 v75, 0xbfb8aa3b, v81
	v_rcp_f32_e32 v71, v71
	v_exp_f32_e32 v75, v75
	v_mul_f32_e32 v67, v67, v70
	v_mul_f32_e32 v70, 0xbfb8aa3b, v73
	v_exp_f32_e32 v70, v70
	v_mul_f32_e32 v68, v68, v72
	v_mul_f32_e32 v72, v71, v68
	v_add_f32_e32 v68, 1.0, v75
	v_mul_f32_e32 v75, 0xbfb8aa3b, v69
	v_mul_f32_e32 v71, 0xbfb8aa3b, v77
	v_exp_f32_e32 v75, v75
	v_exp_f32_e32 v71, v71
	v_add_f32_e32 v70, 1.0, v70
	v_rcp_f32_e32 v70, v70
	v_add_f32_e32 v75, 1.0, v75
	v_add_f32_e32 v71, 1.0, v71
	v_rcp_f32_e32 v75, v75
	v_rcp_f32_e32 v68, v68
	v_rcp_f32_e32 v71, v71
	v_mul_f32_e32 v70, v73, v70
	v_mul_f32_e32 v73, 0xbfb8aa3b, v54
	v_exp_f32_e32 v73, v73
	v_lshlrev_b64 v[82:83], 13, v[82:83]
	v_mul_f32_e32 v69, v69, v75
	v_lshl_add_u64 v[82:83], s[12:13], 0, v[82:83]
	v_mul_f32_e32 v68, v68, v70
	v_mul_f32_e32 v69, v71, v69
	v_lshl_add_u64 v[70:71], v[82:83], 0, v[116:117]
	v_cvt_pk_bf16_f32 v66, v78, v66
	v_cvt_pk_bf16_f32 v67, v67, v68
	v_cvt_pk_bf16_f32 v68, v74, v79
	v_cvt_pk_bf16_f32 v69, v72, v69
	v_add_f32_e32 v72, 1.0, v73
	v_rcp_f32_e32 v72, v72
	global_store_dwordx4 v[70:71], v[66:69], off
	v_add_f32_e32 v62, 1.0, v62
	v_rcp_f32_e32 v62, v62
	v_mul_f32_e32 v66, 0xbfb8aa3b, v50
	v_mul_f32_e32 v58, 0xbfb8aa3b, v58
	v_exp_f32_e32 v66, v66
	v_exp_f32_e32 v58, v58
	v_mul_f32_e32 v54, v54, v72
	v_mul_f32_e32 v54, v62, v54
	v_add_f32_e32 v62, 1.0, v66
	v_add_f32_e32 v58, 1.0, v58
	v_rcp_f32_e32 v62, v62
	v_mul_f32_e32 v63, 0xbfb8aa3b, v63
	v_mul_f32_e32 v66, 0xbfb8aa3b, v55
	v_rcp_f32_e32 v58, v58
	v_exp_f32_e32 v63, v63
	v_exp_f32_e32 v66, v66
	v_mul_f32_e32 v50, v50, v62
	v_mul_f32_e32 v58, v58, v50
	v_add_f32_e32 v50, 1.0, v63
	v_add_f32_e32 v62, 1.0, v66
	v_mul_f32_e32 v63, 0xbfb8aa3b, v51
	v_rcp_f32_e32 v62, v62
	v_exp_f32_e32 v63, v63
	v_mul_f32_e32 v59, 0xbfb8aa3b, v59
	v_rcp_f32_e32 v50, v50
	v_mul_f32_e32 v55, v55, v62
	v_add_f32_e32 v62, 1.0, v63
	v_exp_f32_e32 v59, v59
	v_rcp_f32_e32 v62, v62
	v_mul_f32_e32 v50, v50, v55
	v_mul_f32_e32 v60, 0xbfb8aa3b, v60
	v_add_f32_e32 v55, 1.0, v59
	v_mul_f32_e32 v51, v51, v62
	v_mul_f32_e32 v59, 0xbfb8aa3b, v64
	v_mul_f32_e32 v62, 0xbfb8aa3b, v56
	v_rcp_f32_e32 v55, v55
	v_exp_f32_e32 v59, v59
	v_exp_f32_e32 v62, v62
	v_exp_f32_e32 v60, v60
	v_mul_f32_e32 v55, v55, v51
	v_add_f32_e32 v51, 1.0, v59
	v_add_f32_e32 v59, 1.0, v62
	v_mul_f32_e32 v62, 0xbfb8aa3b, v52
	v_rcp_f32_e32 v59, v59
	v_exp_f32_e32 v62, v62
	v_rcp_f32_e32 v51, v51
	v_cvt_pk_bf16_f32 v50, v54, v50
	v_mul_f32_e32 v56, v56, v59
	v_add_f32_e32 v59, 1.0, v60
	v_add_f32_e32 v60, 1.0, v62
	v_rcp_f32_e32 v60, v60
	v_rcp_f32_e32 v59, v59
	v_mul_f32_e32 v51, v51, v56
	v_mul_f32_e32 v62, 0xbfb8aa3b, v65
	v_mul_f32_e32 v52, v52, v60
	v_mul_f32_e32 v56, v59, v52
	v_mul_f32_e32 v59, 0xbfb8aa3b, v57
	v_mul_f32_e32 v60, 0xbfb8aa3b, v61
	v_mul_f32_e32 v61, 0xbfb8aa3b, v53
	v_exp_f32_e32 v59, v59
	v_exp_f32_e32 v61, v61
	v_exp_f32_e32 v62, v62
	v_exp_f32_e32 v60, v60
	v_add_f32_e32 v59, 1.0, v59
	v_add_f32_e32 v61, 1.0, v61
	v_add_f32_e32 v52, 1.0, v62
	v_rcp_f32_e32 v59, v59
	v_add_f32_e32 v60, 1.0, v60
	v_rcp_f32_e32 v61, v61
	v_rcp_f32_e32 v52, v52
	v_rcp_f32_e32 v60, v60
	v_mul_f32_e32 v57, v57, v59
	v_mul_f32_e32 v53, v53, v61
	v_mul_f32_e32 v52, v52, v57
	v_mul_f32_e32 v53, v60, v53
	v_mul_f32_e32 v54, 0xbfb8aa3b, v38
	v_cvt_pk_bf16_f32 v51, v51, v52
	v_cvt_pk_bf16_f32 v52, v58, v55
	v_cvt_pk_bf16_f32 v53, v56, v53
	v_exp_f32_e32 v56, v54
	v_mul_f32_e32 v46, 0xbfb8aa3b, v46
	v_exp_f32_e32 v46, v46
	s_mov_b32 s19, 0x100000
	v_add_co_u32_e32 v54, vcc, s19, v114
	v_add_f32_e32 v56, 1.0, v56
	s_nop 0
	v_addc_co_u32_e32 v55, vcc, 0, v115, vcc
	v_rcp_f32_e32 v56, v56
	global_store_dwordx4 v[54:55], v[50:53], off
	v_add_f32_e32 v46, 1.0, v46
	v_rcp_f32_e32 v46, v46
	v_mul_f32_e32 v50, 0xbfb8aa3b, v34
	v_mul_f32_e32 v42, 0xbfb8aa3b, v42
	v_exp_f32_e32 v50, v50
	v_exp_f32_e32 v42, v42
	v_mul_f32_e32 v38, v38, v56
	v_mul_f32_e32 v38, v46, v38
	v_add_f32_e32 v46, 1.0, v50
	v_add_f32_e32 v42, 1.0, v42
	v_rcp_f32_e32 v46, v46
	v_mul_f32_e32 v47, 0xbfb8aa3b, v47
	v_mul_f32_e32 v50, 0xbfb8aa3b, v39
	v_rcp_f32_e32 v42, v42
	v_exp_f32_e32 v47, v47
	v_exp_f32_e32 v50, v50
	v_mul_f32_e32 v34, v34, v46
	v_mul_f32_e32 v42, v42, v34
	v_add_f32_e32 v34, 1.0, v47
	v_add_f32_e32 v46, 1.0, v50
	v_mul_f32_e32 v47, 0xbfb8aa3b, v35
	v_rcp_f32_e32 v46, v46
	v_exp_f32_e32 v47, v47
	v_mul_f32_e32 v43, 0xbfb8aa3b, v43
	v_rcp_f32_e32 v34, v34
	v_mul_f32_e32 v39, v39, v46
	v_add_f32_e32 v46, 1.0, v47
	v_exp_f32_e32 v43, v43
	v_rcp_f32_e32 v46, v46
	v_mul_f32_e32 v34, v34, v39
	v_mul_f32_e32 v44, 0xbfb8aa3b, v44
	v_add_f32_e32 v39, 1.0, v43
	v_mul_f32_e32 v35, v35, v46
	v_mul_f32_e32 v43, 0xbfb8aa3b, v48
	v_mul_f32_e32 v46, 0xbfb8aa3b, v40
	v_rcp_f32_e32 v39, v39
	v_exp_f32_e32 v43, v43
	v_exp_f32_e32 v46, v46
	v_exp_f32_e32 v44, v44
	v_mul_f32_e32 v39, v39, v35
	v_add_f32_e32 v35, 1.0, v43
	v_add_f32_e32 v43, 1.0, v46
	v_mul_f32_e32 v46, 0xbfb8aa3b, v36
	v_rcp_f32_e32 v43, v43
	v_exp_f32_e32 v46, v46
	v_rcp_f32_e32 v35, v35
	v_cvt_pk_bf16_f32 v34, v38, v34
	v_mul_f32_e32 v40, v40, v43
	v_add_f32_e32 v43, 1.0, v44
	v_add_f32_e32 v44, 1.0, v46
	v_rcp_f32_e32 v44, v44
	v_rcp_f32_e32 v43, v43
	v_mul_f32_e32 v35, v35, v40
	v_mul_f32_e32 v46, 0xbfb8aa3b, v49
	v_mul_f32_e32 v36, v36, v44
	v_mul_f32_e32 v40, v43, v36
	v_mul_f32_e32 v43, 0xbfb8aa3b, v41
	v_mul_f32_e32 v44, 0xbfb8aa3b, v45
	v_mul_f32_e32 v45, 0xbfb8aa3b, v37
	v_exp_f32_e32 v43, v43
	v_exp_f32_e32 v45, v45
	v_exp_f32_e32 v46, v46
	v_exp_f32_e32 v44, v44
	v_add_f32_e32 v43, 1.0, v43
	v_add_f32_e32 v45, 1.0, v45
	v_add_f32_e32 v36, 1.0, v46
	v_rcp_f32_e32 v43, v43
	v_add_f32_e32 v44, 1.0, v44
	v_rcp_f32_e32 v45, v45
	v_rcp_f32_e32 v36, v36
	v_rcp_f32_e32 v44, v44
	v_mul_f32_e32 v41, v41, v43
	v_mul_f32_e32 v37, v37, v45
	v_mul_f32_e32 v36, v36, v41
	v_mul_f32_e32 v37, v44, v37
	v_mul_f32_e32 v38, 0xbfb8aa3b, v22
	v_cvt_pk_bf16_f32 v35, v35, v36
	v_cvt_pk_bf16_f32 v36, v42, v39
	v_cvt_pk_bf16_f32 v37, v40, v37
	v_exp_f32_e32 v40, v38
	v_mul_f32_e32 v30, 0xbfb8aa3b, v30
	v_exp_f32_e32 v30, v30
	s_mov_b32 s19, 0x120000
	v_add_co_u32_e32 v38, vcc, s19, v114
	v_add_f32_e32 v40, 1.0, v40
	s_nop 0
	v_addc_co_u32_e32 v39, vcc, 0, v115, vcc
	v_rcp_f32_e32 v40, v40
	global_store_dwordx4 v[38:39], v[34:37], off
	v_add_f32_e32 v30, 1.0, v30
	v_rcp_f32_e32 v30, v30
	v_mul_f32_e32 v34, 0xbfb8aa3b, v18
	v_mul_f32_e32 v26, 0xbfb8aa3b, v26
	v_exp_f32_e32 v34, v34
	v_exp_f32_e32 v26, v26
	v_mul_f32_e32 v22, v22, v40
	v_mul_f32_e32 v22, v30, v22
	v_add_f32_e32 v30, 1.0, v34
	v_add_f32_e32 v26, 1.0, v26
	v_rcp_f32_e32 v30, v30
	v_mul_f32_e32 v31, 0xbfb8aa3b, v31
	v_mul_f32_e32 v34, 0xbfb8aa3b, v23
	v_rcp_f32_e32 v26, v26
	v_exp_f32_e32 v31, v31
	v_exp_f32_e32 v34, v34
	v_mul_f32_e32 v18, v18, v30
	v_mul_f32_e32 v26, v26, v18
	v_add_f32_e32 v18, 1.0, v31
	v_add_f32_e32 v30, 1.0, v34
	v_mul_f32_e32 v31, 0xbfb8aa3b, v19
	v_rcp_f32_e32 v30, v30
	v_exp_f32_e32 v31, v31
	v_mul_f32_e32 v27, 0xbfb8aa3b, v27
	v_rcp_f32_e32 v18, v18
	v_mul_f32_e32 v23, v23, v30
	v_add_f32_e32 v30, 1.0, v31
	v_exp_f32_e32 v27, v27
	v_rcp_f32_e32 v30, v30
	v_mul_f32_e32 v18, v18, v23
	v_mul_f32_e32 v28, 0xbfb8aa3b, v28
	v_add_f32_e32 v23, 1.0, v27
	v_mul_f32_e32 v19, v19, v30
	v_mul_f32_e32 v27, 0xbfb8aa3b, v32
	v_mul_f32_e32 v30, 0xbfb8aa3b, v24
	v_rcp_f32_e32 v23, v23
	v_exp_f32_e32 v27, v27
	v_exp_f32_e32 v30, v30
	v_exp_f32_e32 v28, v28
	v_mul_f32_e32 v23, v23, v19
	v_add_f32_e32 v19, 1.0, v27
	v_add_f32_e32 v27, 1.0, v30
	v_mul_f32_e32 v30, 0xbfb8aa3b, v20
	v_rcp_f32_e32 v27, v27
	v_exp_f32_e32 v30, v30
	v_rcp_f32_e32 v19, v19
	v_cvt_pk_bf16_f32 v18, v22, v18
	v_mul_f32_e32 v24, v24, v27
	v_add_f32_e32 v27, 1.0, v28
	v_add_f32_e32 v28, 1.0, v30
	v_rcp_f32_e32 v28, v28
	v_rcp_f32_e32 v27, v27
	v_mul_f32_e32 v19, v19, v24
	v_mul_f32_e32 v30, 0xbfb8aa3b, v33
	v_mul_f32_e32 v20, v20, v28
	v_mul_f32_e32 v24, v27, v20
	v_mul_f32_e32 v27, 0xbfb8aa3b, v25
	v_mul_f32_e32 v28, 0xbfb8aa3b, v29
	v_mul_f32_e32 v29, 0xbfb8aa3b, v21
	v_exp_f32_e32 v27, v27
	v_exp_f32_e32 v29, v29
	v_exp_f32_e32 v30, v30
	v_exp_f32_e32 v28, v28
	v_add_f32_e32 v27, 1.0, v27
	v_add_f32_e32 v29, 1.0, v29
	v_add_f32_e32 v20, 1.0, v30
	v_rcp_f32_e32 v27, v27
	v_add_f32_e32 v28, 1.0, v28
	v_rcp_f32_e32 v29, v29
	v_rcp_f32_e32 v20, v20
	v_rcp_f32_e32 v28, v28
	v_mul_f32_e32 v25, v25, v27
	v_mul_f32_e32 v21, v21, v29
	v_mul_f32_e32 v20, v20, v25
	v_mul_f32_e32 v21, v28, v21
	v_mul_f32_e32 v22, 0xbfb8aa3b, v6
	v_cvt_pk_bf16_f32 v19, v19, v20
	v_cvt_pk_bf16_f32 v20, v26, v23
	v_cvt_pk_bf16_f32 v21, v24, v21
	v_exp_f32_e32 v24, v22
	v_mul_f32_e32 v14, 0xbfb8aa3b, v14
	v_exp_f32_e32 v14, v14
	s_mov_b32 s19, 0x140000
	v_add_co_u32_e32 v22, vcc, s19, v114
	v_add_f32_e32 v24, 1.0, v24
	s_nop 0
	v_addc_co_u32_e32 v23, vcc, 0, v115, vcc
	v_rcp_f32_e32 v24, v24
	global_store_dwordx4 v[22:23], v[18:21], off
	v_add_f32_e32 v14, 1.0, v14
	v_rcp_f32_e32 v14, v14
	v_mul_f32_e32 v18, 0xbfb8aa3b, v2
	v_mul_f32_e32 v10, 0xbfb8aa3b, v10
	v_exp_f32_e32 v18, v18
	v_exp_f32_e32 v10, v10
	v_mul_f32_e32 v6, v6, v24
	v_mul_f32_e32 v6, v14, v6
	v_add_f32_e32 v14, 1.0, v18
	v_add_f32_e32 v10, 1.0, v10
	v_rcp_f32_e32 v14, v14
	v_mul_f32_e32 v15, 0xbfb8aa3b, v15
	v_mul_f32_e32 v18, 0xbfb8aa3b, v7
	v_rcp_f32_e32 v10, v10
	v_exp_f32_e32 v15, v15
	v_exp_f32_e32 v18, v18
	v_mul_f32_e32 v2, v2, v14
	v_mul_f32_e32 v10, v10, v2
	v_add_f32_e32 v2, 1.0, v15
	v_add_f32_e32 v14, 1.0, v18
	v_mul_f32_e32 v15, 0xbfb8aa3b, v3
	v_rcp_f32_e32 v14, v14
	v_exp_f32_e32 v15, v15
	v_mul_f32_e32 v11, 0xbfb8aa3b, v11
	v_rcp_f32_e32 v2, v2
	v_mul_f32_e32 v7, v7, v14
	v_add_f32_e32 v14, 1.0, v15
	v_exp_f32_e32 v11, v11
	v_rcp_f32_e32 v14, v14
	v_mul_f32_e32 v2, v2, v7
	v_mul_f32_e32 v12, 0xbfb8aa3b, v12
	v_add_f32_e32 v7, 1.0, v11
	v_mul_f32_e32 v3, v3, v14
	v_mul_f32_e32 v11, 0xbfb8aa3b, v16
	v_mul_f32_e32 v14, 0xbfb8aa3b, v8
	v_rcp_f32_e32 v7, v7
	v_exp_f32_e32 v11, v11
	v_exp_f32_e32 v14, v14
	v_exp_f32_e32 v12, v12
	v_mul_f32_e32 v7, v7, v3
	v_add_f32_e32 v3, 1.0, v11
	v_add_f32_e32 v11, 1.0, v14
	v_mul_f32_e32 v14, 0xbfb8aa3b, v4
	v_rcp_f32_e32 v11, v11
	v_exp_f32_e32 v14, v14
	v_rcp_f32_e32 v3, v3
	v_cvt_pk_bf16_f32 v2, v6, v2
	v_mul_f32_e32 v8, v8, v11
	v_add_f32_e32 v11, 1.0, v12
	v_add_f32_e32 v12, 1.0, v14
	v_rcp_f32_e32 v12, v12
	v_rcp_f32_e32 v11, v11
	v_mul_f32_e32 v3, v3, v8
	v_mul_f32_e32 v14, 0xbfb8aa3b, v17
	v_mul_f32_e32 v4, v4, v12
	v_mul_f32_e32 v8, v11, v4
	v_mul_f32_e32 v11, 0xbfb8aa3b, v9
	v_exp_f32_e32 v11, v11
	v_exp_f32_e32 v14, v14
	v_mul_f32_e32 v12, 0xbfb8aa3b, v13
	v_mul_f32_e32 v13, 0xbfb8aa3b, v5
	v_exp_f32_e32 v13, v13
	v_exp_f32_e32 v12, v12
	v_add_f32_e32 v11, 1.0, v11
	v_add_f32_e32 v4, 1.0, v14
	v_rcp_f32_e32 v11, v11
	v_rcp_f32_e32 v4, v4
	v_add_f32_e32 v13, 1.0, v13
	v_add_f32_e32 v12, 1.0, v12
	v_rcp_f32_e32 v13, v13
	v_rcp_f32_e32 v12, v12
	v_mul_f32_e32 v9, v9, v11
	v_mul_f32_e32 v4, v4, v9
	v_add_co_u32_e32 v6, vcc, 0x160000, v114
	v_mul_f32_e32 v5, v5, v13
	v_cvt_pk_bf16_f32 v3, v3, v4
	v_cvt_pk_bf16_f32 v4, v10, v7
	s_nop 0
	v_addc_co_u32_e32 v7, vcc, 0, v115, vcc
	v_mul_f32_e32 v5, v12, v5
	s_andn2_b64 vcc, exec, s[0:1]
	s_mov_b64 s[0:1], -1
	v_cvt_pk_bf16_f32 v5, v8, v5
	global_store_dwordx4 v[6:7], v[2:5], off
	s_cbranch_vccnz .LBB0_189
	s_mov_b32 s98, 1
	s_andn2_b64 vcc, exec, s[4:5]
	s_cbranch_vccnz .LBB0_188
	s_barrier
	s_branch .LBB0_188

.LBB0_217:
	ds_read_b128 v[164:167], v153
	ds_read_b128 v[168:171], v153 offset:1024
	ds_read_b128 v[172:175], v153 offset:2048
	ds_read_b128 v[176:179], v153 offset:3072
	ds_read_b128 v[184:187], v160
	ds_read_b128 v[188:191], v160 offset:1024
	ds_read_b128 v[192:195], v160 offset:2048
	ds_read_b128 v[196:199], v160 offset:3072
	s_add_u32 s30, s28, 0xfff00080
	s_addc_u32 s31, s29, -1
	s_cmp_eq_u32 s83, 60
	s_cselect_b32 s35, s21, s31
	s_cselect_b32 s34, s63, s30
	s_cselect_b32 s31, s19, s82
	s_cselect_b32 s30, s80, s81
	v_lshl_add_u64 v[148:149], s[28:29], 0, v[140:141]
	s_add_i32 m0, s27, 0xc000
	ds_read_b128 v[200:203], v161
	ds_read_b128 v[204:207], v161 offset:1024
	ds_read_b128 v[208:211], v161 offset:2048
	ds_read_b128 v[212:215], v161 offset:3072
	ds_read_b128 v[216:219], v161 offset:4096
	ds_read_b128 v[220:223], v161 offset:5120
	ds_read_b128 v[224:227], v161 offset:6144
	ds_read_b128 v[228:231], v161 offset:7168
	global_load_lds_dwordx4 v[148:149], off
	v_lshl_add_u64 v[148:149], s[28:29], 0, v[142:143]
	s_add_i32 m0, s27, 0xe000
	s_nop 0
	global_load_lds_dwordx4 v[148:149], off
	s_cmp_eq_u32 s98, 0
	s_cbranch_scc1 .Lgw217_0a
	s_waitcnt vmcnt(24)
	s_branch .Lgw217_0b

.Lgw217_0b:
	s_waitcnt lgkmcnt(0)
	s_barrier
	s_setprio 1
	s_waitcnt lgkmcnt(0)
	v_mfma_f32_16x16x32_bf16 v[126:129], v[164:167], v[200:203], v[126:129]
	v_mfma_f32_16x16x32_bf16 v[122:125], v[172:175], v[200:203], v[122:125]
	v_mfma_f32_16x16x32_bf16 v[118:121], v[164:167], v[208:211], v[118:121]
	v_mfma_f32_16x16x32_bf16 v[110:113], v[172:175], v[208:211], v[110:113]
	v_mfma_f32_16x16x32_bf16 v[102:105], v[164:167], v[216:219], v[102:105]
	v_mfma_f32_16x16x32_bf16 v[94:97], v[172:175], v[216:219], v[94:97]
	v_mfma_f32_16x16x32_bf16 v[86:89], v[164:167], v[224:227], v[86:89]
	v_mfma_f32_16x16x32_bf16 v[78:81], v[172:175], v[224:227], v[78:81]
	v_mfma_f32_16x16x32_bf16 v[126:129], v[168:171], v[204:207], v[126:129]
	v_mfma_f32_16x16x32_bf16 v[122:125], v[176:179], v[204:207], v[122:125]
	v_mfma_f32_16x16x32_bf16 v[118:121], v[168:171], v[212:215], v[118:121]
	v_mfma_f32_16x16x32_bf16 v[110:113], v[176:179], v[212:215], v[110:113]
	v_mfma_f32_16x16x32_bf16 v[102:105], v[168:171], v[220:223], v[102:105]
	v_mfma_f32_16x16x32_bf16 v[94:97], v[176:179], v[220:223], v[94:97]
	v_mfma_f32_16x16x32_bf16 v[86:89], v[168:171], v[228:231], v[86:89]
	v_mfma_f32_16x16x32_bf16 v[78:81], v[176:179], v[228:231], v[78:81]
	s_setprio 0
	s_setprio 1
	v_mfma_f32_16x16x32_bf16 v[114:117], v[184:187], v[200:203], v[114:117]
	v_mfma_f32_16x16x32_bf16 v[106:109], v[192:195], v[200:203], v[106:109]
	v_mfma_f32_16x16x32_bf16 v[98:101], v[184:187], v[208:211], v[98:101]
	v_mfma_f32_16x16x32_bf16 v[90:93], v[192:195], v[208:211], v[90:93]
	v_mfma_f32_16x16x32_bf16 v[82:85], v[184:187], v[216:219], v[82:85]
	v_mfma_f32_16x16x32_bf16 v[74:77], v[192:195], v[216:219], v[74:77]
	v_mfma_f32_16x16x32_bf16 v[70:73], v[184:187], v[224:227], v[70:73]
	v_mfma_f32_16x16x32_bf16 v[66:69], v[192:195], v[224:227], v[66:69]
	v_mfma_f32_16x16x32_bf16 v[114:117], v[188:191], v[204:207], v[114:117]
	v_mfma_f32_16x16x32_bf16 v[106:109], v[196:199], v[204:207], v[106:109]
	v_mfma_f32_16x16x32_bf16 v[98:101], v[188:191], v[212:215], v[98:101]
	v_mfma_f32_16x16x32_bf16 v[90:93], v[196:199], v[212:215], v[90:93]
	v_mfma_f32_16x16x32_bf16 v[82:85], v[188:191], v[220:223], v[82:85]
	v_mfma_f32_16x16x32_bf16 v[74:77], v[196:199], v[220:223], v[74:77]
	v_mfma_f32_16x16x32_bf16 v[70:73], v[188:191], v[228:231], v[70:73]
	v_mfma_f32_16x16x32_bf16 v[66:69], v[196:199], v[228:231], v[66:69]
	s_setprio 0
	s_barrier
	s_add_i32 s84, s58, s43
	v_lshl_add_u64 v[148:149], s[30:31], 0, v[132:133]
	s_mov_b32 m0, s84
	ds_read_b128 v[200:203], v161 offset:16384
	ds_read_b128 v[204:207], v161 offset:17408
	ds_read_b128 v[208:211], v161 offset:18432
	ds_read_b128 v[212:215], v161 offset:19456
	ds_read_b128 v[216:219], v161 offset:20480
	ds_read_b128 v[220:223], v161 offset:21504
	ds_read_b128 v[224:227], v161 offset:22528
	ds_read_b128 v[228:231], v161 offset:23552
	global_load_lds_dwordx4 v[148:149], off
	s_add_i32 m0, s84, 0x2000
	s_add_u32 s84, s30, 0x100000
	v_lshl_add_u64 v[180:181], s[30:31], 0, v[136:137]
	s_addc_u32 s85, s31, 0
	s_add_i32 s86, s59, s43
	global_load_lds_dwordx4 v[180:181], off
	v_lshl_add_u64 v[232:233], s[84:85], 0, v[132:133]
	s_mov_b32 m0, s86
	v_lshl_add_u64 v[234:235], s[34:35], 0, v[134:135]
	global_load_lds_dwordx4 v[232:233], off
	v_lshl_add_u64 v[232:233], s[84:85], 0, v[136:137]
	s_add_i32 m0, s86, 0x2000
	s_nop 0
	global_load_lds_dwordx4 v[232:233], off
	v_lshl_add_u64 v[232:233], s[34:35], 0, v[130:131]
	s_mov_b32 m0, s27
	s_nop 0
	global_load_lds_dwordx4 v[232:233], off
	s_mov_b32 m0, s46
	s_nop 0
	global_load_lds_dwordx4 v[234:235], off
	s_cmp_eq_u32 s98, 0
	s_cbranch_scc1 .Lgw217_1a
	s_waitcnt vmcnt(24)
	s_branch .Lgw217_1b

.Lgw217_1b:
	s_mov_b32 s98, 0
	s_waitcnt lgkmcnt(0)
	s_barrier
	s_setprio 1
	s_waitcnt lgkmcnt(0)
	v_mfma_f32_16x16x32_bf16 v[62:65], v[164:167], v[200:203], v[62:65]
	v_mfma_f32_16x16x32_bf16 v[58:61], v[172:175], v[200:203], v[58:61]
	v_mfma_f32_16x16x32_bf16 v[54:57], v[164:167], v[208:211], v[54:57]
	v_mfma_f32_16x16x32_bf16 v[46:49], v[172:175], v[208:211], v[46:49]
	v_mfma_f32_16x16x32_bf16 v[38:41], v[164:167], v[216:219], v[38:41]
	v_mfma_f32_16x16x32_bf16 v[30:33], v[172:175], v[216:219], v[30:33]
	v_mfma_f32_16x16x32_bf16 v[22:25], v[164:167], v[224:227], v[22:25]
	v_mfma_f32_16x16x32_bf16 v[14:17], v[172:175], v[224:227], v[14:17]
	v_mfma_f32_16x16x32_bf16 v[62:65], v[168:171], v[204:207], v[62:65]
	v_mfma_f32_16x16x32_bf16 v[58:61], v[176:179], v[204:207], v[58:61]
	v_mfma_f32_16x16x32_bf16 v[54:57], v[168:171], v[212:215], v[54:57]
	v_mfma_f32_16x16x32_bf16 v[46:49], v[176:179], v[212:215], v[46:49]
	v_mfma_f32_16x16x32_bf16 v[38:41], v[168:171], v[220:223], v[38:41]
	v_mfma_f32_16x16x32_bf16 v[30:33], v[176:179], v[220:223], v[30:33]
	v_mfma_f32_16x16x32_bf16 v[22:25], v[168:171], v[228:231], v[22:25]
	v_mfma_f32_16x16x32_bf16 v[14:17], v[176:179], v[228:231], v[14:17]
	s_setprio 0
	s_setprio 1
	v_mfma_f32_16x16x32_bf16 v[50:53], v[184:187], v[200:203], v[50:53]
	v_mfma_f32_16x16x32_bf16 v[42:45], v[192:195], v[200:203], v[42:45]
	v_mfma_f32_16x16x32_bf16 v[34:37], v[184:187], v[208:211], v[34:37]
	v_mfma_f32_16x16x32_bf16 v[26:29], v[192:195], v[208:211], v[26:29]
	v_mfma_f32_16x16x32_bf16 v[18:21], v[184:187], v[216:219], v[18:21]
	v_mfma_f32_16x16x32_bf16 v[10:13], v[192:195], v[216:219], v[10:13]
	v_mfma_f32_16x16x32_bf16 v[6:9], v[184:187], v[224:227], v[6:9]
	v_mfma_f32_16x16x32_bf16 v[2:5], v[192:195], v[224:227], v[2:5]
	v_mfma_f32_16x16x32_bf16 v[50:53], v[188:191], v[204:207], v[50:53]
	v_mfma_f32_16x16x32_bf16 v[42:45], v[196:199], v[204:207], v[42:45]
	v_mfma_f32_16x16x32_bf16 v[34:37], v[188:191], v[212:215], v[34:37]
	v_mfma_f32_16x16x32_bf16 v[26:29], v[196:199], v[212:215], v[26:29]
	v_mfma_f32_16x16x32_bf16 v[18:21], v[188:191], v[220:223], v[18:21]
	v_mfma_f32_16x16x32_bf16 v[10:13], v[196:199], v[220:223], v[10:13]
	v_mfma_f32_16x16x32_bf16 v[6:9], v[188:191], v[228:231], v[6:9]
	v_mfma_f32_16x16x32_bf16 v[2:5], v[196:199], v[228:231], v[2:5]
	s_setprio 0
	s_barrier
	s_add_i32 s84, 0, 0x18000
	v_add_u32_e32 v162, s84, v151
	s_add_i32 s85, 0, 0x1c000
	ds_read_b128 v[164:167], v162
	ds_read_b128 v[168:171], v162 offset:1024
	ds_read_b128 v[172:175], v162 offset:2048
	ds_read_b128 v[176:179], v162 offset:3072
	v_add_u32_e32 v162, s85, v151
	ds_read_b128 v[184:187], v162
	ds_read_b128 v[188:191], v162 offset:1024
	ds_read_b128 v[192:195], v162 offset:2048
	ds_read_b128 v[196:199], v162 offset:3072
	s_add_u32 s34, s34, 0x100000
	s_addc_u32 s35, s35, 0
	s_mov_b32 m0, s47
	v_lshl_add_u64 v[236:237], s[34:35], 0, v[130:131]
	ds_read_b128 v[200:203], v161 offset:32768
	ds_read_b128 v[204:207], v161 offset:33792
	ds_read_b128 v[208:211], v161 offset:34816
	ds_read_b128 v[212:215], v161 offset:35840
	ds_read_b128 v[216:219], v161 offset:36864
	ds_read_b128 v[220:223], v161 offset:37888
	ds_read_b128 v[224:227], v161 offset:38912
	ds_read_b128 v[228:231], v161 offset:39936
	global_load_lds_dwordx4 v[236:237], off
	v_lshl_add_u64 v[236:237], s[34:35], 0, v[134:135]
	s_mov_b32 m0, s50
	s_nop 0
	global_load_lds_dwordx4 v[236:237], off
	s_waitcnt vmcnt(8)
	s_waitcnt lgkmcnt(0)
	s_barrier
	s_setprio 1
	s_waitcnt lgkmcnt(0)
	v_mfma_f32_16x16x32_bf16 v[126:129], v[164:167], v[200:203], v[126:129]
	v_mfma_f32_16x16x32_bf16 v[122:125], v[172:175], v[200:203], v[122:125]
	v_mfma_f32_16x16x32_bf16 v[118:121], v[164:167], v[208:211], v[118:121]
	v_mfma_f32_16x16x32_bf16 v[110:113], v[172:175], v[208:211], v[110:113]
	v_mfma_f32_16x16x32_bf16 v[102:105], v[164:167], v[216:219], v[102:105]
	v_mfma_f32_16x16x32_bf16 v[94:97], v[172:175], v[216:219], v[94:97]
	v_mfma_f32_16x16x32_bf16 v[86:89], v[164:167], v[224:227], v[86:89]
	v_mfma_f32_16x16x32_bf16 v[78:81], v[172:175], v[224:227], v[78:81]
	v_mfma_f32_16x16x32_bf16 v[126:129], v[168:171], v[204:207], v[126:129]
	v_mfma_f32_16x16x32_bf16 v[122:125], v[176:179], v[204:207], v[122:125]
	v_mfma_f32_16x16x32_bf16 v[118:121], v[168:171], v[212:215], v[118:121]
	v_mfma_f32_16x16x32_bf16 v[110:113], v[176:179], v[212:215], v[110:113]
	v_mfma_f32_16x16x32_bf16 v[102:105], v[168:171], v[220:223], v[102:105]
	v_mfma_f32_16x16x32_bf16 v[94:97], v[176:179], v[220:223], v[94:97]
	v_mfma_f32_16x16x32_bf16 v[86:89], v[168:171], v[228:231], v[86:89]
	v_mfma_f32_16x16x32_bf16 v[78:81], v[176:179], v[228:231], v[78:81]
	s_setprio 0
	s_setprio 1
	v_mfma_f32_16x16x32_bf16 v[114:117], v[184:187], v[200:203], v[114:117]
	v_mfma_f32_16x16x32_bf16 v[106:109], v[192:195], v[200:203], v[106:109]
	v_mfma_f32_16x16x32_bf16 v[98:101], v[184:187], v[208:211], v[98:101]
	v_mfma_f32_16x16x32_bf16 v[90:93], v[192:195], v[208:211], v[90:93]
	v_mfma_f32_16x16x32_bf16 v[82:85], v[184:187], v[216:219], v[82:85]
	v_mfma_f32_16x16x32_bf16 v[74:77], v[192:195], v[216:219], v[74:77]
	v_mfma_f32_16x16x32_bf16 v[70:73], v[184:187], v[224:227], v[70:73]
	v_mfma_f32_16x16x32_bf16 v[66:69], v[192:195], v[224:227], v[66:69]
	v_mfma_f32_16x16x32_bf16 v[114:117], v[188:191], v[204:207], v[114:117]
	v_mfma_f32_16x16x32_bf16 v[106:109], v[196:199], v[204:207], v[106:109]
	v_mfma_f32_16x16x32_bf16 v[98:101], v[188:191], v[212:215], v[98:101]
	v_mfma_f32_16x16x32_bf16 v[90:93], v[196:199], v[212:215], v[90:93]
	v_mfma_f32_16x16x32_bf16 v[82:85], v[188:191], v[220:223], v[82:85]
	v_mfma_f32_16x16x32_bf16 v[74:77], v[196:199], v[220:223], v[74:77]
	v_mfma_f32_16x16x32_bf16 v[70:73], v[188:191], v[228:231], v[70:73]
	v_mfma_f32_16x16x32_bf16 v[66:69], v[196:199], v[228:231], v[66:69]
	s_setprio 0
	s_barrier
	s_add_i32 s34, s84, s43
	v_lshl_add_u64 v[148:149], v[148:149], 0, s[14:15]
	s_mov_b32 m0, s34
	ds_read_b128 v[200:203], v161 offset:49152
	ds_read_b128 v[204:207], v161 offset:50176
	ds_read_b128 v[208:211], v161 offset:51200
	ds_read_b128 v[212:215], v161 offset:52224
	ds_read_b128 v[216:219], v161 offset:53248
	ds_read_b128 v[220:223], v161 offset:54272
	ds_read_b128 v[224:227], v161 offset:55296
	ds_read_b128 v[228:231], v161 offset:56320
	global_load_lds_dwordx4 v[148:149], off
	s_add_i32 m0, s34, 0x2000
	s_add_u32 s30, s30, 0x100080
	v_lshl_add_u64 v[148:149], v[180:181], 0, s[14:15]
	s_addc_u32 s31, s31, 0
	s_add_i32 s34, s85, s43
	global_load_lds_dwordx4 v[148:149], off
	v_lshl_add_u64 v[148:149], s[30:31], 0, v[132:133]
	s_mov_b32 m0, s34
	s_nop 0
	global_load_lds_dwordx4 v[148:149], off
	v_lshl_add_u64 v[148:149], s[30:31], 0, v[136:137]
	s_add_i32 m0, s34, 0x2000
	s_nop 0
	global_load_lds_dwordx4 v[148:149], off
	v_lshl_add_u64 v[148:149], v[232:233], 0, s[14:15]
	s_mov_b32 m0, s52
	s_nop 0
	global_load_lds_dwordx4 v[148:149], off
	v_lshl_add_u64 v[148:149], v[234:235], 0, s[14:15]
	s_mov_b32 m0, s53
	s_nop 0
	global_load_lds_dwordx4 v[148:149], off
	s_waitcnt vmcnt(8)
	s_waitcnt lgkmcnt(0)
	s_barrier
	s_setprio 1
	s_waitcnt lgkmcnt(0)
	v_mfma_f32_16x16x32_bf16 v[62:65], v[164:167], v[200:203], v[62:65]
	v_mfma_f32_16x16x32_bf16 v[58:61], v[172:175], v[200:203], v[58:61]
	v_mfma_f32_16x16x32_bf16 v[54:57], v[164:167], v[208:211], v[54:57]
	v_mfma_f32_16x16x32_bf16 v[46:49], v[172:175], v[208:211], v[46:49]
	v_mfma_f32_16x16x32_bf16 v[38:41], v[164:167], v[216:219], v[38:41]
	v_mfma_f32_16x16x32_bf16 v[30:33], v[172:175], v[216:219], v[30:33]
	v_mfma_f32_16x16x32_bf16 v[22:25], v[164:167], v[224:227], v[22:25]
	v_mfma_f32_16x16x32_bf16 v[14:17], v[172:175], v[224:227], v[14:17]
	v_mfma_f32_16x16x32_bf16 v[62:65], v[168:171], v[204:207], v[62:65]
	v_mfma_f32_16x16x32_bf16 v[58:61], v[176:179], v[204:207], v[58:61]
	v_mfma_f32_16x16x32_bf16 v[54:57], v[168:171], v[212:215], v[54:57]
	v_mfma_f32_16x16x32_bf16 v[46:49], v[176:179], v[212:215], v[46:49]
	v_mfma_f32_16x16x32_bf16 v[38:41], v[168:171], v[220:223], v[38:41]
	v_mfma_f32_16x16x32_bf16 v[30:33], v[176:179], v[220:223], v[30:33]
	v_mfma_f32_16x16x32_bf16 v[22:25], v[168:171], v[228:231], v[22:25]
	v_mfma_f32_16x16x32_bf16 v[14:17], v[176:179], v[228:231], v[14:17]
	s_setprio 0
	s_setprio 1
	v_mfma_f32_16x16x32_bf16 v[50:53], v[184:187], v[200:203], v[50:53]
	v_mfma_f32_16x16x32_bf16 v[42:45], v[192:195], v[200:203], v[42:45]
	v_mfma_f32_16x16x32_bf16 v[34:37], v[184:187], v[208:211], v[34:37]
	v_mfma_f32_16x16x32_bf16 v[26:29], v[192:195], v[208:211], v[26:29]
	v_mfma_f32_16x16x32_bf16 v[18:21], v[184:187], v[216:219], v[18:21]
	v_mfma_f32_16x16x32_bf16 v[10:13], v[192:195], v[216:219], v[10:13]
	v_mfma_f32_16x16x32_bf16 v[6:9], v[184:187], v[224:227], v[6:9]
	v_mfma_f32_16x16x32_bf16 v[2:5], v[192:195], v[224:227], v[2:5]
	v_mfma_f32_16x16x32_bf16 v[50:53], v[188:191], v[204:207], v[50:53]
	v_mfma_f32_16x16x32_bf16 v[42:45], v[196:199], v[204:207], v[42:45]
	v_mfma_f32_16x16x32_bf16 v[34:37], v[188:191], v[212:215], v[34:37]
	v_mfma_f32_16x16x32_bf16 v[26:29], v[196:199], v[212:215], v[26:29]
	v_mfma_f32_16x16x32_bf16 v[18:21], v[188:191], v[220:223], v[18:21]
	v_mfma_f32_16x16x32_bf16 v[10:13], v[196:199], v[220:223], v[10:13]
	v_mfma_f32_16x16x32_bf16 v[6:9], v[188:191], v[228:231], v[6:9]
	v_mfma_f32_16x16x32_bf16 v[2:5], v[196:199], v[228:231], v[2:5]
	s_setprio 0
	s_barrier
	s_add_i32 s83, s83, 2
	s_add_u32 s28, s28, 0x100
	s_addc_u32 s29, s29, 0
	s_add_u32 s81, s81, 0x100
	s_addc_u32 s82, s82, 0
	s_cmp_gt_u32 s83, 61
	s_cbranch_scc0 .LBB0_217
	s_and_b64 vcc, exec, s[16:17]
	s_cbranch_vccz .LBB0_220
	s_barrier
.LBB0_220:
	v_lshl_add_u32 v164, s26, 8, v150
	v_lshl_or_b32 v148, s62, 8, v152
	v_ashrrev_i32_e32 v165, 31, v164
	v_ashrrev_i32_e32 v149, 31, v148
	v_lshlrev_b64 v[166:167], 14, v[164:165]
	v_lshl_add_u64 v[166:167], s[12:13], 0, v[166:167]
	v_lshlrev_b64 v[168:169], 1, v[148:149]
	v_lshl_add_u64 v[148:149], v[166:167], 0, v[168:169]
	v_cvt_pk_bf16_f32 v126, v126, v127
	v_cvt_pk_bf16_f32 v127, v128, v129
	v_cvt_pk_bf16_f32 v128, v122, v123
	v_cvt_pk_bf16_f32 v129, v124, v125
	global_store_dwordx4 v[148:149], v[126:129], off
	v_cvt_pk_bf16_f32 v114, v114, v115
	v_cvt_pk_bf16_f32 v115, v116, v117
	v_cvt_pk_bf16_f32 v116, v106, v107
	v_or_b32_e32 v106, 16, v164
	v_ashrrev_i32_e32 v107, 31, v106
	v_lshlrev_b64 v[106:107], 14, v[106:107]
	v_lshl_add_u64 v[106:107], s[12:13], 0, v[106:107]
	v_cvt_pk_bf16_f32 v117, v108, v109
	global_store_dwordx4 v[148:149], v[114:117], off offset:256
	s_mov_b32 s19, 0x200000
	s_mov_b64 s[28:29], 0x200000
	v_lshl_add_u64 v[114:115], v[106:107], 0, v[168:169]
	v_cvt_pk_bf16_f32 v106, v118, v119
	v_cvt_pk_bf16_f32 v107, v120, v121
	v_cvt_pk_bf16_f32 v108, v110, v111
	v_cvt_pk_bf16_f32 v109, v112, v113
	global_store_dwordx4 v[114:115], v[106:109], off
	v_cvt_pk_bf16_f32 v98, v98, v99
	v_cvt_pk_bf16_f32 v99, v100, v101
	v_cvt_pk_bf16_f32 v100, v90, v91
	v_or_b32_e32 v90, 32, v164
	v_ashrrev_i32_e32 v91, 31, v90
	v_lshlrev_b64 v[90:91], 14, v[90:91]
	v_lshl_add_u64 v[90:91], s[12:13], 0, v[90:91]
	v_cvt_pk_bf16_f32 v101, v92, v93
	global_store_dwordx4 v[114:115], v[98:101], off offset:256
	s_nop 1
	v_lshl_add_u64 v[98:99], v[90:91], 0, v[168:169]
	v_cvt_pk_bf16_f32 v90, v102, v103
	v_cvt_pk_bf16_f32 v91, v104, v105
	v_cvt_pk_bf16_f32 v92, v94, v95
	v_cvt_pk_bf16_f32 v93, v96, v97
	global_store_dwordx4 v[98:99], v[90:93], off
	v_cvt_pk_bf16_f32 v82, v82, v83
	v_cvt_pk_bf16_f32 v83, v84, v85
	v_cvt_pk_bf16_f32 v84, v74, v75
	v_or_b32_e32 v74, 48, v164
	v_ashrrev_i32_e32 v75, 31, v74
	v_lshlrev_b64 v[74:75], 14, v[74:75]
	v_lshl_add_u64 v[74:75], s[12:13], 0, v[74:75]
	v_cvt_pk_bf16_f32 v85, v76, v77
	global_store_dwordx4 v[98:99], v[82:85], off offset:256
	s_nop 1
	v_lshl_add_u64 v[82:83], v[74:75], 0, v[168:169]
	v_cvt_pk_bf16_f32 v74, v86, v87
	v_cvt_pk_bf16_f32 v75, v88, v89
	v_cvt_pk_bf16_f32 v76, v78, v79
	v_cvt_pk_bf16_f32 v77, v80, v81
	global_store_dwordx4 v[82:83], v[74:77], off
	v_cvt_pk_bf16_f32 v70, v70, v71
	v_cvt_pk_bf16_f32 v71, v72, v73
	v_cvt_pk_bf16_f32 v72, v66, v67
	v_cvt_pk_bf16_f32 v73, v68, v69
	global_store_dwordx4 v[82:83], v[70:73], off offset:256
	v_cvt_pk_bf16_f32 v62, v62, v63
	v_cvt_pk_bf16_f32 v63, v64, v65
	v_cvt_pk_bf16_f32 v64, v58, v59
	v_add_co_u32_e32 v58, vcc, s19, v148
	v_lshl_add_u64 v[66:67], v[148:149], 0, s[28:29]
	s_nop 0
	v_addc_co_u32_e32 v59, vcc, 0, v149, vcc
	s_mov_b32 s19, 0x240000
	v_cvt_pk_bf16_f32 v65, v60, v61
	global_store_dwordx4 v[58:59], v[62:65], off
	v_cvt_pk_bf16_f32 v50, v50, v51
	v_cvt_pk_bf16_f32 v51, v52, v53
	v_cvt_pk_bf16_f32 v52, v42, v43
	v_cvt_pk_bf16_f32 v53, v44, v45
	global_store_dwordx4 v[66:67], v[50:53], off offset:256
	s_mov_b64 s[28:29], 0x240000
	v_cvt_pk_bf16_f32 v42, v54, v55
	v_cvt_pk_bf16_f32 v43, v56, v57
	v_cvt_pk_bf16_f32 v44, v46, v47
	v_add_co_u32_e32 v46, vcc, s19, v148
	v_lshl_add_u64 v[50:51], v[148:149], 0, s[28:29]
	s_nop 0
	v_addc_co_u32_e32 v47, vcc, 0, v149, vcc
	s_mov_b32 s19, 0x280000
	v_cvt_pk_bf16_f32 v45, v48, v49
	global_store_dwordx4 v[46:47], v[42:45], off
	v_cvt_pk_bf16_f32 v34, v34, v35
	v_cvt_pk_bf16_f32 v35, v36, v37
	v_cvt_pk_bf16_f32 v36, v26, v27
	v_cvt_pk_bf16_f32 v37, v28, v29
	global_store_dwordx4 v[50:51], v[34:37], off offset:256
	s_mov_b64 s[28:29], 0x280000
	v_cvt_pk_bf16_f32 v26, v38, v39
	v_cvt_pk_bf16_f32 v27, v40, v41
	v_cvt_pk_bf16_f32 v28, v30, v31
	v_add_co_u32_e32 v30, vcc, s19, v148
	v_lshl_add_u64 v[34:35], v[148:149], 0, s[28:29]
	s_nop 0
	v_addc_co_u32_e32 v31, vcc, 0, v149, vcc
	s_mov_b32 s19, 0x2c0000
	v_cvt_pk_bf16_f32 v29, v32, v33
	global_store_dwordx4 v[30:31], v[26:29], off
	v_cvt_pk_bf16_f32 v18, v18, v19
	v_cvt_pk_bf16_f32 v19, v20, v21
	v_cvt_pk_bf16_f32 v20, v10, v11
	v_cvt_pk_bf16_f32 v21, v12, v13
	global_store_dwordx4 v[34:35], v[18:21], off offset:256
	v_cvt_pk_bf16_f32 v10, v22, v23
	v_cvt_pk_bf16_f32 v11, v24, v25
	v_cvt_pk_bf16_f32 v12, v14, v15
	v_add_co_u32_e32 v14, vcc, s19, v148
	s_mov_b64 s[28:29], 0x2c0000
	s_nop 0
	v_addc_co_u32_e32 v15, vcc, 0, v149, vcc
	v_lshl_add_u64 v[18:19], v[148:149], 0, s[28:29]
	s_andn2_b64 vcc, exec, s[0:1]
	s_mov_b64 s[0:1], -1
	v_cvt_pk_bf16_f32 v13, v16, v17
	global_store_dwordx4 v[14:15], v[10:13], off
	v_cvt_pk_bf16_f32 v6, v6, v7
	v_cvt_pk_bf16_f32 v7, v8, v9
	v_cvt_pk_bf16_f32 v8, v2, v3
	v_cvt_pk_bf16_f32 v9, v4, v5
	global_store_dwordx4 v[18:19], v[6:9], off offset:256
	s_cbranch_vccnz .LBB0_209
	s_mov_b32 s98, 1
	s_andn2_b64 vcc, exec, s[10:11]
	s_cbranch_vccnz .LBB0_208
	s_barrier
	s_branch .LBB0_208

.LBB0_237:
	ds_read_b128 v[148:151], v164
	ds_read_b128 v[168:171], v164 offset:1024
	ds_read_b128 v[172:175], v164 offset:2048
	ds_read_b128 v[176:179], v164 offset:3072
	ds_read_b128 v[184:187], v165
	ds_read_b128 v[188:191], v165 offset:1024
	ds_read_b128 v[192:195], v165 offset:2048
	ds_read_b128 v[196:199], v165 offset:3072
	s_add_u32 s28, s26, 0xfff00080
	s_addc_u32 s29, s27, -1
	s_cmp_eq_u32 s63, 60
	s_cselect_b32 s31, s19, s29
	s_cselect_b32 s30, s53, s28
	s_cselect_b32 s29, s17, s62
	s_cselect_b32 s28, s58, s59
	v_lshl_add_u64 v[152:153], s[26:27], 0, v[140:141]
	s_add_i32 m0, s25, 0xc000
	ds_read_b128 v[200:203], v166
	ds_read_b128 v[204:207], v166 offset:1024
	ds_read_b128 v[208:211], v166 offset:2048
	ds_read_b128 v[212:215], v166 offset:3072
	ds_read_b128 v[216:219], v166 offset:4096
	ds_read_b128 v[220:223], v166 offset:5120
	ds_read_b128 v[224:227], v166 offset:6144
	ds_read_b128 v[228:231], v166 offset:7168
	global_load_lds_dwordx4 v[152:153], off
	v_lshl_add_u64 v[152:153], s[26:27], 0, v[142:143]
	s_add_i32 m0, s25, 0xe000
	s_nop 0
	global_load_lds_dwordx4 v[152:153], off
	s_cmp_eq_u32 s98, 0
	s_cbranch_scc1 .Lgw237_0a
	s_waitcnt vmcnt(24)
	s_branch .Lgw237_0b

.Lgw237_0b:
	s_waitcnt lgkmcnt(0)
	s_barrier
	s_setprio 1
	s_waitcnt lgkmcnt(0)
	v_mfma_f32_16x16x32_bf16 v[126:129], v[148:151], v[200:203], v[126:129]
	v_mfma_f32_16x16x32_bf16 v[122:125], v[172:175], v[200:203], v[122:125]
	v_mfma_f32_16x16x32_bf16 v[110:113], v[148:151], v[208:211], v[110:113]
	v_mfma_f32_16x16x32_bf16 v[106:109], v[172:175], v[208:211], v[106:109]
	v_mfma_f32_16x16x32_bf16 v[94:97], v[148:151], v[216:219], v[94:97]
	v_mfma_f32_16x16x32_bf16 v[90:93], v[172:175], v[216:219], v[90:93]
	v_mfma_f32_16x16x32_bf16 v[78:81], v[148:151], v[224:227], v[78:81]
	v_mfma_f32_16x16x32_bf16 v[74:77], v[172:175], v[224:227], v[74:77]
	v_mfma_f32_16x16x32_bf16 v[126:129], v[168:171], v[204:207], v[126:129]
	v_mfma_f32_16x16x32_bf16 v[122:125], v[176:179], v[204:207], v[122:125]
	v_mfma_f32_16x16x32_bf16 v[110:113], v[168:171], v[212:215], v[110:113]
	v_mfma_f32_16x16x32_bf16 v[106:109], v[176:179], v[212:215], v[106:109]
	v_mfma_f32_16x16x32_bf16 v[94:97], v[168:171], v[220:223], v[94:97]
	v_mfma_f32_16x16x32_bf16 v[90:93], v[176:179], v[220:223], v[90:93]
	v_mfma_f32_16x16x32_bf16 v[78:81], v[168:171], v[228:231], v[78:81]
	v_mfma_f32_16x16x32_bf16 v[74:77], v[176:179], v[228:231], v[74:77]
	s_setprio 0
	s_setprio 1
	v_mfma_f32_16x16x32_bf16 v[118:121], v[184:187], v[200:203], v[118:121]
	v_mfma_f32_16x16x32_bf16 v[114:117], v[192:195], v[200:203], v[114:117]
	v_mfma_f32_16x16x32_bf16 v[102:105], v[184:187], v[208:211], v[102:105]
	v_mfma_f32_16x16x32_bf16 v[98:101], v[192:195], v[208:211], v[98:101]
	v_mfma_f32_16x16x32_bf16 v[86:89], v[184:187], v[216:219], v[86:89]
	v_mfma_f32_16x16x32_bf16 v[82:85], v[192:195], v[216:219], v[82:85]
	v_mfma_f32_16x16x32_bf16 v[70:73], v[184:187], v[224:227], v[70:73]
	v_mfma_f32_16x16x32_bf16 v[66:69], v[192:195], v[224:227], v[66:69]
	v_mfma_f32_16x16x32_bf16 v[118:121], v[188:191], v[204:207], v[118:121]
	v_mfma_f32_16x16x32_bf16 v[114:117], v[196:199], v[204:207], v[114:117]
	v_mfma_f32_16x16x32_bf16 v[102:105], v[188:191], v[212:215], v[102:105]
	v_mfma_f32_16x16x32_bf16 v[98:101], v[196:199], v[212:215], v[98:101]
	v_mfma_f32_16x16x32_bf16 v[86:89], v[188:191], v[220:223], v[86:89]
	v_mfma_f32_16x16x32_bf16 v[82:85], v[196:199], v[220:223], v[82:85]
	v_mfma_f32_16x16x32_bf16 v[70:73], v[188:191], v[228:231], v[70:73]
	v_mfma_f32_16x16x32_bf16 v[66:69], v[196:199], v[228:231], v[66:69]
	s_setprio 0
	s_barrier
	s_add_i32 s80, s50, s34
	v_lshl_add_u64 v[152:153], s[28:29], 0, v[132:133]
	s_mov_b32 m0, s80
	ds_read_b128 v[200:203], v166 offset:16384
	ds_read_b128 v[204:207], v166 offset:17408
	ds_read_b128 v[208:211], v166 offset:18432
	ds_read_b128 v[212:215], v166 offset:19456
	ds_read_b128 v[216:219], v166 offset:20480
	ds_read_b128 v[220:223], v166 offset:21504
	ds_read_b128 v[224:227], v166 offset:22528
	ds_read_b128 v[228:231], v166 offset:23552
	global_load_lds_dwordx4 v[152:153], off
	s_add_i32 m0, s80, 0x2000
	s_add_u32 s80, s28, 0x100000
	v_lshl_add_u64 v[180:181], s[28:29], 0, v[136:137]
	s_addc_u32 s81, s29, 0
	s_add_i32 s82, s51, s34
	global_load_lds_dwordx4 v[180:181], off
	v_lshl_add_u64 v[232:233], s[80:81], 0, v[132:133]
	s_mov_b32 m0, s82
	v_lshl_add_u64 v[234:235], s[30:31], 0, v[134:135]
	global_load_lds_dwordx4 v[232:233], off
	v_lshl_add_u64 v[232:233], s[80:81], 0, v[136:137]
	s_add_i32 m0, s82, 0x2000
	s_nop 0
	global_load_lds_dwordx4 v[232:233], off
	v_lshl_add_u64 v[232:233], s[30:31], 0, v[130:131]
	s_mov_b32 m0, s25
	s_nop 0
	global_load_lds_dwordx4 v[232:233], off
	s_mov_b32 m0, s41
	s_nop 0
	global_load_lds_dwordx4 v[234:235], off
	s_cmp_eq_u32 s98, 0
	s_cbranch_scc1 .Lgw237_1a
	s_waitcnt vmcnt(24)
	s_branch .Lgw237_1b

.Lgw237_1b:
	s_mov_b32 s98, 0
	s_waitcnt lgkmcnt(0)
	s_barrier
	s_setprio 1
	s_waitcnt lgkmcnt(0)
	v_mfma_f32_16x16x32_bf16 v[62:65], v[148:151], v[200:203], v[62:65]
	v_mfma_f32_16x16x32_bf16 v[58:61], v[172:175], v[200:203], v[58:61]
	v_mfma_f32_16x16x32_bf16 v[46:49], v[148:151], v[208:211], v[46:49]
	v_mfma_f32_16x16x32_bf16 v[42:45], v[172:175], v[208:211], v[42:45]
	v_mfma_f32_16x16x32_bf16 v[30:33], v[148:151], v[216:219], v[30:33]
	v_mfma_f32_16x16x32_bf16 v[26:29], v[172:175], v[216:219], v[26:29]
	v_mfma_f32_16x16x32_bf16 v[14:17], v[148:151], v[224:227], v[14:17]
	v_mfma_f32_16x16x32_bf16 v[10:13], v[172:175], v[224:227], v[10:13]
	v_mfma_f32_16x16x32_bf16 v[62:65], v[168:171], v[204:207], v[62:65]
	v_mfma_f32_16x16x32_bf16 v[58:61], v[176:179], v[204:207], v[58:61]
	v_mfma_f32_16x16x32_bf16 v[46:49], v[168:171], v[212:215], v[46:49]
	v_mfma_f32_16x16x32_bf16 v[42:45], v[176:179], v[212:215], v[42:45]
	v_mfma_f32_16x16x32_bf16 v[30:33], v[168:171], v[220:223], v[30:33]
	v_mfma_f32_16x16x32_bf16 v[26:29], v[176:179], v[220:223], v[26:29]
	v_mfma_f32_16x16x32_bf16 v[14:17], v[168:171], v[228:231], v[14:17]
	v_mfma_f32_16x16x32_bf16 v[10:13], v[176:179], v[228:231], v[10:13]
	s_setprio 0
	s_setprio 1
	v_mfma_f32_16x16x32_bf16 v[54:57], v[184:187], v[200:203], v[54:57]
	v_mfma_f32_16x16x32_bf16 v[50:53], v[192:195], v[200:203], v[50:53]
	v_mfma_f32_16x16x32_bf16 v[38:41], v[184:187], v[208:211], v[38:41]
	v_mfma_f32_16x16x32_bf16 v[34:37], v[192:195], v[208:211], v[34:37]
	v_mfma_f32_16x16x32_bf16 v[22:25], v[184:187], v[216:219], v[22:25]
	v_mfma_f32_16x16x32_bf16 v[18:21], v[192:195], v[216:219], v[18:21]
	v_mfma_f32_16x16x32_bf16 v[6:9], v[184:187], v[224:227], v[6:9]
	v_mfma_f32_16x16x32_bf16 v[2:5], v[192:195], v[224:227], v[2:5]
	v_mfma_f32_16x16x32_bf16 v[54:57], v[188:191], v[204:207], v[54:57]
	v_mfma_f32_16x16x32_bf16 v[50:53], v[196:199], v[204:207], v[50:53]
	v_mfma_f32_16x16x32_bf16 v[38:41], v[188:191], v[212:215], v[38:41]
	v_mfma_f32_16x16x32_bf16 v[34:37], v[196:199], v[212:215], v[34:37]
	v_mfma_f32_16x16x32_bf16 v[22:25], v[188:191], v[220:223], v[22:25]
	v_mfma_f32_16x16x32_bf16 v[18:21], v[196:199], v[220:223], v[18:21]
	v_mfma_f32_16x16x32_bf16 v[6:9], v[188:191], v[228:231], v[6:9]
	v_mfma_f32_16x16x32_bf16 v[2:5], v[196:199], v[228:231], v[2:5]
	s_setprio 0
	s_barrier
	s_add_i32 s80, 0, 0x18000
	v_add_u32_e32 v167, s80, v161
	s_add_i32 s81, 0, 0x1c000
	ds_read_b128 v[148:151], v167
	ds_read_b128 v[168:171], v167 offset:1024
	ds_read_b128 v[172:175], v167 offset:2048
	ds_read_b128 v[176:179], v167 offset:3072
	v_add_u32_e32 v167, s81, v161
	ds_read_b128 v[184:187], v167
	ds_read_b128 v[188:191], v167 offset:1024
	ds_read_b128 v[192:195], v167 offset:2048
	ds_read_b128 v[196:199], v167 offset:3072
	s_add_u32 s30, s30, 0x100000
	s_addc_u32 s31, s31, 0
	s_mov_b32 m0, s42
	v_lshl_add_u64 v[236:237], s[30:31], 0, v[130:131]
	ds_read_b128 v[200:203], v166 offset:32768
	ds_read_b128 v[204:207], v166 offset:33792
	ds_read_b128 v[208:211], v166 offset:34816
	ds_read_b128 v[212:215], v166 offset:35840
	ds_read_b128 v[216:219], v166 offset:36864
	ds_read_b128 v[220:223], v166 offset:37888
	ds_read_b128 v[224:227], v166 offset:38912
	ds_read_b128 v[228:231], v166 offset:39936
	global_load_lds_dwordx4 v[236:237], off
	v_lshl_add_u64 v[236:237], s[30:31], 0, v[134:135]
	s_mov_b32 m0, s44
	s_nop 0
	global_load_lds_dwordx4 v[236:237], off
	s_waitcnt vmcnt(8)
	s_waitcnt lgkmcnt(0)
	s_barrier
	s_setprio 1
	s_waitcnt lgkmcnt(0)
	v_mfma_f32_16x16x32_bf16 v[126:129], v[148:151], v[200:203], v[126:129]
	v_mfma_f32_16x16x32_bf16 v[122:125], v[172:175], v[200:203], v[122:125]
	v_mfma_f32_16x16x32_bf16 v[110:113], v[148:151], v[208:211], v[110:113]
	v_mfma_f32_16x16x32_bf16 v[106:109], v[172:175], v[208:211], v[106:109]
	v_mfma_f32_16x16x32_bf16 v[94:97], v[148:151], v[216:219], v[94:97]
	v_mfma_f32_16x16x32_bf16 v[90:93], v[172:175], v[216:219], v[90:93]
	v_mfma_f32_16x16x32_bf16 v[78:81], v[148:151], v[224:227], v[78:81]
	v_mfma_f32_16x16x32_bf16 v[74:77], v[172:175], v[224:227], v[74:77]
	v_mfma_f32_16x16x32_bf16 v[126:129], v[168:171], v[204:207], v[126:129]
	v_mfma_f32_16x16x32_bf16 v[122:125], v[176:179], v[204:207], v[122:125]
	v_mfma_f32_16x16x32_bf16 v[110:113], v[168:171], v[212:215], v[110:113]
	v_mfma_f32_16x16x32_bf16 v[106:109], v[176:179], v[212:215], v[106:109]
	v_mfma_f32_16x16x32_bf16 v[94:97], v[168:171], v[220:223], v[94:97]
	v_mfma_f32_16x16x32_bf16 v[90:93], v[176:179], v[220:223], v[90:93]
	v_mfma_f32_16x16x32_bf16 v[78:81], v[168:171], v[228:231], v[78:81]
	v_mfma_f32_16x16x32_bf16 v[74:77], v[176:179], v[228:231], v[74:77]
	s_setprio 0
	s_setprio 1
	v_mfma_f32_16x16x32_bf16 v[118:121], v[184:187], v[200:203], v[118:121]
	v_mfma_f32_16x16x32_bf16 v[114:117], v[192:195], v[200:203], v[114:117]
	v_mfma_f32_16x16x32_bf16 v[102:105], v[184:187], v[208:211], v[102:105]
	v_mfma_f32_16x16x32_bf16 v[98:101], v[192:195], v[208:211], v[98:101]
	v_mfma_f32_16x16x32_bf16 v[86:89], v[184:187], v[216:219], v[86:89]
	v_mfma_f32_16x16x32_bf16 v[82:85], v[192:195], v[216:219], v[82:85]
	v_mfma_f32_16x16x32_bf16 v[70:73], v[184:187], v[224:227], v[70:73]
	v_mfma_f32_16x16x32_bf16 v[66:69], v[192:195], v[224:227], v[66:69]
	v_mfma_f32_16x16x32_bf16 v[118:121], v[188:191], v[204:207], v[118:121]
	v_mfma_f32_16x16x32_bf16 v[114:117], v[196:199], v[204:207], v[114:117]
	v_mfma_f32_16x16x32_bf16 v[102:105], v[188:191], v[212:215], v[102:105]
	v_mfma_f32_16x16x32_bf16 v[98:101], v[196:199], v[212:215], v[98:101]
	v_mfma_f32_16x16x32_bf16 v[86:89], v[188:191], v[220:223], v[86:89]
	v_mfma_f32_16x16x32_bf16 v[82:85], v[196:199], v[220:223], v[82:85]
	v_mfma_f32_16x16x32_bf16 v[70:73], v[188:191], v[228:231], v[70:73]
	v_mfma_f32_16x16x32_bf16 v[66:69], v[196:199], v[228:231], v[66:69]
	s_setprio 0
	s_barrier
	s_add_i32 s30, s80, s34
	v_lshl_add_u64 v[152:153], v[152:153], 0, s[12:13]
	s_mov_b32 m0, s30
	ds_read_b128 v[200:203], v166 offset:49152
	ds_read_b128 v[204:207], v166 offset:50176
	ds_read_b128 v[208:211], v166 offset:51200
	ds_read_b128 v[212:215], v166 offset:52224
	ds_read_b128 v[216:219], v166 offset:53248
	ds_read_b128 v[220:223], v166 offset:54272
	ds_read_b128 v[224:227], v166 offset:55296
	ds_read_b128 v[228:231], v166 offset:56320
	global_load_lds_dwordx4 v[152:153], off
	s_add_i32 m0, s30, 0x2000
	s_add_u32 s28, s28, 0x100080
	v_lshl_add_u64 v[152:153], v[180:181], 0, s[12:13]
	s_addc_u32 s29, s29, 0
	s_add_i32 s30, s81, s34
	global_load_lds_dwordx4 v[152:153], off
	v_lshl_add_u64 v[152:153], s[28:29], 0, v[132:133]
	s_mov_b32 m0, s30
	s_nop 0
	global_load_lds_dwordx4 v[152:153], off
	v_lshl_add_u64 v[152:153], s[28:29], 0, v[136:137]
	s_add_i32 m0, s30, 0x2000
	s_nop 0
	global_load_lds_dwordx4 v[152:153], off
	v_lshl_add_u64 v[152:153], v[232:233], 0, s[12:13]
	s_mov_b32 m0, s46
	s_nop 0
	global_load_lds_dwordx4 v[152:153], off
	v_lshl_add_u64 v[152:153], v[234:235], 0, s[12:13]
	s_mov_b32 m0, s47
	s_nop 0
	global_load_lds_dwordx4 v[152:153], off
	s_waitcnt vmcnt(8)
	s_waitcnt lgkmcnt(0)
	s_barrier
	s_setprio 1
	s_waitcnt lgkmcnt(0)
	v_mfma_f32_16x16x32_bf16 v[62:65], v[148:151], v[200:203], v[62:65]
	v_mfma_f32_16x16x32_bf16 v[58:61], v[172:175], v[200:203], v[58:61]
	v_mfma_f32_16x16x32_bf16 v[46:49], v[148:151], v[208:211], v[46:49]
	v_mfma_f32_16x16x32_bf16 v[42:45], v[172:175], v[208:211], v[42:45]
	v_mfma_f32_16x16x32_bf16 v[30:33], v[148:151], v[216:219], v[30:33]
	v_mfma_f32_16x16x32_bf16 v[26:29], v[172:175], v[216:219], v[26:29]
	v_mfma_f32_16x16x32_bf16 v[14:17], v[148:151], v[224:227], v[14:17]
	v_mfma_f32_16x16x32_bf16 v[10:13], v[172:175], v[224:227], v[10:13]
	v_mfma_f32_16x16x32_bf16 v[62:65], v[168:171], v[204:207], v[62:65]
	v_mfma_f32_16x16x32_bf16 v[58:61], v[176:179], v[204:207], v[58:61]
	v_mfma_f32_16x16x32_bf16 v[46:49], v[168:171], v[212:215], v[46:49]
	v_mfma_f32_16x16x32_bf16 v[42:45], v[176:179], v[212:215], v[42:45]
	v_mfma_f32_16x16x32_bf16 v[30:33], v[168:171], v[220:223], v[30:33]
	v_mfma_f32_16x16x32_bf16 v[26:29], v[176:179], v[220:223], v[26:29]
	v_mfma_f32_16x16x32_bf16 v[14:17], v[168:171], v[228:231], v[14:17]
	v_mfma_f32_16x16x32_bf16 v[10:13], v[176:179], v[228:231], v[10:13]
	s_setprio 0
	s_setprio 1
	v_mfma_f32_16x16x32_bf16 v[54:57], v[184:187], v[200:203], v[54:57]
	v_mfma_f32_16x16x32_bf16 v[50:53], v[192:195], v[200:203], v[50:53]
	v_mfma_f32_16x16x32_bf16 v[38:41], v[184:187], v[208:211], v[38:41]
	v_mfma_f32_16x16x32_bf16 v[34:37], v[192:195], v[208:211], v[34:37]
	v_mfma_f32_16x16x32_bf16 v[22:25], v[184:187], v[216:219], v[22:25]
	v_mfma_f32_16x16x32_bf16 v[18:21], v[192:195], v[216:219], v[18:21]
	v_mfma_f32_16x16x32_bf16 v[6:9], v[184:187], v[224:227], v[6:9]
	v_mfma_f32_16x16x32_bf16 v[2:5], v[192:195], v[224:227], v[2:5]
	v_mfma_f32_16x16x32_bf16 v[54:57], v[188:191], v[204:207], v[54:57]
	v_mfma_f32_16x16x32_bf16 v[50:53], v[196:199], v[204:207], v[50:53]
	v_mfma_f32_16x16x32_bf16 v[38:41], v[188:191], v[212:215], v[38:41]
	v_mfma_f32_16x16x32_bf16 v[34:37], v[196:199], v[212:215], v[34:37]
	v_mfma_f32_16x16x32_bf16 v[22:25], v[188:191], v[220:223], v[22:25]
	v_mfma_f32_16x16x32_bf16 v[18:21], v[196:199], v[220:223], v[18:21]
	v_mfma_f32_16x16x32_bf16 v[6:9], v[188:191], v[228:231], v[6:9]
	v_mfma_f32_16x16x32_bf16 v[2:5], v[196:199], v[228:231], v[2:5]
	s_setprio 0
	s_barrier
	s_add_i32 s63, s63, 2
	s_add_u32 s26, s26, 0x100
	s_addc_u32 s27, s27, 0
	s_add_u32 s59, s59, 0x100
	s_addc_u32 s62, s62, 0
	s_cmp_gt_u32 s63, 61
	s_cbranch_scc0 .LBB0_237
	s_and_b64 vcc, exec, s[14:15]
	s_cbranch_vccz .LBB0_240
	s_barrier
.LBB0_240:
	v_lshl_add_u32 v150, s24, 8, v160
	v_lshl_or_b32 v148, s52, 8, v162
	v_ashrrev_i32_e32 v151, 31, v150
	v_ashrrev_i32_e32 v149, 31, v148
	v_lshlrev_b64 v[152:153], 13, v[150:151]
	v_lshl_add_u64 v[168:169], s[10:11], 0, v[152:153]
	v_lshlrev_b64 v[152:153], 1, v[148:149]
	v_mul_f32_e32 v151, 0xbfb8aa3b, v126
	v_lshl_add_u64 v[148:149], v[168:169], 0, v[152:153]
	v_mul_f32_e32 v167, 0xbfb8aa3b, v122
	v_mul_f32_e32 v168, 0xbfb8aa3b, v127
	v_exp_f32_e32 v151, v151
	v_exp_f32_e32 v167, v167
	v_exp_f32_e32 v168, v168
	v_mul_f32_e32 v169, 0xbfb8aa3b, v123
	v_add_f32_e32 v151, 1.0, v151
	v_add_f32_e32 v167, 1.0, v167
	v_add_f32_e32 v168, 1.0, v168
	v_rcp_f32_e32 v151, v151
	v_rcp_f32_e32 v167, v167
	v_rcp_f32_e32 v168, v168
	v_exp_f32_e32 v169, v169
	v_mul_f32_e32 v126, v126, v151
	v_mul_f32_e32 v151, v122, v167
	v_mul_f32_e32 v122, v127, v168
	v_add_f32_e32 v127, 1.0, v169
	v_mul_f32_e32 v167, 0xbfb8aa3b, v128
	v_mul_f32_e32 v168, 0xbfb8aa3b, v124
	v_rcp_f32_e32 v127, v127
	v_exp_f32_e32 v167, v167
	v_exp_f32_e32 v168, v168
	v_mul_f32_e32 v169, 0xbfb8aa3b, v125
	v_mul_f32_e32 v127, v123, v127
	v_add_f32_e32 v123, 1.0, v167
	v_add_f32_e32 v167, 1.0, v168
	v_mul_f32_e32 v168, 0xbfb8aa3b, v129
	v_exp_f32_e32 v168, v168
	v_exp_f32_e32 v169, v169
	v_rcp_f32_e32 v123, v123
	v_rcp_f32_e32 v167, v167
	v_add_f32_e32 v168, 1.0, v168
	v_rcp_f32_e32 v168, v168
	v_add_f32_e32 v169, 1.0, v169
	v_rcp_f32_e32 v169, v169
	v_mul_f32_e32 v123, v128, v123
	v_mul_f32_e32 v128, v124, v167
	v_mul_f32_e32 v124, v129, v168
	v_cvt_pk_bf16_f32 v122, v126, v122
	v_cvt_pk_bf16_f32 v123, v123, v124
	v_mul_f32_e32 v124, 0xbfb8aa3b, v118
	v_mul_f32_e32 v125, v125, v169
	v_exp_f32_e32 v126, v124
	v_cvt_pk_bf16_f32 v124, v151, v127
	v_cvt_pk_bf16_f32 v125, v128, v125
	global_store_dwordx4 v[148:149], v[122:125], off
	s_mov_b32 s17, 0x100000
	s_mov_b64 s[26:27], 0x100000
	v_mul_f32_e32 v123, 0xbfb8aa3b, v114
	v_mul_f32_e32 v124, 0xbfb8aa3b, v119
	v_exp_f32_e32 v123, v123
	v_exp_f32_e32 v124, v124
	v_add_f32_e32 v122, 1.0, v126
	v_mul_f32_e32 v125, 0xbfb8aa3b, v115
	v_add_f32_e32 v123, 1.0, v123
	v_add_f32_e32 v124, 1.0, v124
	v_rcp_f32_e32 v122, v122
	v_rcp_f32_e32 v123, v123
	v_rcp_f32_e32 v124, v124
	v_exp_f32_e32 v125, v125
	v_mul_f32_e32 v118, v118, v122
	v_mul_f32_e32 v122, v114, v123
	v_mul_f32_e32 v114, v119, v124
	v_add_f32_e32 v119, 1.0, v125
	v_mul_f32_e32 v123, 0xbfb8aa3b, v120
	v_mul_f32_e32 v124, 0xbfb8aa3b, v116
	v_rcp_f32_e32 v119, v119
	v_exp_f32_e32 v123, v123
	v_exp_f32_e32 v124, v124
	v_mul_f32_e32 v125, 0xbfb8aa3b, v117
	v_mul_f32_e32 v119, v115, v119
	v_add_f32_e32 v115, 1.0, v123
	v_add_f32_e32 v123, 1.0, v124
	v_mul_f32_e32 v124, 0xbfb8aa3b, v121
	v_exp_f32_e32 v124, v124
	v_exp_f32_e32 v125, v125
	v_rcp_f32_e32 v115, v115
	v_rcp_f32_e32 v123, v123
	v_add_f32_e32 v124, 1.0, v124
	v_add_f32_e32 v125, 1.0, v125
	v_rcp_f32_e32 v124, v124
	v_rcp_f32_e32 v125, v125
	v_mul_f32_e32 v115, v120, v115
	v_mul_f32_e32 v120, v116, v123
	v_mul_f32_e32 v116, v121, v124
	v_mul_f32_e32 v117, v117, v125
	v_cvt_pk_bf16_f32 v114, v118, v114
	v_cvt_pk_bf16_f32 v115, v115, v116
	v_cvt_pk_bf16_f32 v116, v122, v119
	v_cvt_pk_bf16_f32 v117, v120, v117
	global_store_dwordx4 v[148:149], v[114:117], off offset:256
	v_mul_f32_e32 v118, 0xbfb8aa3b, v111
	v_exp_f32_e32 v118, v118
	v_mul_f32_e32 v116, 0xbfb8aa3b, v110
	v_mul_f32_e32 v117, 0xbfb8aa3b, v106
	v_exp_f32_e32 v116, v116
	v_exp_f32_e32 v117, v117
	v_add_f32_e32 v118, 1.0, v118
	v_mul_f32_e32 v119, 0xbfb8aa3b, v107
	v_add_f32_e32 v116, 1.0, v116
	v_add_f32_e32 v117, 1.0, v117
	v_rcp_f32_e32 v116, v116
	v_rcp_f32_e32 v117, v117
	v_rcp_f32_e32 v118, v118
	v_exp_f32_e32 v119, v119
	v_mul_f32_e32 v110, v110, v116
	v_mul_f32_e32 v116, v106, v117
	v_mul_f32_e32 v106, v111, v118
	v_add_f32_e32 v111, 1.0, v119
	v_mul_f32_e32 v117, 0xbfb8aa3b, v112
	v_mul_f32_e32 v118, 0xbfb8aa3b, v108
	v_rcp_f32_e32 v111, v111
	v_exp_f32_e32 v117, v117
	v_exp_f32_e32 v118, v118
	v_mul_f32_e32 v119, 0xbfb8aa3b, v109
	v_mul_f32_e32 v111, v107, v111
	v_add_f32_e32 v107, 1.0, v117
	v_add_f32_e32 v117, 1.0, v118
	v_mul_f32_e32 v118, 0xbfb8aa3b, v113
	v_exp_f32_e32 v118, v118
	v_exp_f32_e32 v119, v119
	v_rcp_f32_e32 v107, v107
	v_rcp_f32_e32 v117, v117
	v_add_f32_e32 v118, 1.0, v118
	v_rcp_f32_e32 v118, v118
	v_add_f32_e32 v119, 1.0, v119
	v_or_b32_e32 v114, 16, v150
	v_rcp_f32_e32 v119, v119
	v_ashrrev_i32_e32 v115, 31, v114
	v_lshlrev_b64 v[114:115], 13, v[114:115]
	v_mul_f32_e32 v107, v112, v107
	v_mul_f32_e32 v112, v108, v117
	v_mul_f32_e32 v108, v113, v118
	v_lshl_add_u64 v[114:115], s[10:11], 0, v[114:115]
	v_cvt_pk_bf16_f32 v106, v110, v106
	v_cvt_pk_bf16_f32 v107, v107, v108
	v_mul_f32_e32 v108, 0xbfb8aa3b, v102
	v_lshl_add_u64 v[114:115], v[114:115], 0, v[152:153]
	v_mul_f32_e32 v109, v109, v119
	v_exp_f32_e32 v110, v108
	v_cvt_pk_bf16_f32 v108, v116, v111
	v_cvt_pk_bf16_f32 v109, v112, v109
	global_store_dwordx4 v[114:115], v[106:109], off
	s_nop 1
	v_mul_f32_e32 v107, 0xbfb8aa3b, v98
	v_mul_f32_e32 v108, 0xbfb8aa3b, v103
	v_exp_f32_e32 v107, v107
	v_exp_f32_e32 v108, v108
	v_add_f32_e32 v106, 1.0, v110
	v_mul_f32_e32 v109, 0xbfb8aa3b, v99
	v_add_f32_e32 v107, 1.0, v107
	v_add_f32_e32 v108, 1.0, v108
	v_rcp_f32_e32 v106, v106
	v_rcp_f32_e32 v107, v107
	v_rcp_f32_e32 v108, v108
	v_exp_f32_e32 v109, v109
	v_mul_f32_e32 v102, v102, v106
	v_mul_f32_e32 v106, v98, v107
	v_mul_f32_e32 v98, v103, v108
	v_add_f32_e32 v103, 1.0, v109
	v_mul_f32_e32 v107, 0xbfb8aa3b, v104
	v_mul_f32_e32 v108, 0xbfb8aa3b, v100
	v_rcp_f32_e32 v103, v103
	v_exp_f32_e32 v107, v107
	v_exp_f32_e32 v108, v108
	v_mul_f32_e32 v109, 0xbfb8aa3b, v101
	v_mul_f32_e32 v103, v99, v103
	v_add_f32_e32 v99, 1.0, v107
	v_add_f32_e32 v107, 1.0, v108
	v_mul_f32_e32 v108, 0xbfb8aa3b, v105
	v_exp_f32_e32 v108, v108
	v_exp_f32_e32 v109, v109
	v_rcp_f32_e32 v99, v99
	v_rcp_f32_e32 v107, v107
	v_add_f32_e32 v108, 1.0, v108
	v_add_f32_e32 v109, 1.0, v109
	v_rcp_f32_e32 v108, v108
	v_rcp_f32_e32 v109, v109
	v_mul_f32_e32 v99, v104, v99
	v_mul_f32_e32 v104, v100, v107
	v_mul_f32_e32 v100, v105, v108
	v_mul_f32_e32 v101, v101, v109
	v_cvt_pk_bf16_f32 v98, v102, v98
	v_cvt_pk_bf16_f32 v99, v99, v100
	v_cvt_pk_bf16_f32 v100, v106, v103
	v_cvt_pk_bf16_f32 v101, v104, v101
	global_store_dwordx4 v[114:115], v[98:101], off offset:256
	v_mul_f32_e32 v102, 0xbfb8aa3b, v95
	v_exp_f32_e32 v102, v102
	v_mul_f32_e32 v100, 0xbfb8aa3b, v94
	v_mul_f32_e32 v101, 0xbfb8aa3b, v90
	v_exp_f32_e32 v100, v100
	v_exp_f32_e32 v101, v101
	v_add_f32_e32 v102, 1.0, v102
	v_mul_f32_e32 v103, 0xbfb8aa3b, v91
	v_add_f32_e32 v100, 1.0, v100
	v_add_f32_e32 v101, 1.0, v101
	v_rcp_f32_e32 v100, v100
	v_rcp_f32_e32 v101, v101
	v_rcp_f32_e32 v102, v102
	v_exp_f32_e32 v103, v103
	v_mul_f32_e32 v94, v94, v100
	v_mul_f32_e32 v100, v90, v101
	v_mul_f32_e32 v90, v95, v102
	v_add_f32_e32 v95, 1.0, v103
	v_mul_f32_e32 v101, 0xbfb8aa3b, v96
	v_mul_f32_e32 v102, 0xbfb8aa3b, v92
	v_rcp_f32_e32 v95, v95
	v_exp_f32_e32 v101, v101
	v_exp_f32_e32 v102, v102
	v_mul_f32_e32 v103, 0xbfb8aa3b, v93
	v_mul_f32_e32 v95, v91, v95
	v_add_f32_e32 v91, 1.0, v101
	v_add_f32_e32 v101, 1.0, v102
	v_mul_f32_e32 v102, 0xbfb8aa3b, v97
	v_exp_f32_e32 v102, v102
	v_exp_f32_e32 v103, v103
	v_rcp_f32_e32 v91, v91
	v_rcp_f32_e32 v101, v101
	v_add_f32_e32 v102, 1.0, v102
	v_rcp_f32_e32 v102, v102
	v_add_f32_e32 v103, 1.0, v103
	v_or_b32_e32 v98, 32, v150
	v_rcp_f32_e32 v103, v103
	v_ashrrev_i32_e32 v99, 31, v98
	v_lshlrev_b64 v[98:99], 13, v[98:99]
	v_mul_f32_e32 v91, v96, v91
	v_mul_f32_e32 v96, v92, v101
	v_mul_f32_e32 v92, v97, v102
	v_lshl_add_u64 v[98:99], s[10:11], 0, v[98:99]
	v_cvt_pk_bf16_f32 v90, v94, v90
	v_cvt_pk_bf16_f32 v91, v91, v92
	v_mul_f32_e32 v92, 0xbfb8aa3b, v86
	v_lshl_add_u64 v[98:99], v[98:99], 0, v[152:153]
	v_mul_f32_e32 v93, v93, v103
	v_exp_f32_e32 v94, v92
	v_cvt_pk_bf16_f32 v92, v100, v95
	v_cvt_pk_bf16_f32 v93, v96, v93
	global_store_dwordx4 v[98:99], v[90:93], off
	s_nop 1
	v_mul_f32_e32 v91, 0xbfb8aa3b, v82
	v_mul_f32_e32 v92, 0xbfb8aa3b, v87
	v_exp_f32_e32 v91, v91
	v_exp_f32_e32 v92, v92
	v_add_f32_e32 v90, 1.0, v94
	v_mul_f32_e32 v93, 0xbfb8aa3b, v83
	v_add_f32_e32 v91, 1.0, v91
	v_add_f32_e32 v92, 1.0, v92
	v_rcp_f32_e32 v90, v90
	v_rcp_f32_e32 v91, v91
	v_rcp_f32_e32 v92, v92
	v_exp_f32_e32 v93, v93
	v_mul_f32_e32 v86, v86, v90
	v_mul_f32_e32 v90, v82, v91
	v_mul_f32_e32 v82, v87, v92
	v_add_f32_e32 v87, 1.0, v93
	v_mul_f32_e32 v91, 0xbfb8aa3b, v88
	v_mul_f32_e32 v92, 0xbfb8aa3b, v84
	v_rcp_f32_e32 v87, v87
	v_exp_f32_e32 v91, v91
	v_exp_f32_e32 v92, v92
	v_mul_f32_e32 v93, 0xbfb8aa3b, v85
	v_mul_f32_e32 v87, v83, v87
	v_add_f32_e32 v83, 1.0, v91
	v_add_f32_e32 v91, 1.0, v92
	v_mul_f32_e32 v92, 0xbfb8aa3b, v89
	v_exp_f32_e32 v92, v92
	v_exp_f32_e32 v93, v93
	v_rcp_f32_e32 v83, v83
	v_rcp_f32_e32 v91, v91
	v_add_f32_e32 v92, 1.0, v92
	v_add_f32_e32 v93, 1.0, v93
	v_rcp_f32_e32 v92, v92
	v_rcp_f32_e32 v93, v93
	v_mul_f32_e32 v83, v88, v83
	v_mul_f32_e32 v88, v84, v91
	v_mul_f32_e32 v84, v89, v92
	v_mul_f32_e32 v85, v85, v93
	v_cvt_pk_bf16_f32 v82, v86, v82
	v_cvt_pk_bf16_f32 v83, v83, v84
	v_cvt_pk_bf16_f32 v84, v90, v87
	v_cvt_pk_bf16_f32 v85, v88, v85
	global_store_dwordx4 v[98:99], v[82:85], off offset:256
	v_mul_f32_e32 v86, 0xbfb8aa3b, v79
	v_exp_f32_e32 v86, v86
	v_mul_f32_e32 v84, 0xbfb8aa3b, v78
	v_mul_f32_e32 v85, 0xbfb8aa3b, v74
	v_exp_f32_e32 v84, v84
	v_exp_f32_e32 v85, v85
	v_add_f32_e32 v86, 1.0, v86
	v_mul_f32_e32 v87, 0xbfb8aa3b, v75
	v_add_f32_e32 v84, 1.0, v84
	v_add_f32_e32 v85, 1.0, v85
	v_rcp_f32_e32 v84, v84
	v_rcp_f32_e32 v85, v85
	v_rcp_f32_e32 v86, v86
	v_exp_f32_e32 v87, v87
	v_mul_f32_e32 v78, v78, v84
	v_mul_f32_e32 v84, v74, v85
	v_mul_f32_e32 v74, v79, v86
	v_add_f32_e32 v79, 1.0, v87
	v_mul_f32_e32 v85, 0xbfb8aa3b, v80
	v_mul_f32_e32 v86, 0xbfb8aa3b, v76
	v_rcp_f32_e32 v79, v79
	v_exp_f32_e32 v85, v85
	v_exp_f32_e32 v86, v86
	v_mul_f32_e32 v87, 0xbfb8aa3b, v77
	v_mul_f32_e32 v79, v75, v79
	v_add_f32_e32 v75, 1.0, v85
	v_add_f32_e32 v85, 1.0, v86
	v_mul_f32_e32 v86, 0xbfb8aa3b, v81
	v_exp_f32_e32 v86, v86
	v_exp_f32_e32 v87, v87
	v_rcp_f32_e32 v75, v75
	v_rcp_f32_e32 v85, v85
	v_add_f32_e32 v86, 1.0, v86
	v_rcp_f32_e32 v86, v86
	v_add_f32_e32 v87, 1.0, v87
	v_or_b32_e32 v82, 48, v150
	v_rcp_f32_e32 v87, v87
	v_ashrrev_i32_e32 v83, 31, v82
	v_lshlrev_b64 v[82:83], 13, v[82:83]
	v_mul_f32_e32 v75, v80, v75
	v_mul_f32_e32 v80, v76, v85
	v_mul_f32_e32 v76, v81, v86
	v_lshl_add_u64 v[82:83], s[10:11], 0, v[82:83]
	v_cvt_pk_bf16_f32 v74, v78, v74
	v_cvt_pk_bf16_f32 v75, v75, v76
	v_mul_f32_e32 v76, 0xbfb8aa3b, v70
	v_lshl_add_u64 v[82:83], v[82:83], 0, v[152:153]
	v_mul_f32_e32 v77, v77, v87
	v_exp_f32_e32 v78, v76
	v_cvt_pk_bf16_f32 v76, v84, v79
	v_cvt_pk_bf16_f32 v77, v80, v77
	global_store_dwordx4 v[82:83], v[74:77], off
	s_nop 1
	v_mul_f32_e32 v75, 0xbfb8aa3b, v66
	v_mul_f32_e32 v76, 0xbfb8aa3b, v71
	v_exp_f32_e32 v75, v75
	v_exp_f32_e32 v76, v76
	v_add_f32_e32 v74, 1.0, v78
	v_mul_f32_e32 v77, 0xbfb8aa3b, v67
	v_add_f32_e32 v75, 1.0, v75
	v_add_f32_e32 v76, 1.0, v76
	v_rcp_f32_e32 v74, v74
	v_rcp_f32_e32 v75, v75
	v_rcp_f32_e32 v76, v76
	v_exp_f32_e32 v77, v77
	v_mul_f32_e32 v70, v70, v74
	v_mul_f32_e32 v74, v66, v75
	v_mul_f32_e32 v66, v71, v76
	v_add_f32_e32 v71, 1.0, v77
	v_mul_f32_e32 v75, 0xbfb8aa3b, v72
	v_mul_f32_e32 v76, 0xbfb8aa3b, v68
	v_rcp_f32_e32 v71, v71
	v_exp_f32_e32 v75, v75
	v_exp_f32_e32 v76, v76
	v_mul_f32_e32 v77, 0xbfb8aa3b, v69
	v_mul_f32_e32 v71, v67, v71
	v_add_f32_e32 v67, 1.0, v75
	v_add_f32_e32 v75, 1.0, v76
	v_mul_f32_e32 v76, 0xbfb8aa3b, v73
	v_exp_f32_e32 v76, v76
	v_exp_f32_e32 v77, v77
	v_rcp_f32_e32 v67, v67
	v_rcp_f32_e32 v75, v75
	v_add_f32_e32 v76, 1.0, v76
	v_add_f32_e32 v77, 1.0, v77
	v_rcp_f32_e32 v76, v76
	v_rcp_f32_e32 v77, v77
	v_mul_f32_e32 v67, v72, v67
	v_mul_f32_e32 v72, v68, v75
	v_mul_f32_e32 v68, v73, v76
	v_mul_f32_e32 v69, v69, v77
	v_cvt_pk_bf16_f32 v66, v70, v66
	v_cvt_pk_bf16_f32 v67, v67, v68
	v_cvt_pk_bf16_f32 v68, v74, v71
	v_cvt_pk_bf16_f32 v69, v72, v69
	global_store_dwordx4 v[82:83], v[66:69], off offset:256
	v_mul_f32_e32 v70, 0xbfb8aa3b, v63
	v_exp_f32_e32 v70, v70
	v_mul_f32_e32 v66, 0xbfb8aa3b, v62
	v_mul_f32_e32 v69, 0xbfb8aa3b, v58
	v_exp_f32_e32 v68, v66
	v_exp_f32_e32 v69, v69
	v_add_f32_e32 v70, 1.0, v70
	v_mul_f32_e32 v71, 0xbfb8aa3b, v59
	v_add_f32_e32 v68, 1.0, v68
	v_add_f32_e32 v69, 1.0, v69
	v_rcp_f32_e32 v68, v68
	v_rcp_f32_e32 v69, v69
	v_rcp_f32_e32 v70, v70
	v_exp_f32_e32 v71, v71
	v_mul_f32_e32 v62, v62, v68
	v_mul_f32_e32 v68, v58, v69
	v_mul_f32_e32 v58, v63, v70
	v_add_f32_e32 v63, 1.0, v71
	v_mul_f32_e32 v69, 0xbfb8aa3b, v64
	v_mul_f32_e32 v70, 0xbfb8aa3b, v60
	v_rcp_f32_e32 v63, v63
	v_exp_f32_e32 v69, v69
	v_exp_f32_e32 v70, v70
	v_mul_f32_e32 v71, 0xbfb8aa3b, v61
	v_mul_f32_e32 v63, v59, v63
	v_add_f32_e32 v59, 1.0, v69
	v_add_f32_e32 v69, 1.0, v70
	v_mul_f32_e32 v70, 0xbfb8aa3b, v65
	v_exp_f32_e32 v70, v70
	v_exp_f32_e32 v71, v71
	v_rcp_f32_e32 v59, v59
	v_rcp_f32_e32 v69, v69
	v_add_f32_e32 v70, 1.0, v70
	v_add_f32_e32 v71, 1.0, v71
	v_rcp_f32_e32 v70, v70
	v_rcp_f32_e32 v71, v71
	v_mul_f32_e32 v59, v64, v59
	v_mul_f32_e32 v64, v60, v69
	v_mul_f32_e32 v60, v65, v70
	v_mul_f32_e32 v61, v61, v71
	v_cvt_pk_bf16_f32 v58, v62, v58
	v_mul_f32_e32 v62, 0xbfb8aa3b, v54
	v_cvt_pk_bf16_f32 v59, v59, v60
	v_cvt_pk_bf16_f32 v60, v68, v63
	v_cvt_pk_bf16_f32 v61, v64, v61
	v_exp_f32_e32 v64, v62
	v_add_co_u32_e32 v62, vcc, s17, v148
	v_lshl_add_u64 v[66:67], v[148:149], 0, s[26:27]
	s_nop 0
	v_addc_co_u32_e32 v63, vcc, 0, v149, vcc
	global_store_dwordx4 v[62:63], v[58:61], off
	s_mov_b32 s17, 0x120000
	s_mov_b64 s[26:27], 0x120000
	v_mul_f32_e32 v59, 0xbfb8aa3b, v50
	v_mul_f32_e32 v60, 0xbfb8aa3b, v55
	v_exp_f32_e32 v59, v59
	v_exp_f32_e32 v60, v60
	v_add_f32_e32 v58, 1.0, v64
	v_mul_f32_e32 v61, 0xbfb8aa3b, v51
	v_add_f32_e32 v59, 1.0, v59
	v_add_f32_e32 v60, 1.0, v60
	v_rcp_f32_e32 v58, v58
	v_rcp_f32_e32 v59, v59
	v_rcp_f32_e32 v60, v60
	v_exp_f32_e32 v61, v61
	v_mul_f32_e32 v54, v54, v58
	v_mul_f32_e32 v58, v50, v59
	v_mul_f32_e32 v50, v55, v60
	v_add_f32_e32 v55, 1.0, v61
	v_mul_f32_e32 v59, 0xbfb8aa3b, v56
	v_mul_f32_e32 v60, 0xbfb8aa3b, v52
	v_rcp_f32_e32 v55, v55
	v_exp_f32_e32 v59, v59
	v_exp_f32_e32 v60, v60
	v_mul_f32_e32 v61, 0xbfb8aa3b, v53
	v_mul_f32_e32 v55, v51, v55
	v_add_f32_e32 v51, 1.0, v59
	v_add_f32_e32 v59, 1.0, v60
	v_mul_f32_e32 v60, 0xbfb8aa3b, v57
	v_exp_f32_e32 v60, v60
	v_exp_f32_e32 v61, v61
	v_rcp_f32_e32 v51, v51
	v_rcp_f32_e32 v59, v59
	v_add_f32_e32 v60, 1.0, v60
	v_add_f32_e32 v61, 1.0, v61
	v_rcp_f32_e32 v60, v60
	v_rcp_f32_e32 v61, v61
	v_mul_f32_e32 v51, v56, v51
	v_mul_f32_e32 v56, v52, v59
	v_mul_f32_e32 v52, v57, v60
	v_mul_f32_e32 v53, v53, v61
	v_cvt_pk_bf16_f32 v50, v54, v50
	v_cvt_pk_bf16_f32 v51, v51, v52
	v_cvt_pk_bf16_f32 v52, v58, v55
	v_cvt_pk_bf16_f32 v53, v56, v53
	global_store_dwordx4 v[66:67], v[50:53], off offset:256
	v_mul_f32_e32 v54, 0xbfb8aa3b, v47
	v_exp_f32_e32 v54, v54
	v_mul_f32_e32 v50, 0xbfb8aa3b, v46
	v_mul_f32_e32 v53, 0xbfb8aa3b, v42
	v_exp_f32_e32 v52, v50
	v_exp_f32_e32 v53, v53
	v_add_f32_e32 v54, 1.0, v54
	v_mul_f32_e32 v55, 0xbfb8aa3b, v43
	v_add_f32_e32 v52, 1.0, v52
	v_add_f32_e32 v53, 1.0, v53
	v_rcp_f32_e32 v52, v52
	v_rcp_f32_e32 v53, v53
	v_rcp_f32_e32 v54, v54
	v_exp_f32_e32 v55, v55
	v_mul_f32_e32 v46, v46, v52
	v_mul_f32_e32 v52, v42, v53
	v_mul_f32_e32 v42, v47, v54
	v_add_f32_e32 v47, 1.0, v55
	v_mul_f32_e32 v53, 0xbfb8aa3b, v48
	v_mul_f32_e32 v54, 0xbfb8aa3b, v44
	v_rcp_f32_e32 v47, v47
	v_exp_f32_e32 v53, v53
	v_exp_f32_e32 v54, v54
	v_mul_f32_e32 v55, 0xbfb8aa3b, v45
	v_mul_f32_e32 v47, v43, v47
	v_add_f32_e32 v43, 1.0, v53
	v_add_f32_e32 v53, 1.0, v54
	v_mul_f32_e32 v54, 0xbfb8aa3b, v49
	v_exp_f32_e32 v54, v54
	v_exp_f32_e32 v55, v55
	v_rcp_f32_e32 v43, v43
	v_rcp_f32_e32 v53, v53
	v_add_f32_e32 v54, 1.0, v54
	v_add_f32_e32 v55, 1.0, v55
	v_rcp_f32_e32 v54, v54
	v_rcp_f32_e32 v55, v55
	v_mul_f32_e32 v43, v48, v43
	v_mul_f32_e32 v48, v44, v53
	v_mul_f32_e32 v44, v49, v54
	v_mul_f32_e32 v45, v45, v55
	v_cvt_pk_bf16_f32 v42, v46, v42
	v_mul_f32_e32 v46, 0xbfb8aa3b, v38
	v_cvt_pk_bf16_f32 v43, v43, v44
	v_cvt_pk_bf16_f32 v44, v52, v47
	v_cvt_pk_bf16_f32 v45, v48, v45
	v_exp_f32_e32 v48, v46
	v_add_co_u32_e32 v46, vcc, s17, v148
	v_lshl_add_u64 v[50:51], v[148:149], 0, s[26:27]
	s_nop 0
	v_addc_co_u32_e32 v47, vcc, 0, v149, vcc
	global_store_dwordx4 v[46:47], v[42:45], off
	s_mov_b32 s17, 0x140000
	s_mov_b64 s[26:27], 0x140000
	v_mul_f32_e32 v43, 0xbfb8aa3b, v34
	v_mul_f32_e32 v44, 0xbfb8aa3b, v39
	v_exp_f32_e32 v43, v43
	v_exp_f32_e32 v44, v44
	v_add_f32_e32 v42, 1.0, v48
	v_mul_f32_e32 v45, 0xbfb8aa3b, v35
	v_add_f32_e32 v43, 1.0, v43
	v_add_f32_e32 v44, 1.0, v44
	v_rcp_f32_e32 v42, v42
	v_rcp_f32_e32 v43, v43
	v_rcp_f32_e32 v44, v44
	v_exp_f32_e32 v45, v45
	v_mul_f32_e32 v38, v38, v42
	v_mul_f32_e32 v42, v34, v43
	v_mul_f32_e32 v34, v39, v44
	v_add_f32_e32 v39, 1.0, v45
	v_mul_f32_e32 v43, 0xbfb8aa3b, v40
	v_mul_f32_e32 v44, 0xbfb8aa3b, v36
	v_rcp_f32_e32 v39, v39
	v_exp_f32_e32 v43, v43
	v_exp_f32_e32 v44, v44
	v_mul_f32_e32 v45, 0xbfb8aa3b, v37
	v_mul_f32_e32 v39, v35, v39
	v_add_f32_e32 v35, 1.0, v43
	v_add_f32_e32 v43, 1.0, v44
	v_mul_f32_e32 v44, 0xbfb8aa3b, v41
	v_exp_f32_e32 v44, v44
	v_exp_f32_e32 v45, v45
	v_rcp_f32_e32 v35, v35
	v_rcp_f32_e32 v43, v43
	v_add_f32_e32 v44, 1.0, v44
	v_add_f32_e32 v45, 1.0, v45
	v_rcp_f32_e32 v44, v44
	v_rcp_f32_e32 v45, v45
	v_mul_f32_e32 v35, v40, v35
	v_mul_f32_e32 v40, v36, v43
	v_mul_f32_e32 v36, v41, v44
	v_mul_f32_e32 v37, v37, v45
	v_cvt_pk_bf16_f32 v34, v38, v34
	v_cvt_pk_bf16_f32 v35, v35, v36
	v_cvt_pk_bf16_f32 v36, v42, v39
	v_cvt_pk_bf16_f32 v37, v40, v37
	global_store_dwordx4 v[50:51], v[34:37], off offset:256
	v_mul_f32_e32 v38, 0xbfb8aa3b, v31
	v_exp_f32_e32 v38, v38
	v_mul_f32_e32 v34, 0xbfb8aa3b, v30
	v_mul_f32_e32 v37, 0xbfb8aa3b, v26
	v_exp_f32_e32 v36, v34
	v_exp_f32_e32 v37, v37
	v_add_f32_e32 v38, 1.0, v38
	v_mul_f32_e32 v39, 0xbfb8aa3b, v27
	v_add_f32_e32 v36, 1.0, v36
	v_add_f32_e32 v37, 1.0, v37
	v_rcp_f32_e32 v36, v36
	v_rcp_f32_e32 v37, v37
	v_rcp_f32_e32 v38, v38
	v_exp_f32_e32 v39, v39
	v_mul_f32_e32 v30, v30, v36
	v_mul_f32_e32 v36, v26, v37
	v_mul_f32_e32 v26, v31, v38
	v_add_f32_e32 v31, 1.0, v39
	v_mul_f32_e32 v37, 0xbfb8aa3b, v32
	v_mul_f32_e32 v38, 0xbfb8aa3b, v28
	v_rcp_f32_e32 v31, v31
	v_exp_f32_e32 v37, v37
	v_exp_f32_e32 v38, v38
	v_mul_f32_e32 v39, 0xbfb8aa3b, v29
	v_mul_f32_e32 v31, v27, v31
	v_add_f32_e32 v27, 1.0, v37
	v_add_f32_e32 v37, 1.0, v38
	v_mul_f32_e32 v38, 0xbfb8aa3b, v33
	v_exp_f32_e32 v38, v38
	v_exp_f32_e32 v39, v39
	v_rcp_f32_e32 v27, v27
	v_rcp_f32_e32 v37, v37
	v_add_f32_e32 v38, 1.0, v38
	v_add_f32_e32 v39, 1.0, v39
	v_rcp_f32_e32 v38, v38
	v_rcp_f32_e32 v39, v39
	v_mul_f32_e32 v27, v32, v27
	v_mul_f32_e32 v32, v28, v37
	v_mul_f32_e32 v28, v33, v38
	v_mul_f32_e32 v29, v29, v39
	v_cvt_pk_bf16_f32 v26, v30, v26
	v_mul_f32_e32 v30, 0xbfb8aa3b, v22
	v_cvt_pk_bf16_f32 v27, v27, v28
	v_cvt_pk_bf16_f32 v28, v36, v31
	v_cvt_pk_bf16_f32 v29, v32, v29
	v_exp_f32_e32 v32, v30
	v_add_co_u32_e32 v30, vcc, s17, v148
	v_lshl_add_u64 v[34:35], v[148:149], 0, s[26:27]
	s_nop 0
	v_addc_co_u32_e32 v31, vcc, 0, v149, vcc
	global_store_dwordx4 v[30:31], v[26:29], off
	s_mov_b32 s17, 0x160000
	s_mov_b64 s[26:27], 0x160000
	v_mul_f32_e32 v27, 0xbfb8aa3b, v18
	v_mul_f32_e32 v28, 0xbfb8aa3b, v23
	v_exp_f32_e32 v27, v27
	v_exp_f32_e32 v28, v28
	v_add_f32_e32 v26, 1.0, v32
	v_mul_f32_e32 v29, 0xbfb8aa3b, v19
	v_add_f32_e32 v27, 1.0, v27
	v_add_f32_e32 v28, 1.0, v28
	v_rcp_f32_e32 v26, v26
	v_rcp_f32_e32 v27, v27
	v_rcp_f32_e32 v28, v28
	v_exp_f32_e32 v29, v29
	v_mul_f32_e32 v22, v22, v26
	v_mul_f32_e32 v26, v18, v27
	v_mul_f32_e32 v18, v23, v28
	v_add_f32_e32 v23, 1.0, v29
	v_mul_f32_e32 v27, 0xbfb8aa3b, v24
	v_mul_f32_e32 v28, 0xbfb8aa3b, v20
	v_rcp_f32_e32 v23, v23
	v_exp_f32_e32 v27, v27
	v_exp_f32_e32 v28, v28
	v_mul_f32_e32 v29, 0xbfb8aa3b, v21
	v_mul_f32_e32 v23, v19, v23
	v_add_f32_e32 v19, 1.0, v27
	v_add_f32_e32 v27, 1.0, v28
	v_mul_f32_e32 v28, 0xbfb8aa3b, v25
	v_exp_f32_e32 v28, v28
	v_exp_f32_e32 v29, v29
	v_rcp_f32_e32 v19, v19
	v_rcp_f32_e32 v27, v27
	v_add_f32_e32 v28, 1.0, v28
	v_add_f32_e32 v29, 1.0, v29
	v_rcp_f32_e32 v28, v28
	v_rcp_f32_e32 v29, v29
	v_mul_f32_e32 v19, v24, v19
	v_mul_f32_e32 v24, v20, v27
	v_mul_f32_e32 v20, v25, v28
	v_mul_f32_e32 v21, v21, v29
	v_cvt_pk_bf16_f32 v18, v22, v18
	v_cvt_pk_bf16_f32 v19, v19, v20
	v_cvt_pk_bf16_f32 v20, v26, v23
	v_cvt_pk_bf16_f32 v21, v24, v21
	global_store_dwordx4 v[34:35], v[18:21], off offset:256
	v_mul_f32_e32 v22, 0xbfb8aa3b, v15
	v_exp_f32_e32 v22, v22
	v_mul_f32_e32 v18, 0xbfb8aa3b, v14
	v_mul_f32_e32 v21, 0xbfb8aa3b, v10
	v_exp_f32_e32 v20, v18
	v_exp_f32_e32 v21, v21
	v_add_f32_e32 v22, 1.0, v22
	v_mul_f32_e32 v23, 0xbfb8aa3b, v11
	v_add_f32_e32 v20, 1.0, v20
	v_add_f32_e32 v21, 1.0, v21
	v_rcp_f32_e32 v20, v20
	v_rcp_f32_e32 v21, v21
	v_rcp_f32_e32 v22, v22
	v_exp_f32_e32 v23, v23
	v_mul_f32_e32 v14, v14, v20
	v_mul_f32_e32 v20, v10, v21
	v_mul_f32_e32 v10, v15, v22
	v_add_f32_e32 v15, 1.0, v23
	v_mul_f32_e32 v21, 0xbfb8aa3b, v16
	v_mul_f32_e32 v22, 0xbfb8aa3b, v12
	v_rcp_f32_e32 v15, v15
	v_exp_f32_e32 v21, v21
	v_exp_f32_e32 v22, v22
	v_mul_f32_e32 v23, 0xbfb8aa3b, v13
	v_mul_f32_e32 v15, v11, v15
	v_add_f32_e32 v11, 1.0, v21
	v_add_f32_e32 v21, 1.0, v22
	v_mul_f32_e32 v22, 0xbfb8aa3b, v17
	v_exp_f32_e32 v22, v22
	v_exp_f32_e32 v23, v23
	v_rcp_f32_e32 v11, v11
	v_rcp_f32_e32 v21, v21
	v_add_f32_e32 v22, 1.0, v22
	v_add_f32_e32 v23, 1.0, v23
	v_rcp_f32_e32 v22, v22
	v_rcp_f32_e32 v23, v23
	v_mul_f32_e32 v11, v16, v11
	v_mul_f32_e32 v16, v12, v21
	v_mul_f32_e32 v12, v17, v22
	v_mul_f32_e32 v13, v13, v23
	v_cvt_pk_bf16_f32 v10, v14, v10
	v_mul_f32_e32 v14, 0xbfb8aa3b, v6
	v_cvt_pk_bf16_f32 v11, v11, v12
	v_cvt_pk_bf16_f32 v12, v20, v15
	v_cvt_pk_bf16_f32 v13, v16, v13
	v_exp_f32_e32 v16, v14
	v_add_co_u32_e32 v14, vcc, s17, v148
	v_lshl_add_u64 v[18:19], v[148:149], 0, s[26:27]
	s_nop 0
	v_addc_co_u32_e32 v15, vcc, 0, v149, vcc
	global_store_dwordx4 v[14:15], v[10:13], off
	s_andn2_b64 vcc, exec, s[0:1]
	s_mov_b64 s[0:1], -1
	v_mul_f32_e32 v11, 0xbfb8aa3b, v2
	v_mul_f32_e32 v12, 0xbfb8aa3b, v7
	v_exp_f32_e32 v11, v11
	v_exp_f32_e32 v12, v12
	v_add_f32_e32 v10, 1.0, v16
	v_mul_f32_e32 v13, 0xbfb8aa3b, v3
	v_add_f32_e32 v11, 1.0, v11
	v_add_f32_e32 v12, 1.0, v12
	v_rcp_f32_e32 v10, v10
	v_rcp_f32_e32 v11, v11
	v_rcp_f32_e32 v12, v12
	v_exp_f32_e32 v13, v13
	v_mul_f32_e32 v6, v6, v10
	v_mul_f32_e32 v10, v2, v11
	v_mul_f32_e32 v2, v7, v12
	v_add_f32_e32 v7, 1.0, v13
	v_mul_f32_e32 v11, 0xbfb8aa3b, v8
	v_mul_f32_e32 v12, 0xbfb8aa3b, v4
	v_rcp_f32_e32 v7, v7
	v_exp_f32_e32 v11, v11
	v_exp_f32_e32 v12, v12
	v_mul_f32_e32 v13, 0xbfb8aa3b, v5
	v_mul_f32_e32 v7, v3, v7
	v_add_f32_e32 v3, 1.0, v11
	v_add_f32_e32 v11, 1.0, v12
	v_mul_f32_e32 v12, 0xbfb8aa3b, v9
	v_exp_f32_e32 v12, v12
	v_exp_f32_e32 v13, v13
	v_rcp_f32_e32 v3, v3
	v_rcp_f32_e32 v11, v11
	v_add_f32_e32 v12, 1.0, v12
	v_add_f32_e32 v13, 1.0, v13
	v_rcp_f32_e32 v12, v12
	v_rcp_f32_e32 v13, v13
	v_mul_f32_e32 v3, v8, v3
	v_mul_f32_e32 v8, v4, v11
	v_mul_f32_e32 v4, v9, v12
	v_mul_f32_e32 v5, v5, v13
	v_cvt_pk_bf16_f32 v2, v6, v2
	v_cvt_pk_bf16_f32 v3, v3, v4
	v_cvt_pk_bf16_f32 v4, v10, v7
	v_cvt_pk_bf16_f32 v5, v8, v5
	global_store_dwordx4 v[18:19], v[2:5], off offset:256
	s_cbranch_vccnz .LBB0_229
	s_mov_b32 s98, 1
	s_andn2_b64 vcc, exec, s[8:9]
	s_cbranch_vccnz .LBB0_228
	s_barrier
	s_branch .LBB0_228

.LBB0_269:
	v_add_u32_e32 v147, s46, v161
	ds_read_b128 v[166:169], v147
	ds_read_b128 v[170:173], v147 offset:1024
	ds_read_b128 v[174:177], v147 offset:2048
	ds_read_b128 v[178:181], v147 offset:3072
	v_add_u32_e32 v147, s47, v161
	ds_read_b128 v[184:187], v147
	ds_read_b128 v[188:191], v147 offset:1024
	ds_read_b128 v[192:195], v147 offset:2048
	ds_read_b128 v[196:199], v147 offset:3072
	s_mov_b32 s34, 0xfff00080
	s_cmp_eq_u32 s30, 60
	s_mov_b32 s35, -1
	v_lshl_add_u64 v[200:201], v[156:157], 0, s[34:35]
	s_cselect_b64 vcc, -1, 0
	v_cndmask_b32_e32 v233, v201, v1, vcc
	v_cndmask_b32_e32 v232, v200, v152, vcc
	v_cndmask_b32_e32 v235, v159, v145, vcc
	v_cndmask_b32_e32 v234, v158, v154, vcc
	v_lshl_add_u64 v[236:237], v[156:157], 0, v[138:139]
	s_add_i32 m0, s39, 0xc000
	ds_read_b128 v[200:203], v155
	ds_read_b128 v[204:207], v155 offset:1024
	ds_read_b128 v[208:211], v155 offset:2048
	ds_read_b128 v[212:215], v155 offset:3072
	ds_read_b128 v[216:219], v155 offset:4096
	ds_read_b128 v[220:223], v155 offset:5120
	ds_read_b128 v[224:227], v155 offset:6144
	ds_read_b128 v[228:231], v155 offset:7168
	global_load_lds_dwordx4 v[236:237], off
	v_lshl_add_u64 v[236:237], v[156:157], 0, v[140:141]
	s_add_i32 m0, s39, 0xe000
	s_nop 0
	global_load_lds_dwordx4 v[236:237], off
	s_cmp_eq_u32 s98, 0
	s_cbranch_scc1 .Lgw269_0a
	s_waitcnt vmcnt(24)
	s_branch .Lgw269_0b

.Lgw269_0b:
	s_waitcnt lgkmcnt(0)
	s_barrier
	s_setprio 1
	s_waitcnt lgkmcnt(0)
	v_mfma_f32_16x16x32_bf16 v[126:129], v[166:169], v[200:203], v[126:129]
	v_mfma_f32_16x16x32_bf16 v[122:125], v[174:177], v[200:203], v[122:125]
	v_mfma_f32_16x16x32_bf16 v[118:121], v[166:169], v[208:211], v[118:121]
	v_mfma_f32_16x16x32_bf16 v[110:113], v[174:177], v[208:211], v[110:113]
	v_mfma_f32_16x16x32_bf16 v[102:105], v[166:169], v[216:219], v[102:105]
	v_mfma_f32_16x16x32_bf16 v[94:97], v[174:177], v[216:219], v[94:97]
	v_mfma_f32_16x16x32_bf16 v[86:89], v[166:169], v[224:227], v[86:89]
	v_mfma_f32_16x16x32_bf16 v[78:81], v[174:177], v[224:227], v[78:81]
	v_mfma_f32_16x16x32_bf16 v[126:129], v[170:173], v[204:207], v[126:129]
	v_mfma_f32_16x16x32_bf16 v[122:125], v[178:181], v[204:207], v[122:125]
	v_mfma_f32_16x16x32_bf16 v[118:121], v[170:173], v[212:215], v[118:121]
	v_mfma_f32_16x16x32_bf16 v[110:113], v[178:181], v[212:215], v[110:113]
	v_mfma_f32_16x16x32_bf16 v[102:105], v[170:173], v[220:223], v[102:105]
	v_mfma_f32_16x16x32_bf16 v[94:97], v[178:181], v[220:223], v[94:97]
	v_mfma_f32_16x16x32_bf16 v[86:89], v[170:173], v[228:231], v[86:89]
	v_mfma_f32_16x16x32_bf16 v[78:81], v[178:181], v[228:231], v[78:81]
	s_setprio 0
	s_setprio 1
	v_mfma_f32_16x16x32_bf16 v[114:117], v[184:187], v[200:203], v[114:117]
	v_mfma_f32_16x16x32_bf16 v[106:109], v[192:195], v[200:203], v[106:109]
	v_mfma_f32_16x16x32_bf16 v[98:101], v[184:187], v[208:211], v[98:101]
	v_mfma_f32_16x16x32_bf16 v[90:93], v[192:195], v[208:211], v[90:93]
	v_mfma_f32_16x16x32_bf16 v[82:85], v[184:187], v[216:219], v[82:85]
	v_mfma_f32_16x16x32_bf16 v[74:77], v[192:195], v[216:219], v[74:77]
	v_mfma_f32_16x16x32_bf16 v[70:73], v[184:187], v[224:227], v[70:73]
	v_mfma_f32_16x16x32_bf16 v[66:69], v[192:195], v[224:227], v[66:69]
	v_mfma_f32_16x16x32_bf16 v[114:117], v[188:191], v[204:207], v[114:117]
	v_mfma_f32_16x16x32_bf16 v[106:109], v[196:199], v[204:207], v[106:109]
	v_mfma_f32_16x16x32_bf16 v[98:101], v[188:191], v[212:215], v[98:101]
	v_mfma_f32_16x16x32_bf16 v[90:93], v[196:199], v[212:215], v[90:93]
	v_mfma_f32_16x16x32_bf16 v[82:85], v[188:191], v[220:223], v[82:85]
	v_mfma_f32_16x16x32_bf16 v[74:77], v[196:199], v[220:223], v[74:77]
	v_mfma_f32_16x16x32_bf16 v[70:73], v[188:191], v[228:231], v[70:73]
	v_mfma_f32_16x16x32_bf16 v[66:69], v[196:199], v[228:231], v[66:69]
	s_setprio 0
	s_barrier
	s_add_i32 s31, s46, s38
	v_lshl_add_u64 v[236:237], v[234:235], 0, v[132:133]
	s_mov_b32 m0, s31
	ds_read_b128 v[200:203], v155 offset:16384
	ds_read_b128 v[204:207], v155 offset:17408
	ds_read_b128 v[208:211], v155 offset:18432
	ds_read_b128 v[212:215], v155 offset:19456
	ds_read_b128 v[216:219], v155 offset:20480
	ds_read_b128 v[220:223], v155 offset:21504
	ds_read_b128 v[224:227], v155 offset:22528
	ds_read_b128 v[228:231], v155 offset:23552
	global_load_lds_dwordx4 v[236:237], off
	v_lshl_add_u64 v[238:239], v[234:235], 0, v[136:137]
	s_add_i32 m0, s31, 0x2000
	v_lshl_add_u64 v[240:241], v[234:235], 0, s[6:7]
	s_add_i32 s31, s47, s38
	global_load_lds_dwordx4 v[238:239], off
	v_lshl_add_u64 v[242:243], v[240:241], 0, v[132:133]
	s_mov_b32 m0, s31
	v_lshl_add_u64 v[240:241], v[240:241], 0, v[136:137]
	global_load_lds_dwordx4 v[242:243], off
	s_add_i32 m0, s31, 0x2000
	v_lshl_add_u64 v[242:243], v[232:233], 0, v[134:135]
	global_load_lds_dwordx4 v[240:241], off
	v_lshl_add_u64 v[240:241], v[232:233], 0, v[130:131]
	s_mov_b32 m0, s39
	s_nop 0
	global_load_lds_dwordx4 v[240:241], off
	s_mov_b32 m0, s40
	s_nop 0
	global_load_lds_dwordx4 v[242:243], off
	s_cmp_eq_u32 s98, 0
	s_cbranch_scc1 .Lgw269_1a
	s_waitcnt vmcnt(24)
	s_branch .Lgw269_1b

.Lgw269_1b:
	s_mov_b32 s98, 0
	s_waitcnt lgkmcnt(0)
	s_barrier
	s_setprio 1
	s_waitcnt lgkmcnt(0)
	v_mfma_f32_16x16x32_bf16 v[62:65], v[166:169], v[200:203], v[62:65]
	v_mfma_f32_16x16x32_bf16 v[58:61], v[174:177], v[200:203], v[58:61]
	v_mfma_f32_16x16x32_bf16 v[54:57], v[166:169], v[208:211], v[54:57]
	v_mfma_f32_16x16x32_bf16 v[46:49], v[174:177], v[208:211], v[46:49]
	v_mfma_f32_16x16x32_bf16 v[38:41], v[166:169], v[216:219], v[38:41]
	v_mfma_f32_16x16x32_bf16 v[30:33], v[174:177], v[216:219], v[30:33]
	v_mfma_f32_16x16x32_bf16 v[22:25], v[166:169], v[224:227], v[22:25]
	v_mfma_f32_16x16x32_bf16 v[14:17], v[174:177], v[224:227], v[14:17]
	v_mfma_f32_16x16x32_bf16 v[62:65], v[170:173], v[204:207], v[62:65]
	v_mfma_f32_16x16x32_bf16 v[58:61], v[178:181], v[204:207], v[58:61]
	v_mfma_f32_16x16x32_bf16 v[54:57], v[170:173], v[212:215], v[54:57]
	v_mfma_f32_16x16x32_bf16 v[46:49], v[178:181], v[212:215], v[46:49]
	v_mfma_f32_16x16x32_bf16 v[38:41], v[170:173], v[220:223], v[38:41]
	v_mfma_f32_16x16x32_bf16 v[30:33], v[178:181], v[220:223], v[30:33]
	v_mfma_f32_16x16x32_bf16 v[22:25], v[170:173], v[228:231], v[22:25]
	v_mfma_f32_16x16x32_bf16 v[14:17], v[178:181], v[228:231], v[14:17]
	s_setprio 0
	s_setprio 1
	v_mfma_f32_16x16x32_bf16 v[50:53], v[184:187], v[200:203], v[50:53]
	v_mfma_f32_16x16x32_bf16 v[42:45], v[192:195], v[200:203], v[42:45]
	v_mfma_f32_16x16x32_bf16 v[34:37], v[184:187], v[208:211], v[34:37]
	v_mfma_f32_16x16x32_bf16 v[26:29], v[192:195], v[208:211], v[26:29]
	v_mfma_f32_16x16x32_bf16 v[18:21], v[184:187], v[216:219], v[18:21]
	v_mfma_f32_16x16x32_bf16 v[10:13], v[192:195], v[216:219], v[10:13]
	v_mfma_f32_16x16x32_bf16 v[6:9], v[184:187], v[224:227], v[6:9]
	v_mfma_f32_16x16x32_bf16 v[2:5], v[192:195], v[224:227], v[2:5]
	v_mfma_f32_16x16x32_bf16 v[50:53], v[188:191], v[204:207], v[50:53]
	v_mfma_f32_16x16x32_bf16 v[42:45], v[196:199], v[204:207], v[42:45]
	v_mfma_f32_16x16x32_bf16 v[34:37], v[188:191], v[212:215], v[34:37]
	v_mfma_f32_16x16x32_bf16 v[26:29], v[196:199], v[212:215], v[26:29]
	v_mfma_f32_16x16x32_bf16 v[18:21], v[188:191], v[220:223], v[18:21]
	v_mfma_f32_16x16x32_bf16 v[10:13], v[196:199], v[220:223], v[10:13]
	v_mfma_f32_16x16x32_bf16 v[6:9], v[188:191], v[228:231], v[6:9]
	v_mfma_f32_16x16x32_bf16 v[2:5], v[196:199], v[228:231], v[2:5]
	s_setprio 0
	s_barrier
	s_add_i32 s31, 0, 0x18000
	v_add_u32_e32 v147, s31, v161
	s_add_i32 s34, 0, 0x1c000
	ds_read_b128 v[166:169], v147
	ds_read_b128 v[170:173], v147 offset:1024
	ds_read_b128 v[174:177], v147 offset:2048
	ds_read_b128 v[178:181], v147 offset:3072
	v_add_u32_e32 v147, s34, v161
	ds_read_b128 v[184:187], v147
	ds_read_b128 v[188:191], v147 offset:1024
	ds_read_b128 v[192:195], v147 offset:2048
	ds_read_b128 v[196:199], v147 offset:3072
	v_lshl_add_u64 v[232:233], v[232:233], 0, s[6:7]
	s_mov_b32 m0, s41
	v_lshl_add_u64 v[244:245], v[232:233], 0, v[130:131]
	ds_read_b128 v[200:203], v155 offset:32768
	ds_read_b128 v[204:207], v155 offset:33792
	ds_read_b128 v[208:211], v155 offset:34816
	ds_read_b128 v[212:215], v155 offset:35840
	ds_read_b128 v[216:219], v155 offset:36864
	ds_read_b128 v[220:223], v155 offset:37888
	ds_read_b128 v[224:227], v155 offset:38912
	ds_read_b128 v[228:231], v155 offset:39936
	global_load_lds_dwordx4 v[244:245], off
	v_lshl_add_u64 v[232:233], v[232:233], 0, v[134:135]
	s_mov_b32 m0, s42
	s_nop 0
	global_load_lds_dwordx4 v[232:233], off
	s_waitcnt vmcnt(8)
	s_waitcnt lgkmcnt(0)
	s_barrier
	s_setprio 1
	s_waitcnt lgkmcnt(0)
	v_mfma_f32_16x16x32_bf16 v[126:129], v[166:169], v[200:203], v[126:129]
	v_mfma_f32_16x16x32_bf16 v[122:125], v[174:177], v[200:203], v[122:125]
	v_mfma_f32_16x16x32_bf16 v[118:121], v[166:169], v[208:211], v[118:121]
	v_mfma_f32_16x16x32_bf16 v[110:113], v[174:177], v[208:211], v[110:113]
	v_mfma_f32_16x16x32_bf16 v[102:105], v[166:169], v[216:219], v[102:105]
	v_mfma_f32_16x16x32_bf16 v[94:97], v[174:177], v[216:219], v[94:97]
	v_mfma_f32_16x16x32_bf16 v[86:89], v[166:169], v[224:227], v[86:89]
	v_mfma_f32_16x16x32_bf16 v[78:81], v[174:177], v[224:227], v[78:81]
	v_mfma_f32_16x16x32_bf16 v[126:129], v[170:173], v[204:207], v[126:129]
	v_mfma_f32_16x16x32_bf16 v[122:125], v[178:181], v[204:207], v[122:125]
	v_mfma_f32_16x16x32_bf16 v[118:121], v[170:173], v[212:215], v[118:121]
	v_mfma_f32_16x16x32_bf16 v[110:113], v[178:181], v[212:215], v[110:113]
	v_mfma_f32_16x16x32_bf16 v[102:105], v[170:173], v[220:223], v[102:105]
	v_mfma_f32_16x16x32_bf16 v[94:97], v[178:181], v[220:223], v[94:97]
	v_mfma_f32_16x16x32_bf16 v[86:89], v[170:173], v[228:231], v[86:89]
	v_mfma_f32_16x16x32_bf16 v[78:81], v[178:181], v[228:231], v[78:81]
	s_setprio 0
	s_setprio 1
	v_mfma_f32_16x16x32_bf16 v[114:117], v[184:187], v[200:203], v[114:117]
	v_mfma_f32_16x16x32_bf16 v[106:109], v[192:195], v[200:203], v[106:109]
	v_mfma_f32_16x16x32_bf16 v[98:101], v[184:187], v[208:211], v[98:101]
	v_mfma_f32_16x16x32_bf16 v[90:93], v[192:195], v[208:211], v[90:93]
	v_mfma_f32_16x16x32_bf16 v[82:85], v[184:187], v[216:219], v[82:85]
	v_mfma_f32_16x16x32_bf16 v[74:77], v[192:195], v[216:219], v[74:77]
	v_mfma_f32_16x16x32_bf16 v[70:73], v[184:187], v[224:227], v[70:73]
	v_mfma_f32_16x16x32_bf16 v[66:69], v[192:195], v[224:227], v[66:69]
	v_mfma_f32_16x16x32_bf16 v[114:117], v[188:191], v[204:207], v[114:117]
	v_mfma_f32_16x16x32_bf16 v[106:109], v[196:199], v[204:207], v[106:109]
	v_mfma_f32_16x16x32_bf16 v[98:101], v[188:191], v[212:215], v[98:101]
	v_mfma_f32_16x16x32_bf16 v[90:93], v[196:199], v[212:215], v[90:93]
	v_mfma_f32_16x16x32_bf16 v[82:85], v[188:191], v[220:223], v[82:85]
	v_mfma_f32_16x16x32_bf16 v[74:77], v[196:199], v[220:223], v[74:77]
	v_mfma_f32_16x16x32_bf16 v[70:73], v[188:191], v[228:231], v[70:73]
	v_mfma_f32_16x16x32_bf16 v[66:69], v[196:199], v[228:231], v[66:69]
	s_setprio 0
	s_barrier
	s_add_i32 s31, s31, s38
	v_lshl_add_u64 v[232:233], v[236:237], 0, s[12:13]
	s_mov_b32 m0, s31
	ds_read_b128 v[200:203], v155 offset:49152
	ds_read_b128 v[204:207], v155 offset:50176
	ds_read_b128 v[208:211], v155 offset:51200
	ds_read_b128 v[212:215], v155 offset:52224
	ds_read_b128 v[216:219], v155 offset:53248
	ds_read_b128 v[220:223], v155 offset:54272
	ds_read_b128 v[224:227], v155 offset:55296
	ds_read_b128 v[228:231], v155 offset:56320
	global_load_lds_dwordx4 v[232:233], off
	v_lshl_add_u64 v[232:233], v[238:239], 0, s[12:13]
	s_add_i32 m0, s31, 0x2000
	s_add_i32 s31, s34, s38
	global_load_lds_dwordx4 v[232:233], off
	v_lshl_add_u64 v[232:233], v[234:235], 0, s[16:17]
	v_lshl_add_u64 v[234:235], v[232:233], 0, v[132:133]
	s_mov_b32 m0, s31
	v_lshl_add_u64 v[232:233], v[232:233], 0, v[136:137]
	global_load_lds_dwordx4 v[234:235], off
	s_add_i32 m0, s31, 0x2000
	s_nop 0
	global_load_lds_dwordx4 v[232:233], off
	v_lshl_add_u64 v[232:233], v[240:241], 0, s[12:13]
	s_mov_b32 m0, s44
	s_nop 0
	global_load_lds_dwordx4 v[232:233], off
	v_lshl_add_u64 v[232:233], v[242:243], 0, s[12:13]
	s_mov_b32 m0, s45
	s_nop 0
	global_load_lds_dwordx4 v[232:233], off
	s_waitcnt vmcnt(8)
	s_waitcnt lgkmcnt(0)
	s_barrier
	s_setprio 1
	s_waitcnt lgkmcnt(0)
	v_mfma_f32_16x16x32_bf16 v[62:65], v[166:169], v[200:203], v[62:65]
	v_mfma_f32_16x16x32_bf16 v[58:61], v[174:177], v[200:203], v[58:61]
	v_mfma_f32_16x16x32_bf16 v[54:57], v[166:169], v[208:211], v[54:57]
	v_mfma_f32_16x16x32_bf16 v[46:49], v[174:177], v[208:211], v[46:49]
	v_mfma_f32_16x16x32_bf16 v[38:41], v[166:169], v[216:219], v[38:41]
	v_mfma_f32_16x16x32_bf16 v[30:33], v[174:177], v[216:219], v[30:33]
	v_mfma_f32_16x16x32_bf16 v[22:25], v[166:169], v[224:227], v[22:25]
	v_mfma_f32_16x16x32_bf16 v[14:17], v[174:177], v[224:227], v[14:17]
	v_mfma_f32_16x16x32_bf16 v[62:65], v[170:173], v[204:207], v[62:65]
	v_mfma_f32_16x16x32_bf16 v[58:61], v[178:181], v[204:207], v[58:61]
	v_mfma_f32_16x16x32_bf16 v[54:57], v[170:173], v[212:215], v[54:57]
	v_mfma_f32_16x16x32_bf16 v[46:49], v[178:181], v[212:215], v[46:49]
	v_mfma_f32_16x16x32_bf16 v[38:41], v[170:173], v[220:223], v[38:41]
	v_mfma_f32_16x16x32_bf16 v[30:33], v[178:181], v[220:223], v[30:33]
	v_mfma_f32_16x16x32_bf16 v[22:25], v[170:173], v[228:231], v[22:25]
	v_mfma_f32_16x16x32_bf16 v[14:17], v[178:181], v[228:231], v[14:17]
	s_setprio 0
	s_setprio 1
	v_mfma_f32_16x16x32_bf16 v[50:53], v[184:187], v[200:203], v[50:53]
	v_mfma_f32_16x16x32_bf16 v[42:45], v[192:195], v[200:203], v[42:45]
	v_mfma_f32_16x16x32_bf16 v[34:37], v[184:187], v[208:211], v[34:37]
	v_mfma_f32_16x16x32_bf16 v[26:29], v[192:195], v[208:211], v[26:29]
	v_mfma_f32_16x16x32_bf16 v[18:21], v[184:187], v[216:219], v[18:21]
	v_mfma_f32_16x16x32_bf16 v[10:13], v[192:195], v[216:219], v[10:13]
	v_mfma_f32_16x16x32_bf16 v[6:9], v[184:187], v[224:227], v[6:9]
	v_mfma_f32_16x16x32_bf16 v[2:5], v[192:195], v[224:227], v[2:5]
	v_mfma_f32_16x16x32_bf16 v[50:53], v[188:191], v[204:207], v[50:53]
	v_mfma_f32_16x16x32_bf16 v[42:45], v[196:199], v[204:207], v[42:45]
	v_mfma_f32_16x16x32_bf16 v[34:37], v[188:191], v[212:215], v[34:37]
	v_mfma_f32_16x16x32_bf16 v[26:29], v[196:199], v[212:215], v[26:29]
	v_mfma_f32_16x16x32_bf16 v[18:21], v[188:191], v[220:223], v[18:21]
	v_mfma_f32_16x16x32_bf16 v[10:13], v[196:199], v[220:223], v[10:13]
	v_mfma_f32_16x16x32_bf16 v[6:9], v[188:191], v[228:231], v[6:9]
	v_mfma_f32_16x16x32_bf16 v[2:5], v[196:199], v[228:231], v[2:5]
	s_setprio 0
	s_barrier
	s_add_i32 s30, s30, 2
	v_lshl_add_u64 v[156:157], v[156:157], 0, s[22:23]
	s_cmp_gt_u32 s30, 61
	v_lshl_add_u64 v[158:159], v[158:159], 0, s[22:23]
	s_cbranch_scc0 .LBB0_269
	s_and_b64 vcc, exec, s[18:19]
	s_cbranch_vccz .LBB0_272
	s_barrier
.LBB0_272:
	v_lshl_add_u32 v156, v164, 8, v160
	v_lshl_or_b32 v152, v153, 8, v162
	v_ashrrev_i32_e32 v157, 31, v156
	v_ashrrev_i32_e32 v153, 31, v152
	v_lshlrev_b64 v[158:159], 15, v[156:157]
	v_lshl_add_u64 v[158:159], s[10:11], 0, v[158:159]
	v_lshlrev_b64 v[164:165], 1, v[152:153]
	v_lshl_add_u64 v[152:153], v[158:159], 0, v[164:165]
	v_cvt_pk_bf16_f32 v126, v126, v127
	v_cvt_pk_bf16_f32 v127, v128, v129
	v_cvt_pk_bf16_f32 v128, v122, v123
	v_cvt_pk_bf16_f32 v129, v124, v125
	global_store_dwordx4 v[152:153], v[126:129], off
	v_cvt_pk_bf16_f32 v114, v114, v115
	v_cvt_pk_bf16_f32 v115, v116, v117
	v_cvt_pk_bf16_f32 v116, v106, v107
	v_or_b32_e32 v106, 16, v156
	v_ashrrev_i32_e32 v107, 31, v106
	v_lshlrev_b64 v[106:107], 15, v[106:107]
	v_lshl_add_u64 v[106:107], s[10:11], 0, v[106:107]
	v_cvt_pk_bf16_f32 v117, v108, v109
	global_store_dwordx4 v[152:153], v[114:117], off offset:256
	s_mov_b64 s[30:31], 0x400000
	s_mov_b64 s[34:35], -1
	v_lshl_add_u64 v[114:115], v[106:107], 0, v[164:165]
	v_cvt_pk_bf16_f32 v106, v118, v119
	v_cvt_pk_bf16_f32 v107, v120, v121
	v_cvt_pk_bf16_f32 v108, v110, v111
	v_cvt_pk_bf16_f32 v109, v112, v113
	global_store_dwordx4 v[114:115], v[106:109], off
	v_cvt_pk_bf16_f32 v98, v98, v99
	v_cvt_pk_bf16_f32 v99, v100, v101
	v_cvt_pk_bf16_f32 v100, v90, v91
	v_or_b32_e32 v90, 32, v156
	v_ashrrev_i32_e32 v91, 31, v90
	v_lshlrev_b64 v[90:91], 15, v[90:91]
	v_lshl_add_u64 v[90:91], s[10:11], 0, v[90:91]
	v_cvt_pk_bf16_f32 v101, v92, v93
	global_store_dwordx4 v[114:115], v[98:101], off offset:256
	s_nop 1
	v_lshl_add_u64 v[98:99], v[90:91], 0, v[164:165]
	v_cvt_pk_bf16_f32 v90, v102, v103
	v_cvt_pk_bf16_f32 v91, v104, v105
	v_cvt_pk_bf16_f32 v92, v94, v95
	v_cvt_pk_bf16_f32 v93, v96, v97
	global_store_dwordx4 v[98:99], v[90:93], off
	v_cvt_pk_bf16_f32 v82, v82, v83
	v_cvt_pk_bf16_f32 v83, v84, v85
	v_cvt_pk_bf16_f32 v84, v74, v75
	v_or_b32_e32 v74, 48, v156
	v_ashrrev_i32_e32 v75, 31, v74
	v_lshlrev_b64 v[74:75], 15, v[74:75]
	v_lshl_add_u64 v[74:75], s[10:11], 0, v[74:75]
	v_cvt_pk_bf16_f32 v85, v76, v77
	global_store_dwordx4 v[98:99], v[82:85], off offset:256
	s_nop 1
	v_lshl_add_u64 v[82:83], v[74:75], 0, v[164:165]
	v_cvt_pk_bf16_f32 v74, v86, v87
	v_cvt_pk_bf16_f32 v75, v88, v89
	v_cvt_pk_bf16_f32 v76, v78, v79
	v_cvt_pk_bf16_f32 v77, v80, v81
	global_store_dwordx4 v[82:83], v[74:77], off
	v_cvt_pk_bf16_f32 v70, v70, v71
	v_cvt_pk_bf16_f32 v71, v72, v73
	v_cvt_pk_bf16_f32 v72, v66, v67
	v_lshl_add_u64 v[66:67], v[152:153], 0, s[30:31]
	s_mov_b32 s30, 0x400000
	v_cvt_pk_bf16_f32 v73, v68, v69
	global_store_dwordx4 v[82:83], v[70:73], off offset:256
	v_cvt_pk_bf16_f32 v62, v62, v63
	v_cvt_pk_bf16_f32 v63, v64, v65
	v_cvt_pk_bf16_f32 v64, v58, v59
	v_add_co_u32_e32 v58, vcc, s30, v152
	v_cvt_pk_bf16_f32 v65, v60, v61
	s_mov_b64 s[30:31], 0x480000
	s_nop 0
	v_addc_co_u32_e32 v59, vcc, 0, v153, vcc
	global_store_dwordx4 v[58:59], v[62:65], off
	v_cvt_pk_bf16_f32 v50, v50, v51
	v_cvt_pk_bf16_f32 v51, v52, v53
	v_cvt_pk_bf16_f32 v52, v42, v43
	v_cvt_pk_bf16_f32 v53, v44, v45
	global_store_dwordx4 v[66:67], v[50:53], off offset:256
	v_cvt_pk_bf16_f32 v42, v54, v55
	v_cvt_pk_bf16_f32 v43, v56, v57
	v_cvt_pk_bf16_f32 v44, v46, v47
	v_cvt_pk_bf16_f32 v45, v48, v49
	s_nop 1
	v_lshl_add_u64 v[50:51], v[152:153], 0, s[30:31]
	s_mov_b32 s30, 0x480000
	v_add_co_u32_e32 v46, vcc, s30, v152
	s_nop 1
	v_addc_co_u32_e32 v47, vcc, 0, v153, vcc
	global_store_dwordx4 v[46:47], v[42:45], off
	v_cvt_pk_bf16_f32 v34, v34, v35
	v_cvt_pk_bf16_f32 v35, v36, v37
	v_cvt_pk_bf16_f32 v36, v26, v27
	v_cvt_pk_bf16_f32 v37, v28, v29
	global_store_dwordx4 v[50:51], v[34:37], off offset:256
	v_cvt_pk_bf16_f32 v26, v38, v39
	v_cvt_pk_bf16_f32 v27, v40, v41
	v_cvt_pk_bf16_f32 v28, v30, v31
	v_add_co_u32_e32 v30, vcc, s50, v152
	s_nop 0
	v_lshl_add_u64 v[34:35], v[152:153], 0, s[24:25]
	v_addc_co_u32_e32 v31, vcc, 0, v153, vcc
	v_cvt_pk_bf16_f32 v29, v32, v33
	global_store_dwordx4 v[30:31], v[26:29], off
	v_cvt_pk_bf16_f32 v18, v18, v19
	v_cvt_pk_bf16_f32 v19, v20, v21
	v_cvt_pk_bf16_f32 v20, v10, v11
	v_cvt_pk_bf16_f32 v21, v12, v13
	global_store_dwordx4 v[34:35], v[18:21], off offset:256
	v_cvt_pk_bf16_f32 v10, v22, v23
	v_cvt_pk_bf16_f32 v11, v24, v25
	v_cvt_pk_bf16_f32 v12, v14, v15
	v_add_co_u32_e32 v14, vcc, s51, v152
	s_nop 0
	v_lshl_add_u64 v[18:19], v[152:153], 0, s[26:27]
	v_addc_co_u32_e32 v15, vcc, 0, v153, vcc
	v_cvt_pk_bf16_f32 v13, v16, v17
	global_store_dwordx4 v[14:15], v[10:13], off
	v_cvt_pk_bf16_f32 v6, v6, v7
	v_cvt_pk_bf16_f32 v7, v8, v9
	v_cvt_pk_bf16_f32 v8, v2, v3
	v_cvt_pk_bf16_f32 v9, v4, v5
	global_store_dwordx4 v[18:19], v[6:9], off offset:256
	s_and_saveexec_b64 s[30:31], s[28:29]
	s_cbranch_execz .LBB0_251
	s_mov_b32 s98, 1
	s_andn2_b64 vcc, exec, s[4:5]
	s_cbranch_vccnz .LBB0_250
	s_barrier
	s_branch .LBB0_250

.LBB0_763:
	ds_read_b128 v[142:145], v165
	ds_read_b128 v[146:149], v165 offset:1024
	ds_read_b128 v[150:153], v165 offset:2048
	ds_read_b128 v[154:157], v165 offset:3072
	ds_read_b128 v[158:161], v166
	ds_read_b128 v[168:171], v166 offset:1024
	ds_read_b128 v[172:175], v166 offset:2048
	ds_read_b128 v[176:179], v166 offset:3072
	s_add_u32 s28, s26, 0xffe00080
	s_addc_u32 s29, s27, -1
	s_cmpk_eq_i32 s59, 0x7c
	s_cselect_b32 s31, s19, s29
	s_cselect_b32 s30, s53, s28
	s_cselect_b32 s29, s17, s58
	s_cselect_b32 s28, s56, s57
	v_lshl_add_u64 v[180:181], s[26:27], 0, v[134:135]
	s_add_i32 m0, s25, 0xc000
	ds_read_b128 v[184:187], v167
	ds_read_b128 v[188:191], v167 offset:1024
	ds_read_b128 v[192:195], v167 offset:2048
	ds_read_b128 v[196:199], v167 offset:3072
	ds_read_b128 v[200:203], v167 offset:4096
	ds_read_b128 v[204:207], v167 offset:5120
	ds_read_b128 v[208:211], v167 offset:6144
	ds_read_b128 v[212:215], v167 offset:7168
	global_load_lds_dwordx4 v[180:181], off
	v_lshl_add_u64 v[180:181], s[26:27], 0, v[136:137]
	s_add_i32 m0, s25, 0xe000
	s_nop 0
	global_load_lds_dwordx4 v[180:181], off
	s_cmp_eq_u32 s98, 0
	s_cbranch_scc1 .Lgw763_0a
	s_waitcnt vmcnt(40)
	s_branch .Lgw763_0b

.Lgw763_0b:
	s_waitcnt lgkmcnt(0)
	s_barrier
	s_setprio 1
	s_waitcnt lgkmcnt(0)
	v_mfma_f32_16x16x32_bf16 v[126:129], v[142:145], v[184:187], v[126:129]
	v_mfma_f32_16x16x32_bf16 v[122:125], v[150:153], v[184:187], v[122:125]
	v_mfma_f32_16x16x32_bf16 v[114:117], v[142:145], v[192:195], v[114:117]
	v_mfma_f32_16x16x32_bf16 v[106:109], v[150:153], v[192:195], v[106:109]
	v_mfma_f32_16x16x32_bf16 v[98:101], v[142:145], v[200:203], v[98:101]
	v_mfma_f32_16x16x32_bf16 v[90:93], v[150:153], v[200:203], v[90:93]
	v_mfma_f32_16x16x32_bf16 v[82:85], v[142:145], v[208:211], v[82:85]
	v_mfma_f32_16x16x32_bf16 v[74:77], v[150:153], v[208:211], v[74:77]
	v_mfma_f32_16x16x32_bf16 v[126:129], v[146:149], v[188:191], v[126:129]
	v_mfma_f32_16x16x32_bf16 v[122:125], v[154:157], v[188:191], v[122:125]
	v_mfma_f32_16x16x32_bf16 v[114:117], v[146:149], v[196:199], v[114:117]
	v_mfma_f32_16x16x32_bf16 v[106:109], v[154:157], v[196:199], v[106:109]
	v_mfma_f32_16x16x32_bf16 v[98:101], v[146:149], v[204:207], v[98:101]
	v_mfma_f32_16x16x32_bf16 v[90:93], v[154:157], v[204:207], v[90:93]
	v_mfma_f32_16x16x32_bf16 v[82:85], v[146:149], v[212:215], v[82:85]
	v_mfma_f32_16x16x32_bf16 v[74:77], v[154:157], v[212:215], v[74:77]
	s_setprio 0
	s_setprio 1
	v_mfma_f32_16x16x32_bf16 v[118:121], v[158:161], v[184:187], v[118:121]
	v_mfma_f32_16x16x32_bf16 v[110:113], v[172:175], v[184:187], v[110:113]
	v_mfma_f32_16x16x32_bf16 v[102:105], v[158:161], v[192:195], v[102:105]
	v_mfma_f32_16x16x32_bf16 v[94:97], v[172:175], v[192:195], v[94:97]
	v_mfma_f32_16x16x32_bf16 v[86:89], v[158:161], v[200:203], v[86:89]
	v_mfma_f32_16x16x32_bf16 v[78:81], v[172:175], v[200:203], v[78:81]
	v_mfma_f32_16x16x32_bf16 v[70:73], v[158:161], v[208:211], v[70:73]
	v_mfma_f32_16x16x32_bf16 v[66:69], v[172:175], v[208:211], v[66:69]
	v_mfma_f32_16x16x32_bf16 v[118:121], v[168:171], v[188:191], v[118:121]
	v_mfma_f32_16x16x32_bf16 v[110:113], v[176:179], v[188:191], v[110:113]
	v_mfma_f32_16x16x32_bf16 v[102:105], v[168:171], v[196:199], v[102:105]
	v_mfma_f32_16x16x32_bf16 v[94:97], v[176:179], v[196:199], v[94:97]
	v_mfma_f32_16x16x32_bf16 v[86:89], v[168:171], v[204:207], v[86:89]
	v_mfma_f32_16x16x32_bf16 v[78:81], v[176:179], v[204:207], v[78:81]
	v_mfma_f32_16x16x32_bf16 v[70:73], v[168:171], v[212:215], v[70:73]
	v_mfma_f32_16x16x32_bf16 v[66:69], v[176:179], v[212:215], v[66:69]
	s_setprio 0
	s_barrier
	s_add_i32 s60, s50, s38
	v_lshl_add_u64 v[180:181], s[28:29], 0, v[130:131]
	s_mov_b32 m0, s60
	ds_read_b128 v[184:187], v167 offset:16384
	ds_read_b128 v[188:191], v167 offset:17408
	ds_read_b128 v[192:195], v167 offset:18432
	ds_read_b128 v[196:199], v167 offset:19456
	ds_read_b128 v[200:203], v167 offset:20480
	ds_read_b128 v[204:207], v167 offset:21504
	ds_read_b128 v[208:211], v167 offset:22528
	ds_read_b128 v[212:215], v167 offset:23552
	global_load_lds_dwordx4 v[180:181], off
	s_add_i32 m0, s60, 0x2000
	s_add_u32 s60, s28, 0x200000
	v_lshl_add_u64 v[216:217], s[28:29], 0, v[132:133]
	s_addc_u32 s61, s29, 0
	s_add_i32 s62, s51, s38
	global_load_lds_dwordx4 v[216:217], off
	v_lshl_add_u64 v[218:219], s[60:61], 0, v[130:131]
	s_mov_b32 m0, s62
	v_lshl_add_u64 v[220:221], s[30:31], 0, v[132:133]
	global_load_lds_dwordx4 v[218:219], off
	v_lshl_add_u64 v[218:219], s[60:61], 0, v[132:133]
	s_add_i32 m0, s62, 0x2000
	s_nop 0
	global_load_lds_dwordx4 v[218:219], off
	v_lshl_add_u64 v[218:219], s[30:31], 0, v[130:131]
	s_mov_b32 m0, s25
	s_nop 0
	global_load_lds_dwordx4 v[218:219], off
	s_mov_b32 m0, s40
	s_nop 0
	global_load_lds_dwordx4 v[220:221], off
	s_cmp_eq_u32 s98, 0
	s_cbranch_scc1 .Lgw763_1a
	s_waitcnt vmcnt(40)
	s_branch .Lgw763_1b

.Lgw763_1b:
	s_mov_b32 s98, 0
	s_waitcnt lgkmcnt(0)
	s_barrier
	s_setprio 1
	s_waitcnt lgkmcnt(0)
	v_mfma_f32_16x16x32_bf16 v[62:65], v[142:145], v[184:187], v[62:65]
	v_mfma_f32_16x16x32_bf16 v[58:61], v[150:153], v[184:187], v[58:61]
	v_mfma_f32_16x16x32_bf16 v[50:53], v[142:145], v[192:195], v[50:53]
	v_mfma_f32_16x16x32_bf16 v[42:45], v[150:153], v[192:195], v[42:45]
	v_mfma_f32_16x16x32_bf16 v[34:37], v[142:145], v[200:203], v[34:37]
	v_mfma_f32_16x16x32_bf16 v[26:29], v[150:153], v[200:203], v[26:29]
	v_mfma_f32_16x16x32_bf16 v[18:21], v[142:145], v[208:211], v[18:21]
	v_mfma_f32_16x16x32_bf16 v[10:13], v[150:153], v[208:211], v[10:13]
	v_mfma_f32_16x16x32_bf16 v[62:65], v[146:149], v[188:191], v[62:65]
	v_mfma_f32_16x16x32_bf16 v[58:61], v[154:157], v[188:191], v[58:61]
	v_mfma_f32_16x16x32_bf16 v[50:53], v[146:149], v[196:199], v[50:53]
	v_mfma_f32_16x16x32_bf16 v[42:45], v[154:157], v[196:199], v[42:45]
	v_mfma_f32_16x16x32_bf16 v[34:37], v[146:149], v[204:207], v[34:37]
	v_mfma_f32_16x16x32_bf16 v[26:29], v[154:157], v[204:207], v[26:29]
	v_mfma_f32_16x16x32_bf16 v[18:21], v[146:149], v[212:215], v[18:21]
	v_mfma_f32_16x16x32_bf16 v[10:13], v[154:157], v[212:215], v[10:13]
	s_setprio 0
	s_setprio 1
	v_mfma_f32_16x16x32_bf16 v[54:57], v[158:161], v[184:187], v[54:57]
	v_mfma_f32_16x16x32_bf16 v[46:49], v[172:175], v[184:187], v[46:49]
	v_mfma_f32_16x16x32_bf16 v[38:41], v[158:161], v[192:195], v[38:41]
	v_mfma_f32_16x16x32_bf16 v[30:33], v[172:175], v[192:195], v[30:33]
	v_mfma_f32_16x16x32_bf16 v[22:25], v[158:161], v[200:203], v[22:25]
	v_mfma_f32_16x16x32_bf16 v[14:17], v[172:175], v[200:203], v[14:17]
	v_mfma_f32_16x16x32_bf16 v[6:9], v[158:161], v[208:211], v[6:9]
	v_mfma_f32_16x16x32_bf16 v[2:5], v[172:175], v[208:211], v[2:5]
	v_mfma_f32_16x16x32_bf16 v[54:57], v[168:171], v[188:191], v[54:57]
	v_mfma_f32_16x16x32_bf16 v[46:49], v[176:179], v[188:191], v[46:49]
	v_mfma_f32_16x16x32_bf16 v[38:41], v[168:171], v[196:199], v[38:41]
	v_mfma_f32_16x16x32_bf16 v[30:33], v[176:179], v[196:199], v[30:33]
	v_mfma_f32_16x16x32_bf16 v[22:25], v[168:171], v[204:207], v[22:25]
	v_mfma_f32_16x16x32_bf16 v[14:17], v[176:179], v[204:207], v[14:17]
	v_mfma_f32_16x16x32_bf16 v[6:9], v[168:171], v[212:215], v[6:9]
	v_mfma_f32_16x16x32_bf16 v[2:5], v[176:179], v[212:215], v[2:5]
	s_setprio 0
	s_barrier
	s_add_i32 s60, 0, 0x18000
	s_add_i32 s61, 0, 0x1c000
	v_add_u32_e32 v154, s60, v162
	v_add_u32_e32 v176, s61, v162
	ds_read_b128 v[142:145], v154
	ds_read_b128 v[146:149], v154 offset:1024
	ds_read_b128 v[150:153], v154 offset:2048
	ds_read_b128 v[154:157], v154 offset:3072
	ds_read_b128 v[158:161], v176
	ds_read_b128 v[168:171], v176 offset:1024
	ds_read_b128 v[172:175], v176 offset:2048
	ds_read_b128 v[176:179], v176 offset:3072
	s_add_u32 s30, s30, 0x200000
	s_addc_u32 s31, s31, 0
	s_mov_b32 m0, s41
	v_lshl_add_u64 v[222:223], s[30:31], 0, v[130:131]
	ds_read_b128 v[184:187], v167 offset:32768
	ds_read_b128 v[188:191], v167 offset:33792
	ds_read_b128 v[192:195], v167 offset:34816
	ds_read_b128 v[196:199], v167 offset:35840
	ds_read_b128 v[200:203], v167 offset:36864
	ds_read_b128 v[204:207], v167 offset:37888
	ds_read_b128 v[208:211], v167 offset:38912
	ds_read_b128 v[212:215], v167 offset:39936
	global_load_lds_dwordx4 v[222:223], off
	v_lshl_add_u64 v[222:223], s[30:31], 0, v[132:133]
	s_mov_b32 m0, s42
	s_nop 0
	global_load_lds_dwordx4 v[222:223], off
	s_waitcnt vmcnt(8)
	s_waitcnt lgkmcnt(0)
	s_barrier
	s_setprio 1
	s_waitcnt lgkmcnt(0)
	v_mfma_f32_16x16x32_bf16 v[126:129], v[142:145], v[184:187], v[126:129]
	v_mfma_f32_16x16x32_bf16 v[122:125], v[150:153], v[184:187], v[122:125]
	v_mfma_f32_16x16x32_bf16 v[114:117], v[142:145], v[192:195], v[114:117]
	v_mfma_f32_16x16x32_bf16 v[106:109], v[150:153], v[192:195], v[106:109]
	v_mfma_f32_16x16x32_bf16 v[98:101], v[142:145], v[200:203], v[98:101]
	v_mfma_f32_16x16x32_bf16 v[90:93], v[150:153], v[200:203], v[90:93]
	v_mfma_f32_16x16x32_bf16 v[82:85], v[142:145], v[208:211], v[82:85]
	v_mfma_f32_16x16x32_bf16 v[74:77], v[150:153], v[208:211], v[74:77]
	v_mfma_f32_16x16x32_bf16 v[126:129], v[146:149], v[188:191], v[126:129]
	v_mfma_f32_16x16x32_bf16 v[122:125], v[154:157], v[188:191], v[122:125]
	v_mfma_f32_16x16x32_bf16 v[114:117], v[146:149], v[196:199], v[114:117]
	v_mfma_f32_16x16x32_bf16 v[106:109], v[154:157], v[196:199], v[106:109]
	v_mfma_f32_16x16x32_bf16 v[98:101], v[146:149], v[204:207], v[98:101]
	v_mfma_f32_16x16x32_bf16 v[90:93], v[154:157], v[204:207], v[90:93]
	v_mfma_f32_16x16x32_bf16 v[82:85], v[146:149], v[212:215], v[82:85]
	v_mfma_f32_16x16x32_bf16 v[74:77], v[154:157], v[212:215], v[74:77]
	s_setprio 0
	s_setprio 1
	v_mfma_f32_16x16x32_bf16 v[118:121], v[158:161], v[184:187], v[118:121]
	v_mfma_f32_16x16x32_bf16 v[110:113], v[172:175], v[184:187], v[110:113]
	v_mfma_f32_16x16x32_bf16 v[102:105], v[158:161], v[192:195], v[102:105]
	v_mfma_f32_16x16x32_bf16 v[94:97], v[172:175], v[192:195], v[94:97]
	v_mfma_f32_16x16x32_bf16 v[86:89], v[158:161], v[200:203], v[86:89]
	v_mfma_f32_16x16x32_bf16 v[78:81], v[172:175], v[200:203], v[78:81]
	v_mfma_f32_16x16x32_bf16 v[70:73], v[158:161], v[208:211], v[70:73]
	v_mfma_f32_16x16x32_bf16 v[66:69], v[172:175], v[208:211], v[66:69]
	v_mfma_f32_16x16x32_bf16 v[118:121], v[168:171], v[188:191], v[118:121]
	v_mfma_f32_16x16x32_bf16 v[110:113], v[176:179], v[188:191], v[110:113]
	v_mfma_f32_16x16x32_bf16 v[102:105], v[168:171], v[196:199], v[102:105]
	v_mfma_f32_16x16x32_bf16 v[94:97], v[176:179], v[196:199], v[94:97]
	v_mfma_f32_16x16x32_bf16 v[86:89], v[168:171], v[204:207], v[86:89]
	v_mfma_f32_16x16x32_bf16 v[78:81], v[176:179], v[204:207], v[78:81]
	v_mfma_f32_16x16x32_bf16 v[70:73], v[168:171], v[212:215], v[70:73]
	v_mfma_f32_16x16x32_bf16 v[66:69], v[176:179], v[212:215], v[66:69]
	s_setprio 0
	s_barrier
	s_add_i32 s30, s60, s38
	v_lshl_add_u64 v[180:181], v[180:181], 0, s[10:11]
	s_mov_b32 m0, s30
	ds_read_b128 v[184:187], v167 offset:49152
	ds_read_b128 v[188:191], v167 offset:50176
	ds_read_b128 v[192:195], v167 offset:51200
	ds_read_b128 v[196:199], v167 offset:52224
	ds_read_b128 v[200:203], v167 offset:53248
	ds_read_b128 v[204:207], v167 offset:54272
	ds_read_b128 v[208:211], v167 offset:55296
	ds_read_b128 v[212:215], v167 offset:56320
	global_load_lds_dwordx4 v[180:181], off
	s_add_i32 m0, s30, 0x2000
	s_add_u32 s28, s28, 0x200080
	v_lshl_add_u64 v[180:181], v[216:217], 0, s[10:11]
	s_addc_u32 s29, s29, 0
	s_add_i32 s30, s61, s38
	global_load_lds_dwordx4 v[180:181], off
	v_lshl_add_u64 v[180:181], s[28:29], 0, v[130:131]
	s_mov_b32 m0, s30
	s_nop 0
	global_load_lds_dwordx4 v[180:181], off
	v_lshl_add_u64 v[180:181], s[28:29], 0, v[132:133]
	s_add_i32 m0, s30, 0x2000
	s_nop 0
	global_load_lds_dwordx4 v[180:181], off
	v_lshl_add_u64 v[180:181], v[218:219], 0, s[10:11]
	s_mov_b32 m0, s45
	s_nop 0
	global_load_lds_dwordx4 v[180:181], off
	v_lshl_add_u64 v[180:181], v[220:221], 0, s[10:11]
	s_mov_b32 m0, s46
	s_nop 0
	global_load_lds_dwordx4 v[180:181], off
	s_waitcnt vmcnt(8)
	s_waitcnt lgkmcnt(0)
	s_barrier
	s_setprio 1
	s_waitcnt lgkmcnt(0)
	v_mfma_f32_16x16x32_bf16 v[62:65], v[142:145], v[184:187], v[62:65]
	v_mfma_f32_16x16x32_bf16 v[58:61], v[150:153], v[184:187], v[58:61]
	v_mfma_f32_16x16x32_bf16 v[50:53], v[142:145], v[192:195], v[50:53]
	v_mfma_f32_16x16x32_bf16 v[42:45], v[150:153], v[192:195], v[42:45]
	v_mfma_f32_16x16x32_bf16 v[34:37], v[142:145], v[200:203], v[34:37]
	v_mfma_f32_16x16x32_bf16 v[26:29], v[150:153], v[200:203], v[26:29]
	v_mfma_f32_16x16x32_bf16 v[18:21], v[142:145], v[208:211], v[18:21]
	v_mfma_f32_16x16x32_bf16 v[10:13], v[150:153], v[208:211], v[10:13]
	v_mfma_f32_16x16x32_bf16 v[62:65], v[146:149], v[188:191], v[62:65]
	v_mfma_f32_16x16x32_bf16 v[58:61], v[154:157], v[188:191], v[58:61]
	v_mfma_f32_16x16x32_bf16 v[50:53], v[146:149], v[196:199], v[50:53]
	v_mfma_f32_16x16x32_bf16 v[42:45], v[154:157], v[196:199], v[42:45]
	v_mfma_f32_16x16x32_bf16 v[34:37], v[146:149], v[204:207], v[34:37]
	v_mfma_f32_16x16x32_bf16 v[26:29], v[154:157], v[204:207], v[26:29]
	v_mfma_f32_16x16x32_bf16 v[18:21], v[146:149], v[212:215], v[18:21]
	v_mfma_f32_16x16x32_bf16 v[10:13], v[154:157], v[212:215], v[10:13]
	s_setprio 0
	s_setprio 1
	v_mfma_f32_16x16x32_bf16 v[54:57], v[158:161], v[184:187], v[54:57]
	v_mfma_f32_16x16x32_bf16 v[46:49], v[172:175], v[184:187], v[46:49]
	v_mfma_f32_16x16x32_bf16 v[38:41], v[158:161], v[192:195], v[38:41]
	v_mfma_f32_16x16x32_bf16 v[30:33], v[172:175], v[192:195], v[30:33]
	v_mfma_f32_16x16x32_bf16 v[22:25], v[158:161], v[200:203], v[22:25]
	v_mfma_f32_16x16x32_bf16 v[14:17], v[172:175], v[200:203], v[14:17]
	v_mfma_f32_16x16x32_bf16 v[6:9], v[158:161], v[208:211], v[6:9]
	v_mfma_f32_16x16x32_bf16 v[2:5], v[172:175], v[208:211], v[2:5]
	v_mfma_f32_16x16x32_bf16 v[54:57], v[168:171], v[188:191], v[54:57]
	v_mfma_f32_16x16x32_bf16 v[46:49], v[176:179], v[188:191], v[46:49]
	v_mfma_f32_16x16x32_bf16 v[38:41], v[168:171], v[196:199], v[38:41]
	v_mfma_f32_16x16x32_bf16 v[30:33], v[176:179], v[196:199], v[30:33]
	v_mfma_f32_16x16x32_bf16 v[22:25], v[168:171], v[204:207], v[22:25]
	v_mfma_f32_16x16x32_bf16 v[14:17], v[176:179], v[204:207], v[14:17]
	v_mfma_f32_16x16x32_bf16 v[6:9], v[168:171], v[212:215], v[6:9]
	v_mfma_f32_16x16x32_bf16 v[2:5], v[176:179], v[212:215], v[2:5]
	s_setprio 0
	s_barrier
	s_add_i32 s59, s59, 2
	s_add_u32 s26, s26, 0x100
	s_addc_u32 s27, s27, 0
	s_add_u32 s57, s57, 0x100
	s_addc_u32 s58, s58, 0
	s_cmpk_gt_u32 s59, 0x7d
	s_cbranch_scc0 .LBB0_763
	s_and_b64 vcc, exec, s[14:15]
	s_cbranch_vccz .LBB0_766
	s_barrier
.LBB0_766:
	s_ashr_i32 s17, s24, 31
	s_lshr_b32 s17, s17, 28
	s_add_i32 s17, s24, s17
	s_ashr_i32 s17, s17, 4
	s_mul_i32 s26, s17, 3
	s_ashr_i32 s27, s26, 31
	v_lshl_or_b32 v180, s52, 8, v164
	s_lshl_b64 s[26:27], s[26:27], 14
	v_readlane_b32 s28, v254, 24
	v_readlane_b32 s29, v254, 25
	s_add_u32 s26, s28, s26
	v_ashrrev_i32_e32 v181, 31, v180
	s_addc_u32 s27, s29, s27
	v_lshlrev_b64 v[158:159], 2, v[180:181]
	v_lshl_add_u64 v[142:143], s[26:27], 0, v[158:159]
	v_lshl_add_u64 v[150:151], v[142:143], 0, s[12:13]
	v_add_co_u32_e32 v142, vcc, s47, v142
	v_lshl_add_u32 v160, s24, 8, v1
	s_nop 0
	v_addc_co_u32_e32 v143, vcc, 0, v143, vcc
	v_ashrrev_i32_e32 v161, 31, v160
	v_lshl_add_u64 v[152:153], s[8:9], 0, v[158:159]
	global_load_dwordx4 v[142:145], v[142:143], off
	s_nop 0
	global_load_dwordx4 v[146:149], v[152:153], off
	global_load_dwordx4 v[168:171], v[152:153], off offset:64
	global_load_dwordx4 v[172:175], v[150:151], off offset:64
	global_load_dwordx4 v[176:179], v[150:151], off offset:512
	global_load_dwordx4 v[184:187], v[150:151], off offset:576
	global_load_dwordx4 v[188:191], v[152:153], off offset:512
	global_load_dwordx4 v[192:195], v[152:153], off offset:576
	v_lshlrev_b64 v[150:151], 14, v[160:161]
	v_lshl_add_u64 v[150:151], s[48:49], 0, v[150:151]
	v_lshl_add_u64 v[150:151], v[150:151], 0, v[158:159]
	global_load_dwordx4 v[196:199], v[150:151], off
	global_load_dwordx4 v[200:203], v[150:151], off offset:64
	global_load_dwordx4 v[204:207], v[150:151], off offset:512
	global_load_dwordx4 v[208:211], v[150:151], off offset:576
	s_waitcnt vmcnt(0)
	v_pk_add_f32 v[154:155], v[144:145], v[148:149]
	v_pk_add_f32 v[156:157], v[142:143], v[146:147]
	v_pk_add_f32 v[150:151], v[174:175], v[170:171]
	v_pk_add_f32 v[152:153], v[172:173], v[168:169]
	v_pk_add_f32 v[146:147], v[178:179], v[190:191]
	v_pk_add_f32 v[148:149], v[176:177], v[188:189]
	v_pk_add_f32 v[142:143], v[186:187], v[194:195]
	v_pk_add_f32 v[144:145], v[184:185], v[192:193]
	v_or_b32_e32 v192, 16, v160
	v_ashrrev_i32_e32 v193, 31, v192
	v_lshlrev_b64 v[168:169], 14, v[192:193]
	v_lshl_add_u64 v[168:169], s[48:49], 0, v[168:169]
	v_lshl_add_u64 v[184:185], v[168:169], 0, v[158:159]
	global_load_dwordx4 v[168:171], v[184:185], off
	global_load_dwordx4 v[172:175], v[184:185], off offset:64
	global_load_dwordx4 v[176:179], v[184:185], off offset:512
	s_nop 0
	global_load_dwordx4 v[184:187], v[184:185], off offset:576
	v_pk_fma_f32 v[126:127], v[126:127], v[156:157], v[196:197]
	v_pk_fma_f32 v[128:129], v[128:129], v[154:155], v[198:199]
	v_cvt_pk_bf16_f32 v188, v126, v127
	v_lshlrev_b64 v[126:127], 13, v[160:161]
	v_cvt_pk_bf16_f32 v189, v128, v129
	v_lshl_add_u64 v[128:129], s[6:7], 0, v[126:127]
	v_lshlrev_b64 v[126:127], 1, v[180:181]
	v_lshl_add_u64 v[128:129], v[128:129], 0, v[126:127]
	v_pk_fma_f32 v[122:123], v[122:123], v[152:153], v[200:201]
	v_pk_fma_f32 v[118:119], v[118:119], v[148:149], v[204:205]
	v_pk_fma_f32 v[110:111], v[110:111], v[144:145], v[208:209]
	global_store_dwordx2 v[128:129], v[188:189], off
	v_pk_fma_f32 v[124:125], v[124:125], v[150:151], v[202:203]
	v_cvt_pk_bf16_f32 v122, v122, v123
	v_pk_fma_f32 v[120:121], v[120:121], v[146:147], v[206:207]
	v_cvt_pk_bf16_f32 v123, v124, v125
	global_store_dwordx2 v[128:129], v[122:123], off offset:32
	v_cvt_pk_bf16_f32 v118, v118, v119
	v_cvt_pk_bf16_f32 v119, v120, v121
	global_store_dwordx2 v[128:129], v[118:119], off offset:256
	v_pk_fma_f32 v[112:113], v[112:113], v[142:143], v[210:211]
	v_cvt_pk_bf16_f32 v110, v110, v111
	s_nop 0
	v_cvt_pk_bf16_f32 v111, v112, v113
	global_store_dwordx2 v[128:129], v[110:111], off offset:288
	v_or_b32_e32 v128, 32, v160
	v_ashrrev_i32_e32 v129, 31, v128
	v_lshlrev_b64 v[110:111], 14, v[128:129]
	v_lshl_add_u64 v[110:111], s[48:49], 0, v[110:111]
	v_lshl_add_u64 v[180:181], v[110:111], 0, v[158:159]
	global_load_dwordx4 v[110:113], v[180:181], off
	global_load_dwordx4 v[118:121], v[180:181], off offset:64
	global_load_dwordx4 v[122:125], v[180:181], off offset:512
	global_load_dwordx4 v[188:191], v[180:181], off offset:576
	s_waitcnt vmcnt(11)
	v_pk_fma_f32 v[116:117], v[116:117], v[154:155], v[170:171]
	v_pk_fma_f32 v[114:115], v[114:115], v[156:157], v[168:169]
	s_waitcnt vmcnt(10)
	v_pk_fma_f32 v[106:107], v[106:107], v[152:153], v[172:173]
	v_cvt_pk_bf16_f32 v114, v114, v115
	v_cvt_pk_bf16_f32 v115, v116, v117
	v_lshlrev_b64 v[116:117], 13, v[192:193]
	v_lshl_add_u64 v[116:117], s[6:7], 0, v[116:117]
	v_lshl_add_u64 v[116:117], v[116:117], 0, v[126:127]
	s_waitcnt vmcnt(9)
	v_pk_fma_f32 v[102:103], v[102:103], v[148:149], v[176:177]
	s_waitcnt vmcnt(8)
	v_pk_fma_f32 v[94:95], v[94:95], v[144:145], v[184:185]
	global_store_dwordx2 v[116:117], v[114:115], off
	v_pk_fma_f32 v[108:109], v[108:109], v[150:151], v[174:175]
	v_cvt_pk_bf16_f32 v106, v106, v107
	v_pk_fma_f32 v[104:105], v[104:105], v[146:147], v[178:179]
	v_cvt_pk_bf16_f32 v107, v108, v109
	global_store_dwordx2 v[116:117], v[106:107], off offset:32
	v_cvt_pk_bf16_f32 v102, v102, v103
	v_cvt_pk_bf16_f32 v103, v104, v105
	global_store_dwordx2 v[116:117], v[102:103], off offset:256
	v_pk_fma_f32 v[96:97], v[96:97], v[142:143], v[186:187]
	v_cvt_pk_bf16_f32 v94, v94, v95
	s_nop 0
	v_cvt_pk_bf16_f32 v95, v96, v97
	global_store_dwordx2 v[116:117], v[94:95], off offset:288
	v_or_b32_e32 v168, 48, v160
	v_ashrrev_i32_e32 v169, 31, v168
	v_lshlrev_b64 v[94:95], 14, v[168:169]
	v_lshl_add_u64 v[94:95], s[48:49], 0, v[94:95]
	v_lshl_add_u64 v[114:115], v[94:95], 0, v[158:159]
	global_load_dwordx4 v[94:97], v[114:115], off
	global_load_dwordx4 v[102:105], v[114:115], off offset:64
	global_load_dwordx4 v[106:109], v[114:115], off offset:512
	s_nop 0
	global_load_dwordx4 v[114:117], v[114:115], off offset:576
	s_waitcnt vmcnt(11)
	v_pk_fma_f32 v[100:101], v[100:101], v[154:155], v[112:113]
	v_pk_fma_f32 v[98:99], v[98:99], v[156:157], v[110:111]
	s_waitcnt vmcnt(10)
	v_pk_fma_f32 v[90:91], v[90:91], v[152:153], v[118:119]
	v_cvt_pk_bf16_f32 v98, v98, v99
	v_cvt_pk_bf16_f32 v99, v100, v101
	v_lshlrev_b64 v[100:101], 13, v[128:129]
	v_lshl_add_u64 v[100:101], s[6:7], 0, v[100:101]
	v_lshl_add_u64 v[100:101], v[100:101], 0, v[126:127]
	s_waitcnt vmcnt(9)
	v_pk_fma_f32 v[86:87], v[86:87], v[148:149], v[122:123]
	s_waitcnt vmcnt(8)
	v_pk_fma_f32 v[78:79], v[78:79], v[144:145], v[188:189]
	global_store_dwordx2 v[100:101], v[98:99], off
	v_pk_fma_f32 v[92:93], v[92:93], v[150:151], v[120:121]
	v_cvt_pk_bf16_f32 v90, v90, v91
	v_pk_fma_f32 v[88:89], v[88:89], v[146:147], v[124:125]
	v_cvt_pk_bf16_f32 v91, v92, v93
	global_store_dwordx2 v[100:101], v[90:91], off offset:32
	v_cvt_pk_bf16_f32 v86, v86, v87
	v_cvt_pk_bf16_f32 v87, v88, v89
	global_store_dwordx2 v[100:101], v[86:87], off offset:256
	v_pk_fma_f32 v[80:81], v[80:81], v[142:143], v[190:191]
	v_cvt_pk_bf16_f32 v78, v78, v79
	s_nop 0
	v_cvt_pk_bf16_f32 v79, v80, v81
	global_store_dwordx2 v[100:101], v[78:79], off offset:288
	v_add_u32_e32 v110, 0x80, v160
	v_ashrrev_i32_e32 v111, 31, v110
	v_lshlrev_b64 v[78:79], 14, v[110:111]
	v_lshl_add_u64 v[78:79], s[48:49], 0, v[78:79]
	v_lshl_add_u64 v[98:99], v[78:79], 0, v[158:159]
	global_load_dwordx4 v[78:81], v[98:99], off
	global_load_dwordx4 v[86:89], v[98:99], off offset:64
	global_load_dwordx4 v[90:93], v[98:99], off offset:512
	s_nop 0
	global_load_dwordx4 v[98:101], v[98:99], off offset:576
	s_waitcnt vmcnt(11)
	v_pk_fma_f32 v[84:85], v[84:85], v[154:155], v[96:97]
	v_pk_fma_f32 v[82:83], v[82:83], v[156:157], v[94:95]
	s_waitcnt vmcnt(10)
	v_pk_fma_f32 v[74:75], v[74:75], v[152:153], v[102:103]
	v_cvt_pk_bf16_f32 v82, v82, v83
	v_cvt_pk_bf16_f32 v83, v84, v85
	v_lshlrev_b64 v[84:85], 13, v[168:169]
	v_lshl_add_u64 v[84:85], s[6:7], 0, v[84:85]
	v_lshl_add_u64 v[84:85], v[84:85], 0, v[126:127]
	s_waitcnt vmcnt(9)
	v_pk_fma_f32 v[70:71], v[70:71], v[148:149], v[106:107]
	s_waitcnt vmcnt(8)
	v_pk_fma_f32 v[66:67], v[66:67], v[144:145], v[114:115]
	global_store_dwordx2 v[84:85], v[82:83], off
	v_pk_fma_f32 v[76:77], v[76:77], v[150:151], v[104:105]
	v_cvt_pk_bf16_f32 v74, v74, v75
	v_pk_fma_f32 v[72:73], v[72:73], v[146:147], v[108:109]
	v_cvt_pk_bf16_f32 v75, v76, v77
	global_store_dwordx2 v[84:85], v[74:75], off offset:32
	v_cvt_pk_bf16_f32 v70, v70, v71
	v_cvt_pk_bf16_f32 v71, v72, v73
	global_store_dwordx2 v[84:85], v[70:71], off offset:256
	v_pk_fma_f32 v[68:69], v[68:69], v[142:143], v[116:117]
	v_cvt_pk_bf16_f32 v66, v66, v67
	s_nop 0
	v_cvt_pk_bf16_f32 v67, v68, v69
	global_store_dwordx2 v[84:85], v[66:67], off offset:288
	v_add_u32_e32 v94, 0x90, v160
	v_ashrrev_i32_e32 v95, 31, v94
	v_lshlrev_b64 v[66:67], 14, v[94:95]
	v_lshl_add_u64 v[66:67], s[48:49], 0, v[66:67]
	v_lshl_add_u64 v[82:83], v[66:67], 0, v[158:159]
	global_load_dwordx4 v[66:69], v[82:83], off
	global_load_dwordx4 v[70:73], v[82:83], off offset:64
	global_load_dwordx4 v[74:77], v[82:83], off offset:512
	s_nop 0
	global_load_dwordx4 v[82:85], v[82:83], off offset:576
	s_waitcnt vmcnt(11)
	v_pk_fma_f32 v[64:65], v[64:65], v[154:155], v[80:81]
	v_pk_fma_f32 v[62:63], v[62:63], v[156:157], v[78:79]
	s_waitcnt vmcnt(10)
	v_pk_fma_f32 v[58:59], v[58:59], v[152:153], v[86:87]
	v_cvt_pk_bf16_f32 v62, v62, v63
	v_cvt_pk_bf16_f32 v63, v64, v65
	v_lshlrev_b64 v[64:65], 13, v[110:111]
	v_lshl_add_u64 v[64:65], s[6:7], 0, v[64:65]
	v_lshl_add_u64 v[64:65], v[64:65], 0, v[126:127]
	s_waitcnt vmcnt(9)
	v_pk_fma_f32 v[54:55], v[54:55], v[148:149], v[90:91]
	s_waitcnt vmcnt(8)
	v_pk_fma_f32 v[46:47], v[46:47], v[144:145], v[98:99]
	global_store_dwordx2 v[64:65], v[62:63], off
	v_pk_fma_f32 v[60:61], v[60:61], v[150:151], v[88:89]
	v_cvt_pk_bf16_f32 v58, v58, v59
	v_pk_fma_f32 v[56:57], v[56:57], v[146:147], v[92:93]
	v_cvt_pk_bf16_f32 v59, v60, v61
	global_store_dwordx2 v[64:65], v[58:59], off offset:32
	v_cvt_pk_bf16_f32 v54, v54, v55
	v_cvt_pk_bf16_f32 v55, v56, v57
	global_store_dwordx2 v[64:65], v[54:55], off offset:256
	v_pk_fma_f32 v[48:49], v[48:49], v[142:143], v[100:101]
	v_cvt_pk_bf16_f32 v46, v46, v47
	s_nop 0
	v_cvt_pk_bf16_f32 v47, v48, v49
	global_store_dwordx2 v[64:65], v[46:47], off offset:288
	v_add_u32_e32 v78, 0xa0, v160
	v_ashrrev_i32_e32 v79, 31, v78
	v_lshlrev_b64 v[46:47], 14, v[78:79]
	v_lshl_add_u64 v[46:47], s[48:49], 0, v[46:47]
	v_lshl_add_u64 v[62:63], v[46:47], 0, v[158:159]
	global_load_dwordx4 v[46:49], v[62:63], off
	global_load_dwordx4 v[54:57], v[62:63], off offset:64
	global_load_dwordx4 v[58:61], v[62:63], off offset:512
	s_nop 0
	global_load_dwordx4 v[62:65], v[62:63], off offset:576
	s_waitcnt vmcnt(11)
	v_pk_fma_f32 v[52:53], v[52:53], v[154:155], v[68:69]
	v_pk_fma_f32 v[50:51], v[50:51], v[156:157], v[66:67]
	s_waitcnt vmcnt(10)
	v_pk_fma_f32 v[42:43], v[42:43], v[152:153], v[70:71]
	v_cvt_pk_bf16_f32 v50, v50, v51
	v_cvt_pk_bf16_f32 v51, v52, v53
	v_lshlrev_b64 v[52:53], 13, v[94:95]
	v_lshl_add_u64 v[52:53], s[6:7], 0, v[52:53]
	v_lshl_add_u64 v[52:53], v[52:53], 0, v[126:127]
	s_waitcnt vmcnt(9)
	v_pk_fma_f32 v[38:39], v[38:39], v[148:149], v[74:75]
	s_waitcnt vmcnt(8)
	v_pk_fma_f32 v[30:31], v[30:31], v[144:145], v[82:83]
	global_store_dwordx2 v[52:53], v[50:51], off
	v_pk_fma_f32 v[44:45], v[44:45], v[150:151], v[72:73]
	v_cvt_pk_bf16_f32 v42, v42, v43
	v_pk_fma_f32 v[40:41], v[40:41], v[146:147], v[76:77]
	v_cvt_pk_bf16_f32 v43, v44, v45
	global_store_dwordx2 v[52:53], v[42:43], off offset:32
	v_cvt_pk_bf16_f32 v38, v38, v39
	v_cvt_pk_bf16_f32 v39, v40, v41
	global_store_dwordx2 v[52:53], v[38:39], off offset:256
	v_pk_fma_f32 v[32:33], v[32:33], v[142:143], v[84:85]
	v_cvt_pk_bf16_f32 v30, v30, v31
	s_nop 0
	v_cvt_pk_bf16_f32 v31, v32, v33
	global_store_dwordx2 v[52:53], v[30:31], off offset:288
	v_add_u32_e32 v66, 0xb0, v160
	v_ashrrev_i32_e32 v67, 31, v66
	v_lshlrev_b64 v[30:31], 14, v[66:67]
	v_lshl_add_u64 v[30:31], s[48:49], 0, v[30:31]
	v_lshl_add_u64 v[50:51], v[30:31], 0, v[158:159]
	global_load_dwordx4 v[30:33], v[50:51], off
	global_load_dwordx4 v[38:41], v[50:51], off offset:64
	global_load_dwordx4 v[42:45], v[50:51], off offset:512
	s_nop 0
	global_load_dwordx4 v[50:53], v[50:51], off offset:576
	s_waitcnt vmcnt(11)
	v_pk_fma_f32 v[36:37], v[36:37], v[154:155], v[48:49]
	v_pk_fma_f32 v[34:35], v[34:35], v[156:157], v[46:47]
	s_waitcnt vmcnt(10)
	v_pk_fma_f32 v[26:27], v[26:27], v[152:153], v[54:55]
	v_cvt_pk_bf16_f32 v34, v34, v35
	v_cvt_pk_bf16_f32 v35, v36, v37
	v_lshlrev_b64 v[36:37], 13, v[78:79]
	v_lshl_add_u64 v[36:37], s[6:7], 0, v[36:37]
	v_lshl_add_u64 v[36:37], v[36:37], 0, v[126:127]
	s_waitcnt vmcnt(9)
	v_pk_fma_f32 v[22:23], v[22:23], v[148:149], v[58:59]
	s_waitcnt vmcnt(8)
	v_pk_fma_f32 v[14:15], v[14:15], v[144:145], v[62:63]
	global_store_dwordx2 v[36:37], v[34:35], off
	v_pk_fma_f32 v[28:29], v[28:29], v[150:151], v[56:57]
	v_cvt_pk_bf16_f32 v26, v26, v27
	v_pk_fma_f32 v[24:25], v[24:25], v[146:147], v[60:61]
	v_cvt_pk_bf16_f32 v27, v28, v29
	global_store_dwordx2 v[36:37], v[26:27], off offset:32
	v_cvt_pk_bf16_f32 v22, v22, v23
	v_cvt_pk_bf16_f32 v23, v24, v25
	global_store_dwordx2 v[36:37], v[22:23], off offset:256
	v_pk_fma_f32 v[16:17], v[16:17], v[142:143], v[64:65]
	v_cvt_pk_bf16_f32 v14, v14, v15
	s_nop 0
	v_cvt_pk_bf16_f32 v15, v16, v17
	global_store_dwordx2 v[36:37], v[14:15], off offset:288
	s_waitcnt vmcnt(7)
	v_pk_fma_f32 v[14:15], v[20:21], v[154:155], v[32:33]
	v_pk_fma_f32 v[16:17], v[18:19], v[156:157], v[30:31]
	s_waitcnt vmcnt(6)
	v_pk_fma_f32 v[10:11], v[10:11], v[152:153], v[38:39]
	v_cvt_pk_bf16_f32 v16, v16, v17
	v_cvt_pk_bf16_f32 v17, v14, v15
	v_lshlrev_b64 v[14:15], 13, v[66:67]
	v_lshl_add_u64 v[14:15], s[6:7], 0, v[14:15]
	v_lshl_add_u64 v[14:15], v[14:15], 0, v[126:127]
	s_waitcnt vmcnt(5)
	v_pk_fma_f32 v[6:7], v[6:7], v[148:149], v[42:43]
	s_waitcnt vmcnt(4)
	v_pk_fma_f32 v[2:3], v[2:3], v[144:145], v[50:51]
	global_store_dwordx2 v[14:15], v[16:17], off
	v_pk_fma_f32 v[12:13], v[12:13], v[150:151], v[40:41]
	v_cvt_pk_bf16_f32 v10, v10, v11
	v_pk_fma_f32 v[8:9], v[8:9], v[146:147], v[44:45]
	v_cvt_pk_bf16_f32 v11, v12, v13
	global_store_dwordx2 v[14:15], v[10:11], off offset:32
	v_cvt_pk_bf16_f32 v6, v6, v7
	v_cvt_pk_bf16_f32 v7, v8, v9
	global_store_dwordx2 v[14:15], v[6:7], off offset:256
	v_pk_fma_f32 v[4:5], v[4:5], v[142:143], v[52:53]
	v_cvt_pk_bf16_f32 v2, v2, v3
	s_nop 0
	v_cvt_pk_bf16_f32 v3, v4, v5
	global_store_dwordx2 v[14:15], v[2:3], off offset:288
	s_andn2_b64 vcc, exec, s[0:1]
	s_mov_b64 s[0:1], -1
	s_cbranch_vccnz .LBB0_755
	s_mov_b32 s98, 1
	s_andn2_b64 vcc, exec, s[4:5]
	s_cbranch_vccnz .LBB0_754
	s_barrier
	s_branch .LBB0_754

.LBB0_916:
	ds_read_b128 v[164:167], v158
	ds_read_b128 v[168:171], v158 offset:1024
	ds_read_b128 v[172:175], v158 offset:2048
	ds_read_b128 v[176:179], v158 offset:3072
	ds_read_b128 v[180:183], v159
	ds_read_b128 v[184:187], v159 offset:1024
	ds_read_b128 v[188:191], v159 offset:2048
	ds_read_b128 v[192:195], v159 offset:3072
	s_add_u32 s28, s26, 0xfff00080
	s_addc_u32 s29, s27, -1
	s_cmp_eq_u32 s59, 60
	s_cselect_b32 s31, s19, s29
	s_cselect_b32 s30, s53, s28
	s_cselect_b32 s29, s17, s58
	s_cselect_b32 s28, s56, s57
	v_lshl_add_u64 v[146:147], s[26:27], 0, v[138:139]
	s_add_i32 m0, s25, 0xc000
	ds_read_b128 v[196:199], v160
	ds_read_b128 v[200:203], v160 offset:1024
	ds_read_b128 v[204:207], v160 offset:2048
	ds_read_b128 v[208:211], v160 offset:3072
	ds_read_b128 v[212:215], v160 offset:4096
	ds_read_b128 v[216:219], v160 offset:5120
	ds_read_b128 v[220:223], v160 offset:6144
	ds_read_b128 v[224:227], v160 offset:7168
	global_load_lds_dwordx4 v[146:147], off
	v_lshl_add_u64 v[146:147], s[26:27], 0, v[140:141]
	s_add_i32 m0, s25, 0xe000
	s_nop 0
	global_load_lds_dwordx4 v[146:147], off
	s_cmp_eq_u32 s98, 0
	s_cbranch_scc1 .Lgw916_0a
	s_waitcnt vmcnt(16)
	s_branch .Lgw916_0b

.Lgw916_0b:
	s_waitcnt lgkmcnt(0)
	s_barrier
	s_setprio 1
	s_waitcnt lgkmcnt(0)
	v_mfma_f32_16x16x32_bf16 v[126:129], v[164:167], v[196:199], v[126:129]
	v_mfma_f32_16x16x32_bf16 v[122:125], v[172:175], v[196:199], v[122:125]
	v_mfma_f32_16x16x32_bf16 v[110:113], v[164:167], v[204:207], v[110:113]
	v_mfma_f32_16x16x32_bf16 v[106:109], v[172:175], v[204:207], v[106:109]
	v_mfma_f32_16x16x32_bf16 v[94:97], v[164:167], v[212:215], v[94:97]
	v_mfma_f32_16x16x32_bf16 v[90:93], v[172:175], v[212:215], v[90:93]
	v_mfma_f32_16x16x32_bf16 v[78:81], v[164:167], v[220:223], v[78:81]
	v_mfma_f32_16x16x32_bf16 v[74:77], v[172:175], v[220:223], v[74:77]
	v_mfma_f32_16x16x32_bf16 v[126:129], v[168:171], v[200:203], v[126:129]
	v_mfma_f32_16x16x32_bf16 v[122:125], v[176:179], v[200:203], v[122:125]
	v_mfma_f32_16x16x32_bf16 v[110:113], v[168:171], v[208:211], v[110:113]
	v_mfma_f32_16x16x32_bf16 v[106:109], v[176:179], v[208:211], v[106:109]
	v_mfma_f32_16x16x32_bf16 v[94:97], v[168:171], v[216:219], v[94:97]
	v_mfma_f32_16x16x32_bf16 v[90:93], v[176:179], v[216:219], v[90:93]
	v_mfma_f32_16x16x32_bf16 v[78:81], v[168:171], v[224:227], v[78:81]
	v_mfma_f32_16x16x32_bf16 v[74:77], v[176:179], v[224:227], v[74:77]
	s_setprio 0
	s_setprio 1
	v_mfma_f32_16x16x32_bf16 v[118:121], v[180:183], v[196:199], v[118:121]
	v_mfma_f32_16x16x32_bf16 v[114:117], v[188:191], v[196:199], v[114:117]
	v_mfma_f32_16x16x32_bf16 v[102:105], v[180:183], v[204:207], v[102:105]
	v_mfma_f32_16x16x32_bf16 v[98:101], v[188:191], v[204:207], v[98:101]
	v_mfma_f32_16x16x32_bf16 v[86:89], v[180:183], v[212:215], v[86:89]
	v_mfma_f32_16x16x32_bf16 v[82:85], v[188:191], v[212:215], v[82:85]
	v_mfma_f32_16x16x32_bf16 v[70:73], v[180:183], v[220:223], v[70:73]
	v_mfma_f32_16x16x32_bf16 v[66:69], v[188:191], v[220:223], v[66:69]
	v_mfma_f32_16x16x32_bf16 v[118:121], v[184:187], v[200:203], v[118:121]
	v_mfma_f32_16x16x32_bf16 v[114:117], v[192:195], v[200:203], v[114:117]
	v_mfma_f32_16x16x32_bf16 v[102:105], v[184:187], v[208:211], v[102:105]
	v_mfma_f32_16x16x32_bf16 v[98:101], v[192:195], v[208:211], v[98:101]
	v_mfma_f32_16x16x32_bf16 v[86:89], v[184:187], v[216:219], v[86:89]
	v_mfma_f32_16x16x32_bf16 v[82:85], v[192:195], v[216:219], v[82:85]
	v_mfma_f32_16x16x32_bf16 v[70:73], v[184:187], v[224:227], v[70:73]
	v_mfma_f32_16x16x32_bf16 v[66:69], v[192:195], v[224:227], v[66:69]
	s_setprio 0
	s_barrier
	s_add_i32 s60, s45, s38
	v_lshl_add_u64 v[146:147], s[28:29], 0, v[132:133]
	s_mov_b32 m0, s60
	ds_read_b128 v[196:199], v160 offset:16384
	ds_read_b128 v[200:203], v160 offset:17408
	ds_read_b128 v[204:207], v160 offset:18432
	ds_read_b128 v[208:211], v160 offset:19456
	ds_read_b128 v[212:215], v160 offset:20480
	ds_read_b128 v[216:219], v160 offset:21504
	ds_read_b128 v[220:223], v160 offset:22528
	ds_read_b128 v[224:227], v160 offset:23552
	global_load_lds_dwordx4 v[146:147], off
	s_add_i32 m0, s60, 0x2000
	s_add_u32 s60, s28, 0x100000
	v_lshl_add_u64 v[228:229], s[28:29], 0, v[136:137]
	s_addc_u32 s61, s29, 0
	s_add_i32 s62, s46, s38
	global_load_lds_dwordx4 v[228:229], off
	v_lshl_add_u64 v[230:231], s[60:61], 0, v[132:133]
	s_mov_b32 m0, s62
	v_lshl_add_u64 v[232:233], s[30:31], 0, v[134:135]
	global_load_lds_dwordx4 v[230:231], off
	v_lshl_add_u64 v[230:231], s[60:61], 0, v[136:137]
	s_add_i32 m0, s62, 0x2000
	s_nop 0
	global_load_lds_dwordx4 v[230:231], off
	v_lshl_add_u64 v[230:231], s[30:31], 0, v[130:131]
	s_mov_b32 m0, s25
	s_nop 0
	global_load_lds_dwordx4 v[230:231], off
	s_mov_b32 m0, s39
	s_nop 0
	global_load_lds_dwordx4 v[232:233], off
	s_cmp_eq_u32 s98, 0
	s_cbranch_scc1 .Lgw916_1a
	s_waitcnt vmcnt(16)
	s_branch .Lgw916_1b

.Lgw916_1b:
	s_mov_b32 s98, 0
	s_waitcnt lgkmcnt(0)
	s_barrier
	s_setprio 1
	s_waitcnt lgkmcnt(0)
	v_mfma_f32_16x16x32_bf16 v[62:65], v[164:167], v[196:199], v[62:65]
	v_mfma_f32_16x16x32_bf16 v[58:61], v[172:175], v[196:199], v[58:61]
	v_mfma_f32_16x16x32_bf16 v[46:49], v[164:167], v[204:207], v[46:49]
	v_mfma_f32_16x16x32_bf16 v[42:45], v[172:175], v[204:207], v[42:45]
	v_mfma_f32_16x16x32_bf16 v[30:33], v[164:167], v[212:215], v[30:33]
	v_mfma_f32_16x16x32_bf16 v[26:29], v[172:175], v[212:215], v[26:29]
	v_mfma_f32_16x16x32_bf16 v[14:17], v[164:167], v[220:223], v[14:17]
	v_mfma_f32_16x16x32_bf16 v[10:13], v[172:175], v[220:223], v[10:13]
	v_mfma_f32_16x16x32_bf16 v[62:65], v[168:171], v[200:203], v[62:65]
	v_mfma_f32_16x16x32_bf16 v[58:61], v[176:179], v[200:203], v[58:61]
	v_mfma_f32_16x16x32_bf16 v[46:49], v[168:171], v[208:211], v[46:49]
	v_mfma_f32_16x16x32_bf16 v[42:45], v[176:179], v[208:211], v[42:45]
	v_mfma_f32_16x16x32_bf16 v[30:33], v[168:171], v[216:219], v[30:33]
	v_mfma_f32_16x16x32_bf16 v[26:29], v[176:179], v[216:219], v[26:29]
	v_mfma_f32_16x16x32_bf16 v[14:17], v[168:171], v[224:227], v[14:17]
	v_mfma_f32_16x16x32_bf16 v[10:13], v[176:179], v[224:227], v[10:13]
	s_setprio 0
	s_setprio 1
	v_mfma_f32_16x16x32_bf16 v[54:57], v[180:183], v[196:199], v[54:57]
	v_mfma_f32_16x16x32_bf16 v[50:53], v[188:191], v[196:199], v[50:53]
	v_mfma_f32_16x16x32_bf16 v[38:41], v[180:183], v[204:207], v[38:41]
	v_mfma_f32_16x16x32_bf16 v[34:37], v[188:191], v[204:207], v[34:37]
	v_mfma_f32_16x16x32_bf16 v[22:25], v[180:183], v[212:215], v[22:25]
	v_mfma_f32_16x16x32_bf16 v[18:21], v[188:191], v[212:215], v[18:21]
	v_mfma_f32_16x16x32_bf16 v[6:9], v[180:183], v[220:223], v[6:9]
	v_mfma_f32_16x16x32_bf16 v[2:5], v[188:191], v[220:223], v[2:5]
	v_mfma_f32_16x16x32_bf16 v[54:57], v[184:187], v[200:203], v[54:57]
	v_mfma_f32_16x16x32_bf16 v[50:53], v[192:195], v[200:203], v[50:53]
	v_mfma_f32_16x16x32_bf16 v[38:41], v[184:187], v[208:211], v[38:41]
	v_mfma_f32_16x16x32_bf16 v[34:37], v[192:195], v[208:211], v[34:37]
	v_mfma_f32_16x16x32_bf16 v[22:25], v[184:187], v[216:219], v[22:25]
	v_mfma_f32_16x16x32_bf16 v[18:21], v[192:195], v[216:219], v[18:21]
	v_mfma_f32_16x16x32_bf16 v[6:9], v[184:187], v[224:227], v[6:9]
	v_mfma_f32_16x16x32_bf16 v[2:5], v[192:195], v[224:227], v[2:5]
	s_setprio 0
	s_barrier
	s_add_i32 s60, 0, 0x18000
	v_add_u32_e32 v161, s60, v156
	s_add_i32 s61, 0, 0x1c000
	ds_read_b128 v[164:167], v161
	ds_read_b128 v[168:171], v161 offset:1024
	ds_read_b128 v[172:175], v161 offset:2048
	ds_read_b128 v[176:179], v161 offset:3072
	v_add_u32_e32 v161, s61, v156
	ds_read_b128 v[180:183], v161
	ds_read_b128 v[184:187], v161 offset:1024
	ds_read_b128 v[188:191], v161 offset:2048
	ds_read_b128 v[192:195], v161 offset:3072
	s_add_u32 s30, s30, 0x100000
	s_addc_u32 s31, s31, 0
	s_mov_b32 m0, s40
	v_lshl_add_u64 v[234:235], s[30:31], 0, v[130:131]
	ds_read_b128 v[196:199], v160 offset:32768
	ds_read_b128 v[200:203], v160 offset:33792
	ds_read_b128 v[204:207], v160 offset:34816
	ds_read_b128 v[208:211], v160 offset:35840
	ds_read_b128 v[212:215], v160 offset:36864
	ds_read_b128 v[216:219], v160 offset:37888
	ds_read_b128 v[220:223], v160 offset:38912
	ds_read_b128 v[224:227], v160 offset:39936
	global_load_lds_dwordx4 v[234:235], off
	v_lshl_add_u64 v[234:235], s[30:31], 0, v[134:135]
	s_mov_b32 m0, s41
	s_nop 0
	global_load_lds_dwordx4 v[234:235], off
	s_waitcnt vmcnt(8)
	s_waitcnt lgkmcnt(0)
	s_barrier
	s_setprio 1
	s_waitcnt lgkmcnt(0)
	v_mfma_f32_16x16x32_bf16 v[126:129], v[164:167], v[196:199], v[126:129]
	v_mfma_f32_16x16x32_bf16 v[122:125], v[172:175], v[196:199], v[122:125]
	v_mfma_f32_16x16x32_bf16 v[110:113], v[164:167], v[204:207], v[110:113]
	v_mfma_f32_16x16x32_bf16 v[106:109], v[172:175], v[204:207], v[106:109]
	v_mfma_f32_16x16x32_bf16 v[94:97], v[164:167], v[212:215], v[94:97]
	v_mfma_f32_16x16x32_bf16 v[90:93], v[172:175], v[212:215], v[90:93]
	v_mfma_f32_16x16x32_bf16 v[78:81], v[164:167], v[220:223], v[78:81]
	v_mfma_f32_16x16x32_bf16 v[74:77], v[172:175], v[220:223], v[74:77]
	v_mfma_f32_16x16x32_bf16 v[126:129], v[168:171], v[200:203], v[126:129]
	v_mfma_f32_16x16x32_bf16 v[122:125], v[176:179], v[200:203], v[122:125]
	v_mfma_f32_16x16x32_bf16 v[110:113], v[168:171], v[208:211], v[110:113]
	v_mfma_f32_16x16x32_bf16 v[106:109], v[176:179], v[208:211], v[106:109]
	v_mfma_f32_16x16x32_bf16 v[94:97], v[168:171], v[216:219], v[94:97]
	v_mfma_f32_16x16x32_bf16 v[90:93], v[176:179], v[216:219], v[90:93]
	v_mfma_f32_16x16x32_bf16 v[78:81], v[168:171], v[224:227], v[78:81]
	v_mfma_f32_16x16x32_bf16 v[74:77], v[176:179], v[224:227], v[74:77]
	s_setprio 0
	s_setprio 1
	v_mfma_f32_16x16x32_bf16 v[118:121], v[180:183], v[196:199], v[118:121]
	v_mfma_f32_16x16x32_bf16 v[114:117], v[188:191], v[196:199], v[114:117]
	v_mfma_f32_16x16x32_bf16 v[102:105], v[180:183], v[204:207], v[102:105]
	v_mfma_f32_16x16x32_bf16 v[98:101], v[188:191], v[204:207], v[98:101]
	v_mfma_f32_16x16x32_bf16 v[86:89], v[180:183], v[212:215], v[86:89]
	v_mfma_f32_16x16x32_bf16 v[82:85], v[188:191], v[212:215], v[82:85]
	v_mfma_f32_16x16x32_bf16 v[70:73], v[180:183], v[220:223], v[70:73]
	v_mfma_f32_16x16x32_bf16 v[66:69], v[188:191], v[220:223], v[66:69]
	v_mfma_f32_16x16x32_bf16 v[118:121], v[184:187], v[200:203], v[118:121]
	v_mfma_f32_16x16x32_bf16 v[114:117], v[192:195], v[200:203], v[114:117]
	v_mfma_f32_16x16x32_bf16 v[102:105], v[184:187], v[208:211], v[102:105]
	v_mfma_f32_16x16x32_bf16 v[98:101], v[192:195], v[208:211], v[98:101]
	v_mfma_f32_16x16x32_bf16 v[86:89], v[184:187], v[216:219], v[86:89]
	v_mfma_f32_16x16x32_bf16 v[82:85], v[192:195], v[216:219], v[82:85]
	v_mfma_f32_16x16x32_bf16 v[70:73], v[184:187], v[224:227], v[70:73]
	v_mfma_f32_16x16x32_bf16 v[66:69], v[192:195], v[224:227], v[66:69]
	s_setprio 0
	s_barrier
	s_add_i32 s30, s60, s38
	v_lshl_add_u64 v[146:147], v[146:147], 0, s[12:13]
	s_mov_b32 m0, s30
	ds_read_b128 v[196:199], v160 offset:49152
	ds_read_b128 v[200:203], v160 offset:50176
	ds_read_b128 v[204:207], v160 offset:51200
	ds_read_b128 v[208:211], v160 offset:52224
	ds_read_b128 v[212:215], v160 offset:53248
	ds_read_b128 v[216:219], v160 offset:54272
	ds_read_b128 v[220:223], v160 offset:55296
	ds_read_b128 v[224:227], v160 offset:56320
	global_load_lds_dwordx4 v[146:147], off
	s_add_i32 m0, s30, 0x2000
	s_add_u32 s28, s28, 0x100080
	v_lshl_add_u64 v[146:147], v[228:229], 0, s[12:13]
	s_addc_u32 s29, s29, 0
	s_add_i32 s30, s61, s38
	global_load_lds_dwordx4 v[146:147], off
	v_lshl_add_u64 v[146:147], s[28:29], 0, v[132:133]
	s_mov_b32 m0, s30
	s_nop 0
	global_load_lds_dwordx4 v[146:147], off
	v_lshl_add_u64 v[146:147], s[28:29], 0, v[136:137]
	s_add_i32 m0, s30, 0x2000
	s_nop 0
	global_load_lds_dwordx4 v[146:147], off
	v_lshl_add_u64 v[146:147], v[230:231], 0, s[12:13]
	s_mov_b32 m0, s42
	s_nop 0
	global_load_lds_dwordx4 v[146:147], off
	v_lshl_add_u64 v[146:147], v[232:233], 0, s[12:13]
	s_mov_b32 m0, s43
	s_nop 0
	global_load_lds_dwordx4 v[146:147], off
	s_waitcnt vmcnt(8)
	s_waitcnt lgkmcnt(0)
	s_barrier
	s_setprio 1
	s_waitcnt lgkmcnt(0)
	v_mfma_f32_16x16x32_bf16 v[62:65], v[164:167], v[196:199], v[62:65]
	v_mfma_f32_16x16x32_bf16 v[58:61], v[172:175], v[196:199], v[58:61]
	v_mfma_f32_16x16x32_bf16 v[46:49], v[164:167], v[204:207], v[46:49]
	v_mfma_f32_16x16x32_bf16 v[42:45], v[172:175], v[204:207], v[42:45]
	v_mfma_f32_16x16x32_bf16 v[30:33], v[164:167], v[212:215], v[30:33]
	v_mfma_f32_16x16x32_bf16 v[26:29], v[172:175], v[212:215], v[26:29]
	v_mfma_f32_16x16x32_bf16 v[14:17], v[164:167], v[220:223], v[14:17]
	v_mfma_f32_16x16x32_bf16 v[10:13], v[172:175], v[220:223], v[10:13]
	v_mfma_f32_16x16x32_bf16 v[62:65], v[168:171], v[200:203], v[62:65]
	v_mfma_f32_16x16x32_bf16 v[58:61], v[176:179], v[200:203], v[58:61]
	v_mfma_f32_16x16x32_bf16 v[46:49], v[168:171], v[208:211], v[46:49]
	v_mfma_f32_16x16x32_bf16 v[42:45], v[176:179], v[208:211], v[42:45]
	v_mfma_f32_16x16x32_bf16 v[30:33], v[168:171], v[216:219], v[30:33]
	v_mfma_f32_16x16x32_bf16 v[26:29], v[176:179], v[216:219], v[26:29]
	v_mfma_f32_16x16x32_bf16 v[14:17], v[168:171], v[224:227], v[14:17]
	v_mfma_f32_16x16x32_bf16 v[10:13], v[176:179], v[224:227], v[10:13]
	s_setprio 0
	s_setprio 1
	v_mfma_f32_16x16x32_bf16 v[54:57], v[180:183], v[196:199], v[54:57]
	v_mfma_f32_16x16x32_bf16 v[50:53], v[188:191], v[196:199], v[50:53]
	v_mfma_f32_16x16x32_bf16 v[38:41], v[180:183], v[204:207], v[38:41]
	v_mfma_f32_16x16x32_bf16 v[34:37], v[188:191], v[204:207], v[34:37]
	v_mfma_f32_16x16x32_bf16 v[22:25], v[180:183], v[212:215], v[22:25]
	v_mfma_f32_16x16x32_bf16 v[18:21], v[188:191], v[212:215], v[18:21]
	v_mfma_f32_16x16x32_bf16 v[6:9], v[180:183], v[220:223], v[6:9]
	v_mfma_f32_16x16x32_bf16 v[2:5], v[188:191], v[220:223], v[2:5]
	v_mfma_f32_16x16x32_bf16 v[54:57], v[184:187], v[200:203], v[54:57]
	v_mfma_f32_16x16x32_bf16 v[50:53], v[192:195], v[200:203], v[50:53]
	v_mfma_f32_16x16x32_bf16 v[38:41], v[184:187], v[208:211], v[38:41]
	v_mfma_f32_16x16x32_bf16 v[34:37], v[192:195], v[208:211], v[34:37]
	v_mfma_f32_16x16x32_bf16 v[22:25], v[184:187], v[216:219], v[22:25]
	v_mfma_f32_16x16x32_bf16 v[18:21], v[192:195], v[216:219], v[18:21]
	v_mfma_f32_16x16x32_bf16 v[6:9], v[184:187], v[224:227], v[6:9]
	v_mfma_f32_16x16x32_bf16 v[2:5], v[192:195], v[224:227], v[2:5]
	s_setprio 0
	s_barrier
	s_add_i32 s59, s59, 2
	s_add_u32 s26, s26, 0x100
	s_addc_u32 s27, s27, 0
	s_add_u32 s57, s57, 0x100
	s_addc_u32 s58, s58, 0
	s_cmp_gt_u32 s59, 61
	s_cbranch_scc0 .LBB0_916
	s_and_b64 vcc, exec, s[14:15]
	s_cbranch_vccz .LBB0_919
	s_barrier
.LBB0_919:
	v_lshl_add_u32 v146, s24, 8, v155
	v_ashrrev_i32_e32 v147, 31, v146
	v_lshlrev_b64 v[166:167], 14, v[146:147]
	v_mul_f32_e32 v147, 0x3dd2d3e7, v126
	v_fmaak_f32 v147, v126, v147, 0x40135761
	v_mul_f32_e64 v147, v126, -v147
	v_exp_f32_e32 v147, v147
	v_mul_f32_e32 v161, 0xbfb8aa3b, v118
	v_exp_f32_e32 v161, v161
	v_mov_b32_e32 v171, v118
	v_add_f32_e32 v147, 1.0, v147
	v_rcp_f32_e32 v168, v147
	v_add_f32_e32 v147, 1.0, v161
	v_mul_f32_e32 v118, 0x3dd2d3e7, v122
	v_rcp_f32_e32 v169, v147
	v_fmaak_f32 v118, v122, v118, 0x40135761
	v_mul_f32_e64 v118, v122, -v118
	v_mov_b32_e32 v170, v126
	v_exp_f32_e32 v118, v118
	v_mul_f32_e32 v126, 0xbfb8aa3b, v114
	v_exp_f32_e32 v126, v126
	v_pk_mul_f32 v[168:169], v[170:171], v[168:169]
	v_add_f32_e32 v118, 1.0, v118
	v_mul_f32_e32 v147, v168, v169
	v_mov_b32_e32 v169, v114
	v_mul_f32_e32 v114, 0x3dd2d3e7, v127
	v_fmaak_f32 v114, v127, v114, 0x40135761
	v_rcp_f32_e32 v170, v118
	v_add_f32_e32 v118, 1.0, v126
	v_mul_f32_e64 v114, v127, -v114
	v_rcp_f32_e32 v171, v118
	v_exp_f32_e32 v114, v114
	v_mul_f32_e32 v118, 0xbfb8aa3b, v119
	v_exp_f32_e32 v118, v118
	v_mov_b32_e32 v168, v122
	v_pk_mul_f32 v[168:169], v[168:169], v[170:171]
	v_add_f32_e32 v114, 1.0, v114
	v_mul_f32_e32 v122, v168, v169
	v_rcp_f32_e32 v168, v114
	v_add_f32_e32 v114, 1.0, v118
	v_rcp_f32_e32 v169, v114
	v_mul_f32_e32 v114, 0x3dd2d3e7, v123
	v_fmaak_f32 v114, v123, v114, 0x40135761
	v_mul_f32_e64 v114, v123, -v114
	v_exp_f32_e32 v114, v114
	v_mul_f32_e32 v118, 0xbfb8aa3b, v115
	v_exp_f32_e32 v161, v118
	v_mov_b32_e32 v118, v127
	v_add_f32_e32 v114, 1.0, v114
	v_pk_mul_f32 v[118:119], v[118:119], v[168:169]
	v_rcp_f32_e32 v126, v114
	v_add_f32_e32 v114, 1.0, v161
	v_mul_f32_e32 v161, v118, v119
	v_mul_f32_e32 v118, 0x3dd2d3e7, v128
	v_rcp_f32_e32 v127, v114
	v_fmaak_f32 v118, v128, v118, 0x40135761
	v_mul_f32_e32 v119, 0xbfb8aa3b, v120
	v_mul_f32_e64 v118, v128, -v118
	v_exp_f32_e32 v119, v119
	v_exp_f32_e32 v118, v118
	v_mov_b32_e32 v114, v123
	v_pk_mul_f32 v[114:115], v[114:115], v[126:127]
	v_mul_f32_e32 v126, 0xbfb8aa3b, v116
	v_mul_f32_e32 v123, v114, v115
	v_add_f32_e32 v115, 1.0, v119
	v_mov_b32_e32 v119, v120
	v_mul_f32_e32 v120, 0x3dd2d3e7, v124
	v_add_f32_e32 v114, 1.0, v118
	v_fmaak_f32 v120, v124, v120, 0x40135761
	v_rcp_f32_e32 v114, v114
	v_rcp_f32_e32 v115, v115
	v_mul_f32_e64 v120, v124, -v120
	v_exp_f32_e32 v120, v120
	v_exp_f32_e32 v126, v126
	v_mov_b32_e32 v118, v128
	v_pk_mul_f32 v[114:115], v[118:119], v[114:115]
	v_add_f32_e32 v118, 1.0, v120
	v_add_f32_e32 v119, 1.0, v126
	v_mul_f32_e32 v126, v114, v115
	v_mov_b32_e32 v115, v116
	v_mul_f32_e32 v116, 0x3dd2d3e7, v129
	v_rcp_f32_e32 v118, v118
	v_rcp_f32_e32 v119, v119
	v_fmaak_f32 v116, v129, v116, 0x40135761
	v_mul_f32_e64 v116, v129, -v116
	v_exp_f32_e32 v116, v116
	v_mov_b32_e32 v114, v124
	v_pk_mul_f32 v[114:115], v[114:115], v[118:119]
	v_mul_f32_e32 v118, 0xbfb8aa3b, v121
	v_exp_f32_e32 v118, v118
	v_mul_f32_e32 v124, v114, v115
	v_add_f32_e32 v114, 1.0, v116
	v_mul_f32_e32 v116, 0x3dd2d3e7, v125
	v_fmaak_f32 v116, v125, v116, 0x40135761
	v_mul_f32_e64 v116, v125, -v116
	v_add_f32_e32 v115, 1.0, v118
	v_exp_f32_e32 v116, v116
	v_mul_f32_e32 v118, 0xbfb8aa3b, v117
	v_exp_f32_e32 v119, v118
	v_rcp_f32_e32 v114, v114
	v_add_f32_e32 v116, 1.0, v116
	v_rcp_f32_e32 v115, v115
	v_rcp_f32_e32 v118, v116
	v_add_f32_e32 v116, 1.0, v119
	v_rcp_f32_e32 v119, v116
	v_lshl_or_b32 v164, s52, 7, v157
	v_mov_b32_e32 v120, v129
	v_ashrrev_i32_e32 v165, 31, v164
	v_pk_mul_f32 v[114:115], v[120:121], v[114:115]
	v_mov_b32_e32 v116, v125
	v_lshl_add_u64 v[166:167], s[10:11], 0, v[166:167]
	v_mul_f32_e32 v120, v114, v115
	v_pk_mul_f32 v[114:115], v[116:117], v[118:119]
	v_lshlrev_b64 v[116:117], 1, v[164:165]
	v_mul_f32_e32 v121, v114, v115
	v_lshl_add_u64 v[114:115], v[166:167], 0, v[116:117]
	v_cvt_pk_bf16_f32 v118, v147, v161
	v_cvt_pk_bf16_f32 v119, v126, v120
	v_cvt_pk_bf16_f32 v120, v122, v123
	v_cvt_pk_bf16_f32 v121, v124, v121
	global_store_dwordx4 v[114:115], v[118:121], off
	v_mov_b32_e32 v123, v102
	v_mov_b32_e32 v122, v110
	v_mul_f32_e32 v120, 0x3dd2d3e7, v110
	v_fmaak_f32 v120, v110, v120, 0x40135761
	v_mul_f32_e64 v120, v110, -v120
	v_mul_f32_e32 v121, 0xbfb8aa3b, v102
	v_exp_f32_e32 v120, v120
	v_exp_f32_e32 v121, v121
	v_mul_f32_e32 v102, 0x3dd2d3e7, v106
	v_fmaak_f32 v102, v106, v102, 0x40135761
	v_add_f32_e32 v120, 1.0, v120
	v_add_f32_e32 v121, 1.0, v121
	v_rcp_f32_e32 v120, v120
	v_rcp_f32_e32 v121, v121
	v_mul_f32_e64 v102, v106, -v102
	v_exp_f32_e32 v102, v102
	v_mul_f32_e32 v110, 0xbfb8aa3b, v98
	v_exp_f32_e32 v110, v110
	v_pk_mul_f32 v[120:121], v[122:123], v[120:121]
	v_add_f32_e32 v102, 1.0, v102
	v_mul_f32_e32 v124, v120, v121
	v_mov_b32_e32 v121, v98
	v_mul_f32_e32 v98, 0x3dd2d3e7, v111
	v_fmaak_f32 v98, v111, v98, 0x40135761
	v_rcp_f32_e32 v122, v102
	v_add_f32_e32 v102, 1.0, v110
	v_mul_f32_e64 v98, v111, -v98
	v_rcp_f32_e32 v123, v102
	v_exp_f32_e32 v98, v98
	v_mul_f32_e32 v102, 0xbfb8aa3b, v103
	v_exp_f32_e32 v102, v102
	v_mov_b32_e32 v120, v106
	v_pk_mul_f32 v[120:121], v[120:121], v[122:123]
	v_add_f32_e32 v98, 1.0, v98
	v_mul_f32_e32 v106, v120, v121
	v_rcp_f32_e32 v120, v98
	v_add_f32_e32 v98, 1.0, v102
	v_rcp_f32_e32 v121, v98
	v_mul_f32_e32 v98, 0x3dd2d3e7, v107
	v_fmaak_f32 v98, v107, v98, 0x40135761
	v_mul_f32_e64 v98, v107, -v98
	v_exp_f32_e32 v98, v98
	v_mul_f32_e32 v102, 0xbfb8aa3b, v99
	v_exp_f32_e32 v122, v102
	v_mov_b32_e32 v102, v111
	v_add_f32_e32 v98, 1.0, v98
	v_pk_mul_f32 v[102:103], v[102:103], v[120:121]
	v_rcp_f32_e32 v110, v98
	v_add_f32_e32 v98, 1.0, v122
	v_mul_f32_e32 v120, v102, v103
	v_mul_f32_e32 v102, 0x3dd2d3e7, v112
	v_rcp_f32_e32 v111, v98
	v_fmaak_f32 v102, v112, v102, 0x40135761
	v_mul_f32_e32 v103, 0xbfb8aa3b, v104
	v_mul_f32_e64 v102, v112, -v102
	v_exp_f32_e32 v103, v103
	v_exp_f32_e32 v102, v102
	v_mov_b32_e32 v98, v107
	v_pk_mul_f32 v[98:99], v[98:99], v[110:111]
	v_mul_f32_e32 v110, 0xbfb8aa3b, v100
	v_mul_f32_e32 v107, v98, v99
	v_add_f32_e32 v99, 1.0, v103
	v_mov_b32_e32 v103, v104
	v_mul_f32_e32 v104, 0x3dd2d3e7, v108
	v_add_f32_e32 v98, 1.0, v102
	v_fmaak_f32 v104, v108, v104, 0x40135761
	v_rcp_f32_e32 v98, v98
	v_rcp_f32_e32 v99, v99
	v_mul_f32_e64 v104, v108, -v104
	v_exp_f32_e32 v104, v104
	v_exp_f32_e32 v110, v110
	v_mov_b32_e32 v102, v112
	v_pk_mul_f32 v[98:99], v[102:103], v[98:99]
	v_add_f32_e32 v102, 1.0, v104
	v_add_f32_e32 v103, 1.0, v110
	v_mul_f32_e32 v110, v98, v99
	v_mov_b32_e32 v99, v100
	v_mul_f32_e32 v100, 0x3dd2d3e7, v113
	v_rcp_f32_e32 v102, v102
	v_rcp_f32_e32 v103, v103
	v_fmaak_f32 v100, v113, v100, 0x40135761
	v_mul_f32_e64 v100, v113, -v100
	v_exp_f32_e32 v100, v100
	v_mov_b32_e32 v98, v108
	v_pk_mul_f32 v[98:99], v[98:99], v[102:103]
	v_mul_f32_e32 v102, 0xbfb8aa3b, v105
	v_exp_f32_e32 v102, v102
	v_mul_f32_e32 v108, v98, v99
	v_add_f32_e32 v98, 1.0, v100
	v_mul_f32_e32 v100, 0x3dd2d3e7, v109
	v_fmaak_f32 v100, v109, v100, 0x40135761
	v_mul_f32_e64 v100, v109, -v100
	v_add_f32_e32 v99, 1.0, v102
	v_exp_f32_e32 v100, v100
	v_mul_f32_e32 v102, 0xbfb8aa3b, v101
	v_exp_f32_e32 v103, v102
	v_rcp_f32_e32 v98, v98
	v_add_f32_e32 v100, 1.0, v100
	v_rcp_f32_e32 v99, v99
	v_rcp_f32_e32 v102, v100
	v_add_f32_e32 v100, 1.0, v103
	v_rcp_f32_e32 v103, v100
	v_or_b32_e32 v118, 16, v146
	v_ashrrev_i32_e32 v119, 31, v118
	v_mov_b32_e32 v104, v113
	v_lshlrev_b64 v[118:119], 14, v[118:119]
	v_pk_mul_f32 v[98:99], v[104:105], v[98:99]
	v_mov_b32_e32 v100, v109
	v_lshl_add_u64 v[118:119], s[10:11], 0, v[118:119]
	v_mul_f32_e32 v104, v98, v99
	v_pk_mul_f32 v[98:99], v[100:101], v[102:103]
	v_lshl_add_u64 v[102:103], v[118:119], 0, v[116:117]
	v_mul_f32_e32 v101, v98, v99
	v_cvt_pk_bf16_f32 v98, v124, v120
	v_cvt_pk_bf16_f32 v99, v110, v104
	v_cvt_pk_bf16_f32 v100, v106, v107
	v_cvt_pk_bf16_f32 v101, v108, v101
	global_store_dwordx4 v[102:103], v[98:101], off
	v_mov_b32_e32 v103, v86
	v_mov_b32_e32 v102, v94
	v_mul_f32_e32 v100, 0x3dd2d3e7, v94
	v_fmaak_f32 v100, v94, v100, 0x40135761
	v_mul_f32_e64 v100, v94, -v100
	v_mul_f32_e32 v101, 0xbfb8aa3b, v86
	v_exp_f32_e32 v100, v100
	v_exp_f32_e32 v101, v101
	v_mul_f32_e32 v86, 0x3dd2d3e7, v90
	v_fmaak_f32 v86, v90, v86, 0x40135761
	v_add_f32_e32 v100, 1.0, v100
	v_add_f32_e32 v101, 1.0, v101
	v_rcp_f32_e32 v100, v100
	v_rcp_f32_e32 v101, v101
	v_mul_f32_e64 v86, v90, -v86
	v_exp_f32_e32 v86, v86
	v_mul_f32_e32 v94, 0xbfb8aa3b, v82
	v_exp_f32_e32 v94, v94
	v_pk_mul_f32 v[100:101], v[102:103], v[100:101]
	v_add_f32_e32 v86, 1.0, v86
	v_mul_f32_e32 v104, v100, v101
	v_mov_b32_e32 v101, v82
	v_mul_f32_e32 v82, 0x3dd2d3e7, v95
	v_fmaak_f32 v82, v95, v82, 0x40135761
	v_rcp_f32_e32 v102, v86
	v_add_f32_e32 v86, 1.0, v94
	v_mul_f32_e64 v82, v95, -v82
	v_rcp_f32_e32 v103, v86
	v_exp_f32_e32 v82, v82
	v_mul_f32_e32 v86, 0xbfb8aa3b, v87
	v_exp_f32_e32 v86, v86
	v_mov_b32_e32 v100, v90
	v_pk_mul_f32 v[100:101], v[100:101], v[102:103]
	v_add_f32_e32 v82, 1.0, v82
	v_mul_f32_e32 v90, v100, v101
	v_rcp_f32_e32 v100, v82
	v_add_f32_e32 v82, 1.0, v86
	v_rcp_f32_e32 v101, v82
	v_mul_f32_e32 v82, 0x3dd2d3e7, v91
	v_fmaak_f32 v82, v91, v82, 0x40135761
	v_mul_f32_e64 v82, v91, -v82
	v_exp_f32_e32 v82, v82
	v_mul_f32_e32 v86, 0xbfb8aa3b, v83
	v_exp_f32_e32 v102, v86
	v_mov_b32_e32 v86, v95
	v_add_f32_e32 v82, 1.0, v82
	v_pk_mul_f32 v[86:87], v[86:87], v[100:101]
	v_rcp_f32_e32 v94, v82
	v_add_f32_e32 v82, 1.0, v102
	v_mul_f32_e32 v100, v86, v87
	v_mul_f32_e32 v86, 0x3dd2d3e7, v96
	v_rcp_f32_e32 v95, v82
	v_fmaak_f32 v86, v96, v86, 0x40135761
	v_mul_f32_e32 v87, 0xbfb8aa3b, v88
	v_mul_f32_e64 v86, v96, -v86
	v_exp_f32_e32 v87, v87
	v_exp_f32_e32 v86, v86
	v_mov_b32_e32 v82, v91
	v_pk_mul_f32 v[82:83], v[82:83], v[94:95]
	v_mul_f32_e32 v94, 0xbfb8aa3b, v84
	v_mul_f32_e32 v91, v82, v83
	v_add_f32_e32 v83, 1.0, v87
	v_mov_b32_e32 v87, v88
	v_mul_f32_e32 v88, 0x3dd2d3e7, v92
	v_add_f32_e32 v82, 1.0, v86
	v_fmaak_f32 v88, v92, v88, 0x40135761
	v_rcp_f32_e32 v82, v82
	v_rcp_f32_e32 v83, v83
	v_mul_f32_e64 v88, v92, -v88
	v_exp_f32_e32 v88, v88
	v_exp_f32_e32 v94, v94
	v_mov_b32_e32 v86, v96
	v_pk_mul_f32 v[82:83], v[86:87], v[82:83]
	v_add_f32_e32 v86, 1.0, v88
	v_add_f32_e32 v87, 1.0, v94
	v_mul_f32_e32 v94, v82, v83
	v_mov_b32_e32 v83, v84
	v_mul_f32_e32 v84, 0x3dd2d3e7, v97
	v_rcp_f32_e32 v86, v86
	v_rcp_f32_e32 v87, v87
	v_fmaak_f32 v84, v97, v84, 0x40135761
	v_mul_f32_e64 v84, v97, -v84
	v_exp_f32_e32 v84, v84
	v_mov_b32_e32 v82, v92
	v_pk_mul_f32 v[82:83], v[82:83], v[86:87]
	v_mul_f32_e32 v86, 0xbfb8aa3b, v89
	v_exp_f32_e32 v86, v86
	v_mul_f32_e32 v92, v82, v83
	v_add_f32_e32 v82, 1.0, v84
	v_mul_f32_e32 v84, 0x3dd2d3e7, v93
	v_fmaak_f32 v84, v93, v84, 0x40135761
	v_mul_f32_e64 v84, v93, -v84
	v_add_f32_e32 v83, 1.0, v86
	v_exp_f32_e32 v84, v84
	v_mul_f32_e32 v86, 0xbfb8aa3b, v85
	v_exp_f32_e32 v87, v86
	v_rcp_f32_e32 v82, v82
	v_add_f32_e32 v84, 1.0, v84
	v_rcp_f32_e32 v83, v83
	v_rcp_f32_e32 v86, v84
	v_add_f32_e32 v84, 1.0, v87
	v_rcp_f32_e32 v87, v84
	v_or_b32_e32 v98, 32, v146
	v_ashrrev_i32_e32 v99, 31, v98
	v_mov_b32_e32 v88, v97
	v_lshlrev_b64 v[98:99], 14, v[98:99]
	v_pk_mul_f32 v[82:83], v[88:89], v[82:83]
	v_mov_b32_e32 v84, v93
	v_lshl_add_u64 v[98:99], s[10:11], 0, v[98:99]
	v_mul_f32_e32 v88, v82, v83
	v_pk_mul_f32 v[82:83], v[84:85], v[86:87]
	v_lshl_add_u64 v[86:87], v[98:99], 0, v[116:117]
	v_mul_f32_e32 v85, v82, v83
	v_cvt_pk_bf16_f32 v82, v104, v100
	v_cvt_pk_bf16_f32 v83, v94, v88
	v_cvt_pk_bf16_f32 v84, v90, v91
	v_cvt_pk_bf16_f32 v85, v92, v85
	global_store_dwordx4 v[86:87], v[82:85], off
	v_mov_b32_e32 v87, v70
	v_mov_b32_e32 v86, v78
	v_mul_f32_e32 v84, 0x3dd2d3e7, v78
	v_fmaak_f32 v84, v78, v84, 0x40135761
	v_mul_f32_e64 v84, v78, -v84
	v_mul_f32_e32 v85, 0xbfb8aa3b, v70
	v_exp_f32_e32 v84, v84
	v_exp_f32_e32 v85, v85
	v_mul_f32_e32 v70, 0x3dd2d3e7, v74
	v_fmaak_f32 v70, v74, v70, 0x40135761
	v_add_f32_e32 v84, 1.0, v84
	v_add_f32_e32 v85, 1.0, v85
	v_rcp_f32_e32 v84, v84
	v_rcp_f32_e32 v85, v85
	v_mul_f32_e64 v70, v74, -v70
	v_exp_f32_e32 v70, v70
	v_mul_f32_e32 v78, 0xbfb8aa3b, v66
	v_exp_f32_e32 v78, v78
	v_pk_mul_f32 v[84:85], v[86:87], v[84:85]
	v_add_f32_e32 v70, 1.0, v70
	v_mul_f32_e32 v88, v84, v85
	v_mov_b32_e32 v85, v66
	v_mul_f32_e32 v66, 0x3dd2d3e7, v79
	v_fmaak_f32 v66, v79, v66, 0x40135761
	v_rcp_f32_e32 v86, v70
	v_add_f32_e32 v70, 1.0, v78
	v_mul_f32_e64 v66, v79, -v66
	v_rcp_f32_e32 v87, v70
	v_exp_f32_e32 v66, v66
	v_mul_f32_e32 v70, 0xbfb8aa3b, v71
	v_exp_f32_e32 v70, v70
	v_mov_b32_e32 v84, v74
	v_pk_mul_f32 v[84:85], v[84:85], v[86:87]
	v_add_f32_e32 v66, 1.0, v66
	v_mul_f32_e32 v74, v84, v85
	v_rcp_f32_e32 v84, v66
	v_add_f32_e32 v66, 1.0, v70
	v_rcp_f32_e32 v85, v66
	v_mul_f32_e32 v66, 0x3dd2d3e7, v75
	v_fmaak_f32 v66, v75, v66, 0x40135761
	v_mul_f32_e64 v66, v75, -v66
	v_exp_f32_e32 v66, v66
	v_mul_f32_e32 v70, 0xbfb8aa3b, v67
	v_exp_f32_e32 v86, v70
	v_mov_b32_e32 v70, v79
	v_add_f32_e32 v66, 1.0, v66
	v_pk_mul_f32 v[70:71], v[70:71], v[84:85]
	v_rcp_f32_e32 v78, v66
	v_add_f32_e32 v66, 1.0, v86
	v_mul_f32_e32 v84, v70, v71
	v_mul_f32_e32 v70, 0x3dd2d3e7, v80
	v_rcp_f32_e32 v79, v66
	v_fmaak_f32 v70, v80, v70, 0x40135761
	v_mul_f32_e32 v71, 0xbfb8aa3b, v72
	v_mul_f32_e64 v70, v80, -v70
	v_exp_f32_e32 v71, v71
	v_exp_f32_e32 v70, v70
	v_mov_b32_e32 v66, v75
	v_pk_mul_f32 v[66:67], v[66:67], v[78:79]
	v_mul_f32_e32 v78, 0xbfb8aa3b, v68
	v_mul_f32_e32 v75, v66, v67
	v_add_f32_e32 v67, 1.0, v71
	v_mov_b32_e32 v71, v72
	v_mul_f32_e32 v72, 0x3dd2d3e7, v76
	v_add_f32_e32 v66, 1.0, v70
	v_fmaak_f32 v72, v76, v72, 0x40135761
	v_rcp_f32_e32 v66, v66
	v_rcp_f32_e32 v67, v67
	v_mul_f32_e64 v72, v76, -v72
	v_exp_f32_e32 v72, v72
	v_exp_f32_e32 v78, v78
	v_mov_b32_e32 v70, v80
	v_pk_mul_f32 v[66:67], v[70:71], v[66:67]
	v_add_f32_e32 v70, 1.0, v72
	v_add_f32_e32 v71, 1.0, v78
	v_mul_f32_e32 v78, v66, v67
	v_mov_b32_e32 v67, v68
	v_mul_f32_e32 v68, 0x3dd2d3e7, v81
	v_rcp_f32_e32 v70, v70
	v_rcp_f32_e32 v71, v71
	v_fmaak_f32 v68, v81, v68, 0x40135761
	v_mul_f32_e64 v68, v81, -v68
	v_exp_f32_e32 v68, v68
	v_mov_b32_e32 v66, v76
	v_pk_mul_f32 v[66:67], v[66:67], v[70:71]
	v_mul_f32_e32 v70, 0xbfb8aa3b, v73
	v_exp_f32_e32 v70, v70
	v_mul_f32_e32 v76, v66, v67
	v_add_f32_e32 v66, 1.0, v68
	v_mul_f32_e32 v68, 0x3dd2d3e7, v77
	v_fmaak_f32 v68, v77, v68, 0x40135761
	v_mul_f32_e64 v68, v77, -v68
	v_add_f32_e32 v67, 1.0, v70
	v_exp_f32_e32 v68, v68
	v_mul_f32_e32 v70, 0xbfb8aa3b, v69
	v_exp_f32_e32 v71, v70
	v_rcp_f32_e32 v66, v66
	v_add_f32_e32 v68, 1.0, v68
	v_rcp_f32_e32 v67, v67
	v_rcp_f32_e32 v70, v68
	v_add_f32_e32 v68, 1.0, v71
	v_rcp_f32_e32 v71, v68
	v_mov_b32_e32 v72, v81
	v_pk_mul_f32 v[66:67], v[72:73], v[66:67]
	v_mov_b32_e32 v68, v77
	v_mul_f32_e32 v72, v66, v67
	v_pk_mul_f32 v[66:67], v[68:69], v[70:71]
	v_or_b32_e32 v82, 48, v146
	v_mul_f32_e32 v69, v66, v67
	v_cvt_pk_bf16_f32 v66, v88, v84
	v_cvt_pk_bf16_f32 v67, v78, v72
	v_mul_f32_e32 v72, 0x3dd2d3e7, v62
	v_fmaak_f32 v72, v62, v72, 0x40135761
	v_mul_f32_e64 v72, v62, -v72
	v_mul_f32_e32 v73, 0xbfb8aa3b, v54
	v_ashrrev_i32_e32 v83, 31, v82
	v_exp_f32_e32 v72, v72
	v_exp_f32_e32 v73, v73
	v_lshlrev_b64 v[82:83], 14, v[82:83]
	v_lshl_add_u64 v[82:83], s[10:11], 0, v[82:83]
	v_lshl_add_u64 v[70:71], v[82:83], 0, v[116:117]
	v_cvt_pk_bf16_f32 v68, v74, v75
	v_cvt_pk_bf16_f32 v69, v76, v69
	global_store_dwordx4 v[70:71], v[66:69], off
	s_nop 1
	v_add_f32_e32 v66, 1.0, v72
	v_add_f32_e32 v67, 1.0, v73
	v_mov_b32_e32 v69, v54
	v_mul_f32_e32 v54, 0x3dd2d3e7, v58
	v_rcp_f32_e32 v66, v66
	v_rcp_f32_e32 v67, v67
	v_fmaak_f32 v54, v58, v54, 0x40135761
	v_mul_f32_e64 v54, v58, -v54
	v_mov_b32_e32 v68, v62
	v_exp_f32_e32 v54, v54
	v_mul_f32_e32 v62, 0xbfb8aa3b, v50
	v_exp_f32_e32 v62, v62
	v_pk_mul_f32 v[66:67], v[68:69], v[66:67]
	v_add_f32_e32 v54, 1.0, v54
	v_mul_f32_e32 v70, v66, v67
	v_mov_b32_e32 v67, v50
	v_mul_f32_e32 v50, 0x3dd2d3e7, v63
	v_fmaak_f32 v50, v63, v50, 0x40135761
	v_rcp_f32_e32 v68, v54
	v_add_f32_e32 v54, 1.0, v62
	v_mul_f32_e64 v50, v63, -v50
	v_rcp_f32_e32 v69, v54
	v_exp_f32_e32 v50, v50
	v_mul_f32_e32 v54, 0xbfb8aa3b, v55
	v_exp_f32_e32 v54, v54
	v_mov_b32_e32 v66, v58
	v_pk_mul_f32 v[66:67], v[66:67], v[68:69]
	v_add_f32_e32 v50, 1.0, v50
	v_mul_f32_e32 v58, v66, v67
	v_rcp_f32_e32 v66, v50
	v_add_f32_e32 v50, 1.0, v54
	v_rcp_f32_e32 v67, v50
	v_mul_f32_e32 v50, 0x3dd2d3e7, v59
	v_fmaak_f32 v50, v59, v50, 0x40135761
	v_mul_f32_e64 v50, v59, -v50
	v_exp_f32_e32 v50, v50
	v_mul_f32_e32 v54, 0xbfb8aa3b, v51
	v_exp_f32_e32 v68, v54
	v_mov_b32_e32 v54, v63
	v_add_f32_e32 v50, 1.0, v50
	v_pk_mul_f32 v[54:55], v[54:55], v[66:67]
	v_rcp_f32_e32 v62, v50
	v_add_f32_e32 v50, 1.0, v68
	v_mul_f32_e32 v66, v54, v55
	v_mul_f32_e32 v54, 0x3dd2d3e7, v64
	v_rcp_f32_e32 v63, v50
	v_fmaak_f32 v54, v64, v54, 0x40135761
	v_mul_f32_e32 v55, 0xbfb8aa3b, v56
	v_mul_f32_e64 v54, v64, -v54
	v_exp_f32_e32 v55, v55
	v_exp_f32_e32 v54, v54
	v_mov_b32_e32 v50, v59
	v_pk_mul_f32 v[50:51], v[50:51], v[62:63]
	v_mul_f32_e32 v62, 0xbfb8aa3b, v52
	v_mul_f32_e32 v59, v50, v51
	v_add_f32_e32 v51, 1.0, v55
	v_mov_b32_e32 v55, v56
	v_mul_f32_e32 v56, 0x3dd2d3e7, v60
	v_add_f32_e32 v50, 1.0, v54
	v_fmaak_f32 v56, v60, v56, 0x40135761
	v_rcp_f32_e32 v50, v50
	v_rcp_f32_e32 v51, v51
	v_mul_f32_e64 v56, v60, -v56
	v_exp_f32_e32 v56, v56
	v_exp_f32_e32 v62, v62
	v_mov_b32_e32 v54, v64
	v_pk_mul_f32 v[50:51], v[54:55], v[50:51]
	v_add_f32_e32 v54, 1.0, v56
	v_add_f32_e32 v55, 1.0, v62
	v_mul_f32_e32 v62, v50, v51
	v_mov_b32_e32 v51, v52
	v_mul_f32_e32 v52, 0x3dd2d3e7, v65
	v_rcp_f32_e32 v54, v54
	v_rcp_f32_e32 v55, v55
	v_fmaak_f32 v52, v65, v52, 0x40135761
	v_mul_f32_e64 v52, v65, -v52
	v_exp_f32_e32 v52, v52
	v_mov_b32_e32 v50, v60
	v_pk_mul_f32 v[50:51], v[50:51], v[54:55]
	v_mul_f32_e32 v54, 0xbfb8aa3b, v57
	v_exp_f32_e32 v54, v54
	v_mul_f32_e32 v60, v50, v51
	v_add_f32_e32 v50, 1.0, v52
	v_mul_f32_e32 v52, 0x3dd2d3e7, v61
	v_fmaak_f32 v52, v61, v52, 0x40135761
	v_mul_f32_e64 v52, v61, -v52
	v_add_f32_e32 v51, 1.0, v54
	v_exp_f32_e32 v52, v52
	v_mul_f32_e32 v54, 0xbfb8aa3b, v53
	v_exp_f32_e32 v55, v54
	v_rcp_f32_e32 v50, v50
	v_add_f32_e32 v52, 1.0, v52
	v_rcp_f32_e32 v51, v51
	v_rcp_f32_e32 v54, v52
	v_add_f32_e32 v52, 1.0, v55
	v_rcp_f32_e32 v55, v52
	v_mov_b32_e32 v56, v65
	v_pk_mul_f32 v[50:51], v[56:57], v[50:51]
	v_mov_b32_e32 v52, v61
	v_mul_f32_e32 v56, v50, v51
	v_pk_mul_f32 v[50:51], v[52:53], v[54:55]
	v_mul_f32_e32 v57, 0xbfb8aa3b, v38
	v_mul_f32_e32 v53, v50, v51
	v_cvt_pk_bf16_f32 v50, v70, v66
	v_cvt_pk_bf16_f32 v51, v62, v56
	v_mul_f32_e32 v56, 0x3dd2d3e7, v46
	v_fmaak_f32 v56, v46, v56, 0x40135761
	v_mul_f32_e64 v56, v46, -v56
	v_exp_f32_e32 v56, v56
	v_exp_f32_e32 v57, v57
	v_add_co_u32_e32 v54, vcc, s47, v114
	v_cvt_pk_bf16_f32 v52, v58, v59
	v_cvt_pk_bf16_f32 v53, v60, v53
	s_nop 1
	v_addc_co_u32_e32 v55, vcc, 0, v115, vcc
	global_store_dwordx4 v[54:55], v[50:53], off
	s_nop 1
	v_add_f32_e32 v50, 1.0, v56
	v_add_f32_e32 v51, 1.0, v57
	v_mov_b32_e32 v53, v38
	v_mul_f32_e32 v38, 0x3dd2d3e7, v42
	v_rcp_f32_e32 v50, v50
	v_rcp_f32_e32 v51, v51
	v_fmaak_f32 v38, v42, v38, 0x40135761
	v_mul_f32_e64 v38, v42, -v38
	v_mov_b32_e32 v52, v46
	v_exp_f32_e32 v38, v38
	v_mul_f32_e32 v46, 0xbfb8aa3b, v34
	v_exp_f32_e32 v46, v46
	v_pk_mul_f32 v[50:51], v[52:53], v[50:51]
	v_add_f32_e32 v38, 1.0, v38
	v_mul_f32_e32 v54, v50, v51
	v_mov_b32_e32 v51, v34
	v_mul_f32_e32 v34, 0x3dd2d3e7, v47
	v_fmaak_f32 v34, v47, v34, 0x40135761
	v_rcp_f32_e32 v52, v38
	v_add_f32_e32 v38, 1.0, v46
	v_mul_f32_e64 v34, v47, -v34
	v_rcp_f32_e32 v53, v38
	v_exp_f32_e32 v34, v34
	v_mul_f32_e32 v38, 0xbfb8aa3b, v39
	v_exp_f32_e32 v38, v38
	v_mov_b32_e32 v50, v42
	v_pk_mul_f32 v[50:51], v[50:51], v[52:53]
	v_add_f32_e32 v34, 1.0, v34
	v_mul_f32_e32 v42, v50, v51
	v_rcp_f32_e32 v50, v34
	v_add_f32_e32 v34, 1.0, v38
	v_rcp_f32_e32 v51, v34
	v_mul_f32_e32 v34, 0x3dd2d3e7, v43
	v_fmaak_f32 v34, v43, v34, 0x40135761
	v_mul_f32_e64 v34, v43, -v34
	v_exp_f32_e32 v34, v34
	v_mul_f32_e32 v38, 0xbfb8aa3b, v35
	v_exp_f32_e32 v52, v38
	v_mov_b32_e32 v38, v47
	v_add_f32_e32 v34, 1.0, v34
	v_pk_mul_f32 v[38:39], v[38:39], v[50:51]
	v_rcp_f32_e32 v46, v34
	v_add_f32_e32 v34, 1.0, v52
	v_mul_f32_e32 v50, v38, v39
	v_mul_f32_e32 v38, 0x3dd2d3e7, v48
	v_rcp_f32_e32 v47, v34
	v_fmaak_f32 v38, v48, v38, 0x40135761
	v_mul_f32_e32 v39, 0xbfb8aa3b, v40
	v_mul_f32_e64 v38, v48, -v38
	v_exp_f32_e32 v39, v39
	v_exp_f32_e32 v38, v38
	v_mov_b32_e32 v34, v43
	v_pk_mul_f32 v[34:35], v[34:35], v[46:47]
	v_mul_f32_e32 v46, 0xbfb8aa3b, v36
	v_mul_f32_e32 v43, v34, v35
	v_add_f32_e32 v35, 1.0, v39
	v_mov_b32_e32 v39, v40
	v_mul_f32_e32 v40, 0x3dd2d3e7, v44
	v_add_f32_e32 v34, 1.0, v38
	v_fmaak_f32 v40, v44, v40, 0x40135761
	v_rcp_f32_e32 v34, v34
	v_rcp_f32_e32 v35, v35
	v_mul_f32_e64 v40, v44, -v40
	v_exp_f32_e32 v40, v40
	v_exp_f32_e32 v46, v46
	v_mov_b32_e32 v38, v48
	v_pk_mul_f32 v[34:35], v[38:39], v[34:35]
	v_add_f32_e32 v38, 1.0, v40
	v_add_f32_e32 v39, 1.0, v46
	v_mul_f32_e32 v46, v34, v35
	v_mov_b32_e32 v35, v36
	v_mul_f32_e32 v36, 0x3dd2d3e7, v49
	v_rcp_f32_e32 v38, v38
	v_rcp_f32_e32 v39, v39
	v_fmaak_f32 v36, v49, v36, 0x40135761
	v_mul_f32_e64 v36, v49, -v36
	v_exp_f32_e32 v36, v36
	v_mov_b32_e32 v34, v44
	v_pk_mul_f32 v[34:35], v[34:35], v[38:39]
	v_mul_f32_e32 v38, 0xbfb8aa3b, v41
	v_exp_f32_e32 v38, v38
	v_mul_f32_e32 v44, v34, v35
	v_add_f32_e32 v34, 1.0, v36
	v_mul_f32_e32 v36, 0x3dd2d3e7, v45
	v_fmaak_f32 v36, v45, v36, 0x40135761
	v_mul_f32_e64 v36, v45, -v36
	v_add_f32_e32 v35, 1.0, v38
	v_exp_f32_e32 v36, v36
	v_mul_f32_e32 v38, 0xbfb8aa3b, v37
	v_exp_f32_e32 v39, v38
	v_rcp_f32_e32 v34, v34
	v_add_f32_e32 v36, 1.0, v36
	v_rcp_f32_e32 v35, v35
	v_rcp_f32_e32 v38, v36
	v_add_f32_e32 v36, 1.0, v39
	v_rcp_f32_e32 v39, v36
	v_mov_b32_e32 v40, v49
	v_pk_mul_f32 v[34:35], v[40:41], v[34:35]
	v_mov_b32_e32 v36, v45
	v_mul_f32_e32 v40, v34, v35
	v_pk_mul_f32 v[34:35], v[36:37], v[38:39]
	v_mul_f32_e32 v41, 0xbfb8aa3b, v22
	v_mul_f32_e32 v37, v34, v35
	v_cvt_pk_bf16_f32 v34, v54, v50
	v_cvt_pk_bf16_f32 v35, v46, v40
	v_mul_f32_e32 v40, 0x3dd2d3e7, v30
	v_fmaak_f32 v40, v30, v40, 0x40135761
	v_mul_f32_e64 v40, v30, -v40
	v_exp_f32_e32 v40, v40
	v_exp_f32_e32 v41, v41
	v_add_co_u32_e32 v38, vcc, s48, v114
	v_cvt_pk_bf16_f32 v36, v42, v43
	v_cvt_pk_bf16_f32 v37, v44, v37
	s_nop 1
	v_addc_co_u32_e32 v39, vcc, 0, v115, vcc
	global_store_dwordx4 v[38:39], v[34:37], off
	s_nop 1
	v_add_f32_e32 v34, 1.0, v40
	v_add_f32_e32 v35, 1.0, v41
	v_mov_b32_e32 v37, v22
	v_mul_f32_e32 v22, 0x3dd2d3e7, v26
	v_rcp_f32_e32 v34, v34
	v_rcp_f32_e32 v35, v35
	v_fmaak_f32 v22, v26, v22, 0x40135761
	v_mul_f32_e64 v22, v26, -v22
	v_mov_b32_e32 v36, v30
	v_exp_f32_e32 v22, v22
	v_mul_f32_e32 v30, 0xbfb8aa3b, v18
	v_exp_f32_e32 v30, v30
	v_pk_mul_f32 v[34:35], v[36:37], v[34:35]
	v_add_f32_e32 v22, 1.0, v22
	v_mul_f32_e32 v38, v34, v35
	v_mov_b32_e32 v35, v18
	v_mul_f32_e32 v18, 0x3dd2d3e7, v31
	v_fmaak_f32 v18, v31, v18, 0x40135761
	v_rcp_f32_e32 v36, v22
	v_add_f32_e32 v22, 1.0, v30
	v_mul_f32_e64 v18, v31, -v18
	v_rcp_f32_e32 v37, v22
	v_exp_f32_e32 v18, v18
	v_mul_f32_e32 v22, 0xbfb8aa3b, v23
	v_exp_f32_e32 v22, v22
	v_mov_b32_e32 v34, v26
	v_pk_mul_f32 v[34:35], v[34:35], v[36:37]
	v_add_f32_e32 v18, 1.0, v18
	v_mul_f32_e32 v26, v34, v35
	v_rcp_f32_e32 v34, v18
	v_add_f32_e32 v18, 1.0, v22
	v_rcp_f32_e32 v35, v18
	v_mul_f32_e32 v18, 0x3dd2d3e7, v27
	v_fmaak_f32 v18, v27, v18, 0x40135761
	v_mul_f32_e64 v18, v27, -v18
	v_exp_f32_e32 v18, v18
	v_mul_f32_e32 v22, 0xbfb8aa3b, v19
	v_exp_f32_e32 v36, v22
	v_mov_b32_e32 v22, v31
	v_add_f32_e32 v18, 1.0, v18
	v_pk_mul_f32 v[22:23], v[22:23], v[34:35]
	v_rcp_f32_e32 v30, v18
	v_add_f32_e32 v18, 1.0, v36
	v_mul_f32_e32 v34, v22, v23
	v_mul_f32_e32 v22, 0x3dd2d3e7, v32
	v_rcp_f32_e32 v31, v18
	v_fmaak_f32 v22, v32, v22, 0x40135761
	v_mul_f32_e32 v23, 0xbfb8aa3b, v24
	v_mul_f32_e64 v22, v32, -v22
	v_exp_f32_e32 v23, v23
	v_exp_f32_e32 v22, v22
	v_mov_b32_e32 v18, v27
	v_pk_mul_f32 v[18:19], v[18:19], v[30:31]
	v_mul_f32_e32 v30, 0xbfb8aa3b, v20
	v_mul_f32_e32 v27, v18, v19
	v_add_f32_e32 v19, 1.0, v23
	v_mov_b32_e32 v23, v24
	v_mul_f32_e32 v24, 0x3dd2d3e7, v28
	v_add_f32_e32 v18, 1.0, v22
	v_fmaak_f32 v24, v28, v24, 0x40135761
	v_rcp_f32_e32 v18, v18
	v_rcp_f32_e32 v19, v19
	v_mul_f32_e64 v24, v28, -v24
	v_exp_f32_e32 v24, v24
	v_exp_f32_e32 v30, v30
	v_mov_b32_e32 v22, v32
	v_pk_mul_f32 v[18:19], v[22:23], v[18:19]
	v_add_f32_e32 v22, 1.0, v24
	v_add_f32_e32 v23, 1.0, v30
	v_mul_f32_e32 v30, v18, v19
	v_mov_b32_e32 v19, v20
	v_mul_f32_e32 v20, 0x3dd2d3e7, v33
	v_rcp_f32_e32 v22, v22
	v_rcp_f32_e32 v23, v23
	v_fmaak_f32 v20, v33, v20, 0x40135761
	v_mul_f32_e64 v20, v33, -v20
	v_exp_f32_e32 v20, v20
	v_mov_b32_e32 v18, v28
	v_pk_mul_f32 v[18:19], v[18:19], v[22:23]
	v_mul_f32_e32 v22, 0xbfb8aa3b, v25
	v_exp_f32_e32 v22, v22
	v_mul_f32_e32 v28, v18, v19
	v_add_f32_e32 v18, 1.0, v20
	v_mul_f32_e32 v20, 0x3dd2d3e7, v29
	v_fmaak_f32 v20, v29, v20, 0x40135761
	v_mul_f32_e64 v20, v29, -v20
	v_add_f32_e32 v19, 1.0, v22
	v_exp_f32_e32 v20, v20
	v_mul_f32_e32 v22, 0xbfb8aa3b, v21
	v_exp_f32_e32 v23, v22
	v_rcp_f32_e32 v18, v18
	v_add_f32_e32 v20, 1.0, v20
	v_rcp_f32_e32 v19, v19
	v_rcp_f32_e32 v22, v20
	v_add_f32_e32 v20, 1.0, v23
	v_rcp_f32_e32 v23, v20
	v_mov_b32_e32 v24, v33
	v_pk_mul_f32 v[18:19], v[24:25], v[18:19]
	v_mov_b32_e32 v20, v29
	v_mul_f32_e32 v24, v18, v19
	v_pk_mul_f32 v[18:19], v[20:21], v[22:23]
	v_mul_f32_e32 v25, 0xbfb8aa3b, v6
	v_mul_f32_e32 v21, v18, v19
	v_cvt_pk_bf16_f32 v18, v38, v34
	v_cvt_pk_bf16_f32 v19, v30, v24
	v_mul_f32_e32 v24, 0x3dd2d3e7, v14
	v_fmaak_f32 v24, v14, v24, 0x40135761
	v_mul_f32_e64 v24, v14, -v24
	v_exp_f32_e32 v24, v24
	v_exp_f32_e32 v25, v25
	v_add_co_u32_e32 v22, vcc, s49, v114
	v_cvt_pk_bf16_f32 v20, v26, v27
	v_cvt_pk_bf16_f32 v21, v28, v21
	s_nop 1
	v_addc_co_u32_e32 v23, vcc, 0, v115, vcc
	global_store_dwordx4 v[22:23], v[18:21], off
	s_nop 1
	v_add_f32_e32 v18, 1.0, v24
	v_add_f32_e32 v19, 1.0, v25
	v_mov_b32_e32 v21, v6
	v_mul_f32_e32 v6, 0x3dd2d3e7, v10
	v_rcp_f32_e32 v18, v18
	v_rcp_f32_e32 v19, v19
	v_fmaak_f32 v6, v10, v6, 0x40135761
	v_mul_f32_e64 v6, v10, -v6
	v_mov_b32_e32 v20, v14
	v_exp_f32_e32 v6, v6
	v_mul_f32_e32 v14, 0xbfb8aa3b, v2
	v_exp_f32_e32 v14, v14
	v_pk_mul_f32 v[18:19], v[20:21], v[18:19]
	v_add_f32_e32 v6, 1.0, v6
	v_mul_f32_e32 v22, v18, v19
	v_mov_b32_e32 v19, v2
	v_mul_f32_e32 v2, 0x3dd2d3e7, v15
	v_fmaak_f32 v2, v15, v2, 0x40135761
	v_rcp_f32_e32 v20, v6
	v_add_f32_e32 v6, 1.0, v14
	v_mul_f32_e64 v2, v15, -v2
	v_rcp_f32_e32 v21, v6
	v_exp_f32_e32 v2, v2
	v_mul_f32_e32 v6, 0xbfb8aa3b, v7
	v_exp_f32_e32 v6, v6
	v_mov_b32_e32 v18, v10
	v_pk_mul_f32 v[18:19], v[18:19], v[20:21]
	v_add_f32_e32 v2, 1.0, v2
	v_mul_f32_e32 v10, v18, v19
	v_rcp_f32_e32 v18, v2
	v_add_f32_e32 v2, 1.0, v6
	v_rcp_f32_e32 v19, v2
	v_mul_f32_e32 v2, 0x3dd2d3e7, v11
	v_fmaak_f32 v2, v11, v2, 0x40135761
	v_mul_f32_e64 v2, v11, -v2
	v_exp_f32_e32 v2, v2
	v_mul_f32_e32 v6, 0xbfb8aa3b, v3
	v_exp_f32_e32 v20, v6
	v_mov_b32_e32 v6, v15
	v_add_f32_e32 v2, 1.0, v2
	v_pk_mul_f32 v[6:7], v[6:7], v[18:19]
	v_rcp_f32_e32 v14, v2
	v_add_f32_e32 v2, 1.0, v20
	v_mul_f32_e32 v18, v6, v7
	v_mul_f32_e32 v6, 0x3dd2d3e7, v16
	v_rcp_f32_e32 v15, v2
	v_fmaak_f32 v6, v16, v6, 0x40135761
	v_mul_f32_e32 v7, 0xbfb8aa3b, v8
	v_mul_f32_e64 v6, v16, -v6
	v_exp_f32_e32 v7, v7
	v_exp_f32_e32 v6, v6
	v_mov_b32_e32 v2, v11
	v_pk_mul_f32 v[2:3], v[2:3], v[14:15]
	v_mul_f32_e32 v14, 0xbfb8aa3b, v4
	v_mul_f32_e32 v11, v2, v3
	v_add_f32_e32 v3, 1.0, v7
	v_mov_b32_e32 v7, v8
	v_mul_f32_e32 v8, 0x3dd2d3e7, v12
	v_add_f32_e32 v2, 1.0, v6
	v_fmaak_f32 v8, v12, v8, 0x40135761
	v_rcp_f32_e32 v2, v2
	v_rcp_f32_e32 v3, v3
	v_mul_f32_e64 v8, v12, -v8
	v_exp_f32_e32 v8, v8
	v_exp_f32_e32 v14, v14
	v_mov_b32_e32 v6, v16
	v_pk_mul_f32 v[2:3], v[6:7], v[2:3]
	v_add_f32_e32 v6, 1.0, v8
	v_add_f32_e32 v7, 1.0, v14
	v_mul_f32_e32 v14, v2, v3
	v_mov_b32_e32 v3, v4
	v_mul_f32_e32 v4, 0x3dd2d3e7, v17
	v_rcp_f32_e32 v6, v6
	v_rcp_f32_e32 v7, v7
	v_fmaak_f32 v4, v17, v4, 0x40135761
	v_mul_f32_e64 v4, v17, -v4
	v_exp_f32_e32 v4, v4
	v_mov_b32_e32 v2, v12
	v_pk_mul_f32 v[2:3], v[2:3], v[6:7]
	v_mul_f32_e32 v6, 0xbfb8aa3b, v9
	v_exp_f32_e32 v6, v6
	v_mul_f32_e32 v12, v2, v3
	v_add_f32_e32 v2, 1.0, v4
	v_mul_f32_e32 v4, 0x3dd2d3e7, v13
	v_fmaak_f32 v4, v13, v4, 0x40135761
	v_mul_f32_e64 v4, v13, -v4
	v_add_f32_e32 v3, 1.0, v6
	v_exp_f32_e32 v4, v4
	v_mul_f32_e32 v6, 0xbfb8aa3b, v5
	v_exp_f32_e32 v7, v6
	v_rcp_f32_e32 v2, v2
	v_add_f32_e32 v4, 1.0, v4
	v_rcp_f32_e32 v3, v3
	v_rcp_f32_e32 v6, v4
	v_add_f32_e32 v4, 1.0, v7
	v_rcp_f32_e32 v7, v4
	v_mov_b32_e32 v8, v17
	v_pk_mul_f32 v[2:3], v[8:9], v[2:3]
	v_mov_b32_e32 v4, v13
	v_mul_f32_e32 v8, v2, v3
	v_pk_mul_f32 v[2:3], v[4:5], v[6:7]
	v_add_co_u32_e32 v6, vcc, 0x2c0000, v114
	v_mul_f32_e32 v5, v2, v3
	s_nop 0
	v_addc_co_u32_e32 v7, vcc, 0, v115, vcc
	s_andn2_b64 vcc, exec, s[0:1]
	s_mov_b64 s[0:1], -1
	v_cvt_pk_bf16_f32 v2, v22, v18
	v_cvt_pk_bf16_f32 v3, v14, v8
	v_cvt_pk_bf16_f32 v4, v10, v11
	v_cvt_pk_bf16_f32 v5, v12, v5
	global_store_dwordx4 v[6:7], v[2:5], off
	s_cbranch_vccnz .LBB0_908
	s_mov_b32 s98, 1
	s_andn2_b64 vcc, exec, s[8:9]
	s_cbranch_vccnz .LBB0_907
	s_barrier
	s_branch .LBB0_907

.LBB0_948:
	v_add_u32_e32 v147, s63, v161
	ds_read_b128 v[168:171], v147
	ds_read_b128 v[172:175], v147 offset:1024
	ds_read_b128 v[176:179], v147 offset:2048
	ds_read_b128 v[180:183], v147 offset:3072
	v_add_u32_e32 v147, s64, v161
	ds_read_b128 v[184:187], v147
	ds_read_b128 v[188:191], v147 offset:1024
	ds_read_b128 v[192:195], v147 offset:2048
	ds_read_b128 v[196:199], v147 offset:3072
	s_cmp_eq_u32 s46, 60
	v_lshl_add_u64 v[200:201], v[156:157], 0, s[34:35]
	s_cselect_b64 vcc, -1, 0
	v_cndmask_b32_e32 v233, v201, v1, vcc
	v_cndmask_b32_e32 v232, v200, v152, vcc
	v_cndmask_b32_e32 v235, v159, v145, vcc
	v_cndmask_b32_e32 v234, v158, v154, vcc
	v_lshl_add_u64 v[236:237], v[156:157], 0, v[138:139]
	s_add_i32 m0, s56, 0xc000
	ds_read_b128 v[200:203], v164
	ds_read_b128 v[204:207], v164 offset:1024
	ds_read_b128 v[208:211], v164 offset:2048
	ds_read_b128 v[212:215], v164 offset:3072
	ds_read_b128 v[216:219], v164 offset:4096
	ds_read_b128 v[220:223], v164 offset:5120
	ds_read_b128 v[224:227], v164 offset:6144
	ds_read_b128 v[228:231], v164 offset:7168
	global_load_lds_dwordx4 v[236:237], off
	v_lshl_add_u64 v[236:237], v[156:157], 0, v[140:141]
	s_add_i32 m0, s56, 0xe000
	s_nop 0
	global_load_lds_dwordx4 v[236:237], off
	s_cmp_eq_u32 s98, 0
	s_cbranch_scc1 .Lgw948_0a
	s_waitcnt vmcnt(24)
	s_branch .Lgw948_0b

.Lgw948_0b:
	s_waitcnt lgkmcnt(0)
	s_barrier
	s_setprio 1
	s_waitcnt lgkmcnt(0)
	v_mfma_f32_16x16x32_bf16 v[126:129], v[168:171], v[200:203], v[126:129]
	v_mfma_f32_16x16x32_bf16 v[122:125], v[176:179], v[200:203], v[122:125]
	v_mfma_f32_16x16x32_bf16 v[110:113], v[168:171], v[208:211], v[110:113]
	v_mfma_f32_16x16x32_bf16 v[106:109], v[176:179], v[208:211], v[106:109]
	v_mfma_f32_16x16x32_bf16 v[94:97], v[168:171], v[216:219], v[94:97]
	v_mfma_f32_16x16x32_bf16 v[90:93], v[176:179], v[216:219], v[90:93]
	v_mfma_f32_16x16x32_bf16 v[78:81], v[168:171], v[224:227], v[78:81]
	v_mfma_f32_16x16x32_bf16 v[74:77], v[176:179], v[224:227], v[74:77]
	v_mfma_f32_16x16x32_bf16 v[126:129], v[172:175], v[204:207], v[126:129]
	v_mfma_f32_16x16x32_bf16 v[122:125], v[180:183], v[204:207], v[122:125]
	v_mfma_f32_16x16x32_bf16 v[110:113], v[172:175], v[212:215], v[110:113]
	v_mfma_f32_16x16x32_bf16 v[106:109], v[180:183], v[212:215], v[106:109]
	v_mfma_f32_16x16x32_bf16 v[94:97], v[172:175], v[220:223], v[94:97]
	v_mfma_f32_16x16x32_bf16 v[90:93], v[180:183], v[220:223], v[90:93]
	v_mfma_f32_16x16x32_bf16 v[78:81], v[172:175], v[228:231], v[78:81]
	v_mfma_f32_16x16x32_bf16 v[74:77], v[180:183], v[228:231], v[74:77]
	s_setprio 0
	s_setprio 1
	v_mfma_f32_16x16x32_bf16 v[118:121], v[184:187], v[200:203], v[118:121]
	v_mfma_f32_16x16x32_bf16 v[114:117], v[192:195], v[200:203], v[114:117]
	v_mfma_f32_16x16x32_bf16 v[102:105], v[184:187], v[208:211], v[102:105]
	v_mfma_f32_16x16x32_bf16 v[98:101], v[192:195], v[208:211], v[98:101]
	v_mfma_f32_16x16x32_bf16 v[86:89], v[184:187], v[216:219], v[86:89]
	v_mfma_f32_16x16x32_bf16 v[82:85], v[192:195], v[216:219], v[82:85]
	v_mfma_f32_16x16x32_bf16 v[70:73], v[184:187], v[224:227], v[70:73]
	v_mfma_f32_16x16x32_bf16 v[66:69], v[192:195], v[224:227], v[66:69]
	v_mfma_f32_16x16x32_bf16 v[118:121], v[188:191], v[204:207], v[118:121]
	v_mfma_f32_16x16x32_bf16 v[114:117], v[196:199], v[204:207], v[114:117]
	v_mfma_f32_16x16x32_bf16 v[102:105], v[188:191], v[212:215], v[102:105]
	v_mfma_f32_16x16x32_bf16 v[98:101], v[196:199], v[212:215], v[98:101]
	v_mfma_f32_16x16x32_bf16 v[86:89], v[188:191], v[220:223], v[86:89]
	v_mfma_f32_16x16x32_bf16 v[82:85], v[196:199], v[220:223], v[82:85]
	v_mfma_f32_16x16x32_bf16 v[70:73], v[188:191], v[228:231], v[70:73]
	v_mfma_f32_16x16x32_bf16 v[66:69], v[196:199], v[228:231], v[66:69]
	s_setprio 0
	s_barrier
	s_add_i32 s47, s63, s53
	v_lshl_add_u64 v[236:237], v[234:235], 0, v[132:133]
	s_mov_b32 m0, s47
	ds_read_b128 v[200:203], v164 offset:16384
	ds_read_b128 v[204:207], v164 offset:17408
	ds_read_b128 v[208:211], v164 offset:18432
	ds_read_b128 v[212:215], v164 offset:19456
	ds_read_b128 v[216:219], v164 offset:20480
	ds_read_b128 v[220:223], v164 offset:21504
	ds_read_b128 v[224:227], v164 offset:22528
	ds_read_b128 v[228:231], v164 offset:23552
	global_load_lds_dwordx4 v[236:237], off
	v_lshl_add_u64 v[238:239], v[234:235], 0, v[136:137]
	s_add_i32 m0, s47, 0x2000
	v_lshl_add_u64 v[240:241], v[234:235], 0, s[10:11]
	s_add_i32 s47, s64, s53
	global_load_lds_dwordx4 v[238:239], off
	v_lshl_add_u64 v[242:243], v[240:241], 0, v[132:133]
	s_mov_b32 m0, s47
	v_lshl_add_u64 v[240:241], v[240:241], 0, v[136:137]
	global_load_lds_dwordx4 v[242:243], off
	s_add_i32 m0, s47, 0x2000
	v_lshl_add_u64 v[242:243], v[232:233], 0, v[134:135]
	global_load_lds_dwordx4 v[240:241], off
	v_lshl_add_u64 v[240:241], v[232:233], 0, v[130:131]
	s_mov_b32 m0, s56
	s_nop 0
	global_load_lds_dwordx4 v[240:241], off
	s_mov_b32 m0, s57
	s_nop 0
	global_load_lds_dwordx4 v[242:243], off
	s_cmp_eq_u32 s98, 0
	s_cbranch_scc1 .Lgw948_1a
	s_waitcnt vmcnt(24)
	s_branch .Lgw948_1b

.Lgw948_1b:
	s_mov_b32 s98, 0
	s_waitcnt lgkmcnt(0)
	s_barrier
	s_setprio 1
	s_waitcnt lgkmcnt(0)
	v_mfma_f32_16x16x32_bf16 v[62:65], v[168:171], v[200:203], v[62:65]
	v_mfma_f32_16x16x32_bf16 v[58:61], v[176:179], v[200:203], v[58:61]
	v_mfma_f32_16x16x32_bf16 v[46:49], v[168:171], v[208:211], v[46:49]
	v_mfma_f32_16x16x32_bf16 v[42:45], v[176:179], v[208:211], v[42:45]
	v_mfma_f32_16x16x32_bf16 v[30:33], v[168:171], v[216:219], v[30:33]
	v_mfma_f32_16x16x32_bf16 v[26:29], v[176:179], v[216:219], v[26:29]
	v_mfma_f32_16x16x32_bf16 v[14:17], v[168:171], v[224:227], v[14:17]
	v_mfma_f32_16x16x32_bf16 v[10:13], v[176:179], v[224:227], v[10:13]
	v_mfma_f32_16x16x32_bf16 v[62:65], v[172:175], v[204:207], v[62:65]
	v_mfma_f32_16x16x32_bf16 v[58:61], v[180:183], v[204:207], v[58:61]
	v_mfma_f32_16x16x32_bf16 v[46:49], v[172:175], v[212:215], v[46:49]
	v_mfma_f32_16x16x32_bf16 v[42:45], v[180:183], v[212:215], v[42:45]
	v_mfma_f32_16x16x32_bf16 v[30:33], v[172:175], v[220:223], v[30:33]
	v_mfma_f32_16x16x32_bf16 v[26:29], v[180:183], v[220:223], v[26:29]
	v_mfma_f32_16x16x32_bf16 v[14:17], v[172:175], v[228:231], v[14:17]
	v_mfma_f32_16x16x32_bf16 v[10:13], v[180:183], v[228:231], v[10:13]
	s_setprio 0
	s_setprio 1
	v_mfma_f32_16x16x32_bf16 v[54:57], v[184:187], v[200:203], v[54:57]
	v_mfma_f32_16x16x32_bf16 v[50:53], v[192:195], v[200:203], v[50:53]
	v_mfma_f32_16x16x32_bf16 v[38:41], v[184:187], v[208:211], v[38:41]
	v_mfma_f32_16x16x32_bf16 v[34:37], v[192:195], v[208:211], v[34:37]
	v_mfma_f32_16x16x32_bf16 v[22:25], v[184:187], v[216:219], v[22:25]
	v_mfma_f32_16x16x32_bf16 v[18:21], v[192:195], v[216:219], v[18:21]
	v_mfma_f32_16x16x32_bf16 v[6:9], v[184:187], v[224:227], v[6:9]
	v_mfma_f32_16x16x32_bf16 v[2:5], v[192:195], v[224:227], v[2:5]
	v_mfma_f32_16x16x32_bf16 v[54:57], v[188:191], v[204:207], v[54:57]
	v_mfma_f32_16x16x32_bf16 v[50:53], v[196:199], v[204:207], v[50:53]
	v_mfma_f32_16x16x32_bf16 v[38:41], v[188:191], v[212:215], v[38:41]
	v_mfma_f32_16x16x32_bf16 v[34:37], v[196:199], v[212:215], v[34:37]
	v_mfma_f32_16x16x32_bf16 v[22:25], v[188:191], v[220:223], v[22:25]
	v_mfma_f32_16x16x32_bf16 v[18:21], v[196:199], v[220:223], v[18:21]
	v_mfma_f32_16x16x32_bf16 v[6:9], v[188:191], v[228:231], v[6:9]
	v_mfma_f32_16x16x32_bf16 v[2:5], v[196:199], v[228:231], v[2:5]
	s_setprio 0
	s_barrier
	s_add_i32 s47, 0, 0x18000
	v_add_u32_e32 v147, s47, v161
	s_add_i32 s48, 0, 0x1c000
	ds_read_b128 v[168:171], v147
	ds_read_b128 v[172:175], v147 offset:1024
	ds_read_b128 v[176:179], v147 offset:2048
	ds_read_b128 v[180:183], v147 offset:3072
	v_add_u32_e32 v147, s48, v161
	ds_read_b128 v[184:187], v147
	ds_read_b128 v[188:191], v147 offset:1024
	ds_read_b128 v[192:195], v147 offset:2048
	ds_read_b128 v[196:199], v147 offset:3072
	v_lshl_add_u64 v[232:233], v[232:233], 0, s[10:11]
	s_mov_b32 m0, s58
	v_lshl_add_u64 v[244:245], v[232:233], 0, v[130:131]
	ds_read_b128 v[200:203], v164 offset:32768
	ds_read_b128 v[204:207], v164 offset:33792
	ds_read_b128 v[208:211], v164 offset:34816
	ds_read_b128 v[212:215], v164 offset:35840
	ds_read_b128 v[216:219], v164 offset:36864
	ds_read_b128 v[220:223], v164 offset:37888
	ds_read_b128 v[224:227], v164 offset:38912
	ds_read_b128 v[228:231], v164 offset:39936
	global_load_lds_dwordx4 v[244:245], off
	v_lshl_add_u64 v[232:233], v[232:233], 0, v[134:135]
	s_mov_b32 m0, s59
	s_nop 0
	global_load_lds_dwordx4 v[232:233], off
	s_waitcnt vmcnt(8)
	s_waitcnt lgkmcnt(0)
	s_barrier
	s_setprio 1
	s_waitcnt lgkmcnt(0)
	v_mfma_f32_16x16x32_bf16 v[126:129], v[168:171], v[200:203], v[126:129]
	v_mfma_f32_16x16x32_bf16 v[122:125], v[176:179], v[200:203], v[122:125]
	v_mfma_f32_16x16x32_bf16 v[110:113], v[168:171], v[208:211], v[110:113]
	v_mfma_f32_16x16x32_bf16 v[106:109], v[176:179], v[208:211], v[106:109]
	v_mfma_f32_16x16x32_bf16 v[94:97], v[168:171], v[216:219], v[94:97]
	v_mfma_f32_16x16x32_bf16 v[90:93], v[176:179], v[216:219], v[90:93]
	v_mfma_f32_16x16x32_bf16 v[78:81], v[168:171], v[224:227], v[78:81]
	v_mfma_f32_16x16x32_bf16 v[74:77], v[176:179], v[224:227], v[74:77]
	v_mfma_f32_16x16x32_bf16 v[126:129], v[172:175], v[204:207], v[126:129]
	v_mfma_f32_16x16x32_bf16 v[122:125], v[180:183], v[204:207], v[122:125]
	v_mfma_f32_16x16x32_bf16 v[110:113], v[172:175], v[212:215], v[110:113]
	v_mfma_f32_16x16x32_bf16 v[106:109], v[180:183], v[212:215], v[106:109]
	v_mfma_f32_16x16x32_bf16 v[94:97], v[172:175], v[220:223], v[94:97]
	v_mfma_f32_16x16x32_bf16 v[90:93], v[180:183], v[220:223], v[90:93]
	v_mfma_f32_16x16x32_bf16 v[78:81], v[172:175], v[228:231], v[78:81]
	v_mfma_f32_16x16x32_bf16 v[74:77], v[180:183], v[228:231], v[74:77]
	s_setprio 0
	s_setprio 1
	v_mfma_f32_16x16x32_bf16 v[118:121], v[184:187], v[200:203], v[118:121]
	v_mfma_f32_16x16x32_bf16 v[114:117], v[192:195], v[200:203], v[114:117]
	v_mfma_f32_16x16x32_bf16 v[102:105], v[184:187], v[208:211], v[102:105]
	v_mfma_f32_16x16x32_bf16 v[98:101], v[192:195], v[208:211], v[98:101]
	v_mfma_f32_16x16x32_bf16 v[86:89], v[184:187], v[216:219], v[86:89]
	v_mfma_f32_16x16x32_bf16 v[82:85], v[192:195], v[216:219], v[82:85]
	v_mfma_f32_16x16x32_bf16 v[70:73], v[184:187], v[224:227], v[70:73]
	v_mfma_f32_16x16x32_bf16 v[66:69], v[192:195], v[224:227], v[66:69]
	v_mfma_f32_16x16x32_bf16 v[118:121], v[188:191], v[204:207], v[118:121]
	v_mfma_f32_16x16x32_bf16 v[114:117], v[196:199], v[204:207], v[114:117]
	v_mfma_f32_16x16x32_bf16 v[102:105], v[188:191], v[212:215], v[102:105]
	v_mfma_f32_16x16x32_bf16 v[98:101], v[196:199], v[212:215], v[98:101]
	v_mfma_f32_16x16x32_bf16 v[86:89], v[188:191], v[220:223], v[86:89]
	v_mfma_f32_16x16x32_bf16 v[82:85], v[196:199], v[220:223], v[82:85]
	v_mfma_f32_16x16x32_bf16 v[70:73], v[188:191], v[228:231], v[70:73]
	v_mfma_f32_16x16x32_bf16 v[66:69], v[196:199], v[228:231], v[66:69]
	s_setprio 0
	s_barrier
	s_add_i32 s47, s47, s53
	v_lshl_add_u64 v[232:233], v[236:237], 0, s[18:19]
	s_mov_b32 m0, s47
	ds_read_b128 v[200:203], v164 offset:49152
	ds_read_b128 v[204:207], v164 offset:50176
	ds_read_b128 v[208:211], v164 offset:51200
	ds_read_b128 v[212:215], v164 offset:52224
	ds_read_b128 v[216:219], v164 offset:53248
	ds_read_b128 v[220:223], v164 offset:54272
	ds_read_b128 v[224:227], v164 offset:55296
	ds_read_b128 v[228:231], v164 offset:56320
	global_load_lds_dwordx4 v[232:233], off
	v_lshl_add_u64 v[232:233], v[238:239], 0, s[18:19]
	s_add_i32 m0, s47, 0x2000
	s_add_i32 s47, s48, s53
	global_load_lds_dwordx4 v[232:233], off
	v_lshl_add_u64 v[232:233], v[234:235], 0, s[22:23]
	v_lshl_add_u64 v[234:235], v[232:233], 0, v[132:133]
	s_mov_b32 m0, s47
	v_lshl_add_u64 v[232:233], v[232:233], 0, v[136:137]
	global_load_lds_dwordx4 v[234:235], off
	s_add_i32 m0, s47, 0x2000
	s_nop 0
	global_load_lds_dwordx4 v[232:233], off
	v_lshl_add_u64 v[232:233], v[240:241], 0, s[18:19]
	s_mov_b32 m0, s61
	s_nop 0
	global_load_lds_dwordx4 v[232:233], off
	v_lshl_add_u64 v[232:233], v[242:243], 0, s[18:19]
	s_mov_b32 m0, s62
	s_nop 0
	global_load_lds_dwordx4 v[232:233], off
	s_waitcnt vmcnt(8)
	s_waitcnt lgkmcnt(0)
	s_barrier
	s_setprio 1
	s_waitcnt lgkmcnt(0)
	v_mfma_f32_16x16x32_bf16 v[62:65], v[168:171], v[200:203], v[62:65]
	v_mfma_f32_16x16x32_bf16 v[58:61], v[176:179], v[200:203], v[58:61]
	v_mfma_f32_16x16x32_bf16 v[46:49], v[168:171], v[208:211], v[46:49]
	v_mfma_f32_16x16x32_bf16 v[42:45], v[176:179], v[208:211], v[42:45]
	v_mfma_f32_16x16x32_bf16 v[30:33], v[168:171], v[216:219], v[30:33]
	v_mfma_f32_16x16x32_bf16 v[26:29], v[176:179], v[216:219], v[26:29]
	v_mfma_f32_16x16x32_bf16 v[14:17], v[168:171], v[224:227], v[14:17]
	v_mfma_f32_16x16x32_bf16 v[10:13], v[176:179], v[224:227], v[10:13]
	v_mfma_f32_16x16x32_bf16 v[62:65], v[172:175], v[204:207], v[62:65]
	v_mfma_f32_16x16x32_bf16 v[58:61], v[180:183], v[204:207], v[58:61]
	v_mfma_f32_16x16x32_bf16 v[46:49], v[172:175], v[212:215], v[46:49]
	v_mfma_f32_16x16x32_bf16 v[42:45], v[180:183], v[212:215], v[42:45]
	v_mfma_f32_16x16x32_bf16 v[30:33], v[172:175], v[220:223], v[30:33]
	v_mfma_f32_16x16x32_bf16 v[26:29], v[180:183], v[220:223], v[26:29]
	v_mfma_f32_16x16x32_bf16 v[14:17], v[172:175], v[228:231], v[14:17]
	v_mfma_f32_16x16x32_bf16 v[10:13], v[180:183], v[228:231], v[10:13]
	s_setprio 0
	s_setprio 1
	v_mfma_f32_16x16x32_bf16 v[54:57], v[184:187], v[200:203], v[54:57]
	v_mfma_f32_16x16x32_bf16 v[50:53], v[192:195], v[200:203], v[50:53]
	v_mfma_f32_16x16x32_bf16 v[38:41], v[184:187], v[208:211], v[38:41]
	v_mfma_f32_16x16x32_bf16 v[34:37], v[192:195], v[208:211], v[34:37]
	v_mfma_f32_16x16x32_bf16 v[22:25], v[184:187], v[216:219], v[22:25]
	v_mfma_f32_16x16x32_bf16 v[18:21], v[192:195], v[216:219], v[18:21]
	v_mfma_f32_16x16x32_bf16 v[6:9], v[184:187], v[224:227], v[6:9]
	v_mfma_f32_16x16x32_bf16 v[2:5], v[192:195], v[224:227], v[2:5]
	v_mfma_f32_16x16x32_bf16 v[54:57], v[188:191], v[204:207], v[54:57]
	v_mfma_f32_16x16x32_bf16 v[50:53], v[196:199], v[204:207], v[50:53]
	v_mfma_f32_16x16x32_bf16 v[38:41], v[188:191], v[212:215], v[38:41]
	v_mfma_f32_16x16x32_bf16 v[34:37], v[196:199], v[212:215], v[34:37]
	v_mfma_f32_16x16x32_bf16 v[22:25], v[188:191], v[220:223], v[22:25]
	v_mfma_f32_16x16x32_bf16 v[18:21], v[196:199], v[220:223], v[18:21]
	v_mfma_f32_16x16x32_bf16 v[6:9], v[188:191], v[228:231], v[6:9]
	v_mfma_f32_16x16x32_bf16 v[2:5], v[196:199], v[228:231], v[2:5]
	s_setprio 0
	s_barrier
	s_add_i32 s46, s46, 2
	v_lshl_add_u64 v[156:157], v[156:157], 0, s[30:31]
	s_cmp_gt_u32 s46, 61
	v_lshl_add_u64 v[158:159], v[158:159], 0, s[30:31]
	s_cbranch_scc0 .LBB0_948
	s_and_b64 vcc, exec, s[24:25]
	s_cbranch_vccz .LBB0_951
	s_barrier

.LBB0_953:
	s_or_b64 exec, exec, s[46:47]
	s_mov_b64 s[48:49], -1
	s_and_saveexec_b64 s[46:47], s[44:45]
	s_cbranch_execz .LBB0_930
	s_mov_b32 s98, 1
	s_andn2_b64 vcc, exec, s[8:9]
	s_cbranch_vccnz .LBB0_929
	s_barrier
	s_branch .LBB0_929

.LBB0_1098:
	ds_read_b128 v[140:143], v165
	ds_read_b128 v[144:147], v165 offset:1024
	ds_read_b128 v[148:151], v165 offset:2048
	ds_read_b128 v[152:155], v165 offset:3072
	ds_read_b128 v[156:159], v166
	ds_read_b128 v[168:171], v166 offset:1024
	ds_read_b128 v[172:175], v166 offset:2048
	ds_read_b128 v[176:179], v166 offset:3072
	s_add_u32 s28, s26, 0xffe00080
	s_addc_u32 s29, s27, -1
	s_cmpk_eq_i32 s55, 0x7c
	s_cselect_b32 s31, s19, s29
	s_cselect_b32 s30, s51, s28
	s_cselect_b32 s29, s17, s54
	s_cselect_b32 s28, s52, s53
	v_lshl_add_u64 v[160:161], s[26:27], 0, v[132:133]
	s_add_i32 m0, s25, 0xc000
	ds_read_b128 v[180:183], v167
	ds_read_b128 v[184:187], v167 offset:1024
	ds_read_b128 v[188:191], v167 offset:2048
	ds_read_b128 v[192:195], v167 offset:3072
	ds_read_b128 v[196:199], v167 offset:4096
	ds_read_b128 v[200:203], v167 offset:5120
	ds_read_b128 v[204:207], v167 offset:6144
	ds_read_b128 v[208:211], v167 offset:7168
	global_load_lds_dwordx4 v[160:161], off
	v_lshl_add_u64 v[160:161], s[26:27], 0, v[134:135]
	s_add_i32 m0, s25, 0xe000
	s_nop 0
	global_load_lds_dwordx4 v[160:161], off
	s_cmp_eq_u32 s98, 0
	s_cbranch_scc1 .Lgw1098_0a
	s_waitcnt vmcnt(40)
	s_branch .Lgw1098_0b

.Lgw1098_0b:
	s_waitcnt lgkmcnt(0)
	s_barrier
	s_setprio 1
	s_waitcnt lgkmcnt(0)
	v_mfma_f32_16x16x32_bf16 v[124:127], v[140:143], v[180:183], v[124:127]
	v_mfma_f32_16x16x32_bf16 v[120:123], v[148:151], v[180:183], v[120:123]
	v_mfma_f32_16x16x32_bf16 v[108:111], v[140:143], v[188:191], v[108:111]
	v_mfma_f32_16x16x32_bf16 v[104:107], v[148:151], v[188:191], v[104:107]
	v_mfma_f32_16x16x32_bf16 v[92:95], v[140:143], v[196:199], v[92:95]
	v_mfma_f32_16x16x32_bf16 v[88:91], v[148:151], v[196:199], v[88:91]
	v_mfma_f32_16x16x32_bf16 v[76:79], v[140:143], v[204:207], v[76:79]
	v_mfma_f32_16x16x32_bf16 v[72:75], v[148:151], v[204:207], v[72:75]
	v_mfma_f32_16x16x32_bf16 v[124:127], v[144:147], v[184:187], v[124:127]
	v_mfma_f32_16x16x32_bf16 v[120:123], v[152:155], v[184:187], v[120:123]
	v_mfma_f32_16x16x32_bf16 v[108:111], v[144:147], v[192:195], v[108:111]
	v_mfma_f32_16x16x32_bf16 v[104:107], v[152:155], v[192:195], v[104:107]
	v_mfma_f32_16x16x32_bf16 v[92:95], v[144:147], v[200:203], v[92:95]
	v_mfma_f32_16x16x32_bf16 v[88:91], v[152:155], v[200:203], v[88:91]
	v_mfma_f32_16x16x32_bf16 v[76:79], v[144:147], v[208:211], v[76:79]
	v_mfma_f32_16x16x32_bf16 v[72:75], v[152:155], v[208:211], v[72:75]
	s_setprio 0
	s_setprio 1
	v_mfma_f32_16x16x32_bf16 v[116:119], v[156:159], v[180:183], v[116:119]
	v_mfma_f32_16x16x32_bf16 v[112:115], v[172:175], v[180:183], v[112:115]
	v_mfma_f32_16x16x32_bf16 v[100:103], v[156:159], v[188:191], v[100:103]
	v_mfma_f32_16x16x32_bf16 v[96:99], v[172:175], v[188:191], v[96:99]
	v_mfma_f32_16x16x32_bf16 v[84:87], v[156:159], v[196:199], v[84:87]
	v_mfma_f32_16x16x32_bf16 v[80:83], v[172:175], v[196:199], v[80:83]
	v_mfma_f32_16x16x32_bf16 v[68:71], v[156:159], v[204:207], v[68:71]
	v_mfma_f32_16x16x32_bf16 v[64:67], v[172:175], v[204:207], v[64:67]
	v_mfma_f32_16x16x32_bf16 v[116:119], v[168:171], v[184:187], v[116:119]
	v_mfma_f32_16x16x32_bf16 v[112:115], v[176:179], v[184:187], v[112:115]
	v_mfma_f32_16x16x32_bf16 v[100:103], v[168:171], v[192:195], v[100:103]
	v_mfma_f32_16x16x32_bf16 v[96:99], v[176:179], v[192:195], v[96:99]
	v_mfma_f32_16x16x32_bf16 v[84:87], v[168:171], v[200:203], v[84:87]
	v_mfma_f32_16x16x32_bf16 v[80:83], v[176:179], v[200:203], v[80:83]
	v_mfma_f32_16x16x32_bf16 v[68:71], v[168:171], v[208:211], v[68:71]
	v_mfma_f32_16x16x32_bf16 v[64:67], v[176:179], v[208:211], v[64:67]
	s_setprio 0
	s_barrier
	s_add_i32 s56, s48, s38
	v_lshl_add_u64 v[160:161], s[28:29], 0, v[128:129]
	s_mov_b32 m0, s56
	ds_read_b128 v[180:183], v167 offset:16384
	ds_read_b128 v[184:187], v167 offset:17408
	ds_read_b128 v[188:191], v167 offset:18432
	ds_read_b128 v[192:195], v167 offset:19456
	ds_read_b128 v[196:199], v167 offset:20480
	ds_read_b128 v[200:203], v167 offset:21504
	ds_read_b128 v[204:207], v167 offset:22528
	ds_read_b128 v[208:211], v167 offset:23552
	global_load_lds_dwordx4 v[160:161], off
	s_add_i32 m0, s56, 0x2000
	s_add_u32 s56, s28, 0x200000
	v_lshl_add_u64 v[212:213], s[28:29], 0, v[130:131]
	s_addc_u32 s57, s29, 0
	s_add_i32 s58, s49, s38
	global_load_lds_dwordx4 v[212:213], off
	v_lshl_add_u64 v[214:215], s[56:57], 0, v[128:129]
	s_mov_b32 m0, s58
	v_lshl_add_u64 v[216:217], s[30:31], 0, v[130:131]
	global_load_lds_dwordx4 v[214:215], off
	v_lshl_add_u64 v[214:215], s[56:57], 0, v[130:131]
	s_add_i32 m0, s58, 0x2000
	s_nop 0
	global_load_lds_dwordx4 v[214:215], off
	v_lshl_add_u64 v[214:215], s[30:31], 0, v[128:129]
	s_mov_b32 m0, s25
	s_nop 0
	global_load_lds_dwordx4 v[214:215], off
	s_mov_b32 m0, s40
	s_nop 0
	global_load_lds_dwordx4 v[216:217], off
	s_cmp_eq_u32 s98, 0
	s_cbranch_scc1 .Lgw1098_1a
	s_waitcnt vmcnt(40)
	s_branch .Lgw1098_1b

.Lgw1098_1b:
	s_mov_b32 s98, 0
	s_waitcnt lgkmcnt(0)
	s_barrier
	s_setprio 1
	s_waitcnt lgkmcnt(0)
	v_mfma_f32_16x16x32_bf16 v[60:63], v[140:143], v[180:183], v[60:63]
	v_mfma_f32_16x16x32_bf16 v[56:59], v[148:151], v[180:183], v[56:59]
	v_mfma_f32_16x16x32_bf16 v[44:47], v[140:143], v[188:191], v[44:47]
	v_mfma_f32_16x16x32_bf16 v[40:43], v[148:151], v[188:191], v[40:43]
	v_mfma_f32_16x16x32_bf16 v[28:31], v[140:143], v[196:199], v[28:31]
	v_mfma_f32_16x16x32_bf16 v[24:27], v[148:151], v[196:199], v[24:27]
	v_mfma_f32_16x16x32_bf16 v[16:19], v[140:143], v[204:207], v[16:19]
	v_mfma_f32_16x16x32_bf16 v[8:11], v[148:151], v[204:207], v[8:11]
	v_mfma_f32_16x16x32_bf16 v[60:63], v[144:147], v[184:187], v[60:63]
	v_mfma_f32_16x16x32_bf16 v[56:59], v[152:155], v[184:187], v[56:59]
	v_mfma_f32_16x16x32_bf16 v[44:47], v[144:147], v[192:195], v[44:47]
	v_mfma_f32_16x16x32_bf16 v[40:43], v[152:155], v[192:195], v[40:43]
	v_mfma_f32_16x16x32_bf16 v[28:31], v[144:147], v[200:203], v[28:31]
	v_mfma_f32_16x16x32_bf16 v[24:27], v[152:155], v[200:203], v[24:27]
	v_mfma_f32_16x16x32_bf16 v[16:19], v[144:147], v[208:211], v[16:19]
	v_mfma_f32_16x16x32_bf16 v[8:11], v[152:155], v[208:211], v[8:11]
	s_setprio 0
	s_setprio 1
	v_mfma_f32_16x16x32_bf16 v[52:55], v[156:159], v[180:183], v[52:55]
	v_mfma_f32_16x16x32_bf16 v[48:51], v[172:175], v[180:183], v[48:51]
	v_mfma_f32_16x16x32_bf16 v[36:39], v[156:159], v[188:191], v[36:39]
	v_mfma_f32_16x16x32_bf16 v[32:35], v[172:175], v[188:191], v[32:35]
	v_mfma_f32_16x16x32_bf16 v[20:23], v[156:159], v[196:199], v[20:23]
	v_mfma_f32_16x16x32_bf16 v[12:15], v[172:175], v[196:199], v[12:15]
	v_mfma_f32_16x16x32_bf16 v[4:7], v[156:159], v[204:207], v[4:7]
	v_mfma_f32_16x16x32_bf16 v[0:3], v[172:175], v[204:207], v[0:3]
	v_mfma_f32_16x16x32_bf16 v[52:55], v[168:171], v[184:187], v[52:55]
	v_mfma_f32_16x16x32_bf16 v[48:51], v[176:179], v[184:187], v[48:51]
	v_mfma_f32_16x16x32_bf16 v[36:39], v[168:171], v[192:195], v[36:39]
	v_mfma_f32_16x16x32_bf16 v[32:35], v[176:179], v[192:195], v[32:35]
	v_mfma_f32_16x16x32_bf16 v[20:23], v[168:171], v[200:203], v[20:23]
	v_mfma_f32_16x16x32_bf16 v[12:15], v[176:179], v[200:203], v[12:15]
	v_mfma_f32_16x16x32_bf16 v[4:7], v[168:171], v[208:211], v[4:7]
	v_mfma_f32_16x16x32_bf16 v[0:3], v[176:179], v[208:211], v[0:3]
	s_setprio 0
	s_barrier
	s_add_i32 s56, 0, 0x18000
	s_add_i32 s57, 0, 0x1c000
	v_add_u32_e32 v152, s56, v163
	v_add_u32_e32 v176, s57, v163
	ds_read_b128 v[140:143], v152
	ds_read_b128 v[144:147], v152 offset:1024
	ds_read_b128 v[148:151], v152 offset:2048
	ds_read_b128 v[152:155], v152 offset:3072
	ds_read_b128 v[156:159], v176
	ds_read_b128 v[168:171], v176 offset:1024
	ds_read_b128 v[172:175], v176 offset:2048
	ds_read_b128 v[176:179], v176 offset:3072
	s_add_u32 s30, s30, 0x200000
	s_addc_u32 s31, s31, 0
	s_mov_b32 m0, s41
	v_lshl_add_u64 v[218:219], s[30:31], 0, v[128:129]
	ds_read_b128 v[180:183], v167 offset:32768
	ds_read_b128 v[184:187], v167 offset:33792
	ds_read_b128 v[188:191], v167 offset:34816
	ds_read_b128 v[192:195], v167 offset:35840
	ds_read_b128 v[196:199], v167 offset:36864
	ds_read_b128 v[200:203], v167 offset:37888
	ds_read_b128 v[204:207], v167 offset:38912
	ds_read_b128 v[208:211], v167 offset:39936
	global_load_lds_dwordx4 v[218:219], off
	v_lshl_add_u64 v[218:219], s[30:31], 0, v[130:131]
	s_mov_b32 m0, s42
	s_nop 0
	global_load_lds_dwordx4 v[218:219], off
	s_waitcnt vmcnt(8)
	s_waitcnt lgkmcnt(0)
	s_barrier
	s_setprio 1
	s_waitcnt lgkmcnt(0)
	v_mfma_f32_16x16x32_bf16 v[124:127], v[140:143], v[180:183], v[124:127]
	v_mfma_f32_16x16x32_bf16 v[120:123], v[148:151], v[180:183], v[120:123]
	v_mfma_f32_16x16x32_bf16 v[108:111], v[140:143], v[188:191], v[108:111]
	v_mfma_f32_16x16x32_bf16 v[104:107], v[148:151], v[188:191], v[104:107]
	v_mfma_f32_16x16x32_bf16 v[92:95], v[140:143], v[196:199], v[92:95]
	v_mfma_f32_16x16x32_bf16 v[88:91], v[148:151], v[196:199], v[88:91]
	v_mfma_f32_16x16x32_bf16 v[76:79], v[140:143], v[204:207], v[76:79]
	v_mfma_f32_16x16x32_bf16 v[72:75], v[148:151], v[204:207], v[72:75]
	v_mfma_f32_16x16x32_bf16 v[124:127], v[144:147], v[184:187], v[124:127]
	v_mfma_f32_16x16x32_bf16 v[120:123], v[152:155], v[184:187], v[120:123]
	v_mfma_f32_16x16x32_bf16 v[108:111], v[144:147], v[192:195], v[108:111]
	v_mfma_f32_16x16x32_bf16 v[104:107], v[152:155], v[192:195], v[104:107]
	v_mfma_f32_16x16x32_bf16 v[92:95], v[144:147], v[200:203], v[92:95]
	v_mfma_f32_16x16x32_bf16 v[88:91], v[152:155], v[200:203], v[88:91]
	v_mfma_f32_16x16x32_bf16 v[76:79], v[144:147], v[208:211], v[76:79]
	v_mfma_f32_16x16x32_bf16 v[72:75], v[152:155], v[208:211], v[72:75]
	s_setprio 0
	s_setprio 1
	v_mfma_f32_16x16x32_bf16 v[116:119], v[156:159], v[180:183], v[116:119]
	v_mfma_f32_16x16x32_bf16 v[112:115], v[172:175], v[180:183], v[112:115]
	v_mfma_f32_16x16x32_bf16 v[100:103], v[156:159], v[188:191], v[100:103]
	v_mfma_f32_16x16x32_bf16 v[96:99], v[172:175], v[188:191], v[96:99]
	v_mfma_f32_16x16x32_bf16 v[84:87], v[156:159], v[196:199], v[84:87]
	v_mfma_f32_16x16x32_bf16 v[80:83], v[172:175], v[196:199], v[80:83]
	v_mfma_f32_16x16x32_bf16 v[68:71], v[156:159], v[204:207], v[68:71]
	v_mfma_f32_16x16x32_bf16 v[64:67], v[172:175], v[204:207], v[64:67]
	v_mfma_f32_16x16x32_bf16 v[116:119], v[168:171], v[184:187], v[116:119]
	v_mfma_f32_16x16x32_bf16 v[112:115], v[176:179], v[184:187], v[112:115]
	v_mfma_f32_16x16x32_bf16 v[100:103], v[168:171], v[192:195], v[100:103]
	v_mfma_f32_16x16x32_bf16 v[96:99], v[176:179], v[192:195], v[96:99]
	v_mfma_f32_16x16x32_bf16 v[84:87], v[168:171], v[200:203], v[84:87]
	v_mfma_f32_16x16x32_bf16 v[80:83], v[176:179], v[200:203], v[80:83]
	v_mfma_f32_16x16x32_bf16 v[68:71], v[168:171], v[208:211], v[68:71]
	v_mfma_f32_16x16x32_bf16 v[64:67], v[176:179], v[208:211], v[64:67]
	s_setprio 0
	s_barrier
	s_add_i32 s30, s56, s38
	v_lshl_add_u64 v[160:161], v[160:161], 0, s[10:11]
	s_mov_b32 m0, s30
	ds_read_b128 v[180:183], v167 offset:49152
	ds_read_b128 v[184:187], v167 offset:50176
	ds_read_b128 v[188:191], v167 offset:51200
	ds_read_b128 v[192:195], v167 offset:52224
	ds_read_b128 v[196:199], v167 offset:53248
	ds_read_b128 v[200:203], v167 offset:54272
	ds_read_b128 v[204:207], v167 offset:55296
	ds_read_b128 v[208:211], v167 offset:56320
	global_load_lds_dwordx4 v[160:161], off
	s_add_i32 m0, s30, 0x2000
	s_add_u32 s28, s28, 0x200080
	v_lshl_add_u64 v[160:161], v[212:213], 0, s[10:11]
	s_addc_u32 s29, s29, 0
	s_add_i32 s30, s57, s38
	global_load_lds_dwordx4 v[160:161], off
	v_lshl_add_u64 v[160:161], s[28:29], 0, v[128:129]
	s_mov_b32 m0, s30
	s_nop 0
	global_load_lds_dwordx4 v[160:161], off
	v_lshl_add_u64 v[160:161], s[28:29], 0, v[130:131]
	s_add_i32 m0, s30, 0x2000
	s_nop 0
	global_load_lds_dwordx4 v[160:161], off
	v_lshl_add_u64 v[160:161], v[214:215], 0, s[10:11]
	s_mov_b32 m0, s45
	s_nop 0
	global_load_lds_dwordx4 v[160:161], off
	v_lshl_add_u64 v[160:161], v[216:217], 0, s[10:11]
	s_mov_b32 m0, s46
	s_nop 0
	global_load_lds_dwordx4 v[160:161], off
	s_waitcnt vmcnt(8)
	s_waitcnt lgkmcnt(0)
	s_barrier
	s_setprio 1
	s_waitcnt lgkmcnt(0)
	v_mfma_f32_16x16x32_bf16 v[60:63], v[140:143], v[180:183], v[60:63]
	v_mfma_f32_16x16x32_bf16 v[56:59], v[148:151], v[180:183], v[56:59]
	v_mfma_f32_16x16x32_bf16 v[44:47], v[140:143], v[188:191], v[44:47]
	v_mfma_f32_16x16x32_bf16 v[40:43], v[148:151], v[188:191], v[40:43]
	v_mfma_f32_16x16x32_bf16 v[28:31], v[140:143], v[196:199], v[28:31]
	v_mfma_f32_16x16x32_bf16 v[24:27], v[148:151], v[196:199], v[24:27]
	v_mfma_f32_16x16x32_bf16 v[16:19], v[140:143], v[204:207], v[16:19]
	v_mfma_f32_16x16x32_bf16 v[8:11], v[148:151], v[204:207], v[8:11]
	v_mfma_f32_16x16x32_bf16 v[60:63], v[144:147], v[184:187], v[60:63]
	v_mfma_f32_16x16x32_bf16 v[56:59], v[152:155], v[184:187], v[56:59]
	v_mfma_f32_16x16x32_bf16 v[44:47], v[144:147], v[192:195], v[44:47]
	v_mfma_f32_16x16x32_bf16 v[40:43], v[152:155], v[192:195], v[40:43]
	v_mfma_f32_16x16x32_bf16 v[28:31], v[144:147], v[200:203], v[28:31]
	v_mfma_f32_16x16x32_bf16 v[24:27], v[152:155], v[200:203], v[24:27]
	v_mfma_f32_16x16x32_bf16 v[16:19], v[144:147], v[208:211], v[16:19]
	v_mfma_f32_16x16x32_bf16 v[8:11], v[152:155], v[208:211], v[8:11]
	s_setprio 0
	s_setprio 1
	v_mfma_f32_16x16x32_bf16 v[52:55], v[156:159], v[180:183], v[52:55]
	v_mfma_f32_16x16x32_bf16 v[48:51], v[172:175], v[180:183], v[48:51]
	v_mfma_f32_16x16x32_bf16 v[36:39], v[156:159], v[188:191], v[36:39]
	v_mfma_f32_16x16x32_bf16 v[32:35], v[172:175], v[188:191], v[32:35]
	v_mfma_f32_16x16x32_bf16 v[20:23], v[156:159], v[196:199], v[20:23]
	v_mfma_f32_16x16x32_bf16 v[12:15], v[172:175], v[196:199], v[12:15]
	v_mfma_f32_16x16x32_bf16 v[4:7], v[156:159], v[204:207], v[4:7]
	v_mfma_f32_16x16x32_bf16 v[0:3], v[172:175], v[204:207], v[0:3]
	v_mfma_f32_16x16x32_bf16 v[52:55], v[168:171], v[184:187], v[52:55]
	v_mfma_f32_16x16x32_bf16 v[48:51], v[176:179], v[184:187], v[48:51]
	v_mfma_f32_16x16x32_bf16 v[36:39], v[168:171], v[192:195], v[36:39]
	v_mfma_f32_16x16x32_bf16 v[32:35], v[176:179], v[192:195], v[32:35]
	v_mfma_f32_16x16x32_bf16 v[20:23], v[168:171], v[200:203], v[20:23]
	v_mfma_f32_16x16x32_bf16 v[12:15], v[176:179], v[200:203], v[12:15]
	v_mfma_f32_16x16x32_bf16 v[4:7], v[168:171], v[208:211], v[4:7]
	v_mfma_f32_16x16x32_bf16 v[0:3], v[176:179], v[208:211], v[0:3]
	s_setprio 0
	s_barrier
	s_add_i32 s55, s55, 2
	s_add_u32 s26, s26, 0x100
	s_addc_u32 s27, s27, 0
	s_add_u32 s53, s53, 0x100
	s_addc_u32 s54, s54, 0
	s_cmpk_gt_u32 s55, 0x7d
	s_cbranch_scc0 .LBB0_1098
	s_and_b64 vcc, exec, s[14:15]
	s_cbranch_vccz .LBB0_1101
	s_barrier
.LBB0_1101:
	s_ashr_i32 s17, s24, 31
	s_lshr_b32 s17, s17, 28
	s_add_i32 s17, s24, s17
	s_ashr_i32 s17, s17, 4
	s_mul_i32 s26, s17, 3
	s_ashr_i32 s27, s26, 31
	v_lshl_or_b32 v154, s50, 8, v164
	s_lshl_b64 s[26:27], s[26:27], 14
	s_add_u32 s26, s2, s26
	v_ashrrev_i32_e32 v155, 31, v154
	s_addc_u32 s27, s3, s27
	v_lshlrev_b64 v[140:141], 2, v[154:155]
	v_lshl_add_u64 v[142:143], s[26:27], 0, v[140:141]
	v_lshl_add_u64 v[156:157], v[142:143], 0, s[12:13]
	v_add_co_u32_e32 v142, vcc, s47, v142
	v_lshl_add_u64 v[158:159], s[8:9], 0, v[140:141]
	s_nop 0
	v_addc_co_u32_e32 v143, vcc, 0, v143, vcc
	global_load_dwordx4 v[142:145], v[142:143], off
	s_nop 0
	global_load_dwordx4 v[146:149], v[158:159], off
	global_load_dwordx4 v[150:153], v[158:159], off offset:64
	global_load_dwordx4 v[168:171], v[156:157], off offset:64
	global_load_dwordx4 v[172:175], v[156:157], off offset:512
	global_load_dwordx4 v[176:179], v[156:157], off offset:576
	global_load_dwordx4 v[180:183], v[158:159], off offset:512
	global_load_dwordx4 v[184:187], v[158:159], off offset:576
	v_lshl_add_u32 v158, s24, 8, v162
	v_ashrrev_i32_e32 v159, 31, v158
	v_lshlrev_b64 v[156:157], 13, v[158:159]
	v_lshl_add_u64 v[156:157], s[6:7], 0, v[156:157]
	v_lshlrev_b64 v[160:161], 1, v[154:155]
	v_lshl_add_u64 v[154:155], v[156:157], 0, v[160:161]
	global_load_dwordx2 v[188:189], v[154:155], off offset:32
	global_load_dwordx2 v[190:191], v[154:155], off offset:256
	global_load_dwordx2 v[192:193], v[154:155], off offset:288
	global_load_dwordx2 v[194:195], v[154:155], off
	s_waitcnt vmcnt(0)
	v_pk_add_f32 v[156:157], v[144:145], v[148:149]
	v_pk_add_f32 v[154:155], v[142:143], v[146:147]
	v_pk_add_f32 v[152:153], v[170:171], v[152:153]
	v_pk_add_f32 v[150:151], v[168:169], v[150:151]
	v_pk_add_f32 v[148:149], v[174:175], v[182:183]
	v_pk_add_f32 v[146:147], v[172:173], v[180:181]
	v_pk_add_f32 v[144:145], v[178:179], v[186:187]
	v_pk_add_f32 v[142:143], v[176:177], v[184:185]
	v_or_b32_e32 v168, 16, v158
	v_ashrrev_i32_e32 v169, 31, v168
	v_lshlrev_b64 v[170:171], 13, v[168:169]
	v_lshl_add_u64 v[170:171], s[6:7], 0, v[170:171]
	v_lshl_add_u64 v[170:171], v[170:171], 0, v[160:161]
	global_load_dwordx2 v[172:173], v[170:171], off
	global_load_dwordx2 v[174:175], v[170:171], off offset:32
	global_load_dwordx2 v[176:177], v[170:171], off offset:256
	s_nop 0
	global_load_dwordx2 v[170:171], v[170:171], off offset:288
	v_lshlrev_b32_e32 v178, 16, v194
	v_and_b32_e32 v179, 0xffff0000, v194
	v_pk_fma_f32 v[124:125], v[124:125], v[154:155], v[178:179]
	v_lshlrev_b64 v[178:179], 14, v[158:159]
	v_lshlrev_b32_e32 v180, 16, v195
	v_and_b32_e32 v181, 0xffff0000, v195
	v_lshl_add_u64 v[178:179], s[66:67], 0, v[178:179]
	v_pk_fma_f32 v[126:127], v[126:127], v[156:157], v[180:181]
	v_lshl_add_u64 v[178:179], v[178:179], 0, v[140:141]
	global_store_dwordx4 v[178:179], v[124:127], off
	s_nop 1
	v_lshlrev_b32_e32 v124, 16, v188
	v_and_b32_e32 v125, 0xffff0000, v188
	v_lshlrev_b32_e32 v126, 16, v189
	v_and_b32_e32 v127, 0xffff0000, v189
	v_pk_fma_f32 v[122:123], v[122:123], v[152:153], v[126:127]
	v_pk_fma_f32 v[120:121], v[120:121], v[150:151], v[124:125]
	global_store_dwordx4 v[178:179], v[120:123], off offset:64
	s_nop 1
	v_lshlrev_b32_e32 v120, 16, v190
	v_and_b32_e32 v121, 0xffff0000, v190
	v_lshlrev_b32_e32 v122, 16, v191
	v_and_b32_e32 v123, 0xffff0000, v191
	v_pk_fma_f32 v[118:119], v[118:119], v[148:149], v[122:123]
	v_pk_fma_f32 v[116:117], v[116:117], v[146:147], v[120:121]
	global_store_dwordx4 v[178:179], v[116:119], off offset:512
	s_nop 1
	v_lshlrev_b32_e32 v116, 16, v192
	v_and_b32_e32 v117, 0xffff0000, v192
	v_lshlrev_b32_e32 v118, 16, v193
	v_and_b32_e32 v119, 0xffff0000, v193
	v_pk_fma_f32 v[114:115], v[114:115], v[144:145], v[118:119]
	v_pk_fma_f32 v[112:113], v[112:113], v[142:143], v[116:117]
	global_store_dwordx4 v[178:179], v[112:115], off offset:576
	s_nop 1
	v_or_b32_e32 v112, 32, v158
	v_ashrrev_i32_e32 v113, 31, v112
	v_lshlrev_b64 v[114:115], 13, v[112:113]
	v_lshl_add_u64 v[114:115], s[6:7], 0, v[114:115]
	v_lshl_add_u64 v[114:115], v[114:115], 0, v[160:161]
	global_load_dwordx2 v[116:117], v[114:115], off
	global_load_dwordx2 v[118:119], v[114:115], off offset:32
	global_load_dwordx2 v[120:121], v[114:115], off offset:256
	s_nop 0
	global_load_dwordx2 v[114:115], v[114:115], off offset:288
	s_waitcnt vmcnt(11)
	v_lshlrev_b32_e32 v122, 16, v172
	v_and_b32_e32 v123, 0xffff0000, v172
	v_pk_fma_f32 v[108:109], v[108:109], v[154:155], v[122:123]
	v_lshlrev_b64 v[122:123], 14, v[168:169]
	v_lshlrev_b32_e32 v124, 16, v173
	v_and_b32_e32 v125, 0xffff0000, v173
	v_lshl_add_u64 v[122:123], s[66:67], 0, v[122:123]
	v_pk_fma_f32 v[110:111], v[110:111], v[156:157], v[124:125]
	v_lshl_add_u64 v[122:123], v[122:123], 0, v[140:141]
	global_store_dwordx4 v[122:123], v[108:111], off
	s_waitcnt vmcnt(11)
	s_nop 0
	v_lshlrev_b32_e32 v108, 16, v174
	v_and_b32_e32 v109, 0xffff0000, v174
	v_lshlrev_b32_e32 v110, 16, v175
	v_and_b32_e32 v111, 0xffff0000, v175
	v_pk_fma_f32 v[106:107], v[106:107], v[152:153], v[110:111]
	v_pk_fma_f32 v[104:105], v[104:105], v[150:151], v[108:109]
	global_store_dwordx4 v[122:123], v[104:107], off offset:64
	s_waitcnt vmcnt(11)
	s_nop 0
	v_lshlrev_b32_e32 v104, 16, v176
	v_and_b32_e32 v105, 0xffff0000, v176
	v_lshlrev_b32_e32 v106, 16, v177
	v_and_b32_e32 v107, 0xffff0000, v177
	v_pk_fma_f32 v[102:103], v[102:103], v[148:149], v[106:107]
	v_pk_fma_f32 v[100:101], v[100:101], v[146:147], v[104:105]
	global_store_dwordx4 v[122:123], v[100:103], off offset:512
	s_waitcnt vmcnt(11)
	s_nop 0
	v_lshlrev_b32_e32 v100, 16, v170
	v_and_b32_e32 v101, 0xffff0000, v170
	v_lshlrev_b32_e32 v102, 16, v171
	v_and_b32_e32 v103, 0xffff0000, v171
	v_pk_fma_f32 v[98:99], v[98:99], v[144:145], v[102:103]
	v_pk_fma_f32 v[96:97], v[96:97], v[142:143], v[100:101]
	global_store_dwordx4 v[122:123], v[96:99], off offset:576
	s_nop 1
	v_or_b32_e32 v96, 48, v158
	v_ashrrev_i32_e32 v97, 31, v96
	v_lshlrev_b64 v[98:99], 13, v[96:97]
	v_lshl_add_u64 v[98:99], s[6:7], 0, v[98:99]
	v_lshl_add_u64 v[98:99], v[98:99], 0, v[160:161]
	global_load_dwordx2 v[100:101], v[98:99], off
	global_load_dwordx2 v[102:103], v[98:99], off offset:32
	global_load_dwordx2 v[104:105], v[98:99], off offset:256
	s_nop 0
	global_load_dwordx2 v[98:99], v[98:99], off offset:288
	s_waitcnt vmcnt(11)
	v_lshlrev_b32_e32 v106, 16, v116
	v_and_b32_e32 v107, 0xffff0000, v116
	v_pk_fma_f32 v[92:93], v[92:93], v[154:155], v[106:107]
	v_lshlrev_b64 v[106:107], 14, v[112:113]
	v_lshlrev_b32_e32 v108, 16, v117
	v_and_b32_e32 v109, 0xffff0000, v117
	v_lshl_add_u64 v[106:107], s[66:67], 0, v[106:107]
	v_pk_fma_f32 v[94:95], v[94:95], v[156:157], v[108:109]
	v_lshl_add_u64 v[106:107], v[106:107], 0, v[140:141]
	global_store_dwordx4 v[106:107], v[92:95], off
	s_waitcnt vmcnt(11)
	s_nop 0
	v_lshlrev_b32_e32 v92, 16, v118
	v_and_b32_e32 v93, 0xffff0000, v118
	v_lshlrev_b32_e32 v94, 16, v119
	v_and_b32_e32 v95, 0xffff0000, v119
	v_pk_fma_f32 v[90:91], v[90:91], v[152:153], v[94:95]
	v_pk_fma_f32 v[88:89], v[88:89], v[150:151], v[92:93]
	global_store_dwordx4 v[106:107], v[88:91], off offset:64
	s_waitcnt vmcnt(11)
	s_nop 0
	v_lshlrev_b32_e32 v88, 16, v120
	v_and_b32_e32 v89, 0xffff0000, v120
	v_lshlrev_b32_e32 v90, 16, v121
	v_and_b32_e32 v91, 0xffff0000, v121
	v_pk_fma_f32 v[86:87], v[86:87], v[148:149], v[90:91]
	v_pk_fma_f32 v[84:85], v[84:85], v[146:147], v[88:89]
	global_store_dwordx4 v[106:107], v[84:87], off offset:512
	s_waitcnt vmcnt(11)
	s_nop 0
	v_lshlrev_b32_e32 v84, 16, v114
	v_and_b32_e32 v85, 0xffff0000, v114
	v_lshlrev_b32_e32 v86, 16, v115
	v_and_b32_e32 v87, 0xffff0000, v115
	v_pk_fma_f32 v[82:83], v[82:83], v[144:145], v[86:87]
	v_pk_fma_f32 v[80:81], v[80:81], v[142:143], v[84:85]
	global_store_dwordx4 v[106:107], v[80:83], off offset:576
	s_nop 1
	v_add_u32_e32 v80, 0x80, v158
	v_ashrrev_i32_e32 v81, 31, v80
	v_lshlrev_b64 v[82:83], 13, v[80:81]
	v_lshl_add_u64 v[82:83], s[6:7], 0, v[82:83]
	v_lshl_add_u64 v[82:83], v[82:83], 0, v[160:161]
	global_load_dwordx2 v[84:85], v[82:83], off
	global_load_dwordx2 v[86:87], v[82:83], off offset:32
	global_load_dwordx2 v[88:89], v[82:83], off offset:256
	s_nop 0
	global_load_dwordx2 v[82:83], v[82:83], off offset:288
	s_waitcnt vmcnt(11)
	v_lshlrev_b32_e32 v90, 16, v100
	v_and_b32_e32 v91, 0xffff0000, v100
	v_pk_fma_f32 v[76:77], v[76:77], v[154:155], v[90:91]
	v_lshlrev_b64 v[90:91], 14, v[96:97]
	v_lshlrev_b32_e32 v92, 16, v101
	v_and_b32_e32 v93, 0xffff0000, v101
	v_lshl_add_u64 v[90:91], s[66:67], 0, v[90:91]
	v_pk_fma_f32 v[78:79], v[78:79], v[156:157], v[92:93]
	v_lshl_add_u64 v[90:91], v[90:91], 0, v[140:141]
	global_store_dwordx4 v[90:91], v[76:79], off
	s_waitcnt vmcnt(11)
	s_nop 0
	v_lshlrev_b32_e32 v76, 16, v102
	v_and_b32_e32 v77, 0xffff0000, v102
	v_lshlrev_b32_e32 v78, 16, v103
	v_and_b32_e32 v79, 0xffff0000, v103
	v_pk_fma_f32 v[74:75], v[74:75], v[152:153], v[78:79]
	v_pk_fma_f32 v[72:73], v[72:73], v[150:151], v[76:77]
	global_store_dwordx4 v[90:91], v[72:75], off offset:64
	s_waitcnt vmcnt(11)
	s_nop 0
	v_lshlrev_b32_e32 v72, 16, v104
	v_and_b32_e32 v73, 0xffff0000, v104
	v_lshlrev_b32_e32 v74, 16, v105
	v_and_b32_e32 v75, 0xffff0000, v105
	v_pk_fma_f32 v[70:71], v[70:71], v[148:149], v[74:75]
	v_pk_fma_f32 v[68:69], v[68:69], v[146:147], v[72:73]
	global_store_dwordx4 v[90:91], v[68:71], off offset:512
	s_waitcnt vmcnt(11)
	s_nop 0
	v_lshlrev_b32_e32 v68, 16, v98
	v_and_b32_e32 v69, 0xffff0000, v98
	v_lshlrev_b32_e32 v70, 16, v99
	v_and_b32_e32 v71, 0xffff0000, v99
	v_pk_fma_f32 v[66:67], v[66:67], v[144:145], v[70:71]
	v_pk_fma_f32 v[64:65], v[64:65], v[142:143], v[68:69]
	global_store_dwordx4 v[90:91], v[64:67], off offset:576
	s_nop 1
	v_add_u32_e32 v64, 0x90, v158
	v_ashrrev_i32_e32 v65, 31, v64
	v_lshlrev_b64 v[66:67], 13, v[64:65]
	v_lshl_add_u64 v[66:67], s[6:7], 0, v[66:67]
	v_lshl_add_u64 v[66:67], v[66:67], 0, v[160:161]
	global_load_dwordx2 v[68:69], v[66:67], off
	global_load_dwordx2 v[70:71], v[66:67], off offset:32
	global_load_dwordx2 v[72:73], v[66:67], off offset:256
	global_load_dwordx2 v[74:75], v[66:67], off offset:288
	s_waitcnt vmcnt(11)
	v_lshlrev_b32_e32 v66, 16, v84
	v_and_b32_e32 v67, 0xffff0000, v84
	v_pk_fma_f32 v[60:61], v[60:61], v[154:155], v[66:67]
	v_lshlrev_b64 v[66:67], 14, v[80:81]
	v_lshlrev_b32_e32 v76, 16, v85
	v_and_b32_e32 v77, 0xffff0000, v85
	v_lshl_add_u64 v[66:67], s[66:67], 0, v[66:67]
	v_pk_fma_f32 v[62:63], v[62:63], v[156:157], v[76:77]
	v_lshl_add_u64 v[66:67], v[66:67], 0, v[140:141]
	global_store_dwordx4 v[66:67], v[60:63], off
	s_waitcnt vmcnt(11)
	s_nop 0
	v_lshlrev_b32_e32 v60, 16, v86
	v_and_b32_e32 v61, 0xffff0000, v86
	v_lshlrev_b32_e32 v62, 16, v87
	v_and_b32_e32 v63, 0xffff0000, v87
	v_pk_fma_f32 v[58:59], v[58:59], v[152:153], v[62:63]
	v_pk_fma_f32 v[56:57], v[56:57], v[150:151], v[60:61]
	global_store_dwordx4 v[66:67], v[56:59], off offset:64
	s_waitcnt vmcnt(11)
	s_nop 0
	v_lshlrev_b32_e32 v56, 16, v88
	v_and_b32_e32 v57, 0xffff0000, v88
	v_lshlrev_b32_e32 v58, 16, v89
	v_and_b32_e32 v59, 0xffff0000, v89
	v_pk_fma_f32 v[54:55], v[54:55], v[148:149], v[58:59]
	v_pk_fma_f32 v[52:53], v[52:53], v[146:147], v[56:57]
	global_store_dwordx4 v[66:67], v[52:55], off offset:512
	s_waitcnt vmcnt(11)
	s_nop 0
	v_lshlrev_b32_e32 v52, 16, v82
	v_and_b32_e32 v53, 0xffff0000, v82
	v_lshlrev_b32_e32 v54, 16, v83
	v_and_b32_e32 v55, 0xffff0000, v83
	v_pk_fma_f32 v[50:51], v[50:51], v[144:145], v[54:55]
	v_pk_fma_f32 v[48:49], v[48:49], v[142:143], v[52:53]
	global_store_dwordx4 v[66:67], v[48:51], off offset:576
	s_nop 1
	v_add_u32_e32 v48, 0xa0, v158
	v_ashrrev_i32_e32 v49, 31, v48
	v_lshlrev_b64 v[50:51], 13, v[48:49]
	v_lshl_add_u64 v[50:51], s[6:7], 0, v[50:51]
	v_lshl_add_u64 v[50:51], v[50:51], 0, v[160:161]
	global_load_dwordx2 v[52:53], v[50:51], off
	global_load_dwordx2 v[54:55], v[50:51], off offset:32
	global_load_dwordx2 v[56:57], v[50:51], off offset:256
	global_load_dwordx2 v[58:59], v[50:51], off offset:288
	s_waitcnt vmcnt(11)
	v_lshlrev_b32_e32 v50, 16, v68
	v_and_b32_e32 v51, 0xffff0000, v68
	v_pk_fma_f32 v[44:45], v[44:45], v[154:155], v[50:51]
	v_lshlrev_b64 v[50:51], 14, v[64:65]
	v_lshlrev_b32_e32 v60, 16, v69
	v_and_b32_e32 v61, 0xffff0000, v69
	v_lshl_add_u64 v[50:51], s[66:67], 0, v[50:51]
	v_pk_fma_f32 v[46:47], v[46:47], v[156:157], v[60:61]
	v_lshl_add_u64 v[50:51], v[50:51], 0, v[140:141]
	global_store_dwordx4 v[50:51], v[44:47], off
	s_waitcnt vmcnt(11)
	s_nop 0
	v_lshlrev_b32_e32 v44, 16, v70
	v_and_b32_e32 v45, 0xffff0000, v70
	v_lshlrev_b32_e32 v46, 16, v71
	v_and_b32_e32 v47, 0xffff0000, v71
	v_pk_fma_f32 v[42:43], v[42:43], v[152:153], v[46:47]
	v_pk_fma_f32 v[40:41], v[40:41], v[150:151], v[44:45]
	global_store_dwordx4 v[50:51], v[40:43], off offset:64
	s_waitcnt vmcnt(11)
	s_nop 0
	v_lshlrev_b32_e32 v40, 16, v72
	v_and_b32_e32 v41, 0xffff0000, v72
	v_lshlrev_b32_e32 v42, 16, v73
	v_and_b32_e32 v43, 0xffff0000, v73
	v_pk_fma_f32 v[38:39], v[38:39], v[148:149], v[42:43]
	v_pk_fma_f32 v[36:37], v[36:37], v[146:147], v[40:41]
	global_store_dwordx4 v[50:51], v[36:39], off offset:512
	s_waitcnt vmcnt(11)
	s_nop 0
	v_lshlrev_b32_e32 v36, 16, v74
	v_and_b32_e32 v37, 0xffff0000, v74
	v_lshlrev_b32_e32 v38, 16, v75
	v_and_b32_e32 v39, 0xffff0000, v75
	v_pk_fma_f32 v[34:35], v[34:35], v[144:145], v[38:39]
	v_pk_fma_f32 v[32:33], v[32:33], v[142:143], v[36:37]
	global_store_dwordx4 v[50:51], v[32:35], off offset:576
	s_nop 1
	v_add_u32_e32 v32, 0xb0, v158
	v_ashrrev_i32_e32 v33, 31, v32
	v_lshlrev_b64 v[34:35], 13, v[32:33]
	v_lshl_add_u64 v[34:35], s[6:7], 0, v[34:35]
	v_lshl_add_u64 v[34:35], v[34:35], 0, v[160:161]
	global_load_dwordx2 v[36:37], v[34:35], off
	global_load_dwordx2 v[38:39], v[34:35], off offset:32
	global_load_dwordx2 v[40:41], v[34:35], off offset:256
	global_load_dwordx2 v[42:43], v[34:35], off offset:288
	s_waitcnt vmcnt(11)
	v_lshlrev_b32_e32 v34, 16, v52
	v_and_b32_e32 v35, 0xffff0000, v52
	v_pk_fma_f32 v[28:29], v[28:29], v[154:155], v[34:35]
	v_lshlrev_b64 v[34:35], 14, v[48:49]
	v_lshlrev_b32_e32 v44, 16, v53
	v_and_b32_e32 v45, 0xffff0000, v53
	v_lshl_add_u64 v[34:35], s[66:67], 0, v[34:35]
	v_pk_fma_f32 v[30:31], v[30:31], v[156:157], v[44:45]
	v_lshl_add_u64 v[34:35], v[34:35], 0, v[140:141]
	global_store_dwordx4 v[34:35], v[28:31], off
	s_waitcnt vmcnt(11)
	s_nop 0
	v_lshlrev_b32_e32 v28, 16, v54
	v_and_b32_e32 v29, 0xffff0000, v54
	v_lshlrev_b32_e32 v30, 16, v55
	v_and_b32_e32 v31, 0xffff0000, v55
	v_pk_fma_f32 v[26:27], v[26:27], v[152:153], v[30:31]
	v_pk_fma_f32 v[24:25], v[24:25], v[150:151], v[28:29]
	global_store_dwordx4 v[34:35], v[24:27], off offset:64
	s_waitcnt vmcnt(11)
	s_nop 0
	v_lshlrev_b32_e32 v24, 16, v56
	v_and_b32_e32 v25, 0xffff0000, v56
	v_lshlrev_b32_e32 v26, 16, v57
	v_and_b32_e32 v27, 0xffff0000, v57
	v_pk_fma_f32 v[22:23], v[22:23], v[148:149], v[26:27]
	v_pk_fma_f32 v[20:21], v[20:21], v[146:147], v[24:25]
	global_store_dwordx4 v[34:35], v[20:23], off offset:512
	s_waitcnt vmcnt(11)
	s_nop 0
	v_lshlrev_b32_e32 v20, 16, v58
	v_and_b32_e32 v21, 0xffff0000, v58
	v_lshlrev_b32_e32 v22, 16, v59
	v_and_b32_e32 v23, 0xffff0000, v59
	v_pk_fma_f32 v[14:15], v[14:15], v[144:145], v[22:23]
	v_pk_fma_f32 v[12:13], v[12:13], v[142:143], v[20:21]
	global_store_dwordx4 v[34:35], v[12:15], off offset:576
	s_waitcnt vmcnt(7)
	s_nop 0
	v_lshlrev_b32_e32 v12, 16, v36
	v_and_b32_e32 v13, 0xffff0000, v36
	v_pk_fma_f32 v[12:13], v[16:17], v[154:155], v[12:13]
	v_lshlrev_b64 v[16:17], 14, v[32:33]
	v_lshlrev_b32_e32 v14, 16, v37
	v_and_b32_e32 v15, 0xffff0000, v37
	v_lshl_add_u64 v[16:17], s[66:67], 0, v[16:17]
	v_pk_fma_f32 v[14:15], v[18:19], v[156:157], v[14:15]
	v_lshl_add_u64 v[16:17], v[16:17], 0, v[140:141]
	global_store_dwordx4 v[16:17], v[12:15], off
	s_waitcnt vmcnt(7)
	s_nop 0
	v_lshlrev_b32_e32 v12, 16, v38
	v_and_b32_e32 v13, 0xffff0000, v38
	v_lshlrev_b32_e32 v14, 16, v39
	v_and_b32_e32 v15, 0xffff0000, v39
	v_pk_fma_f32 v[10:11], v[10:11], v[152:153], v[14:15]
	v_pk_fma_f32 v[8:9], v[8:9], v[150:151], v[12:13]
	global_store_dwordx4 v[16:17], v[8:11], off offset:64
	s_waitcnt vmcnt(7)
	s_nop 0
	v_lshlrev_b32_e32 v8, 16, v40
	v_and_b32_e32 v9, 0xffff0000, v40
	v_lshlrev_b32_e32 v10, 16, v41
	v_and_b32_e32 v11, 0xffff0000, v41
	v_pk_fma_f32 v[6:7], v[6:7], v[148:149], v[10:11]
	v_pk_fma_f32 v[4:5], v[4:5], v[146:147], v[8:9]
	global_store_dwordx4 v[16:17], v[4:7], off offset:512
	s_waitcnt vmcnt(7)
	s_nop 0
	v_lshlrev_b32_e32 v4, 16, v42
	v_and_b32_e32 v5, 0xffff0000, v42
	v_lshlrev_b32_e32 v6, 16, v43
	v_and_b32_e32 v7, 0xffff0000, v43
	v_pk_fma_f32 v[2:3], v[2:3], v[144:145], v[6:7]
	v_pk_fma_f32 v[0:1], v[0:1], v[142:143], v[4:5]
	global_store_dwordx4 v[16:17], v[0:3], off offset:576
	s_andn2_b64 vcc, exec, s[0:1]
	s_mov_b64 s[0:1], -1
	s_cbranch_vccnz .LBB0_1090
	s_mov_b32 s98, 1
	s_andn2_b64 vcc, exec, s[4:5]
	s_cbranch_vccnz .LBB0_1089
	s_barrier
	s_branch .LBB0_1089

	.amdhsa_kernel _Z6mk_fwd4Args
		.amdhsa_group_segment_fixed_size 0
		.amdhsa_private_segment_fixed_size 0
		.amdhsa_kernarg_size 448
		.amdhsa_user_sgpr_count 2
		.amdhsa_user_sgpr_dispatch_ptr 0
		.amdhsa_user_sgpr_queue_ptr 0
		.amdhsa_user_sgpr_kernarg_segment_ptr 1
		.amdhsa_user_sgpr_dispatch_id 0
		.amdhsa_user_sgpr_kernarg_preload_length 0
		.amdhsa_user_sgpr_kernarg_preload_offset 0
		.amdhsa_user_sgpr_private_segment_size 0
		.amdhsa_uses_dynamic_stack 0
		.amdhsa_enable_private_segment 0
		.amdhsa_system_sgpr_workgroup_id_x 1
		.amdhsa_system_sgpr_workgroup_id_y 0
		.amdhsa_system_sgpr_workgroup_id_z 0
		.amdhsa_system_sgpr_workgroup_info 0
		.amdhsa_system_vgpr_workitem_id 0
		.amdhsa_next_free_vgpr 256
		.amdhsa_next_free_sgpr 102
		.amdhsa_accum_offset 256
		.amdhsa_reserve_vcc 1
		.amdhsa_float_round_mode_32 0
		.amdhsa_float_round_mode_16_64 0
		.amdhsa_float_denorm_mode_32 3
		.amdhsa_float_denorm_mode_16_64 3
		.amdhsa_dx10_clamp 1
		.amdhsa_ieee_mode 1
		.amdhsa_fp16_overflow 0
		.amdhsa_tg_split 0
		.amdhsa_exception_fp_ieee_invalid_op 0
		.amdhsa_exception_fp_denorm_src 0
		.amdhsa_exception_fp_ieee_div_zero 0
		.amdhsa_exception_fp_ieee_overflow 0
		.amdhsa_exception_fp_ieee_underflow 0
		.amdhsa_exception_fp_ieee_inexact 0
		.amdhsa_exception_int_div_zero 0
	.end_amdhsa_kernel

amdhsa.kernels:
  - .agpr_count:     0
    .args:
      - .offset:         0
        .size:           192
        .value_kind:     by_value
      - .offset:         192
        .size:           4
        .value_kind:     hidden_block_count_x
      - .offset:         196
        .size:           4
        .value_kind:     hidden_block_count_y
      - .offset:         200
        .size:           4
        .value_kind:     hidden_block_count_z
      - .offset:         204
        .size:           2
        .value_kind:     hidden_group_size_x
      - .offset:         206
        .size:           2
        .value_kind:     hidden_group_size_y
      - .offset:         208
        .size:           2
        .value_kind:     hidden_group_size_z
      - .offset:         210
        .size:           2
        .value_kind:     hidden_remainder_x
      - .offset:         212
        .size:           2
        .value_kind:     hidden_remainder_y
      - .offset:         214
        .size:           2
        .value_kind:     hidden_remainder_z
      - .offset:         232
        .size:           8
        .value_kind:     hidden_global_offset_x
      - .offset:         240
        .size:           8
        .value_kind:     hidden_global_offset_y
      - .offset:         248
        .size:           8
        .value_kind:     hidden_global_offset_z
      - .offset:         256
        .size:           2
        .value_kind:     hidden_grid_dims
      - .offset:         312
        .size:           4
        .value_kind:     hidden_dynamic_lds_size
    .group_segment_fixed_size: 0
    .kernarg_segment_align: 8
    .kernarg_segment_size: 448
    .language:       OpenCL C
    .language_version:
      - 2
      - 0
    .max_flat_workgroup_size: 512
    .name:           _Z6mk_fwd4Args
    .private_segment_fixed_size: 0
    .sgpr_count:     108
    .sgpr_spill_count: 121
    .symbol:         _Z6mk_fwd4Args.kd
    .uniform_work_group_size: 1
    .uses_dynamic_stack: false
    .vgpr_count:     256
    .vgpr_spill_count: 0
    .wavefront_size: 64
